# attention loops gen2: clamp only when needed (max3 check in PV phase), running DMA pointers, fewer waits; all unit-scale fp8 MFMAs without scale prefix
# speedup vs baseline: 1.0759x; 1.0392x over previous
.LBB0_639:
	s_waitcnt vmcnt(20)
	s_nop 0
	v_mfma_f32_32x32x64_f8f6f4 v[2:17], v[106:113], v[66:73], v[2:17]
	s_and_b64 s[28:29], s[20:21], exec
	s_mov_b32 s29, s17
	s_cselect_b32 s16, s22, 0x380
	s_cselect_b32 s28, s23, 0x380
	s_mov_b32 s31, s17
	s_cselect_b32 s30, s24, 0x380
	v_lshl_add_u64 v[194:195], v[186:187], 0, s[30:31]
	v_lshl_add_u64 v[196:197], v[188:189], 0, s[30:31]
	v_cndmask_b32_e64 v193, 0, 1, s[20:21]
	v_cmp_ne_u32_e32 vcc, 1, v193
	s_mov_b64 s[20:21], 0
	s_and_b64 vcc, exec, vcc
	s_waitcnt vmcnt(16)
	v_mfma_f32_32x32x64_f8f6f4 v[2:17], v[90:97], v[50:57], v[2:17]
	s_waitcnt vmcnt(12)
	v_mfma_f32_32x32x64_f8f6f4 v[2:17], v[114:121], v[74:81], v[2:17]
	s_waitcnt vmcnt(8)
	v_mfma_f32_32x32x64_f8f6f4 v[2:17], v[82:89], v[34:41], v[2:17]
	v_lshl_add_u64 v[34:35], v[186:187], 0, s[16:17]
	v_lshl_add_u64 v[36:37], v[188:189], 0, s[16:17]
	v_lshl_add_u64 v[38:39], v[186:187], 0, s[28:29]
	v_lshl_add_u64 v[86:87], v[188:189], 0, s[28:29]
	global_load_dwordx4 v[66:69], v[34:35], off
	global_load_dwordx4 v[70:73], v[34:35], off offset:16
	global_load_dwordx4 v[106:109], v[36:37], off
	global_load_dwordx4 v[110:113], v[36:37], off offset:16
	global_load_dwordx4 v[50:53], v[34:35], off offset:32
	s_waitcnt vmcnt(9)
	v_mfma_f32_32x32x64_f8f6f4 v[2:17], v[130:137], v[42:49], v[2:17]
	global_load_dwordx4 v[54:57], v[34:35], off offset:48
	global_load_dwordx4 v[90:93], v[36:37], off offset:32
	global_load_dwordx4 v[94:97], v[36:37], off offset:48
	global_load_dwordx4 v[74:77], v[38:39], off
	global_load_dwordx4 v[78:81], v[38:39], off offset:16
	global_load_dwordx4 v[114:117], v[86:87], off
	global_load_dwordx4 v[118:121], v[86:87], off offset:16
	s_nop 0
	global_load_dwordx4 v[34:37], v[38:39], off offset:32
	s_nop 0
	global_load_dwordx4 v[38:41], v[38:39], off offset:48
	s_nop 0
	global_load_dwordx4 v[82:85], v[86:87], off offset:32
	s_nop 0
	global_load_dwordx4 v[86:89], v[86:87], off offset:48
	s_nop 0
	global_load_dwordx4 v[42:45], v[194:195], off
	global_load_dwordx4 v[46:49], v[194:195], off offset:16
	global_load_dwordx4 v[130:133], v[196:197], off
	global_load_dwordx4 v[134:137], v[196:197], off offset:16
	s_waitcnt vmcnt(20)
	v_mfma_f32_32x32x64_f8f6f4 v[2:17], v[26:33], v[18:25], v[2:17]
	global_load_dwordx4 v[18:21], v[194:195], off offset:32
	global_load_dwordx4 v[22:25], v[194:195], off offset:48
	global_load_dwordx4 v[26:29], v[196:197], off offset:32
	global_load_dwordx4 v[30:33], v[196:197], off offset:48
	s_waitcnt vmcnt(32)
	v_mfma_f32_32x32x64_f8f6f4 v[2:17], v[138:145], v[98:105], v[2:17]
	s_waitcnt vmcnt(29)
	v_mov_b32_e32 v98, v154
	v_mov_b32_e32 v99, v155
	v_mov_b32_e32 v100, v156
	v_mov_b32_e32 v101, v157
	s_waitcnt vmcnt(28)
	v_mov_b32_e32 v102, v158
	v_mov_b32_e32 v103, v159
	v_mov_b32_e32 v104, v160
	v_mov_b32_e32 v105, v161
	s_waitcnt vmcnt(25)
	v_mov_b32_e32 v138, v170
	v_mov_b32_e32 v139, v171
	v_mov_b32_e32 v140, v172
	v_mov_b32_e32 v141, v173
	s_waitcnt vmcnt(24)
	v_mov_b32_e32 v142, v174
	v_mov_b32_e32 v143, v175
	v_mov_b32_e32 v144, v176
	v_mfma_f32_32x32x64_f8f6f4 v[2:17], v[122:129], v[58:65], v[2:17]
	v_mov_b32_e32 v145, v177
	v_mov_b32_e32 v58, v146
	v_mov_b32_e32 v59, v147
	v_mov_b32_e32 v60, v148
	v_mov_b32_e32 v61, v149
	v_mov_b32_e32 v62, v150
	v_mov_b32_e32 v63, v151
	v_mov_b32_e32 v64, v152
	v_mov_b32_e32 v65, v153
	v_mov_b32_e32 v122, v162
	v_mov_b32_e32 v123, v163
	v_mov_b32_e32 v124, v164
	v_mov_b32_e32 v125, v165
	v_mov_b32_e32 v126, v166
	v_mov_b32_e32 v127, v167
	v_mov_b32_e32 v128, v168
	v_mov_b32_e32 v129, v169
	s_cbranch_vccz .LBB0_639
	s_nop 1
	v_pk_mul_f32 v[4:5], v[4:5], s[18:19] op_sel_hi:[1,0]
	v_pk_mul_f32 v[2:3], v[2:3], s[18:19] op_sel_hi:[1,0]
	s_waitcnt vmcnt(3)
	v_or_b32_e32 v18, v185, v178
	v_cvt_pk_bf16_f32 v2, v2, v3
	v_cvt_pk_bf16_f32 v3, v4, v5
	v_mov_b64_e32 v[4:5], s[10:11]
	v_mad_i64_i32 v[4:5], s[20:21], v184, s25, v[4:5]
	v_ashrrev_i32_e32 v19, 31, v18
	v_lshl_add_u64 v[4:5], v[18:19], 1, v[4:5]
	global_store_dwordx2 v[4:5], v[2:3], off
	v_pk_mul_f32 v[2:3], v[8:9], s[18:19] op_sel_hi:[1,0]
	v_pk_mul_f32 v[6:7], v[6:7], s[18:19] op_sel_hi:[1,0]
	v_add_u32_e32 v1, s54, v1
	v_cvt_pk_bf16_f32 v6, v6, v7
	v_cvt_pk_bf16_f32 v7, v2, v3
	global_store_dwordx2 v[4:5], v[6:7], off offset:16
	v_pk_mul_f32 v[2:3], v[12:13], s[18:19] op_sel_hi:[1,0]
	v_pk_mul_f32 v[6:7], v[10:11], s[18:19] op_sel_hi:[1,0]
	v_cmp_lt_i32_e32 vcc, s26, v1
	v_cvt_pk_bf16_f32 v6, v6, v7
	v_cvt_pk_bf16_f32 v7, v2, v3
	global_store_dwordx2 v[4:5], v[6:7], off offset:32
	v_pk_mul_f32 v[2:3], v[16:17], s[18:19] op_sel_hi:[1,0]
	v_pk_mul_f32 v[6:7], v[14:15], s[18:19] op_sel_hi:[1,0]
	s_or_b64 s[14:15], vcc, s[14:15]
	v_cvt_pk_bf16_f32 v6, v6, v7
	v_cvt_pk_bf16_f32 v7, v2, v3
	global_store_dwordx2 v[4:5], v[6:7], off offset:48
	s_andn2_b64 exec, exec, s[14:15]
	s_cbranch_execnz .LBB0_638

.LBB0_648:
	ds_read_b128 v[2:5], v167
	ds_read_b128 v[6:9], v171
	ds_read_b128 v[10:13], v172
	ds_read_b128 v[14:17], v173
	s_add_u32 s30, s28, 0xfffe0080
	s_addc_u32 s31, s29, -1
	s_cmp_eq_u32 s68, 4
	s_cselect_b32 s35, s21, s31
	s_cselect_b32 s34, s62, s30
	s_cselect_b32 s31, s19, s65
	s_cselect_b32 s30, s63, s64
	v_lshl_add_u64 v[158:159], s[28:29], 0, v[152:153]
	s_add_i32 m0, s27, 0xc000
	ds_read_b128 v[186:189], v184
	ds_read_b128 v[190:193], v184 offset:1024
	ds_read_b128 v[194:197], v184 offset:2048
	ds_read_b128 v[198:201], v184 offset:3072
	ds_read_b128 v[202:205], v184 offset:4096
	ds_read_b128 v[206:209], v184 offset:5120
	ds_read_b128 v[210:213], v184 offset:6144
	ds_read_b128 v[214:217], v184 offset:7168
	global_load_lds_dwordx4 v[158:159], off
	v_lshl_add_u64 v[158:159], s[28:29], 0, v[150:151]
	s_add_i32 m0, s27, 0xe000
	s_nop 0
	global_load_lds_dwordx4 v[158:159], off
	s_waitcnt lgkmcnt(8)
	s_barrier
	s_waitcnt lgkmcnt(0)
	s_setprio 1
	s_waitcnt lgkmcnt(0)
	v_mfma_f32_16x16x128_f8f6f4 v[142:145], v[2:9], v[186:193], v[142:145]
	v_mfma_f32_16x16x128_f8f6f4 v[138:141], v[10:17], v[186:193], v[138:141]
	v_mfma_f32_16x16x128_f8f6f4 v[134:137], v[2:9], v[194:201], v[134:137]
	v_mfma_f32_16x16x128_f8f6f4 v[126:129], v[10:17], v[194:201], v[126:129]
	v_mfma_f32_16x16x128_f8f6f4 v[118:121], v[2:9], v[202:209], v[118:121]
	v_mfma_f32_16x16x128_f8f6f4 v[110:113], v[10:17], v[202:209], v[110:113]
	v_mfma_f32_16x16x128_f8f6f4 v[102:105], v[2:9], v[210:217], v[102:105]
	v_mfma_f32_16x16x128_f8f6f4 v[94:97], v[10:17], v[210:217], v[94:97]
	s_setprio 0
	s_barrier
	s_mov_b32 m0, s37
	v_lshl_add_u64 v[158:159], s[30:31], 0, v[148:149]
	ds_read_b128 v[220:223], v168
	ds_read_b128 v[224:227], v174
	ds_read_b128 v[228:231], v175
	ds_read_b128 v[232:235], v176
	global_load_lds_dwordx4 v[158:159], off
	v_lshl_add_u64 v[160:161], s[30:31], 0, v[146:147]
	s_mov_b32 m0, s38
	s_nop 0
	global_load_lds_dwordx4 v[160:161], off
	s_barrier
	s_waitcnt lgkmcnt(0)
	s_setprio 1
	s_waitcnt lgkmcnt(0)
	v_mfma_f32_16x16x128_f8f6f4 v[130:133], v[220:227], v[186:193], v[130:133]
	v_mfma_f32_16x16x128_f8f6f4 v[122:125], v[228:235], v[186:193], v[122:125]
	v_mfma_f32_16x16x128_f8f6f4 v[114:117], v[220:227], v[194:201], v[114:117]
	v_mfma_f32_16x16x128_f8f6f4 v[106:109], v[228:235], v[194:201], v[106:109]
	v_mfma_f32_16x16x128_f8f6f4 v[98:101], v[220:227], v[202:209], v[98:101]
	v_mfma_f32_16x16x128_f8f6f4 v[90:93], v[228:235], v[202:209], v[90:93]
	v_mfma_f32_16x16x128_f8f6f4 v[86:89], v[220:227], v[210:217], v[86:89]
	v_mfma_f32_16x16x128_f8f6f4 v[82:85], v[228:235], v[210:217], v[82:85]
	s_setprio 0
	s_mov_b32 m0, s27
	v_lshl_add_u64 v[162:163], s[34:35], 0, v[148:149]
	s_barrier
	ds_read_b128 v[186:189], v184 offset:16384
	ds_read_b128 v[190:193], v184 offset:17408
	ds_read_b128 v[194:197], v184 offset:18432
	ds_read_b128 v[198:201], v184 offset:19456
	ds_read_b128 v[202:205], v184 offset:20480
	ds_read_b128 v[206:209], v184 offset:21504
	ds_read_b128 v[210:213], v184 offset:22528
	ds_read_b128 v[214:217], v184 offset:23552
	global_load_lds_dwordx4 v[162:163], off
	v_lshl_add_u64 v[164:165], s[34:35], 0, v[146:147]
	s_mov_b32 m0, s39
	s_nop 0
	global_load_lds_dwordx4 v[164:165], off
	s_barrier
	s_waitcnt lgkmcnt(0)
	s_setprio 1
	s_waitcnt lgkmcnt(0)
	v_mfma_f32_16x16x128_f8f6f4 v[78:81], v[2:9], v[186:193], v[78:81]
	v_mfma_f32_16x16x128_f8f6f4 v[74:77], v[10:17], v[186:193], v[74:77]
	v_mfma_f32_16x16x128_f8f6f4 v[70:73], v[2:9], v[194:201], v[70:73]
	v_mfma_f32_16x16x128_f8f6f4 v[62:65], v[10:17], v[194:201], v[62:65]
	v_mfma_f32_16x16x128_f8f6f4 v[54:57], v[2:9], v[202:209], v[54:57]
	v_mfma_f32_16x16x128_f8f6f4 v[46:49], v[10:17], v[202:209], v[46:49]
	v_mfma_f32_16x16x128_f8f6f4 v[38:41], v[2:9], v[210:217], v[38:41]
	v_mfma_f32_16x16x128_f8f6f4 v[30:33], v[10:17], v[210:217], v[30:33]
	s_setprio 0
	s_barrier
	s_add_u32 s70, s30, 0x20000
	s_addc_u32 s71, s31, 0
	s_mov_b32 m0, s40
	v_lshl_add_u64 v[2:3], s[70:71], 0, v[148:149]
	global_load_lds_dwordx4 v[2:3], off
	v_lshl_add_u64 v[2:3], s[70:71], 0, v[146:147]
	s_mov_b32 m0, s41
	s_nop 0
	global_load_lds_dwordx4 v[2:3], off
	s_waitcnt vmcnt(6)
	s_barrier
	s_setprio 1
	v_mfma_f32_16x16x128_f8f6f4 v[66:69], v[220:227], v[186:193], v[66:69]
	v_mfma_f32_16x16x128_f8f6f4 v[58:61], v[228:235], v[186:193], v[58:61]
	v_mfma_f32_16x16x128_f8f6f4 v[50:53], v[220:227], v[194:201], v[50:53]
	v_mfma_f32_16x16x128_f8f6f4 v[42:45], v[228:235], v[194:201], v[42:45]
	v_mfma_f32_16x16x128_f8f6f4 v[34:37], v[220:227], v[202:209], v[34:37]
	v_mfma_f32_16x16x128_f8f6f4 v[26:29], v[228:235], v[202:209], v[26:29]
	v_mfma_f32_16x16x128_f8f6f4 v[22:25], v[220:227], v[210:217], v[22:25]
	v_mfma_f32_16x16x128_f8f6f4 v[18:21], v[228:235], v[210:217], v[18:21]
	s_setprio 0
	s_barrier
	ds_read_b128 v[2:5], v169
	ds_read_b128 v[6:9], v177
	ds_read_b128 v[10:13], v178
	ds_read_b128 v[14:17], v179
	s_add_u32 s34, s34, 0x20000
	s_addc_u32 s35, s35, 0
	s_mov_b32 m0, s42
	v_lshl_add_u64 v[220:221], s[34:35], 0, v[148:149]
	ds_read_b128 v[186:189], v184 offset:32768
	ds_read_b128 v[190:193], v184 offset:33792
	ds_read_b128 v[194:197], v184 offset:34816
	ds_read_b128 v[198:201], v184 offset:35840
	ds_read_b128 v[202:205], v184 offset:36864
	ds_read_b128 v[206:209], v184 offset:37888
	ds_read_b128 v[210:213], v184 offset:38912
	ds_read_b128 v[214:217], v184 offset:39936
	global_load_lds_dwordx4 v[220:221], off
	v_lshl_add_u64 v[220:221], s[34:35], 0, v[146:147]
	s_mov_b32 m0, s43
	s_nop 0
	global_load_lds_dwordx4 v[220:221], off
	s_waitcnt lgkmcnt(8)
	s_barrier
	s_waitcnt lgkmcnt(0)
	s_setprio 1
	s_waitcnt lgkmcnt(0)
	v_mfma_f32_16x16x128_f8f6f4 v[142:145], v[2:9], v[186:193], v[142:145]
	v_mfma_f32_16x16x128_f8f6f4 v[138:141], v[10:17], v[186:193], v[138:141]
	v_mfma_f32_16x16x128_f8f6f4 v[134:137], v[2:9], v[194:201], v[134:137]
	v_mfma_f32_16x16x128_f8f6f4 v[126:129], v[10:17], v[194:201], v[126:129]
	v_mfma_f32_16x16x128_f8f6f4 v[118:121], v[2:9], v[202:209], v[118:121]
	v_mfma_f32_16x16x128_f8f6f4 v[110:113], v[10:17], v[202:209], v[110:113]
	v_mfma_f32_16x16x128_f8f6f4 v[102:105], v[2:9], v[210:217], v[102:105]
	v_mfma_f32_16x16x128_f8f6f4 v[94:97], v[10:17], v[210:217], v[94:97]
	s_setprio 0
	s_barrier
	s_mov_b32 m0, s46
	v_lshl_add_u64 v[158:159], v[158:159], 0, s[14:15]
	ds_read_b128 v[220:223], v170
	ds_read_b128 v[224:227], v180
	ds_read_b128 v[228:231], v181
	ds_read_b128 v[232:235], v182
	global_load_lds_dwordx4 v[158:159], off
	v_lshl_add_u64 v[158:159], v[160:161], 0, s[14:15]
	s_mov_b32 m0, s47
	s_nop 0
	global_load_lds_dwordx4 v[158:159], off
	s_barrier
	s_waitcnt lgkmcnt(0)
	s_setprio 1
	s_waitcnt lgkmcnt(0)
	v_mfma_f32_16x16x128_f8f6f4 v[130:133], v[220:227], v[186:193], v[130:133]
	v_mfma_f32_16x16x128_f8f6f4 v[122:125], v[228:235], v[186:193], v[122:125]
	v_mfma_f32_16x16x128_f8f6f4 v[114:117], v[220:227], v[194:201], v[114:117]
	v_mfma_f32_16x16x128_f8f6f4 v[106:109], v[228:235], v[194:201], v[106:109]
	v_mfma_f32_16x16x128_f8f6f4 v[98:101], v[220:227], v[202:209], v[98:101]
	v_mfma_f32_16x16x128_f8f6f4 v[90:93], v[228:235], v[202:209], v[90:93]
	v_mfma_f32_16x16x128_f8f6f4 v[86:89], v[220:227], v[210:217], v[86:89]
	v_mfma_f32_16x16x128_f8f6f4 v[82:85], v[228:235], v[210:217], v[82:85]
	s_setprio 0
	s_mov_b32 m0, s48
	v_lshl_add_u64 v[158:159], v[162:163], 0, s[14:15]
	s_barrier
	ds_read_b128 v[186:189], v184 offset:49152
	ds_read_b128 v[190:193], v184 offset:50176
	ds_read_b128 v[194:197], v184 offset:51200
	ds_read_b128 v[198:201], v184 offset:52224
	ds_read_b128 v[202:205], v184 offset:53248
	ds_read_b128 v[206:209], v184 offset:54272
	ds_read_b128 v[210:213], v184 offset:55296
	ds_read_b128 v[214:217], v184 offset:56320
	global_load_lds_dwordx4 v[158:159], off
	v_lshl_add_u64 v[158:159], v[164:165], 0, s[14:15]
	s_mov_b32 m0, s49
	s_nop 0
	global_load_lds_dwordx4 v[158:159], off
	s_barrier
	s_waitcnt lgkmcnt(0)
	s_setprio 1
	s_waitcnt lgkmcnt(0)
	v_mfma_f32_16x16x128_f8f6f4 v[78:81], v[2:9], v[186:193], v[78:81]
	v_mfma_f32_16x16x128_f8f6f4 v[74:77], v[10:17], v[186:193], v[74:77]
	v_mfma_f32_16x16x128_f8f6f4 v[70:73], v[2:9], v[194:201], v[70:73]
	v_mfma_f32_16x16x128_f8f6f4 v[62:65], v[10:17], v[194:201], v[62:65]
	v_mfma_f32_16x16x128_f8f6f4 v[54:57], v[2:9], v[202:209], v[54:57]
	v_mfma_f32_16x16x128_f8f6f4 v[46:49], v[10:17], v[202:209], v[46:49]
	v_mfma_f32_16x16x128_f8f6f4 v[38:41], v[2:9], v[210:217], v[38:41]
	v_mfma_f32_16x16x128_f8f6f4 v[30:33], v[10:17], v[210:217], v[30:33]
	s_setprio 0
	s_barrier
	s_add_u32 s30, s30, 0x20080
	s_addc_u32 s31, s31, 0
	s_mov_b32 m0, s50
	v_lshl_add_u64 v[2:3], s[30:31], 0, v[148:149]
	global_load_lds_dwordx4 v[2:3], off
	v_lshl_add_u64 v[2:3], s[30:31], 0, v[146:147]
	s_mov_b32 m0, s51
	s_nop 0
	global_load_lds_dwordx4 v[2:3], off
	s_waitcnt vmcnt(6)
	s_barrier
	s_setprio 1
	v_mfma_f32_16x16x128_f8f6f4 v[66:69], v[220:227], v[186:193], v[66:69]
	v_mfma_f32_16x16x128_f8f6f4 v[58:61], v[228:235], v[186:193], v[58:61]
	v_mfma_f32_16x16x128_f8f6f4 v[50:53], v[220:227], v[194:201], v[50:53]
	v_mfma_f32_16x16x128_f8f6f4 v[42:45], v[228:235], v[194:201], v[42:45]
	v_mfma_f32_16x16x128_f8f6f4 v[34:37], v[220:227], v[202:209], v[34:37]
	v_mfma_f32_16x16x128_f8f6f4 v[26:29], v[228:235], v[202:209], v[26:29]
	v_mfma_f32_16x16x128_f8f6f4 v[22:25], v[220:227], v[210:217], v[22:25]
	v_mfma_f32_16x16x128_f8f6f4 v[18:21], v[228:235], v[210:217], v[18:21]
	s_setprio 0
	s_add_i32 s68, s68, 2
	s_add_u32 s64, s64, 0x100
	s_addc_u32 s65, s65, 0
	s_add_u32 s28, s28, 0x100
	s_addc_u32 s29, s29, 0
	s_cmp_gt_u32 s68, 5
	s_barrier
	s_cbranch_scc0 .LBB0_648
	v_lshl_or_b32 v4, s55, 8, v183
	v_pk_mul_f32 v[2:3], v[144:145], s[16:17] op_sel_hi:[1,0]
	v_pk_mul_f32 v[6:7], v[142:143], s[16:17] op_sel_hi:[1,0]
	v_lshl_add_u32 v12, s26, 8, v166
	v_cvt_pk_bf16_f32 v6, v6, v7
	v_cvt_pk_bf16_f32 v7, v2, v3
	v_mov_b64_e32 v[2:3], s[10:11]
	v_ashrrev_i32_e32 v5, 31, v4
	v_mad_i64_i32 v[8:9], s[28:29], v12, s53, v[2:3]
	v_lshlrev_b64 v[4:5], 1, v[4:5]
	v_lshl_add_u64 v[8:9], v[8:9], 0, v[4:5]
	s_nop 15
	s_nop 15
	global_store_dwordx2 v[8:9], v[6:7], off
	v_pk_mul_f32 v[6:7], v[140:141], s[16:17] op_sel_hi:[1,0]
	v_pk_mul_f32 v[10:11], v[138:139], s[16:17] op_sel_hi:[1,0]
	s_and_b64 vcc, exec, s[6:7]
	v_cvt_pk_bf16_f32 v10, v10, v11
	v_cvt_pk_bf16_f32 v11, v6, v7
	global_store_dwordx2 v[8:9], v[10:11], off offset:32
	v_pk_mul_f32 v[6:7], v[132:133], s[16:17] op_sel_hi:[1,0]
	v_pk_mul_f32 v[10:11], v[130:131], s[16:17] op_sel_hi:[1,0]
	s_mov_b32 s55, s18
	v_cvt_pk_bf16_f32 v10, v10, v11
	v_cvt_pk_bf16_f32 v11, v6, v7
	global_store_dwordx2 v[8:9], v[10:11], off offset:256
	v_pk_mul_f32 v[6:7], v[124:125], s[16:17] op_sel_hi:[1,0]
	v_pk_mul_f32 v[10:11], v[122:123], s[16:17] op_sel_hi:[1,0]
	s_mov_b32 s26, s20
	v_cvt_pk_bf16_f32 v10, v10, v11
	v_cvt_pk_bf16_f32 v11, v6, v7
	global_store_dwordx2 v[8:9], v[10:11], off offset:288
	v_or_b32_e32 v10, 16, v12
	v_pk_mul_f32 v[6:7], v[136:137], s[16:17] op_sel_hi:[1,0]
	v_pk_mul_f32 v[8:9], v[134:135], s[16:17] op_sel_hi:[1,0]
	s_mov_b64 s[30:31], s[22:23]
	v_cvt_pk_bf16_f32 v8, v8, v9
	v_cvt_pk_bf16_f32 v9, v6, v7
	v_mad_i64_i32 v[6:7], s[28:29], v10, s53, v[2:3]
	v_lshl_add_u64 v[6:7], v[6:7], 0, v[4:5]
	global_store_dwordx2 v[6:7], v[8:9], off
	v_pk_mul_f32 v[8:9], v[128:129], s[16:17] op_sel_hi:[1,0]
	v_pk_mul_f32 v[10:11], v[126:127], s[16:17] op_sel_hi:[1,0]
	s_nop 0
	v_cvt_pk_bf16_f32 v10, v10, v11
	v_cvt_pk_bf16_f32 v11, v8, v9
	global_store_dwordx2 v[6:7], v[10:11], off offset:32
	v_pk_mul_f32 v[8:9], v[116:117], s[16:17] op_sel_hi:[1,0]
	v_pk_mul_f32 v[10:11], v[114:115], s[16:17] op_sel_hi:[1,0]
	s_nop 0
	v_cvt_pk_bf16_f32 v10, v10, v11
	v_cvt_pk_bf16_f32 v11, v8, v9
	global_store_dwordx2 v[6:7], v[10:11], off offset:256
	v_pk_mul_f32 v[8:9], v[108:109], s[16:17] op_sel_hi:[1,0]
	v_pk_mul_f32 v[10:11], v[106:107], s[16:17] op_sel_hi:[1,0]
	s_nop 0
	v_cvt_pk_bf16_f32 v10, v10, v11
	v_cvt_pk_bf16_f32 v11, v8, v9
	global_store_dwordx2 v[6:7], v[10:11], off offset:288
	v_or_b32_e32 v10, 32, v12
	v_pk_mul_f32 v[6:7], v[120:121], s[16:17] op_sel_hi:[1,0]
	v_pk_mul_f32 v[8:9], v[118:119], s[16:17] op_sel_hi:[1,0]
	s_nop 0
	v_cvt_pk_bf16_f32 v8, v8, v9
	v_cvt_pk_bf16_f32 v9, v6, v7
	v_mad_i64_i32 v[6:7], s[28:29], v10, s53, v[2:3]
	v_lshl_add_u64 v[6:7], v[6:7], 0, v[4:5]
	global_store_dwordx2 v[6:7], v[8:9], off
	v_pk_mul_f32 v[8:9], v[112:113], s[16:17] op_sel_hi:[1,0]
	v_pk_mul_f32 v[10:11], v[110:111], s[16:17] op_sel_hi:[1,0]
	s_nop 0
	v_cvt_pk_bf16_f32 v10, v10, v11
	v_cvt_pk_bf16_f32 v11, v8, v9
	global_store_dwordx2 v[6:7], v[10:11], off offset:32
	v_pk_mul_f32 v[8:9], v[100:101], s[16:17] op_sel_hi:[1,0]
	v_pk_mul_f32 v[10:11], v[98:99], s[16:17] op_sel_hi:[1,0]
	s_nop 0
	v_cvt_pk_bf16_f32 v10, v10, v11
	v_cvt_pk_bf16_f32 v11, v8, v9
	global_store_dwordx2 v[6:7], v[10:11], off offset:256
	v_pk_mul_f32 v[8:9], v[92:93], s[16:17] op_sel_hi:[1,0]
	v_pk_mul_f32 v[10:11], v[90:91], s[16:17] op_sel_hi:[1,0]
	s_nop 0
	v_cvt_pk_bf16_f32 v10, v10, v11
	v_cvt_pk_bf16_f32 v11, v8, v9
	global_store_dwordx2 v[6:7], v[10:11], off offset:288
	v_or_b32_e32 v10, 48, v12
	v_pk_mul_f32 v[6:7], v[104:105], s[16:17] op_sel_hi:[1,0]
	v_pk_mul_f32 v[8:9], v[102:103], s[16:17] op_sel_hi:[1,0]
	s_nop 0
	v_cvt_pk_bf16_f32 v8, v8, v9
	v_cvt_pk_bf16_f32 v9, v6, v7
	v_mad_i64_i32 v[6:7], s[28:29], v10, s53, v[2:3]
	v_lshl_add_u64 v[6:7], v[6:7], 0, v[4:5]
	global_store_dwordx2 v[6:7], v[8:9], off
	v_pk_mul_f32 v[8:9], v[96:97], s[16:17] op_sel_hi:[1,0]
	v_pk_mul_f32 v[10:11], v[94:95], s[16:17] op_sel_hi:[1,0]
	s_nop 0
	v_cvt_pk_bf16_f32 v10, v10, v11
	v_cvt_pk_bf16_f32 v11, v8, v9
	global_store_dwordx2 v[6:7], v[10:11], off offset:32
	v_pk_mul_f32 v[8:9], v[88:89], s[16:17] op_sel_hi:[1,0]
	v_pk_mul_f32 v[10:11], v[86:87], s[16:17] op_sel_hi:[1,0]
	s_nop 0
	v_cvt_pk_bf16_f32 v10, v10, v11
	v_cvt_pk_bf16_f32 v11, v8, v9
	global_store_dwordx2 v[6:7], v[10:11], off offset:256
	v_pk_mul_f32 v[8:9], v[84:85], s[16:17] op_sel_hi:[1,0]
	v_pk_mul_f32 v[10:11], v[82:83], s[16:17] op_sel_hi:[1,0]
	s_nop 0
	v_cvt_pk_bf16_f32 v10, v10, v11
	v_cvt_pk_bf16_f32 v11, v8, v9
	global_store_dwordx2 v[6:7], v[10:11], off offset:288
	v_add_u32_e32 v10, 0x80, v12
	v_pk_mul_f32 v[6:7], v[80:81], s[16:17] op_sel_hi:[1,0]
	v_pk_mul_f32 v[8:9], v[78:79], s[16:17] op_sel_hi:[1,0]
	s_nop 0
	v_cvt_pk_bf16_f32 v8, v8, v9
	v_cvt_pk_bf16_f32 v9, v6, v7
	v_mad_i64_i32 v[6:7], s[28:29], v10, s53, v[2:3]
	v_lshl_add_u64 v[6:7], v[6:7], 0, v[4:5]
	global_store_dwordx2 v[6:7], v[8:9], off
	v_pk_mul_f32 v[8:9], v[76:77], s[16:17] op_sel_hi:[1,0]
	v_pk_mul_f32 v[10:11], v[74:75], s[16:17] op_sel_hi:[1,0]
	s_nop 0
	v_cvt_pk_bf16_f32 v10, v10, v11
	v_cvt_pk_bf16_f32 v11, v8, v9
	global_store_dwordx2 v[6:7], v[10:11], off offset:32
	v_pk_mul_f32 v[8:9], v[68:69], s[16:17] op_sel_hi:[1,0]
	v_pk_mul_f32 v[10:11], v[66:67], s[16:17] op_sel_hi:[1,0]
	s_nop 0
	v_cvt_pk_bf16_f32 v10, v10, v11
	v_cvt_pk_bf16_f32 v11, v8, v9
	global_store_dwordx2 v[6:7], v[10:11], off offset:256
	v_pk_mul_f32 v[8:9], v[60:61], s[16:17] op_sel_hi:[1,0]
	v_pk_mul_f32 v[10:11], v[58:59], s[16:17] op_sel_hi:[1,0]
	s_nop 0
	v_cvt_pk_bf16_f32 v10, v10, v11
	v_cvt_pk_bf16_f32 v11, v8, v9
	global_store_dwordx2 v[6:7], v[10:11], off offset:288
	v_add_u32_e32 v10, 0x90, v12
	v_pk_mul_f32 v[6:7], v[72:73], s[16:17] op_sel_hi:[1,0]
	v_pk_mul_f32 v[8:9], v[70:71], s[16:17] op_sel_hi:[1,0]
	s_nop 0
	v_cvt_pk_bf16_f32 v8, v8, v9
	v_cvt_pk_bf16_f32 v9, v6, v7
	v_mad_i64_i32 v[6:7], s[28:29], v10, s53, v[2:3]
	v_lshl_add_u64 v[6:7], v[6:7], 0, v[4:5]
	global_store_dwordx2 v[6:7], v[8:9], off
	v_pk_mul_f32 v[8:9], v[64:65], s[16:17] op_sel_hi:[1,0]
	v_pk_mul_f32 v[10:11], v[62:63], s[16:17] op_sel_hi:[1,0]
	s_nop 0
	v_cvt_pk_bf16_f32 v10, v10, v11
	v_cvt_pk_bf16_f32 v11, v8, v9
	global_store_dwordx2 v[6:7], v[10:11], off offset:32
	v_pk_mul_f32 v[8:9], v[52:53], s[16:17] op_sel_hi:[1,0]
	v_pk_mul_f32 v[10:11], v[50:51], s[16:17] op_sel_hi:[1,0]
	s_nop 0
	v_cvt_pk_bf16_f32 v10, v10, v11
	v_cvt_pk_bf16_f32 v11, v8, v9
	global_store_dwordx2 v[6:7], v[10:11], off offset:256
	v_pk_mul_f32 v[8:9], v[44:45], s[16:17] op_sel_hi:[1,0]
	v_pk_mul_f32 v[10:11], v[42:43], s[16:17] op_sel_hi:[1,0]
	s_nop 0
	v_cvt_pk_bf16_f32 v10, v10, v11
	v_cvt_pk_bf16_f32 v11, v8, v9
	global_store_dwordx2 v[6:7], v[10:11], off offset:288
	v_add_u32_e32 v10, 0xa0, v12
	v_pk_mul_f32 v[6:7], v[56:57], s[16:17] op_sel_hi:[1,0]
	v_pk_mul_f32 v[8:9], v[54:55], s[16:17] op_sel_hi:[1,0]
	s_nop 0
	v_cvt_pk_bf16_f32 v8, v8, v9
	v_cvt_pk_bf16_f32 v9, v6, v7
	v_mad_i64_i32 v[6:7], s[28:29], v10, s53, v[2:3]
	v_lshl_add_u64 v[6:7], v[6:7], 0, v[4:5]
	global_store_dwordx2 v[6:7], v[8:9], off
	v_pk_mul_f32 v[8:9], v[48:49], s[16:17] op_sel_hi:[1,0]
	v_pk_mul_f32 v[10:11], v[46:47], s[16:17] op_sel_hi:[1,0]
	s_nop 0
	v_cvt_pk_bf16_f32 v10, v10, v11
	v_cvt_pk_bf16_f32 v11, v8, v9
	global_store_dwordx2 v[6:7], v[10:11], off offset:32
	v_pk_mul_f32 v[8:9], v[36:37], s[16:17] op_sel_hi:[1,0]
	v_pk_mul_f32 v[10:11], v[34:35], s[16:17] op_sel_hi:[1,0]
	s_nop 0
	v_cvt_pk_bf16_f32 v10, v10, v11
	v_cvt_pk_bf16_f32 v11, v8, v9
	global_store_dwordx2 v[6:7], v[10:11], off offset:256
	v_pk_mul_f32 v[8:9], v[28:29], s[16:17] op_sel_hi:[1,0]
	v_pk_mul_f32 v[10:11], v[26:27], s[16:17] op_sel_hi:[1,0]
	s_nop 0
	v_cvt_pk_bf16_f32 v10, v10, v11
	v_cvt_pk_bf16_f32 v11, v8, v9
	global_store_dwordx2 v[6:7], v[10:11], off offset:288
	v_add_u32_e32 v10, 0xb0, v12
	v_pk_mul_f32 v[6:7], v[40:41], s[16:17] op_sel_hi:[1,0]
	v_pk_mul_f32 v[8:9], v[38:39], s[16:17] op_sel_hi:[1,0]
	v_mad_i64_i32 v[2:3], s[28:29], v10, s53, v[2:3]
	v_cvt_pk_bf16_f32 v8, v8, v9
	v_cvt_pk_bf16_f32 v9, v6, v7
	v_lshl_add_u64 v[2:3], v[2:3], 0, v[4:5]
	v_pk_mul_f32 v[4:5], v[32:33], s[16:17] op_sel_hi:[1,0]
	v_pk_mul_f32 v[6:7], v[30:31], s[16:17] op_sel_hi:[1,0]
	s_mov_b64 s[28:29], s[24:25]
	v_cvt_pk_bf16_f32 v6, v6, v7
	v_cvt_pk_bf16_f32 v7, v4, v5
	global_store_dwordx2 v[2:3], v[6:7], off offset:32
	v_pk_mul_f32 v[4:5], v[24:25], s[16:17] op_sel_hi:[1,0]
	v_pk_mul_f32 v[6:7], v[22:23], s[16:17] op_sel_hi:[1,0]
	global_store_dwordx2 v[2:3], v[8:9], off
	v_cvt_pk_bf16_f32 v6, v6, v7
	v_cvt_pk_bf16_f32 v7, v4, v5
	global_store_dwordx2 v[2:3], v[6:7], off offset:256
	v_pk_mul_f32 v[4:5], v[20:21], s[16:17] op_sel_hi:[1,0]
	v_pk_mul_f32 v[6:7], v[18:19], s[16:17] op_sel_hi:[1,0]
	s_nop 0
	v_cvt_pk_bf16_f32 v6, v6, v7
	v_cvt_pk_bf16_f32 v7, v4, v5
	global_store_dwordx2 v[2:3], v[6:7], off offset:288
	s_cbranch_vccz .LBB0_645
	s_waitcnt vmcnt(0)
	s_cmpk_gt_u32 s3, 0xff
	v_readlane_b32 s2, v252, 8
	s_cbranch_scc1 .LBB0_652
	s_barrier

.LBB0_1288:
	s_ashr_i32 s8, s6, 6
	s_and_b32 s9, s6, 63
	s_lshr_b32 s6, s42, 1
	s_add_i32 s20, s6, s30
	s_lshl_b32 s6, s42, 5
	s_and_b32 s6, s6, 32
	s_add_i32 s26, s6, s29
	s_and_b64 s[6:7], s[14:15], exec
	s_cselect_b32 s8, s20, s8
	s_cselect_b32 s6, s26, s9
	s_lshr_b32 s7, s8, 3
	s_mulk_i32 s7, 0x4100
	s_lshl_b32 s6, s6, 8
	s_and_b32 s9, s8, 7
	s_add_i32 s7, s7, s6
	v_add_u32_e32 v166, s7, v170
	s_lshl_b32 s20, s9, 7
	s_lshl_b32 s6, s9, 2
	s_mul_i32 s44, s8, 0x208000
	v_ashrrev_i32_e32 v167, 31, v166
	s_mul_hi_i32 s45, s8, 0x208000
	s_add_u32 s53, s31, s44
	v_lshlrev_b64 v[4:5], 5, v[166:167]
	s_addc_u32 s55, s34, s45
	s_mul_i32 s50, s8, 0x104000
	v_lshl_add_u64 v[4:5], s[12:13], 0, v[4:5]
	s_mov_b32 s7, s21
	s_mul_hi_i32 s51, s8, 0x104000
	s_add_u32 s62, s35, s50
	v_lshl_add_u64 v[4:5], v[4:5], 0, s[6:7]
	s_addc_u32 s63, s36, s51
	s_add_i32 s6, s8, 32
	v_lshlrev_b64 v[2:3], 10, v[166:167]
	s_ashr_i32 s7, s6, 31
	v_lshl_add_u64 v[2:3], s[16:17], 0, v[2:3]
	s_lshl_b64 s[6:7], s[6:7], 2
	v_lshl_add_u64 v[2:3], v[2:3], 0, s[20:21]
	s_add_u32 s6, s3, s6
	s_addc_u32 s7, s28, s7
	v_lshl_add_u64 v[2:3], v[2:3], 0, v[178:179]
	global_load_dword v58, v[4:5], off
	global_load_dword v50, v163, s[6:7]
	global_load_dwordx4 v[142:145], v[2:3], off offset:16
	global_load_dwordx4 v[138:141], v[2:3], off
	global_load_dwordx4 v[150:153], v[2:3], off offset:80
	global_load_dwordx4 v[146:149], v[2:3], off offset:64
	v_readfirstlane_b32 s6, v1
	s_ashr_i32 s26, s6, 6
	s_cmp_lt_i32 s26, 6
	s_mul_i32 s46, s26, 0xc00
	s_cselect_b64 s[8:9], -1, 0
	s_add_i32 s52, s46, 0xffffc000
	s_add_u32 s27, s62, s52
	s_addc_u32 s43, s63, 0
	s_ashr_i32 s47, s46, 31
	s_add_u32 s49, s53, s46
	s_addc_u32 s64, s55, s47
	s_and_b64 s[6:7], s[8:9], exec
	s_cselect_b32 s7, s64, s43
	s_cselect_b32 s6, s49, s27
	s_add_i32 s43, s46, 0
	s_cmp_lt_i32 s26, 5
	s_cselect_b64 s[26:27], -1, 0
	s_add_i32 s65, s46, 0x400
	s_ashr_i32 s66, s65, 31
	s_add_u32 s67, s49, 0x400
	s_addc_u32 s68, s64, 0
	s_add_i32 s48, s46, 0xffffc400
	s_add_u32 s69, s62, s48
	s_addc_u32 s70, s63, 0
	v_lshl_add_u64 v[2:3], s[6:7], 0, v[164:165]
	s_and_b64 s[6:7], s[26:27], exec
	s_mov_b32 m0, s43
	s_cselect_b32 s7, s68, s70
	s_cselect_b32 s6, s67, s69
	s_add_i32 s67, s46, 0x800
	v_lshrrev_b32 v154, 2, v0
	v_xor_b32 v154, v154, v0
	v_bfe_u32 v154, v154, 2, 1
	v_add_u32 v154, -1, v154
	v_and_b32 v154, 0x38383838, v154
	v_mov_b32 v155, v154
	v_mov_b32 v156, v154
	v_mov_b32 v157, v154
	v_mov_b32 v158, v154
	v_mov_b32 v159, v154
	v_mov_b32 v160, v154
	v_mov_b32 v161, v154
	global_load_lds_dwordx4 v[2:3], off
	s_add_i32 m0, s43, 0x400
	s_ashr_i32 s68, s67, 31
	s_add_u32 s69, s49, 0x800
	s_addc_u32 s64, s64, 0
	s_add_i32 s49, s46, 0xffffc800
	s_add_u32 s70, s62, s49
	s_addc_u32 s71, s63, 0
	v_lshl_add_u64 v[2:3], s[6:7], 0, v[164:165]
	s_and_b64 s[6:7], s[26:27], exec
	global_load_lds_dwordx4 v[2:3], off
	s_cselect_b32 s7, s64, s71
	s_cselect_b32 s6, s69, s70
	s_add_i32 m0, s43, 0x800
	s_add_u32 s62, s62, 0x2000
	s_addc_u32 s63, s63, 0
	s_add_u32 s53, s53, 0x4000
	s_addc_u32 s55, s55, 0
	s_add_u32 s64, s53, s46
	s_addc_u32 s69, s55, s47
	s_add_u32 s70, s62, s52
	s_addc_u32 s71, s63, 0
	v_lshl_add_u64 v[2:3], s[6:7], 0, v[164:165]
	s_and_b64 s[6:7], s[8:9], exec
	global_load_lds_dwordx4 v[2:3], off
	s_cselect_b32 s7, s69, s71
	s_cselect_b32 s6, s64, s70
	s_add_i32 m0, s43, 0x6000
	s_add_u32 s64, s53, s65
	s_addc_u32 s65, s55, s66
	s_add_u32 s66, s62, s48
	s_addc_u32 s69, s63, 0
	v_lshl_add_u64 v[2:3], s[6:7], 0, v[164:165]
	s_and_b64 s[6:7], s[26:27], exec
	global_load_lds_dwordx4 v[2:3], off
	s_cselect_b32 s7, s65, s69
	s_cselect_b32 s6, s64, s66
	s_add_i32 m0, s43, 0x6400
	s_add_u32 s53, s53, s67
	s_addc_u32 s55, s55, s68
	s_add_u32 s62, s62, s49
	s_addc_u32 s63, s63, 0
	v_lshl_add_u64 v[2:3], s[6:7], 0, v[164:165]
	s_and_b64 s[6:7], s[26:27], exec
	s_cselect_b32 s7, s55, s63
	s_cselect_b32 s6, s53, s62
	global_load_lds_dwordx4 v[2:3], off
	v_lshl_add_u64 v[2:3], s[6:7], 0, v[164:165]
	s_add_i32 m0, s43, 0x6800
	s_waitcnt vmcnt(0)
	v_mul_f32_e32 v51, 0x4f800000, v50
	global_load_lds_dwordx4 v[2:3], off
	s_waitcnt vmcnt(3)
	s_barrier
	ds_read_b128 v[2:5], v171
	ds_read_b128 v[6:9], v171 offset:1024
	s_waitcnt lgkmcnt(0)
	v_mfma_f32_32x32x64_f8f6f4 v[2:17], v[2:9], v[138:145], 0
	ds_read_b128 v[18:21], v171 offset:2048
	ds_read_b128 v[22:25], v171 offset:3072
	v_cmp_gt_f32_e32 vcc, s37, v50
	s_add_u32 s44, s44, s46
	s_addc_u32 s45, s45, s47
	v_cndmask_b32_e32 v59, v50, v51, vcc
	v_sqrt_f32_e32 v60, v59
	s_add_u32 s46, s50, s49
	s_addc_u32 s47, s51, 0
	s_add_u32 s48, s50, s48
	v_add_u32_e32 v61, -1, v60
	v_fma_f32 v62, -v61, v60, v59
	v_cmp_ge_f32_e64 s[6:7], 0, v62
	v_add_u32_e32 v62, 1, v60
	s_addc_u32 s49, s51, 0
	v_cndmask_b32_e64 v61, v60, v61, s[6:7]
	s_waitcnt lgkmcnt(0)
	v_mfma_f32_32x32x64_f8f6f4 v[2:17], v[18:25], v[146:153], v[2:17]
	ds_read_b128 v[18:21], v171 offset:4096
	ds_read_b128 v[22:25], v171 offset:5120
	ds_read_b128 v[34:37], v171 offset:6144
	ds_read_b128 v[38:41], v171 offset:7168
	v_fma_f32 v60, -v62, v60, v59
	v_cmp_lt_f32_e64 s[6:7], 0, v60
	s_add_u32 s50, s50, s52
	s_addc_u32 s51, s51, 0
	v_cndmask_b32_e64 v60, v61, v62, s[6:7]
	s_mov_b32 s55, 0
	s_mov_b32 s52, 0
	v_mov_b32_e32 v61, v163
	v_mov_b32_e32 v62, v163
	v_mov_b32_e32 v63, v163
	v_mov_b32_e32 v64, v163
	v_mov_b32_e32 v65, v163
	s_nop 3
	v_max3_f32 v2, v2, s39, v3
	s_waitcnt lgkmcnt(0)
	v_mfma_f32_32x32x64_f8f6f4 v[18:33], v[18:25], v[138:145], 0
	v_max3_f32 v2, v2, v4, v5
	v_max3_f32 v2, v2, v6, v7
	v_max3_f32 v2, v2, v8, v9
	v_max3_f32 v2, v2, v10, v11
	v_max3_f32 v2, v2, v12, v13
	v_max3_f32 v2, v2, v14, v15
	v_max3_f32 v2, v2, v16, v17
	v_mfma_f32_32x32x64_f8f6f4 v[18:33], v[34:41], v[146:153], v[18:33]
	ds_read_b128 v[34:37], v171 offset:8192
	ds_read_b128 v[38:41], v171 offset:9216
	ds_read_b128 v[50:53], v171 offset:10240
	ds_read_b128 v[54:57], v171 offset:11264
	s_waitcnt lgkmcnt(0)
	v_mfma_f32_32x32x64_f8f6f4 v[34:49], v[34:41], v[138:145], 0
	s_nop 13
	v_max3_f32 v2, v2, v18, v19
	v_max3_f32 v2, v2, v20, v21
	v_max3_f32 v18, v2, v22, v23
	v_max3_f32 v18, v18, v24, v25
	v_max3_f32 v18, v18, v26, v27
	v_max3_f32 v18, v18, v28, v29
	v_max3_f32 v18, v18, v30, v31
	v_max3_f32 v26, v18, v32, v33
	v_mov_b32_e32 v27, v163
	v_mov_b32_e32 v28, v163
	v_mov_b32_e32 v29, v163
	v_mov_b32_e32 v30, v163
	v_mov_b32_e32 v31, v163
	v_mov_b32_e32 v32, v163
	v_mov_b32_e32 v33, v163
	v_mfma_f32_32x32x64_f8f6f4 v[34:49], v[50:57], v[146:153], v[34:49]
	v_mul_f32_e32 v50, 0x37800000, v60
	v_cndmask_b32_e32 v60, v60, v50, vcc
	ds_read_b128 v[50:53], v171 offset:12288
	ds_read_b128 v[54:57], v171 offset:13312
	ds_read_b128 v[18:21], v171 offset:14336
	ds_read_b128 v[22:25], v171 offset:15360
	v_cmp_lt_i32_e32 vcc, v176, v177
	s_nop 12
	v_max3_f32 v26, v26, v34, v35
	s_waitcnt lgkmcnt(0)
	v_mfma_f32_32x32x64_f8f6f4 v[2:17], v[50:57], v[138:145], 0
	v_max3_f32 v26, v26, v36, v37
	v_max3_f32 v26, v26, v38, v39
	v_max3_f32 v26, v26, v40, v41
	v_max3_f32 v26, v26, v42, v43
	v_max3_f32 v26, v26, v44, v45
	v_max3_f32 v26, v26, v46, v47
	v_max3_f32 v26, v26, v48, v49
	v_mov_b32_e32 v50, 0
	v_mov_b32_e32 v51, v163
	v_mov_b32_e32 v52, v163
	v_mov_b32_e32 v53, v163
	v_mov_b32_e32 v54, v163
	v_mov_b32_e32 v55, v163
	v_mov_b32_e32 v56, v163
	v_mov_b32_e32 v57, v163
	v_mfma_f32_32x32x64_f8f6f4 v[2:17], v[18:25], v[146:153], v[2:17]
	v_mov_b32_e32 v18, 0
	v_mov_b32_e32 v19, v163
	v_mov_b32_e32 v20, v163
	v_mov_b32_e32 v21, v163
	v_mov_b32_e32 v22, v163
	v_mov_b32_e32 v23, v163
	v_mov_b32_e32 v24, v163
	v_mov_b32_e32 v25, v163
	s_nop 11
	v_max3_f32 v2, v26, v2, v3
	v_max3_f32 v2, v2, v4, v5
	v_max3_f32 v2, v2, v6, v7
	v_max3_f32 v2, v2, v8, v9
	v_max3_f32 v2, v2, v10, v11
	v_max3_f32 v2, v2, v12, v13
	v_max3_f32 v2, v2, v14, v15
	v_cndmask_b32_e32 v3, v175, v176, vcc
	v_max3_f32 v2, v2, v16, v17
	v_lshlrev_b32_e32 v3, 2, v3
	ds_bpermute_b32 v3, v3, v2
	v_cmp_class_f32_e32 vcc, v59, v172
	v_mov_b32_e32 v26, v163
	v_mov_b32_e32 v5, v163
	v_cndmask_b32_e32 v4, v60, v59, vcc
	s_waitcnt lgkmcnt(0)
	v_max_f32_e32 v3, v3, v3
	v_mul_f32_e32 v4, v58, v4
	v_max_f32_e32 v2, v2, v3
	v_fmamk_f32 v4, v4, 0x3f90a3d7, v173
	v_add_f32_e32 v2, 0x42800000, v2
	v_min_f32_e32 v2, v4, v2
	v_add_f32_e32 v2, 0xc2ec0000, v2
	v_xor_b32_e32 v34, 0x80000000, v2
	v_mov_b32_e32 v35, v34
	v_mov_b32_e32 v36, v34
	v_mov_b32_e32 v37, v34
	v_mov_b32_e32 v38, v34
	v_mov_b32_e32 v39, v34
	v_mov_b32_e32 v40, v34
	v_mov_b32_e32 v41, v34
	v_mov_b32_e32 v42, v34
	v_mov_b32_e32 v43, v34
	v_mov_b32_e32 v44, v34
	v_mov_b32_e32 v45, v34
	v_mov_b32_e32 v46, v34
	v_mov_b32_e32 v47, v34
	v_mov_b32_e32 v48, v34
	v_mov_b32_e32 v49, v34
	v_mov_b32_e32 v58, v163
	v_mov_b32_e32 v59, v163
	v_mov_b32_e32 v60, v163
	v_mov_b32_e32 v2, 0
	v_mov_b32_e32 v3, v163
	v_mov_b32_e32 v4, v163
	v_mov_b32_e32 v6, v163
	v_mov_b32_e32 v7, v163
	v_mov_b32_e32 v8, v163
	v_mov_b32_e32 v9, v163
	v_mov_b32_e32 v10, v163
	v_mov_b32_e32 v11, v163
	v_mov_b32_e32 v12, v163
	v_mov_b32_e32 v13, v163
	v_mov_b32_e32 v14, v163
	v_mov_b32_e32 v15, v163
	v_mov_b32_e32 v16, v163
	v_mov_b32_e32 v17, v163
	v_mov_b32_e32 v86, v163
	v_mov_b32_e32 v87, v163
	v_mov_b32_e32 v88, v163
	v_mov_b32_e32 v89, v163
	v_mov_b32_e32 v90, v163
	v_mov_b32_e32 v91, v163
	v_mov_b32_e32 v92, v163
	v_mov_b32_e32 v93, v163
	v_mov_b32_e32 v94, v163
	v_mov_b32_e32 v95, v163
	v_mov_b32_e32 v96, v163
	v_mov_b32_e32 v97, v163
	v_mov_b32_e32 v98, v163
	v_mov_b32_e32 v99, v163
	v_mov_b32_e32 v100, v163
	v_mov_b32_e32 v101, v163
	v_mov_b32_e32 v102, v163
	v_mov_b32_e32 v103, v163
	v_mov_b32_e32 v104, v163
	v_mov_b32_e32 v105, v163
	v_mov_b32_e32 v106, v163
	v_mov_b32_e32 v107, v163
	v_mov_b32_e32 v108, v163
	v_mov_b32_e32 v109, v163
	v_mov_b32_e32 v110, v163
	v_mov_b32_e32 v111, v163
	v_mov_b32_e32 v112, v163
	v_mov_b32_e32 v113, v163
	v_mov_b32_e32 v114, v163
	v_mov_b32_e32 v115, v163
	v_mov_b32_e32 v116, v163
	v_mov_b32_e32 v117, v163
	v_mov_b32_e32 v228, v163
	v_mov_b32_e32 v229, v163
	v_mov_b32_e32 v230, v163
	v_mov_b32_e32 v231, v163
	v_mov_b32_e32 v232, v163
	v_mov_b32_e32 v233, v163
	v_mov_b32_e32 v234, v163
	v_mov_b32_e32 v235, v163
	v_mov_b32_e32 v236, v163
	v_mov_b32_e32 v237, v163
	v_mov_b32_e32 v238, v163
	v_mov_b32_e32 v239, v163
	v_mov_b32_e32 v240, v163
	v_mov_b32_e32 v241, v163
	v_mov_b32_e32 v242, v163
	v_mov_b32_e32 v243, v163
	s_add_u32 s98, s18, s44
	s_addc_u32 s99, s19, s45
	s_add_u32 s98, s98, 0x23076100
	s_addc_u32 s99, s99, 0
	s_add_u32 s100, s18, s50
	s_addc_u32 s101, s19, s51
	s_add_u32 s100, s100, 0x26132100
	s_addc_u32 s101, s101, 0
	s_movk_i32 s74, 0x2000
	s_and_b64 s[62:63], s[8:9], exec
	s_cselect_b32 s63, s99, s101
	s_cselect_b32 s62, s98, s100
	s_cselect_b32 s74, 0x4000, s74
	s_add_u32 s68, s62, s74
	s_addc_u32 s69, s63, 0
	s_lshl_b32 s74, s74, 1
	s_add_u32 s98, s18, s44
	s_addc_u32 s99, s19, s45
	s_add_u32 s98, s98, 0x23076500
	s_addc_u32 s99, s99, 0
	s_add_u32 s100, s18, s48
	s_addc_u32 s101, s19, s49
	s_add_u32 s100, s100, 0x26132100
	s_addc_u32 s101, s101, 0
	s_movk_i32 s75, 0x2000
	s_and_b64 s[64:65], s[26:27], exec
	s_cselect_b32 s65, s99, s101
	s_cselect_b32 s64, s98, s100
	s_cselect_b32 s75, 0x4000, s75
	s_add_u32 s70, s64, s75
	s_addc_u32 s71, s65, 0
	s_lshl_b32 s75, s75, 1
	s_add_u32 s98, s18, s44
	s_addc_u32 s99, s19, s45
	s_add_u32 s98, s98, 0x23076900
	s_addc_u32 s99, s99, 0
	s_add_u32 s100, s18, s46
	s_addc_u32 s101, s19, s47
	s_add_u32 s100, s100, 0x26132100
	s_addc_u32 s101, s101, 0
	s_movk_i32 s76, 0x2000
	s_and_b64 s[66:67], s[26:27], exec
	s_cselect_b32 s67, s99, s101
	s_cselect_b32 s66, s98, s100
	s_cselect_b32 s76, 0x4000, s76
	s_add_u32 s72, s66, s76
	s_addc_u32 s73, s67, 0
	s_lshl_b32 s76, s76, 1
	s_mov_b64 s[98:99], 0
	s_branch .LBB0_1290
.LBB0_1290:
	s_waitcnt vmcnt(0) lgkmcnt(0)
	s_barrier
	s_cmpk_gt_u32 s52, 0x7f
	s_cselect_b64 vcc, 0, exec
	s_mul_i32 s100, s55, 0x6000
	s_add_i32 s52, s52, 2
	s_xor_b32 s55, s55, 2
	v_add_u32_e32 v167, s100, v171
.LBB0_1289:
	ds_read_b128 v[190:193], v167
	ds_read_b128 v[194:197], v167 offset:1024
	ds_read_b128 v[198:201], v167 offset:2048
	ds_read_b128 v[202:205], v167 offset:3072
	ds_read_b128 v[206:209], v167 offset:4096
	ds_read_b128 v[210:213], v167 offset:5120
	ds_read_b128 v[220:223], v167 offset:6144
	ds_read_b128 v[224:227], v167 offset:7168
	s_cmp_lg_u64 s[98:99], 0
	s_cbranch_scc1 .Lslow_mla0_0
.Lback_mla0_0:
	v_cvt_pk_u8_f32 v118, v86, 0, 0
	v_cvt_pk_u8_f32 v119, v90, 0, 0
	v_cvt_pk_u8_f32 v120, v94, 0, 0
	v_cvt_pk_u8_f32 v121, v98, 0, 0
	v_cvt_pk_u8_f32 v118, v87, 1, v118
	v_cvt_pk_u8_f32 v119, v91, 1, v119
	v_cvt_pk_u8_f32 v120, v95, 1, v120
	v_cvt_pk_u8_f32 v121, v99, 1, v121
	s_waitcnt lgkmcnt(6)
	v_mfma_f32_32x32x64_f8f6f4 v[54:69], v[190:197], v[138:145], v[34:49]
	v_cvt_pk_u8_f32 v118, v88, 2, v118
	v_cvt_pk_u8_f32 v119, v92, 2, v119
	v_cvt_pk_u8_f32 v120, v96, 2, v120
	v_cvt_pk_u8_f32 v121, v100, 2, v121
	v_cvt_pk_u8_f32 v118, v89, 3, v118
	v_cvt_pk_u8_f32 v119, v93, 3, v119
	v_cvt_pk_u8_f32 v120, v97, 3, v120
	v_cvt_pk_u8_f32 v121, v101, 3, v121
	s_waitcnt lgkmcnt(4)
	v_mfma_f32_32x32x64_f8f6f4 v[54:69], v[198:205], v[146:153], v[54:69]
	v_cvt_pk_u8_f32 v122, v102, 0, 0
	v_cvt_pk_u8_f32 v123, v106, 0, 0
	v_cvt_pk_u8_f32 v124, v110, 0, 0
	v_cvt_pk_u8_f32 v125, v114, 0, 0
	v_cvt_pk_u8_f32 v122, v103, 1, v122
	v_cvt_pk_u8_f32 v123, v107, 1, v123
	v_cvt_pk_u8_f32 v124, v111, 1, v124
	v_cvt_pk_u8_f32 v125, v115, 1, v125
	s_waitcnt lgkmcnt(2)
	v_mfma_f32_32x32x64_f8f6f4 v[70:85], v[206:213], v[138:145], v[34:49]
	v_cvt_pk_u8_f32 v122, v104, 2, v122
	v_cvt_pk_u8_f32 v123, v108, 2, v123
	v_cvt_pk_u8_f32 v124, v112, 2, v124
	v_cvt_pk_u8_f32 v125, v116, 2, v125
	v_cvt_pk_u8_f32 v122, v105, 3, v122
	v_cvt_pk_u8_f32 v123, v109, 3, v123
	v_cvt_pk_u8_f32 v124, v113, 3, v124
	v_cvt_pk_u8_f32 v125, v117, 3, v125
	s_waitcnt lgkmcnt(0)
	v_mfma_f32_32x32x64_f8f6f4 v[70:85], v[220:227], v[146:153], v[70:85]
	s_nop 0
	s_nop 0
	v_mfma_f32_32x32x64_f8f6f4 v[18:33], v[228:235], v[118:125], v[18:33] blgp:1
	ds_read_b128 v[190:193], v167 offset:8192
	ds_read_b128 v[194:197], v167 offset:9216
	ds_read_b128 v[198:201], v167 offset:10240
	ds_read_b128 v[202:205], v167 offset:11264
	s_cbranch_vccz .Ldma_mla0_skip0
	s_mul_i32 s101, s55, 0x6000
	s_add_i32 s101, s101, s43
	s_mov_b32 m0, s101
	s_nop 0
	global_load_lds_dwordx4 v164, s[62:63]
.Ldma_mla0_skip0:
	v_mfma_f32_32x32x64_f8f6f4 v[2:17], v[236:243], v[118:125], v[2:17] blgp:1
	ds_read_b128 v[206:209], v167 offset:12288
	ds_read_b128 v[210:213], v167 offset:13312
	ds_read_b128 v[220:223], v167 offset:14336
	ds_read_b128 v[224:227], v167 offset:15360
	v_max3_f32 v126, v54, v55, v56
	v_max3_f32 v126, v126, v57, v58
	v_max3_f32 v126, v126, v59, v60
	v_max3_f32 v126, v126, v61, v62
	v_max3_f32 v126, v126, v63, v64
	v_max3_f32 v126, v126, v65, v66
	v_max3_f32 v126, v126, v67, v68
	v_max3_f32 v126, v126, v69, v69
	s_cbranch_vccz .Ldma_mla0_skip1
	s_add_i32 m0, s101, 0x400
	s_add_u32 s62, s62, s74
	s_addc_u32 s63, s63, 0
	global_load_lds_dwordx4 v164, s[64:65]
.Ldma_mla0_skip1:
	v_mfma_f32_16x16x128_f8f6f4 v[50:53], v[154:161], v[118:125], v[50:53] blgp:1
	ds_read_b128 v[228:231], v167 offset:16384
	ds_read_b128 v[232:235], v167 offset:17408
	ds_read_b128 v[236:239], v167 offset:18432
	ds_read_b128 v[240:243], v167 offset:19456
	v_max3_f32 v126, v126, v70, v71
	v_max3_f32 v126, v126, v72, v73
	v_max3_f32 v126, v126, v74, v75
	v_max3_f32 v126, v126, v76, v77
	v_max3_f32 v126, v126, v78, v79
	v_max3_f32 v126, v126, v80, v81
	v_max3_f32 v126, v126, v82, v83
	v_max3_f32 v126, v126, v84, v85
	v_cmp_gt_f32_e64 s[98:99], v126, v180
	s_cmp_lg_u64 s[98:99], 0
	s_cbranch_scc1 .Lslow_mla0_1
.Lback_mla0_1:
	v_cvt_pk_u8_f32 v118, v54, 0, 0
	v_cvt_pk_u8_f32 v119, v58, 0, 0
	v_cvt_pk_u8_f32 v120, v62, 0, 0
	v_cvt_pk_u8_f32 v121, v66, 0, 0
	v_cvt_pk_u8_f32 v118, v55, 1, v118
	v_cvt_pk_u8_f32 v119, v59, 1, v119
	v_cvt_pk_u8_f32 v120, v63, 1, v120
	v_cvt_pk_u8_f32 v121, v67, 1, v121
	s_waitcnt lgkmcnt(4)
	v_mfma_f32_32x32x64_f8f6f4 v[86:101], v[190:197], v[138:145], v[34:49]
	v_cvt_pk_u8_f32 v118, v56, 2, v118
	v_cvt_pk_u8_f32 v119, v60, 2, v119
	v_cvt_pk_u8_f32 v120, v64, 2, v120
	v_cvt_pk_u8_f32 v121, v68, 2, v121
	v_cvt_pk_u8_f32 v118, v57, 3, v118
	v_cvt_pk_u8_f32 v119, v61, 3, v119
	v_cvt_pk_u8_f32 v120, v65, 3, v120
	v_cvt_pk_u8_f32 v121, v69, 3, v121
	v_mfma_f32_32x32x64_f8f6f4 v[86:101], v[198:205], v[146:153], v[86:101]
	v_cvt_pk_u8_f32 v122, v70, 0, 0
	v_cvt_pk_u8_f32 v123, v74, 0, 0
	v_cvt_pk_u8_f32 v124, v78, 0, 0
	v_cvt_pk_u8_f32 v125, v82, 0, 0
	v_cvt_pk_u8_f32 v122, v71, 1, v122
	v_cvt_pk_u8_f32 v123, v75, 1, v123
	v_cvt_pk_u8_f32 v124, v79, 1, v124
	v_cvt_pk_u8_f32 v125, v83, 1, v125
	v_mfma_f32_32x32x64_f8f6f4 v[102:117], v[206:213], v[138:145], v[34:49]
	v_cvt_pk_u8_f32 v122, v72, 2, v122
	v_cvt_pk_u8_f32 v123, v76, 2, v123
	v_cvt_pk_u8_f32 v124, v80, 2, v124
	v_cvt_pk_u8_f32 v125, v84, 2, v125
	v_cvt_pk_u8_f32 v122, v73, 3, v122
	v_cvt_pk_u8_f32 v123, v77, 3, v123
	v_cvt_pk_u8_f32 v124, v81, 3, v124
	v_cvt_pk_u8_f32 v125, v85, 3, v125
	v_mfma_f32_32x32x64_f8f6f4 v[102:117], v[220:227], v[146:153], v[102:117]
	s_nop 0
	s_waitcnt lgkmcnt(0)
	v_mfma_f32_32x32x64_f8f6f4 v[18:33], v[228:235], v[118:125], v[18:33] blgp:1
	ds_read_b128 v[190:193], v167 offset:24576
	ds_read_b128 v[194:197], v167 offset:25600
	ds_read_b128 v[198:201], v167 offset:26624
	ds_read_b128 v[202:205], v167 offset:27648
	s_cbranch_vccz .Ldma_mla0_skip2
	s_add_i32 m0, s101, 0x800
	s_add_u32 s64, s64, s75
	s_addc_u32 s65, s65, 0
	global_load_lds_dwordx4 v164, s[66:67]
.Ldma_mla0_skip2:
	v_mfma_f32_32x32x64_f8f6f4 v[2:17], v[236:243], v[118:125], v[2:17] blgp:1
	ds_read_b128 v[206:209], v167 offset:28672
	ds_read_b128 v[210:213], v167 offset:29696
	ds_read_b128 v[220:223], v167 offset:30720
	ds_read_b128 v[224:227], v167 offset:31744
	v_max3_f32 v126, v86, v87, v88
	v_max3_f32 v126, v126, v89, v90
	v_max3_f32 v126, v126, v91, v92
	v_max3_f32 v126, v126, v93, v94
	v_max3_f32 v126, v126, v95, v96
	v_max3_f32 v126, v126, v97, v98
	v_max3_f32 v126, v126, v99, v100
	v_max3_f32 v126, v126, v101, v101
	s_cbranch_vccz .Ldma_mla0_skip3
	s_add_i32 m0, s101, 0x6000
	s_add_u32 s66, s66, s76
	s_addc_u32 s67, s67, 0
	global_load_lds_dwordx4 v164, s[68:69]
.Ldma_mla0_skip3:
	v_mfma_f32_16x16x128_f8f6f4 v[50:53], v[154:161], v[118:125], v[50:53] blgp:1
	ds_read_b128 v[228:231], v167 offset:20480
	ds_read_b128 v[232:235], v167 offset:21504
	ds_read_b128 v[236:239], v167 offset:22528
	ds_read_b128 v[240:243], v167 offset:23552
	v_max3_f32 v126, v126, v102, v103
	v_max3_f32 v126, v126, v104, v105
	v_max3_f32 v126, v126, v106, v107
	v_max3_f32 v126, v126, v108, v109
	v_max3_f32 v126, v126, v110, v111
	v_max3_f32 v126, v126, v112, v113
	v_max3_f32 v126, v126, v114, v115
	v_max3_f32 v126, v126, v116, v117
	v_cmp_gt_f32_e64 s[98:99], v126, v180
	s_cmp_lg_u64 s[98:99], 0
	s_cbranch_scc1 .Lslow_mla0_2
.Lback_mla0_2:
	v_cvt_pk_u8_f32 v118, v86, 0, 0
	v_cvt_pk_u8_f32 v119, v90, 0, 0
	v_cvt_pk_u8_f32 v120, v94, 0, 0
	v_cvt_pk_u8_f32 v121, v98, 0, 0
	v_cvt_pk_u8_f32 v118, v87, 1, v118
	v_cvt_pk_u8_f32 v119, v91, 1, v119
	v_cvt_pk_u8_f32 v120, v95, 1, v120
	v_cvt_pk_u8_f32 v121, v99, 1, v121
	s_waitcnt lgkmcnt(4)
	v_mfma_f32_32x32x64_f8f6f4 v[54:69], v[190:197], v[138:145], v[34:49]
	v_cvt_pk_u8_f32 v118, v88, 2, v118
	v_cvt_pk_u8_f32 v119, v92, 2, v119
	v_cvt_pk_u8_f32 v120, v96, 2, v120
	v_cvt_pk_u8_f32 v121, v100, 2, v121
	v_cvt_pk_u8_f32 v118, v89, 3, v118
	v_cvt_pk_u8_f32 v119, v93, 3, v119
	v_cvt_pk_u8_f32 v120, v97, 3, v120
	v_cvt_pk_u8_f32 v121, v101, 3, v121
	v_mfma_f32_32x32x64_f8f6f4 v[54:69], v[198:205], v[146:153], v[54:69]
	v_cvt_pk_u8_f32 v122, v102, 0, 0
	v_cvt_pk_u8_f32 v123, v106, 0, 0
	v_cvt_pk_u8_f32 v124, v110, 0, 0
	v_cvt_pk_u8_f32 v125, v114, 0, 0
	v_cvt_pk_u8_f32 v122, v103, 1, v122
	v_cvt_pk_u8_f32 v123, v107, 1, v123
	v_cvt_pk_u8_f32 v124, v111, 1, v124
	v_cvt_pk_u8_f32 v125, v115, 1, v125
	v_mfma_f32_32x32x64_f8f6f4 v[70:85], v[206:213], v[138:145], v[34:49]
	v_cvt_pk_u8_f32 v122, v104, 2, v122
	v_cvt_pk_u8_f32 v123, v108, 2, v123
	v_cvt_pk_u8_f32 v124, v112, 2, v124
	v_cvt_pk_u8_f32 v125, v116, 2, v125
	v_cvt_pk_u8_f32 v122, v105, 3, v122
	v_cvt_pk_u8_f32 v123, v109, 3, v123
	v_cvt_pk_u8_f32 v124, v113, 3, v124
	v_cvt_pk_u8_f32 v125, v117, 3, v125
	v_mfma_f32_32x32x64_f8f6f4 v[70:85], v[220:227], v[146:153], v[70:85]
	s_nop 0
	s_waitcnt lgkmcnt(0)
	v_mfma_f32_32x32x64_f8f6f4 v[18:33], v[228:235], v[118:125], v[18:33] blgp:1
	ds_read_b128 v[190:193], v167 offset:32768
	ds_read_b128 v[194:197], v167 offset:33792
	ds_read_b128 v[198:201], v167 offset:34816
	ds_read_b128 v[202:205], v167 offset:35840
	s_cbranch_vccz .Ldma_mla0_skip4
	s_add_i32 m0, s101, 0x6400
	s_add_u32 s68, s68, s74
	s_addc_u32 s69, s69, 0
	global_load_lds_dwordx4 v164, s[70:71]
.Ldma_mla0_skip4:
	v_mfma_f32_32x32x64_f8f6f4 v[2:17], v[236:243], v[118:125], v[2:17] blgp:1
	ds_read_b128 v[206:209], v167 offset:36864
	ds_read_b128 v[210:213], v167 offset:37888
	ds_read_b128 v[220:223], v167 offset:38912
	ds_read_b128 v[224:227], v167 offset:39936
	v_max3_f32 v126, v54, v55, v56
	v_max3_f32 v126, v126, v57, v58
	v_max3_f32 v126, v126, v59, v60
	v_max3_f32 v126, v126, v61, v62
	v_max3_f32 v126, v126, v63, v64
	v_max3_f32 v126, v126, v65, v66
	v_max3_f32 v126, v126, v67, v68
	v_max3_f32 v126, v126, v69, v69
	s_cbranch_vccz .Ldma_mla0_skip5
	s_add_i32 m0, s101, 0x6800
	s_add_u32 s70, s70, s75
	s_addc_u32 s71, s71, 0
	global_load_lds_dwordx4 v164, s[72:73]
	s_add_u32 s72, s72, s76
	s_addc_u32 s73, s73, 0
.Ldma_mla0_skip5:
	v_mfma_f32_16x16x128_f8f6f4 v[50:53], v[154:161], v[118:125], v[50:53] blgp:1
	ds_read_b128 v[228:231], v167 offset:40960
	ds_read_b128 v[232:235], v167 offset:41984
	ds_read_b128 v[236:239], v167 offset:43008
	ds_read_b128 v[240:243], v167 offset:44032
	v_max3_f32 v126, v126, v70, v71
	v_max3_f32 v126, v126, v72, v73
	v_max3_f32 v126, v126, v74, v75
	v_max3_f32 v126, v126, v76, v77
	v_max3_f32 v126, v126, v78, v79
	v_max3_f32 v126, v126, v80, v81
	v_max3_f32 v126, v126, v82, v83
	v_max3_f32 v126, v126, v84, v85
	v_cmp_gt_f32_e64 s[98:99], v126, v180
	s_cmp_lg_u64 s[98:99], 0
	s_cbranch_scc1 .Lslow_mla0_3
.Lback_mla0_3:
	v_cvt_pk_u8_f32 v118, v54, 0, 0
	v_cvt_pk_u8_f32 v119, v58, 0, 0
	v_cvt_pk_u8_f32 v120, v62, 0, 0
	v_cvt_pk_u8_f32 v121, v66, 0, 0
	v_cvt_pk_u8_f32 v118, v55, 1, v118
	v_cvt_pk_u8_f32 v119, v59, 1, v119
	v_cvt_pk_u8_f32 v120, v63, 1, v120
	v_cvt_pk_u8_f32 v121, v67, 1, v121
	s_waitcnt lgkmcnt(4)
	v_mfma_f32_32x32x64_f8f6f4 v[86:101], v[190:197], v[138:145], v[34:49]
	v_cvt_pk_u8_f32 v118, v56, 2, v118
	v_cvt_pk_u8_f32 v119, v60, 2, v119
	v_cvt_pk_u8_f32 v120, v64, 2, v120
	v_cvt_pk_u8_f32 v121, v68, 2, v121
	v_cvt_pk_u8_f32 v118, v57, 3, v118
	v_cvt_pk_u8_f32 v119, v61, 3, v119
	v_cvt_pk_u8_f32 v120, v65, 3, v120
	v_cvt_pk_u8_f32 v121, v69, 3, v121
	v_mfma_f32_32x32x64_f8f6f4 v[86:101], v[198:205], v[146:153], v[86:101]
	v_cvt_pk_u8_f32 v122, v70, 0, 0
	v_cvt_pk_u8_f32 v123, v74, 0, 0
	v_cvt_pk_u8_f32 v124, v78, 0, 0
	v_cvt_pk_u8_f32 v125, v82, 0, 0
	v_cvt_pk_u8_f32 v122, v71, 1, v122
	v_cvt_pk_u8_f32 v123, v75, 1, v123
	v_cvt_pk_u8_f32 v124, v79, 1, v124
	v_cvt_pk_u8_f32 v125, v83, 1, v125
	v_mfma_f32_32x32x64_f8f6f4 v[102:117], v[206:213], v[138:145], v[34:49]
	v_cvt_pk_u8_f32 v122, v72, 2, v122
	v_cvt_pk_u8_f32 v123, v76, 2, v123
	v_cvt_pk_u8_f32 v124, v80, 2, v124
	v_cvt_pk_u8_f32 v125, v84, 2, v125
	v_cvt_pk_u8_f32 v122, v73, 3, v122
	v_cvt_pk_u8_f32 v123, v77, 3, v123
	v_cvt_pk_u8_f32 v124, v81, 3, v124
	v_cvt_pk_u8_f32 v125, v85, 3, v125
	v_mfma_f32_32x32x64_f8f6f4 v[102:117], v[220:227], v[146:153], v[102:117]
	s_nop 0
	s_waitcnt lgkmcnt(0)
	v_mfma_f32_32x32x64_f8f6f4 v[18:33], v[228:235], v[118:125], v[18:33] blgp:1
	v_mfma_f32_32x32x64_f8f6f4 v[2:17], v[236:243], v[118:125], v[2:17] blgp:1
	v_max3_f32 v126, v86, v87, v88
	v_max3_f32 v126, v126, v89, v90
	v_max3_f32 v126, v126, v91, v92
	v_max3_f32 v126, v126, v93, v94
	v_max3_f32 v126, v126, v95, v96
	v_max3_f32 v126, v126, v97, v98
	v_max3_f32 v126, v126, v99, v100
	v_max3_f32 v126, v126, v101, v101
	v_mfma_f32_16x16x128_f8f6f4 v[50:53], v[154:161], v[118:125], v[50:53] blgp:1
	ds_read_b128 v[228:231], v167 offset:45056
	ds_read_b128 v[232:235], v167 offset:46080
	ds_read_b128 v[236:239], v167 offset:47104
	ds_read_b128 v[240:243], v167 offset:48128
	s_nop 2
	v_max3_f32 v126, v126, v102, v103
	v_max3_f32 v126, v126, v104, v105
	v_max3_f32 v126, v126, v106, v107
	v_max3_f32 v126, v126, v108, v109
	v_max3_f32 v126, v126, v110, v111
	v_max3_f32 v126, v126, v112, v113
	v_max3_f32 v126, v126, v114, v115
	v_max3_f32 v126, v126, v116, v117
	v_cmp_gt_f32_e64 s[98:99], v126, v180
	s_cbranch_vccnz .LBB0_1290
	s_waitcnt lgkmcnt(0)
	s_cmp_lg_u64 s[98:99], 0
	s_cbranch_scc1 .Lslow_mla0_4
.Lback_mla0_4:
	v_cvt_pk_u8_f32 v118, v86, 0, 0
	v_cvt_pk_u8_f32 v119, v90, 0, 0
	v_cvt_pk_u8_f32 v120, v94, 0, 0
	v_cvt_pk_u8_f32 v121, v98, 0, 0
	v_cvt_pk_u8_f32 v118, v87, 1, v118
	v_cvt_pk_u8_f32 v119, v91, 1, v119
	v_cvt_pk_u8_f32 v120, v95, 1, v120
	v_cvt_pk_u8_f32 v121, v99, 1, v121
	v_cvt_pk_u8_f32 v118, v88, 2, v118
	v_cvt_pk_u8_f32 v119, v92, 2, v119
	v_cvt_pk_u8_f32 v120, v96, 2, v120
	v_cvt_pk_u8_f32 v121, v100, 2, v121
	v_cvt_pk_u8_f32 v118, v89, 3, v118
	v_cvt_pk_u8_f32 v119, v93, 3, v119
	v_cvt_pk_u8_f32 v120, v97, 3, v120
	v_cvt_pk_u8_f32 v121, v101, 3, v121
	v_cvt_pk_u8_f32 v122, v102, 0, 0
	v_cvt_pk_u8_f32 v123, v106, 0, 0
	v_cvt_pk_u8_f32 v124, v110, 0, 0
	v_cvt_pk_u8_f32 v125, v114, 0, 0
	v_cvt_pk_u8_f32 v122, v103, 1, v122
	v_cvt_pk_u8_f32 v123, v107, 1, v123
	v_cvt_pk_u8_f32 v124, v111, 1, v124
	v_cvt_pk_u8_f32 v125, v115, 1, v125
	v_cvt_pk_u8_f32 v122, v104, 2, v122
	v_cvt_pk_u8_f32 v123, v108, 2, v123
	v_cvt_pk_u8_f32 v124, v112, 2, v124
	v_cvt_pk_u8_f32 v125, v116, 2, v125
	v_cvt_pk_u8_f32 v122, v105, 3, v122
	v_cvt_pk_u8_f32 v123, v109, 3, v123
	v_cvt_pk_u8_f32 v124, v113, 3, v124
	v_cvt_pk_u8_f32 v125, v117, 3, v125
	s_nop 0
	s_nop 0
	v_mfma_f32_32x32x64_f8f6f4 v[18:33], v[228:235], v[118:125], v[18:33] blgp:1
	v_mfma_f32_32x32x64_f8f6f4 v[2:17], v[236:243], v[118:125], v[2:17] blgp:1
	v_mfma_f32_16x16x128_f8f6f4 v[50:53], v[154:161], v[118:125], v[50:53] blgp:1
	s_branch .LBB0_1287
.Lslow_mla0_0:
	v_med3_f32 v86, v86, 0, v180
	v_med3_f32 v87, v87, 0, v180
	v_med3_f32 v88, v88, 0, v180
	v_med3_f32 v89, v89, 0, v180
	v_med3_f32 v90, v90, 0, v180
	v_med3_f32 v91, v91, 0, v180
	v_med3_f32 v92, v92, 0, v180
	v_med3_f32 v93, v93, 0, v180
	v_med3_f32 v94, v94, 0, v180
	v_med3_f32 v95, v95, 0, v180
	v_med3_f32 v96, v96, 0, v180
	v_med3_f32 v97, v97, 0, v180
	v_med3_f32 v98, v98, 0, v180
	v_med3_f32 v99, v99, 0, v180
	v_med3_f32 v100, v100, 0, v180
	v_med3_f32 v101, v101, 0, v180
	v_med3_f32 v102, v102, 0, v180
	v_med3_f32 v103, v103, 0, v180
	v_med3_f32 v104, v104, 0, v180
	v_med3_f32 v105, v105, 0, v180
	v_med3_f32 v106, v106, 0, v180
	v_med3_f32 v107, v107, 0, v180
	v_med3_f32 v108, v108, 0, v180
	v_med3_f32 v109, v109, 0, v180
	v_med3_f32 v110, v110, 0, v180
	v_med3_f32 v111, v111, 0, v180
	v_med3_f32 v112, v112, 0, v180
	v_med3_f32 v113, v113, 0, v180
	v_med3_f32 v114, v114, 0, v180
	v_med3_f32 v115, v115, 0, v180
	v_med3_f32 v116, v116, 0, v180
	v_med3_f32 v117, v117, 0, v180
	s_branch .Lback_mla0_0
.Lslow_mla0_1:
	v_med3_f32 v54, v54, 0, v180
	v_med3_f32 v55, v55, 0, v180
	v_med3_f32 v56, v56, 0, v180
	v_med3_f32 v57, v57, 0, v180
	v_med3_f32 v58, v58, 0, v180
	v_med3_f32 v59, v59, 0, v180
	v_med3_f32 v60, v60, 0, v180
	v_med3_f32 v61, v61, 0, v180
	v_med3_f32 v62, v62, 0, v180
	v_med3_f32 v63, v63, 0, v180
	v_med3_f32 v64, v64, 0, v180
	v_med3_f32 v65, v65, 0, v180
	v_med3_f32 v66, v66, 0, v180
	v_med3_f32 v67, v67, 0, v180
	v_med3_f32 v68, v68, 0, v180
	v_med3_f32 v69, v69, 0, v180
	v_med3_f32 v70, v70, 0, v180
	v_med3_f32 v71, v71, 0, v180
	v_med3_f32 v72, v72, 0, v180
	v_med3_f32 v73, v73, 0, v180
	v_med3_f32 v74, v74, 0, v180
	v_med3_f32 v75, v75, 0, v180
	v_med3_f32 v76, v76, 0, v180
	v_med3_f32 v77, v77, 0, v180
	v_med3_f32 v78, v78, 0, v180
	v_med3_f32 v79, v79, 0, v180
	v_med3_f32 v80, v80, 0, v180
	v_med3_f32 v81, v81, 0, v180
	v_med3_f32 v82, v82, 0, v180
	v_med3_f32 v83, v83, 0, v180
	v_med3_f32 v84, v84, 0, v180
	v_med3_f32 v85, v85, 0, v180
	s_branch .Lback_mla0_1

.LBB0_1294:
	s_lshr_b32 s6, s34, 3
	s_mulk_i32 s6, 0x4100
	v_add_u32_e32 v2, s6, v188
	v_ashrrev_i32_e32 v3, 31, v2
	s_and_b32 s7, s34, 7
	v_lshlrev_b64 v[6:7], 5, v[2:3]
	s_lshl_b32 s16, s7, 7
	v_lshl_add_u64 v[6:7], s[12:13], 0, v[6:7]
	s_lshl_b32 s6, s7, 2
	s_mov_b32 s7, s17
	v_lshl_add_u64 v[6:7], v[6:7], 0, s[6:7]
	s_mul_i32 s7, s34, 0x208000
	s_mul_hi_i32 s6, s34, 0x208000
	s_add_u32 s35, s20, s7
	s_addc_u32 s36, s21, s6
	s_mul_i32 s7, s34, 0x104000
	s_mul_hi_i32 s6, s34, 0x104000
	s_add_u32 s37, s22, s7
	s_addc_u32 s38, s23, s6
	s_add_i32 s6, s34, 32
	s_ashr_i32 s7, s6, 31
	s_lshl_b64 s[6:7], s[6:7], 2
	s_add_u32 s6, s3, s6
	s_addc_u32 s7, s28, s7
	global_load_dword v6, v[6:7], off
	v_lshlrev_b64 v[4:5], 10, v[2:3]
	global_load_dword v7, v179, s[6:7]
	v_lshl_add_u64 v[4:5], s[8:9], 0, v[4:5]
	v_lshl_add_u64 v[4:5], v[4:5], 0, s[16:17]
	v_mad_i64_i32 v[2:3], s[6:7], v2, s26, v[182:183]
	v_lshl_add_u64 v[186:187], v[2:3], 0, s[16:17]
	v_lshl_add_u64 v[2:3], v[4:5], 0, v[178:179]
	global_load_dwordx4 v[126:129], v[2:3], off offset:16
	global_load_dwordx4 v[122:125], v[2:3], off
	global_load_dwordx4 v[134:137], v[2:3], off offset:80
	global_load_dwordx4 v[130:133], v[2:3], off offset:64
	v_readfirstlane_b32 s16, v1
	v_mov_b32 v114, 0x38383838
	v_mov_b32 v115, 0x38383838
	v_mov_b32 v116, 0x38383838
	v_mov_b32 v117, 0x38383838
	v_mov_b32 v118, 0x38383838
	v_mov_b32 v119, 0x38383838
	v_mov_b32 v120, 0x38383838
	v_mov_b32 v121, 0x38383838
	v_readlane_b32 s2, v252, 8
	s_waitcnt vmcnt(0)
	v_cmp_gt_f32_e32 vcc, s27, v7
	v_mul_f32_e32 v2, 0x4f800000, v7
	s_nop 0
	v_cndmask_b32_e32 v2, v7, v2, vcc
	v_sqrt_f32_e32 v3, v2
	s_nop 0
	v_add_u32_e32 v4, -1, v3
	v_fma_f32 v5, -v4, v3, v2
	v_cmp_ge_f32_e64 s[6:7], 0, v5
	v_add_u32_e32 v5, 1, v3
	s_nop 0
	v_cndmask_b32_e64 v4, v3, v4, s[6:7]
	v_fma_f32 v3, -v5, v3, v2
	v_cmp_lt_f32_e64 s[6:7], 0, v3
	s_nop 1
	v_cndmask_b32_e64 v3, v4, v5, s[6:7]
	s_ashr_i32 s7, s16, 6
	s_mul_i32 s16, s7, 0xc00
	s_add_i32 s39, s16, 0xffffc000
	s_add_u32 s40, s37, s39
	s_addc_u32 s41, s38, 0
	s_ashr_i32 s42, s16, 31
	s_add_u32 s43, s35, s16
	s_addc_u32 s44, s36, s42
	s_add_i32 s45, s16, 0x400
	s_add_i32 s6, s16, 0
	s_ashr_i32 s46, s45, 31
	s_add_u32 s47, s43, 0x400
	s_addc_u32 s48, s44, 0
	s_add_i32 s49, s16, 0xffffc400
	s_add_u32 s50, s37, s49
	s_addc_u32 s51, s38, 0
	s_add_i32 s53, s16, 0x800
	s_add_i32 s52, s6, 0x400
	s_ashr_i32 s55, s53, 31
	s_add_u32 s62, s43, 0x800
	s_addc_u32 s63, s44, 0
	s_add_i32 s64, s16, 0xffffc800
	s_add_u32 s65, s37, s64
	s_addc_u32 s66, s38, 0
	s_add_i32 s67, s6, 0x800
	s_add_u32 s68, s37, 0x2000
	s_addc_u32 s38, s38, 0
	s_add_u32 s35, s35, 0x4000
	s_addc_u32 s69, s36, 0
	s_add_u32 s16, s35, s16
	s_addc_u32 s42, s69, s42
	s_add_u32 s39, s68, s39
	v_mul_f32_e32 v4, 0x37800000, v3
	s_addc_u32 s70, s38, 0
	v_cndmask_b32_e32 v3, v3, v4, vcc
	v_cmp_class_f32_e32 vcc, v2, v190
	s_cmp_lt_i32 s7, 6
	s_cselect_b32 s37, s44, s41
	v_cndmask_b32_e32 v2, v3, v2, vcc
	s_cselect_b32 s36, s43, s40
	v_mul_f32_e32 v4, v6, v2
	v_lshl_add_u64 v[2:3], s[36:37], 0, v[180:181]
	s_cselect_b32 s36, s16, s39
	s_cselect_b32 s37, s42, s70
	s_add_i32 s16, s6, 0x6000
	s_add_u32 s40, s35, s45
	s_addc_u32 s41, s69, s46
	s_add_u32 s42, s68, s49
	s_addc_u32 s43, s38, 0
	s_add_i32 s44, s6, 0x6400
	s_add_u32 s35, s35, s53
	s_addc_u32 s45, s69, s55
	s_add_u32 s46, s68, s64
	s_addc_u32 s49, s38, 0
	s_cmp_lt_i32 s7, 5
	s_mov_b32 m0, s6
	s_cselect_b32 s39, s48, s51
	s_cselect_b32 s38, s47, s50
	global_load_lds_dwordx4 v[2:3], off
	v_lshl_add_u64 v[2:3], s[38:39], 0, v[180:181]
	s_mov_b32 m0, s52
	s_cselect_b32 s39, s63, s66
	s_cselect_b32 s38, s62, s65
	global_load_lds_dwordx4 v[2:3], off
	v_lshl_add_u64 v[2:3], s[38:39], 0, v[180:181]
	s_mov_b32 m0, s67
	v_fmamk_f32 v26, v4, 0x3f90a3d7, v191
	global_load_lds_dwordx4 v[2:3], off
	v_lshl_add_u64 v[2:3], s[36:37], 0, v[180:181]
	s_mov_b32 m0, s16
	s_cselect_b32 s37, s41, s43
	s_cselect_b32 s36, s40, s42
	global_load_lds_dwordx4 v[2:3], off
	v_lshl_add_u64 v[2:3], s[36:37], 0, v[180:181]
	s_mov_b32 m0, s44
	s_cselect_b32 s37, s45, s49
	s_cselect_b32 s36, s35, s46
	global_load_lds_dwordx4 v[2:3], off
	v_lshl_add_u64 v[2:3], s[36:37], 0, v[180:181]
	s_add_i32 m0, s6, 0x6800
	v_cmp_lt_i32_e32 vcc, v194, v195
	global_load_lds_dwordx4 v[2:3], off
	s_waitcnt vmcnt(3)
	s_barrier
	ds_read_b128 v[2:5], v189
	ds_read_b128 v[6:9], v189 offset:1024
	s_waitcnt lgkmcnt(0)
	v_mfma_f32_32x32x64_f8f6f4 v[2:17], v[2:9], v[122:129], 0
	ds_read_b128 v[18:21], v189 offset:2048
	ds_read_b128 v[22:25], v189 offset:3072
	s_add_i32 s34, s34, s2
	s_waitcnt lgkmcnt(0)
	v_mfma_f32_32x32x64_f8f6f4 v[2:17], v[18:25], v[130:137], v[2:17]
	s_nop 15
	s_nop 3
	v_max3_f32 v2, v2, s29, v3
	v_max3_f32 v2, v2, v4, v5
	v_max3_f32 v2, v2, v6, v7
	v_max3_f32 v2, v2, v8, v9
	v_max3_f32 v2, v2, v10, v11
	v_max3_f32 v2, v2, v12, v13
	v_max3_f32 v2, v2, v14, v15
	v_max3_f32 v27, v2, v16, v17
	ds_read_b128 v[2:5], v189 offset:4096
	ds_read_b128 v[6:9], v189 offset:5120
	s_waitcnt lgkmcnt(0)
	v_mfma_f32_32x32x64_f8f6f4 v[2:17], v[2:9], v[122:129], 0
	ds_read_b128 v[18:21], v189 offset:6144
	ds_read_b128 v[22:25], v189 offset:7168
	s_waitcnt lgkmcnt(0)
	v_mfma_f32_32x32x64_f8f6f4 v[2:17], v[18:25], v[130:137], v[2:17]
	s_nop 15
	s_nop 3
	v_max3_f32 v2, v27, v2, v3
	v_max3_f32 v2, v2, v4, v5
	v_max3_f32 v2, v2, v6, v7
	v_max3_f32 v2, v2, v8, v9
	v_max3_f32 v2, v2, v10, v11
	v_max3_f32 v2, v2, v12, v13
	v_max3_f32 v2, v2, v14, v15
	v_max3_f32 v27, v2, v16, v17
	ds_read_b128 v[2:5], v189 offset:8192
	ds_read_b128 v[6:9], v189 offset:9216
	s_waitcnt lgkmcnt(0)
	v_mfma_f32_32x32x64_f8f6f4 v[2:17], v[2:9], v[122:129], 0
	ds_read_b128 v[18:21], v189 offset:10240
	ds_read_b128 v[22:25], v189 offset:11264
	s_waitcnt lgkmcnt(0)
	v_mfma_f32_32x32x64_f8f6f4 v[2:17], v[18:25], v[130:137], v[2:17]
	s_nop 15
	s_nop 3
	v_max3_f32 v2, v27, v2, v3
	v_max3_f32 v2, v2, v4, v5
	v_max3_f32 v2, v2, v6, v7
	v_max3_f32 v2, v2, v8, v9
	v_max3_f32 v2, v2, v10, v11
	v_max3_f32 v2, v2, v12, v13
	v_max3_f32 v2, v2, v14, v15
	v_max3_f32 v27, v2, v16, v17
	ds_read_b128 v[2:5], v189 offset:12288
	ds_read_b128 v[6:9], v189 offset:13312
	s_waitcnt lgkmcnt(0)
	v_mfma_f32_32x32x64_f8f6f4 v[2:17], v[2:9], v[122:129], 0
	ds_read_b128 v[18:21], v189 offset:14336
	ds_read_b128 v[22:25], v189 offset:15360
	s_waitcnt vmcnt(0)
	s_barrier
	s_waitcnt lgkmcnt(0)
	v_mfma_f32_32x32x64_f8f6f4 v[2:17], v[18:25], v[130:137], v[2:17]
	ds_read_b128 v[34:37], v189
	ds_read_b128 v[38:41], v189 offset:1024
	ds_read_b128 v[50:53], v189 offset:2048
	ds_read_b128 v[54:57], v189 offset:3072
	ds_read_b128 v[18:21], v189 offset:4096
	ds_read_b128 v[22:25], v189 offset:5120
	ds_read_b128 v[42:45], v189 offset:6144
	ds_read_b128 v[46:49], v189 offset:7168
	ds_read_b128 v[82:85], v189 offset:16384
	ds_read_b128 v[86:89], v189 offset:17408
	ds_read_b128 v[90:93], v189 offset:18432
	ds_read_b128 v[94:97], v189 offset:19456
	s_nop 7
	v_max3_f32 v2, v27, v2, v3
	v_max3_f32 v2, v2, v4, v5
	v_max3_f32 v2, v2, v6, v7
	v_max3_f32 v2, v2, v8, v9
	v_max3_f32 v2, v2, v10, v11
	v_max3_f32 v2, v2, v12, v13
	v_max3_f32 v2, v2, v14, v15
	v_cndmask_b32_e32 v3, v193, v194, vcc
	v_max3_f32 v2, v2, v16, v17
	v_lshlrev_b32_e32 v3, 2, v3
	ds_bpermute_b32 v3, v3, v2
	s_waitcnt lgkmcnt(0)
	v_max_f32_e32 v3, v3, v3
	v_max_f32_e32 v2, v2, v3
	v_add_f32_e32 v2, 0x42800000, v2
	v_min_f32_e32 v2, v26, v2
	v_add_f32_e32 v2, 0xc2ec0000, v2
	v_xor_b32_e32 v2, 0x80000000, v2
	v_mov_b32_e32 v3, v2
	v_mov_b32_e32 v4, v2
	v_mov_b32_e32 v5, v2
	v_mov_b32_e32 v6, v2
	v_mov_b32_e32 v7, v2
	v_mov_b32_e32 v8, v2
	v_mov_b32_e32 v9, v2
	v_mov_b32_e32 v10, v2
	v_mov_b32_e32 v11, v2
	v_mov_b32_e32 v12, v2
	v_mov_b32_e32 v13, v2
	v_mov_b32_e32 v14, v2
	v_mov_b32_e32 v15, v2
	v_mov_b32_e32 v16, v2
	v_mov_b32_e32 v17, v2
	s_nop 1
	v_mfma_f32_32x32x64_f8f6f4 v[18:33], v[18:25], v[122:129], v[2:17]
	ds_read_b128 v[66:69], v189 offset:8192
	ds_read_b128 v[70:73], v189 offset:9216
	ds_read_b128 v[98:101], v189 offset:10240
	ds_read_b128 v[102:105], v189 offset:11264
	ds_read_b128 v[58:61], v189 offset:12288
	ds_read_b128 v[62:65], v189 offset:13312
	ds_read_b128 v[74:77], v189 offset:14336
	ds_read_b128 v[78:81], v189 offset:15360
	v_mfma_f32_32x32x64_f8f6f4 v[18:33], v[42:49], v[130:137], v[18:33]
	v_mfma_f32_32x32x64_f8f6f4 v[34:49], v[34:41], v[122:129], v[2:17]
	s_nop 15
	s_nop 2
	v_med3_f32 v18, v18, 0, v196
	v_med3_f32 v19, v19, 0, v196
	v_cvt_pk_u8_f32 v18, v18, 0, 0
	v_med3_f32 v20, v20, 0, v196
	v_cvt_pk_u8_f32 v18, v19, 1, v18
	v_med3_f32 v21, v21, 0, v196
	v_cvt_pk_u8_f32 v18, v20, 2, v18
	v_cvt_pk_u8_f32 v166, v21, 3, v18
	v_med3_f32 v21, v22, 0, v196
	v_med3_f32 v20, v23, 0, v196
	v_cvt_pk_u8_f32 v21, v21, 0, 0
	v_med3_f32 v19, v24, 0, v196
	v_cvt_pk_u8_f32 v20, v20, 1, v21
	v_med3_f32 v21, v26, 0, v196
	v_mfma_f32_32x32x64_f8f6f4 v[34:49], v[50:57], v[130:137], v[34:49]
	v_med3_f32 v18, v25, 0, v196
	v_cvt_pk_u8_f32 v19, v19, 2, v20
	v_med3_f32 v20, v27, 0, v196
	v_cvt_pk_u8_f32 v21, v21, 0, 0
	v_cvt_pk_u8_f32 v167, v18, 3, v19
	v_med3_f32 v19, v28, 0, v196
	v_cvt_pk_u8_f32 v20, v20, 1, v21
	v_med3_f32 v21, v30, 0, v196
	v_med3_f32 v18, v29, 0, v196
	v_cvt_pk_u8_f32 v19, v19, 2, v20
	v_med3_f32 v20, v31, 0, v196
	v_cvt_pk_u8_f32 v21, v21, 0, 0
	v_cvt_pk_u8_f32 v168, v18, 3, v19
	v_med3_f32 v19, v32, 0, v196
	v_cvt_pk_u8_f32 v20, v20, 1, v21
	s_waitcnt lgkmcnt(0)
	v_mfma_f32_32x32x64_f8f6f4 v[50:65], v[58:65], v[122:129], v[2:17]
	ds_read_b128 v[138:141], v189 offset:20480
	ds_read_b128 v[142:145], v189 offset:21504
	ds_read_b128 v[146:149], v189 offset:22528
	ds_read_b128 v[150:153], v189 offset:23552
	v_med3_f32 v34, v34, 0, v196
	v_med3_f32 v35, v35, 0, v196
	v_cvt_pk_u8_f32 v34, v34, 0, 0
	v_med3_f32 v36, v36, 0, v196
	v_cvt_pk_u8_f32 v34, v35, 1, v34
	v_med3_f32 v37, v37, 0, v196
	v_cvt_pk_u8_f32 v34, v36, 2, v34
	v_cvt_pk_u8_f32 v162, v37, 3, v34
	v_med3_f32 v37, v38, 0, v196
	v_med3_f32 v36, v39, 0, v196
	v_cvt_pk_u8_f32 v37, v37, 0, 0
	v_med3_f32 v35, v40, 0, v196
	v_cvt_pk_u8_f32 v36, v36, 1, v37
	v_med3_f32 v37, v42, 0, v196
	v_mfma_f32_32x32x64_f8f6f4 v[50:65], v[74:81], v[130:137], v[50:65]
	v_med3_f32 v34, v41, 0, v196
	v_cvt_pk_u8_f32 v35, v35, 2, v36
	v_med3_f32 v36, v43, 0, v196
	v_cvt_pk_u8_f32 v37, v37, 0, 0
	v_cvt_pk_u8_f32 v163, v34, 3, v35
	v_med3_f32 v35, v44, 0, v196
	v_cvt_pk_u8_f32 v36, v36, 1, v37
	v_med3_f32 v37, v46, 0, v196
	v_med3_f32 v34, v45, 0, v196
	v_cvt_pk_u8_f32 v35, v35, 2, v36
	v_med3_f32 v36, v47, 0, v196
	v_cvt_pk_u8_f32 v37, v37, 0, 0
	v_cvt_pk_u8_f32 v164, v34, 3, v35
	v_med3_f32 v35, v48, 0, v196
	v_cvt_pk_u8_f32 v36, v36, 1, v37
	v_mfma_f32_32x32x64_f8f6f4 v[66:81], v[66:73], v[122:129], v[2:17]
	v_med3_f32 v34, v49, 0, v196
	v_cvt_pk_u8_f32 v35, v35, 2, v36
	v_med3_f32 v18, v33, 0, v196
	v_cvt_pk_u8_f32 v19, v19, 2, v20
	v_cvt_pk_u8_f32 v165, v34, 3, v35
	v_cvt_pk_u8_f32 v169, v18, 3, v19
	v_med3_f32 v50, v50, 0, v196
	v_med3_f32 v51, v51, 0, v196
	v_cvt_pk_u8_f32 v50, v50, 0, 0
	v_med3_f32 v52, v52, 0, v196
	v_cvt_pk_u8_f32 v50, v51, 1, v50
	v_med3_f32 v53, v53, 0, v196
	v_cvt_pk_u8_f32 v50, v52, 2, v50
	v_cvt_pk_u8_f32 v158, v53, 3, v50
	v_mfma_f32_32x32x64_f8f6f4 v[66:81], v[98:105], v[130:137], v[66:81]
	v_med3_f32 v53, v54, 0, v196
	v_med3_f32 v52, v55, 0, v196
	v_cvt_pk_u8_f32 v53, v53, 0, 0
	v_med3_f32 v51, v56, 0, v196
	v_cvt_pk_u8_f32 v52, v52, 1, v53
	v_med3_f32 v53, v58, 0, v196
	v_med3_f32 v50, v57, 0, v196
	v_cvt_pk_u8_f32 v51, v51, 2, v52
	v_med3_f32 v52, v59, 0, v196
	v_cvt_pk_u8_f32 v53, v53, 0, 0
	v_cvt_pk_u8_f32 v159, v50, 3, v51
	v_med3_f32 v51, v60, 0, v196
	v_cvt_pk_u8_f32 v52, v52, 1, v53
	v_med3_f32 v53, v62, 0, v196
	v_med3_f32 v50, v61, 0, v196
	v_mfma_f32_32x32x64_f8f6f4 v[34:49], v[82:89], v[162:169], 0 blgp:1
	ds_read_b128 v[98:101], v189 offset:24576
	ds_read_b128 v[102:105], v189 offset:25600
	ds_read_b128 v[170:173], v189 offset:26624
	ds_read_b128 v[174:177], v189 offset:27648
	ds_read_b128 v[82:85], v189 offset:28672
	ds_read_b128 v[86:89], v189 offset:29696
	ds_read_b128 v[106:109], v189 offset:30720
	ds_read_b128 v[110:113], v189 offset:31744
	v_med3_f32 v66, v66, 0, v196
	v_med3_f32 v67, v67, 0, v196
	v_cvt_pk_u8_f32 v66, v66, 0, 0
	v_med3_f32 v68, v68, 0, v196
	v_cvt_pk_u8_f32 v66, v67, 1, v66
	v_med3_f32 v69, v69, 0, v196
	v_cvt_pk_u8_f32 v66, v68, 2, v66
	v_cvt_pk_u8_f32 v154, v69, 3, v66
	v_med3_f32 v69, v70, 0, v196
	v_med3_f32 v68, v71, 0, v196
	v_cvt_pk_u8_f32 v69, v69, 0, 0
	v_med3_f32 v67, v72, 0, v196
	v_cvt_pk_u8_f32 v68, v68, 1, v69
	v_mfma_f32_32x32x64_f8f6f4 v[18:33], v[90:97], v[162:169], 0 blgp:1
	v_med3_f32 v69, v74, 0, v196
	v_med3_f32 v66, v73, 0, v196
	v_cvt_pk_u8_f32 v67, v67, 2, v68
	v_med3_f32 v68, v75, 0, v196
	v_cvt_pk_u8_f32 v69, v69, 0, 0
	v_cvt_pk_u8_f32 v155, v66, 3, v67
	v_med3_f32 v67, v76, 0, v196
	v_cvt_pk_u8_f32 v68, v68, 1, v69
	v_med3_f32 v69, v78, 0, v196
	v_med3_f32 v66, v77, 0, v196
	v_cvt_pk_u8_f32 v67, v67, 2, v68
	v_med3_f32 v68, v79, 0, v196
	v_cvt_pk_u8_f32 v69, v69, 0, 0
	v_cvt_pk_u8_f32 v51, v51, 2, v52
	v_med3_f32 v52, v63, 0, v196
	s_waitcnt lgkmcnt(0)
	v_mfma_f32_32x32x64_f8f6f4 v[82:97], v[82:89], v[122:129], v[2:17]
	v_cvt_pk_u8_f32 v53, v53, 0, 0
	v_cvt_pk_u8_f32 v156, v66, 3, v67
	v_med3_f32 v67, v80, 0, v196
	v_cvt_pk_u8_f32 v68, v68, 1, v69
	v_cvt_pk_u8_f32 v160, v50, 3, v51
	v_med3_f32 v51, v64, 0, v196
	v_cvt_pk_u8_f32 v52, v52, 1, v53
	v_med3_f32 v66, v81, 0, v196
	v_cvt_pk_u8_f32 v67, v67, 2, v68
	v_med3_f32 v50, v65, 0, v196
	v_cvt_pk_u8_f32 v51, v51, 2, v52
	v_cvt_pk_u8_f32 v157, v66, 3, v67
	v_cvt_pk_u8_f32 v161, v50, 3, v51
	v_mfma_f32_32x32x64_f8f6f4 v[82:97], v[106:113], v[130:137], v[82:97]
	v_mfma_f32_32x32x64_f8f6f4 v[98:113], v[98:105], v[122:129], v[2:17]
	s_nop 15
	s_nop 2
	v_med3_f32 v82, v82, 0, v196
	v_med3_f32 v83, v83, 0, v196
	v_cvt_pk_u8_f32 v82, v82, 0, 0
	v_med3_f32 v84, v84, 0, v196
	v_cvt_pk_u8_f32 v82, v83, 1, v82
	v_med3_f32 v85, v85, 0, v196
	v_cvt_pk_u8_f32 v82, v84, 2, v82
	v_med3_f32 v84, v87, 0, v196
	v_med3_f32 v83, v88, 0, v196
	v_mfma_f32_32x32x64_f8f6f4 v[98:113], v[170:177], v[130:137], v[98:113]
	v_mfma_f32_32x32x64_f8f6f4 v[50:65], v[114:121], v[162:169], 0 blgp:1
	s_nop 15
	s_nop 2
	v_med3_f32 v98, v98, 0, v196
	v_med3_f32 v99, v99, 0, v196
	v_cvt_pk_u8_f32 v98, v98, 0, 0
	v_med3_f32 v100, v100, 0, v196
	v_cvt_pk_u8_f32 v98, v99, 1, v98
	v_med3_f32 v101, v101, 0, v196
	v_cvt_pk_u8_f32 v98, v100, 2, v98
	v_med3_f32 v102, v102, 0, v196
	v_cvt_pk_u8_f32 v98, v101, 3, v98
	v_med3_f32 v101, v103, 0, v196
	v_cvt_pk_u8_f32 v102, v102, 0, 0
	v_med3_f32 v103, v106, 0, v196
	v_med3_f32 v100, v104, 0, v196
	v_cvt_pk_u8_f32 v101, v101, 1, v102
	v_med3_f32 v102, v107, 0, v196
	v_mfma_f32_32x32x64_f8f6f4 v[34:49], v[138:145], v[154:161], v[34:49] blgp:1
	v_cvt_pk_u8_f32 v103, v103, 0, 0
	v_med3_f32 v104, v110, 0, v196
	v_med3_f32 v99, v105, 0, v196
	v_cvt_pk_u8_f32 v100, v100, 2, v101
	v_med3_f32 v101, v108, 0, v196
	v_cvt_pk_u8_f32 v102, v102, 1, v103
	v_med3_f32 v103, v111, 0, v196
	v_cvt_pk_u8_f32 v104, v104, 0, 0
	v_cvt_pk_u8_f32 v99, v99, 3, v100
	v_med3_f32 v100, v109, 0, v196
	v_cvt_pk_u8_f32 v101, v101, 2, v102
	v_med3_f32 v102, v112, 0, v196
	v_cvt_pk_u8_f32 v103, v103, 1, v104
	v_cvt_pk_u8_f32 v100, v100, 3, v101
	v_med3_f32 v101, v113, 0, v196
	v_mfma_f32_32x32x64_f8f6f4 v[18:33], v[146:153], v[154:161], v[18:33] blgp:1
	ds_read_b128 v[138:141], v189 offset:32768
	ds_read_b128 v[142:145], v189 offset:33792
	ds_read_b128 v[146:149], v189 offset:34816
	ds_read_b128 v[150:153], v189 offset:35840
	ds_read_b128 v[66:69], v189 offset:36864
	ds_read_b128 v[70:73], v189 offset:37888
	ds_read_b128 v[162:165], v189 offset:38912
	ds_read_b128 v[166:169], v189 offset:39936
	ds_read_b128 v[170:173], v189 offset:40960
	ds_read_b128 v[174:177], v189 offset:41984
	ds_read_b128 v[198:201], v189 offset:43008
	ds_read_b128 v[202:205], v189 offset:44032
	v_cvt_pk_u8_f32 v102, v102, 2, v103
	v_cvt_pk_u8_f32 v101, v101, 3, v102
	v_cvt_pk_u8_f32 v102, v85, 3, v82
	v_med3_f32 v85, v86, 0, v196
	v_cvt_pk_u8_f32 v85, v85, 0, 0
	v_cvt_pk_u8_f32 v84, v84, 1, v85
	v_med3_f32 v85, v90, 0, v196
	v_med3_f32 v82, v89, 0, v196
	v_cvt_pk_u8_f32 v83, v83, 2, v84
	v_med3_f32 v84, v91, 0, v196
	v_cvt_pk_u8_f32 v85, v85, 0, 0
	v_cvt_pk_u8_f32 v103, v82, 3, v83
	v_med3_f32 v83, v92, 0, v196
	s_waitcnt lgkmcnt(0)
	v_mfma_f32_32x32x64_f8f6f4 v[66:81], v[66:73], v[122:129], v[2:17]
	v_cvt_pk_u8_f32 v84, v84, 1, v85
	v_med3_f32 v85, v94, 0, v196
	v_med3_f32 v82, v93, 0, v196
	v_cvt_pk_u8_f32 v83, v83, 2, v84
	v_med3_f32 v84, v95, 0, v196
	v_cvt_pk_u8_f32 v85, v85, 0, 0
	v_cvt_pk_u8_f32 v104, v82, 3, v83
	v_med3_f32 v83, v96, 0, v196
	v_cvt_pk_u8_f32 v84, v84, 1, v85
	v_med3_f32 v82, v97, 0, v196
	v_cvt_pk_u8_f32 v83, v83, 2, v84
	v_cvt_pk_u8_f32 v105, v82, 3, v83
	ds_read_b128 v[90:93], v189 offset:45056
	ds_read_b128 v[94:97], v189 offset:46080
	ds_read_b128 v[82:85], v189 offset:47104
	ds_read_b128 v[86:89], v189 offset:48128
	v_mfma_f32_32x32x64_f8f6f4 v[2:17], v[138:145], v[122:129], v[2:17]
	v_mfma_f32_32x32x64_f8f6f4 v[50:65], v[114:121], v[154:161], v[50:65] blgp:1
	v_mfma_f32_32x32x64_f8f6f4 v[2:17], v[146:153], v[130:137], v[2:17]
	v_mfma_f32_32x32x64_f8f6f4 v[66:81], v[162:169], v[130:137], v[66:81]
	s_nop 15
	s_nop 2
	v_med3_f32 v2, v2, 0, v196
	v_med3_f32 v3, v3, 0, v196
	v_cvt_pk_u8_f32 v2, v2, 0, 0
	v_med3_f32 v4, v4, 0, v196
	v_cvt_pk_u8_f32 v2, v3, 1, v2
	v_med3_f32 v5, v5, 0, v196
	v_cvt_pk_u8_f32 v2, v4, 2, v2
	v_med3_f32 v6, v6, 0, v196
	v_cvt_pk_u8_f32 v2, v5, 3, v2
	v_med3_f32 v5, v7, 0, v196
	v_cvt_pk_u8_f32 v6, v6, 0, 0
	v_med3_f32 v7, v10, 0, v196
	v_med3_f32 v4, v8, 0, v196
	v_cvt_pk_u8_f32 v5, v5, 1, v6
	v_med3_f32 v6, v11, 0, v196
	v_mfma_f32_32x32x64_f8f6f4 v[50:65], v[114:121], v[98:105], v[50:65] blgp:1
	v_cvt_pk_u8_f32 v7, v7, 0, 0
	v_med3_f32 v8, v14, 0, v196
	v_med3_f32 v3, v9, 0, v196
	v_cvt_pk_u8_f32 v4, v4, 2, v5
	v_med3_f32 v5, v12, 0, v196
	v_cvt_pk_u8_f32 v6, v6, 1, v7
	v_med3_f32 v7, v15, 0, v196
	v_cvt_pk_u8_f32 v8, v8, 0, 0
	v_med3_f32 v9, v66, 0, v196
	v_cvt_pk_u8_f32 v3, v3, 3, v4
	v_med3_f32 v4, v13, 0, v196
	v_cvt_pk_u8_f32 v5, v5, 2, v6
	v_med3_f32 v6, v16, 0, v196
	v_cvt_pk_u8_f32 v7, v7, 1, v8
	v_med3_f32 v8, v67, 0, v196
	v_cvt_pk_u8_f32 v9, v9, 0, 0
	v_med3_f32 v10, v70, 0, v196
	v_cvt_pk_u8_f32 v4, v4, 3, v5
	v_med3_f32 v5, v17, 0, v196
	v_cvt_pk_u8_f32 v6, v6, 2, v7
	v_med3_f32 v7, v68, 0, v196
	v_cvt_pk_u8_f32 v8, v8, 1, v9
	v_med3_f32 v9, v71, 0, v196
	v_cvt_pk_u8_f32 v10, v10, 0, 0
	v_med3_f32 v11, v74, 0, v196
	v_cvt_pk_u8_f32 v5, v5, 3, v6
	v_med3_f32 v6, v69, 0, v196
	v_cvt_pk_u8_f32 v7, v7, 2, v8
	v_med3_f32 v8, v72, 0, v196
	v_cvt_pk_u8_f32 v9, v9, 1, v10
	v_med3_f32 v10, v75, 0, v196
	v_cvt_pk_u8_f32 v11, v11, 0, 0
	v_med3_f32 v12, v78, 0, v196
	v_cvt_pk_u8_f32 v6, v6, 3, v7
	v_med3_f32 v7, v73, 0, v196
	v_cvt_pk_u8_f32 v8, v8, 2, v9
	v_med3_f32 v9, v76, 0, v196
	v_cvt_pk_u8_f32 v10, v10, 1, v11
	v_med3_f32 v11, v79, 0, v196
	v_cvt_pk_u8_f32 v12, v12, 0, 0
	v_cvt_pk_u8_f32 v7, v7, 3, v8
	v_med3_f32 v8, v77, 0, v196
	v_cvt_pk_u8_f32 v9, v9, 2, v10
	v_med3_f32 v10, v80, 0, v196
	v_cvt_pk_u8_f32 v11, v11, 1, v12
	v_mfma_f32_32x32x64_f8f6f4 v[34:49], v[170:177], v[98:105], v[34:49] blgp:1
	v_cvt_pk_u8_f32 v8, v8, 3, v9
	v_med3_f32 v9, v81, 0, v196
	v_cvt_pk_u8_f32 v10, v10, 2, v11
	v_cvt_pk_u8_f32 v9, v9, 3, v10
	v_mfma_f32_32x32x64_f8f6f4 v[18:33], v[198:205], v[98:105], v[18:33] blgp:1
	s_nop 0
	v_mfma_f32_32x32x64_f8f6f4 v[50:65], v[114:121], v[2:9], v[50:65] blgp:1
	s_waitcnt lgkmcnt(0)
	v_mfma_f32_32x32x64_f8f6f4 v[34:49], v[90:97], v[2:9], v[34:49] blgp:1
	s_nop 15
	s_nop 1
	v_cmp_nlt_f32_e32 vcc, 0, v50
	v_cmp_ngt_f32_e64 s[6:7], s30, v50
	s_or_b64 s[6:7], vcc, s[6:7]
	s_cmp_gt_i32 s34, 15
	v_mfma_f32_32x32x64_f8f6f4 v[18:33], v[82:89], v[2:9], v[18:33] blgp:1
	v_div_scale_f32 v2, s[36:37], v50, v50, 1.0
	v_rcp_f32_e32 v3, v2
	s_nop 0
	v_fma_f32 v4, -v2, v3, 1.0
	v_fmac_f32_e32 v3, v4, v3
	v_div_scale_f32 v4, vcc, 1.0, v50, 1.0
	v_mul_f32_e32 v5, v4, v3
	v_fma_f32 v6, -v2, v5, v4
	v_fmac_f32_e32 v5, v6, v3
	v_fma_f32 v2, -v2, v5, v4
	v_div_fmas_f32 v2, v2, v3, v5
	v_div_fixup_f32 v2, v2, v50, 1.0
	v_cndmask_b32_e64 v4, v2, 0, s[6:7]
	v_lshl_add_u64 v[6:7], v[186:187], 0, v[184:185]
	v_lshl_add_u64 v[2:3], v[6:7], 0, s[18:19]
	v_pk_mul_f32 v[8:9], v[34:35], v[4:5] op_sel_hi:[1,0]
	v_pk_mul_f32 v[10:11], v[36:37], v[4:5] op_sel_hi:[1,0]
	v_add_co_u32_e32 v6, vcc, s31, v6
	v_cvt_pk_bf16_f32 v8, v8, v9
	v_cvt_pk_bf16_f32 v9, v10, v11
	v_addc_co_u32_e32 v7, vcc, 0, v7, vcc
	global_store_dwordx2 v[6:7], v[8:9], off offset:1280
	v_pk_mul_f32 v[6:7], v[38:39], v[4:5] op_sel_hi:[1,0]
	v_pk_mul_f32 v[8:9], v[40:41], v[4:5] op_sel_hi:[1,0]
	v_cvt_pk_bf16_f32 v6, v6, v7
	v_cvt_pk_bf16_f32 v7, v8, v9
	global_store_dwordx2 v[2:3], v[6:7], off offset:16
	v_pk_mul_f32 v[6:7], v[42:43], v[4:5] op_sel_hi:[1,0]
	v_pk_mul_f32 v[8:9], v[44:45], v[4:5] op_sel_hi:[1,0]
	v_cvt_pk_bf16_f32 v6, v6, v7
	v_cvt_pk_bf16_f32 v7, v8, v9
	global_store_dwordx2 v[2:3], v[6:7], off offset:32
	v_pk_mul_f32 v[6:7], v[46:47], v[4:5] op_sel_hi:[1,0]
	v_pk_mul_f32 v[8:9], v[48:49], v[4:5] op_sel_hi:[1,0]
	v_cvt_pk_bf16_f32 v6, v6, v7
	v_cvt_pk_bf16_f32 v7, v8, v9
	global_store_dwordx2 v[2:3], v[6:7], off offset:48
	v_pk_mul_f32 v[6:7], v[18:19], v[4:5] op_sel_hi:[1,0]
	v_pk_mul_f32 v[8:9], v[20:21], v[4:5] op_sel_hi:[1,0]
	v_cvt_pk_bf16_f32 v6, v6, v7
	v_cvt_pk_bf16_f32 v7, v8, v9
	global_store_dwordx2 v[2:3], v[6:7], off offset:64
	v_pk_mul_f32 v[6:7], v[22:23], v[4:5] op_sel_hi:[1,0]
	v_pk_mul_f32 v[8:9], v[24:25], v[4:5] op_sel_hi:[1,0]
	v_cvt_pk_bf16_f32 v6, v6, v7
	v_cvt_pk_bf16_f32 v7, v8, v9
	global_store_dwordx2 v[2:3], v[6:7], off offset:80
	v_pk_mul_f32 v[6:7], v[26:27], v[4:5] op_sel_hi:[1,0]
	v_pk_mul_f32 v[8:9], v[28:29], v[4:5] op_sel_hi:[1,0]
	v_cvt_pk_bf16_f32 v6, v6, v7
	v_cvt_pk_bf16_f32 v7, v8, v9
	global_store_dwordx2 v[2:3], v[6:7], off offset:96
	v_pk_mul_f32 v[6:7], v[30:31], v[4:5] op_sel_hi:[1,0]
	v_pk_mul_f32 v[4:5], v[32:33], v[4:5] op_sel_hi:[1,0]
	v_cvt_pk_bf16_f32 v6, v6, v7
	v_cvt_pk_bf16_f32 v7, v4, v5
	global_store_dwordx2 v[2:3], v[6:7], off offset:112
	s_barrier
	s_cbranch_scc0 .LBB0_1294

.LBB0_1298:
	s_ashr_i32 s10, s8, 6
	s_and_b32 s11, s8, 63
	s_lshr_b32 s8, s42, 1
	s_add_i32 s22, s8, s34
	s_lshl_b32 s8, s42, 5
	s_and_b32 s8, s8, 32
	s_add_i32 s26, s8, s31
	s_and_b64 s[8:9], s[16:17], exec
	s_cselect_b32 s9, s22, s10
	s_cselect_b32 s8, s26, s11
	s_ashr_i32 s10, s9, 3
	s_mul_i32 s11, s10, 0x4100
	s_lshl_b32 s8, s8, 8
	s_add_i32 s11, s11, s8
	v_add_u32_e32 v166, s11, v170
	v_ashrrev_i32_e32 v167, 31, v166
	s_and_b32 s43, s9, 7
	v_lshlrev_b64 v[2:3], 9, v[166:167]
	v_lshl_add_u64 v[2:3], s[18:19], 0, v[2:3]
	s_lshl_b32 s22, s43, 6
	v_lshl_add_u64 v[2:3], v[2:3], 0, s[22:23]
	s_lshl_b32 s22, s43, 2
	s_mul_i32 s44, s9, 0x104000
	s_mul_hi_i32 s45, s9, 0x104000
	s_add_u32 s53, s35, s44
	s_addc_u32 s55, s36, s45
	s_lshl_b32 s8, s10, 2
	s_bfe_u32 s10, s9, 0x20001
	s_or_b32 s50, s8, s10
	s_mul_hi_i32 s51, s50, 0x208000
	s_mul_i32 s50, s50, 0x208000
	s_add_u32 s62, s37, s50
	s_addc_u32 s63, s38, s51
	s_add_i32 s8, s9, 16
	s_ashr_i32 s9, s8, 31
	v_lshlrev_b64 v[4:5], 5, v[166:167]
	s_lshl_b64 s[8:9], s[8:9], 2
	v_lshl_add_u64 v[4:5], s[12:13], 0, v[4:5]
	s_add_u32 s8, s3, s8
	v_lshl_add_u64 v[4:5], v[4:5], 0, s[22:23]
	s_addc_u32 s9, s28, s9
	global_load_dword v42, v[4:5], off
	global_load_dword v18, v163, s[8:9]
	v_lshl_add_u64 v[2:3], v[2:3], 0, v[210:211]
	global_load_dwordx4 v[150:153], v[2:3], off offset:16
	global_load_dwordx4 v[146:149], v[2:3], off
	v_readfirstlane_b32 s8, v1
	s_ashr_i32 s26, s8, 6
	s_cmp_lt_i32 s26, 3
	s_mul_i32 s46, s26, 0xc00
	s_cselect_b64 s[10:11], -1, 0
	s_add_i32 s52, s46, 0xffffe000
	s_add_u32 s22, s62, s52
	s_addc_u32 s27, s63, 0
	s_ashr_i32 s47, s46, 31
	s_add_u32 s49, s53, s46
	s_addc_u32 s64, s55, s47
	s_and_b64 s[8:9], s[10:11], exec
	s_cselect_b32 s9, s64, s27
	s_cselect_b32 s8, s49, s22
	s_add_i32 s65, s46, 0x400
	s_add_i32 s22, s46, 0
	s_ashr_i32 s66, s65, 31
	s_add_u32 s27, s49, 0x400
	s_addc_u32 s67, s64, 0
	s_add_i32 s48, s46, 0xffffe400
	s_add_u32 s68, s62, s48
	s_addc_u32 s69, s63, 0
	v_lshl_add_u64 v[2:3], s[8:9], 0, v[164:165]
	s_mov_b32 m0, s22
	s_and_b64 s[8:9], s[10:11], exec
	v_lshrrev_b32 v154, 2, v0
	v_xor_b32 v154, v154, v0
	v_bfe_u32 v154, v154, 2, 1
	v_add_u32 v154, -1, v154
	v_and_b32 v154, 0x38383838, v154
	v_mov_b32 v155, v154
	v_mov_b32 v156, v154
	v_mov_b32 v157, v154
	v_mov_b32 v158, v154
	v_mov_b32 v159, v154
	v_mov_b32 v160, v154
	v_mov_b32 v161, v154
	global_load_lds_dwordx4 v[2:3], off
	s_cselect_b32 s9, s67, s69
	s_cselect_b32 s8, s27, s68
	s_add_i32 m0, s22, 0x400
	s_cmp_lt_i32 s26, 2
	s_cselect_b64 s[26:27], -1, 0
	s_add_i32 s67, s46, 0x800
	s_ashr_i32 s68, s67, 31
	s_add_u32 s69, s49, 0x800
	s_addc_u32 s64, s64, 0
	s_add_i32 s49, s46, 0xffffe800
	s_add_u32 s70, s62, s49
	s_addc_u32 s71, s63, 0
	v_lshl_add_u64 v[2:3], s[8:9], 0, v[164:165]
	s_and_b64 s[8:9], s[26:27], exec
	global_load_lds_dwordx4 v[2:3], off
	s_cselect_b32 s9, s64, s71
	s_cselect_b32 s8, s69, s70
	s_add_i32 m0, s22, 0x800
	s_add_u32 s62, s62, 0x4000
	s_addc_u32 s63, s63, 0
	s_add_u32 s53, s53, 0x2000
	s_addc_u32 s55, s55, 0
	s_add_u32 s64, s53, s46
	s_addc_u32 s69, s55, s47
	s_add_u32 s70, s62, s52
	s_addc_u32 s71, s63, 0
	v_lshl_add_u64 v[2:3], s[8:9], 0, v[164:165]
	s_and_b64 s[8:9], s[10:11], exec
	global_load_lds_dwordx4 v[2:3], off
	s_cselect_b32 s9, s69, s71
	s_cselect_b32 s8, s64, s70
	s_add_i32 m0, s22, 0x6000
	s_add_u32 s64, s53, s65
	s_addc_u32 s65, s55, s66
	s_add_u32 s66, s62, s48
	s_addc_u32 s69, s63, 0
	v_lshl_add_u64 v[2:3], s[8:9], 0, v[164:165]
	s_and_b64 s[8:9], s[10:11], exec
	global_load_lds_dwordx4 v[2:3], off
	s_cselect_b32 s9, s65, s69
	s_cselect_b32 s8, s64, s66
	s_add_i32 m0, s22, 0x6400
	s_add_u32 s53, s53, s67
	s_addc_u32 s55, s55, s68
	s_add_u32 s62, s62, s49
	s_addc_u32 s63, s63, 0
	v_lshl_add_u64 v[2:3], s[8:9], 0, v[164:165]
	s_and_b64 s[8:9], s[26:27], exec
	s_cselect_b32 s9, s55, s63
	s_cselect_b32 s8, s53, s62
	global_load_lds_dwordx4 v[2:3], off
	v_lshl_add_u64 v[2:3], s[8:9], 0, v[164:165]
	s_add_i32 m0, s22, 0x6800
	s_waitcnt vmcnt(0)
	v_mul_f32_e32 v19, 0x4f800000, v18
	global_load_lds_dwordx4 v[2:3], off
	s_waitcnt vmcnt(3)
	s_barrier
	ds_read_b128 v[2:5], v171
	ds_read_b128 v[6:9], v171 offset:1024
	v_cmp_gt_f32_e32 vcc, s39, v18
	s_waitcnt lgkmcnt(0)
	v_mfma_f32_32x32x64_f8f6f4 v[2:17], v[2:9], v[146:153], 0
	v_cndmask_b32_e32 v43, v18, v19, vcc
	v_sqrt_f32_e32 v26, v43
	ds_read_b128 v[18:21], v171 offset:2048
	ds_read_b128 v[22:25], v171 offset:3072
	s_add_u32 s44, s44, s46
	s_addc_u32 s45, s45, s47
	v_add_u32_e32 v27, -1, v26
	v_fma_f32 v28, -v27, v26, v43
	v_cmp_ge_f32_e64 s[8:9], 0, v28
	v_add_u32_e32 v28, 1, v26
	s_add_u32 s46, s50, s49
	v_cndmask_b32_e64 v27, v26, v27, s[8:9]
	v_fma_f32 v26, -v28, v26, v43
	v_cmp_lt_f32_e64 s[8:9], 0, v26
	s_addc_u32 s47, s51, 0
	s_add_u32 s48, s50, s48
	v_cndmask_b32_e64 v34, v27, v28, s[8:9]
	s_waitcnt lgkmcnt(0)
	v_mfma_f32_32x32x64_f8f6f4 v[18:33], v[18:25], v[146:153], 0
	v_max3_f32 v2, v2, s40, v3
	v_max3_f32 v2, v2, v4, v5
	v_max3_f32 v2, v2, v6, v7
	v_max3_f32 v2, v2, v8, v9
	v_mul_f32_e32 v35, 0x37800000, v34
	v_max3_f32 v2, v2, v10, v11
	v_cndmask_b32_e32 v44, v34, v35, vcc
	ds_read_b128 v[34:37], v171 offset:4096
	ds_read_b128 v[38:41], v171 offset:5120
	v_max3_f32 v2, v2, v12, v13
	v_max3_f32 v2, v2, v14, v15
	v_max3_f32 v2, v2, v16, v17
	v_cmp_lt_i32_e32 vcc, v176, v177
	s_addc_u32 s49, s51, 0
	s_add_u32 s50, s50, s52
	s_addc_u32 s51, s51, 0
	s_nop 3
	v_max3_f32 v2, v2, v18, v19
	v_max3_f32 v2, v2, v20, v21
	v_max3_f32 v18, v2, v22, v23
	s_waitcnt lgkmcnt(0)
	v_mfma_f32_32x32x64_f8f6f4 v[2:17], v[34:41], v[146:153], 0
	v_max3_f32 v18, v18, v24, v25
	v_max3_f32 v18, v18, v26, v27
	v_max3_f32 v18, v18, v28, v29
	v_max3_f32 v18, v18, v30, v31
	v_max3_f32 v26, v18, v32, v33
	ds_read_b128 v[18:21], v171 offset:6144
	ds_read_b128 v[22:25], v171 offset:7168
	s_mov_b32 s55, 0
	s_mov_b32 s52, 0
	v_mov_b32_e32 v27, v163
	v_mov_b32_e32 v28, v163
	v_mov_b32_e32 v29, v163
	v_mov_b32_e32 v30, v163
	v_mov_b32_e32 v31, v163
	v_mov_b32_e32 v32, v163
	v_mov_b32_e32 v33, v163
	s_nop 3
	v_max3_f32 v2, v26, v2, v3
	v_max3_f32 v2, v2, v4, v5
	v_max3_f32 v2, v2, v6, v7
	v_max3_f32 v2, v2, v8, v9
	v_max3_f32 v2, v2, v10, v11
	v_max3_f32 v2, v2, v12, v13
	v_max3_f32 v2, v2, v14, v15
	v_max3_f32 v26, v2, v16, v17
	s_waitcnt lgkmcnt(0)
	v_mfma_f32_32x32x64_f8f6f4 v[2:17], v[18:25], v[146:153], 0
	v_mov_b32_e32 v18, 0
	v_mov_b32_e32 v19, v163
	v_mov_b32_e32 v20, v163
	v_mov_b32_e32 v21, v163
	v_mov_b32_e32 v22, v163
	v_mov_b32_e32 v23, v163
	v_mov_b32_e32 v24, v163
	v_mov_b32_e32 v25, v163
	v_mov_b32_e32 v34, 0
	v_mov_b32_e32 v35, v163
	v_mov_b32_e32 v36, v163
	v_mov_b32_e32 v37, v163
	v_mov_b32_e32 v38, v163
	v_mov_b32_e32 v39, v163
	v_mov_b32_e32 v40, v163
	s_nop 4
	v_max3_f32 v2, v26, v2, v3
	v_max3_f32 v2, v2, v4, v5
	v_max3_f32 v2, v2, v6, v7
	v_max3_f32 v2, v2, v8, v9
	v_max3_f32 v2, v2, v10, v11
	v_max3_f32 v2, v2, v12, v13
	v_max3_f32 v2, v2, v14, v15
	v_cndmask_b32_e32 v3, v175, v176, vcc
	v_max3_f32 v2, v2, v16, v17
	v_lshlrev_b32_e32 v3, 2, v3
	ds_bpermute_b32 v3, v3, v2
	v_cmp_class_f32_e32 vcc, v43, v172
	v_mov_b32_e32 v5, v163
	v_mov_b32_e32 v6, v163
	v_cndmask_b32_e32 v4, v44, v43, vcc
	s_waitcnt lgkmcnt(0)
	v_max_f32_e32 v3, v3, v3
	v_mul_f32_e32 v4, v42, v4
	v_max_f32_e32 v2, v2, v3
	v_fmamk_f32 v4, v4, 0x3f90a3d7, v173
	v_add_f32_e32 v2, 0x42800000, v2
	v_min_f32_e32 v2, v4, v2
	v_add_f32_e32 v2, 0xc2ec0000, v2
	v_xor_b32_e32 v50, 0x80000000, v2
	v_mov_b32_e32 v51, v50
	v_mov_b32_e32 v52, v50
	v_mov_b32_e32 v53, v50
	v_mov_b32_e32 v54, v50
	v_mov_b32_e32 v55, v50
	v_mov_b32_e32 v56, v50
	v_mov_b32_e32 v57, v50
	v_mov_b32_e32 v58, v50
	v_mov_b32_e32 v59, v50
	v_mov_b32_e32 v60, v50
	v_mov_b32_e32 v61, v50
	v_mov_b32_e32 v62, v50
	v_mov_b32_e32 v63, v50
	v_mov_b32_e32 v64, v50
	v_mov_b32_e32 v65, v50
	v_mov_b32_e32 v2, 0
	v_mov_b32_e32 v3, v163
	v_mov_b32_e32 v4, v163
	v_mov_b32_e32 v7, v163
	v_mov_b32_e32 v8, v163
	v_mov_b32_e32 v9, v163
	v_mov_b32_e32 v10, v163
	v_mov_b32_e32 v11, v163
	v_mov_b32_e32 v12, v163
	v_mov_b32_e32 v13, v163
	v_mov_b32_e32 v14, v163
	v_mov_b32_e32 v15, v163
	v_mov_b32_e32 v16, v163
	v_mov_b32_e32 v17, v163
	v_mov_b32_e32 v26, v163
	v_mov_b32_e32 v41, v163
	v_mov_b32_e32 v42, v163
	v_mov_b32_e32 v43, v163
	v_mov_b32_e32 v44, v163
	v_mov_b32_e32 v45, v163
	v_mov_b32_e32 v46, v163
	v_mov_b32_e32 v47, v163
	v_mov_b32_e32 v48, v163
	v_mov_b32_e32 v49, v163
	v_mov_b32_e32 v66, 0
	v_mov_b32_e32 v67, v163
	v_mov_b32_e32 v68, v163
	v_mov_b32_e32 v69, v163
	v_mov_b32_e32 v70, v163
	v_mov_b32_e32 v71, v163
	v_mov_b32_e32 v72, v163
	v_mov_b32_e32 v73, v163
	v_mov_b32_e32 v74, v163
	v_mov_b32_e32 v75, v163
	v_mov_b32_e32 v76, v163
	v_mov_b32_e32 v77, v163
	v_mov_b32_e32 v78, v163
	v_mov_b32_e32 v79, v163
	v_mov_b32_e32 v80, v163
	v_mov_b32_e32 v81, v163
	v_mov_b32_e32 v82, 0
	v_mov_b32_e32 v83, v163
	v_mov_b32_e32 v84, v163
	v_mov_b32_e32 v85, v163
	v_mov_b32_e32 v86, v163
	v_mov_b32_e32 v87, v163
	v_mov_b32_e32 v88, v163
	v_mov_b32_e32 v89, v163
	v_mov_b32_e32 v90, v163
	v_mov_b32_e32 v91, v163
	v_mov_b32_e32 v92, v163
	v_mov_b32_e32 v93, v163
	v_mov_b32_e32 v94, v163
	v_mov_b32_e32 v95, v163
	v_mov_b32_e32 v96, v163
	v_mov_b32_e32 v97, v163
	v_mov_b32_e32 v142, v210
	v_mov_b32_e32 v143, v211
	v_mov_b32_e32 v144, v218
	v_mov_b32_e32 v145, v219
	v_mov_b32_e32 v118, v163
	v_mov_b32_e32 v119, v163
	v_mov_b32_e32 v120, v163
	v_mov_b32_e32 v121, v163
	v_mov_b32_e32 v122, v163
	v_mov_b32_e32 v123, v163
	v_mov_b32_e32 v124, v163
	v_mov_b32_e32 v125, v163
	v_mov_b32_e32 v126, v163
	v_mov_b32_e32 v127, v163
	v_mov_b32_e32 v128, v163
	v_mov_b32_e32 v129, v163
	v_mov_b32_e32 v130, v163
	v_mov_b32_e32 v131, v163
	v_mov_b32_e32 v132, v163
	v_mov_b32_e32 v133, v163
	v_mov_b32_e32 v180, v163
	v_mov_b32_e32 v181, v163
	v_mov_b32_e32 v182, v163
	v_mov_b32_e32 v183, v163
	v_mov_b32_e32 v184, v163
	v_mov_b32_e32 v185, v163
	v_mov_b32_e32 v186, v163
	v_mov_b32_e32 v187, v163
	v_mov_b32_e32 v188, v163
	v_mov_b32_e32 v189, v163
	v_mov_b32_e32 v190, v163
	v_mov_b32_e32 v191, v163
	v_mov_b32_e32 v192, v163
	v_mov_b32_e32 v193, v163
	v_mov_b32_e32 v194, v163
	v_mov_b32_e32 v195, v163
	v_mov_b32_e32 v220, v163
	v_mov_b32_e32 v221, v163
	v_mov_b32_e32 v222, v163
	v_mov_b32_e32 v223, v163
	v_mov_b32_e32 v224, v163
	v_mov_b32_e32 v225, v163
	v_mov_b32_e32 v226, v163
	v_mov_b32_e32 v227, v163
	v_mov_b32_e32 v228, v163
	v_mov_b32_e32 v229, v163
	v_mov_b32_e32 v230, v163
	v_mov_b32_e32 v231, v163
	v_mov_b32_e32 v232, v163
	v_mov_b32_e32 v233, v163
	v_mov_b32_e32 v234, v163
	v_mov_b32_e32 v235, v163
	v_mov_b32_e32 v236, v163
	v_mov_b32_e32 v237, v163
	v_mov_b32_e32 v238, v163
	v_mov_b32_e32 v239, v163
	v_mov_b32_e32 v240, v163
	v_mov_b32_e32 v241, v163
	v_mov_b32_e32 v242, v163
	v_mov_b32_e32 v243, v163
	v_mov_b32_e32 v244, v163
	v_mov_b32_e32 v245, v163
	v_mov_b32_e32 v246, v163
	v_mov_b32_e32 v247, v163
	v_mov_b32_e32 v248, v163
	v_mov_b32_e32 v249, v163
	v_mov_b32_e32 v250, v163
	v_mov_b32_e32 v251, v163
	s_add_u32 s98, s29, s44
	s_addc_u32 s99, s30, s45
	s_add_u32 s98, s98, 0x36532100
	s_addc_u32 s99, s99, 0
	s_add_u32 s100, s29, s50
	s_addc_u32 s101, s30, s51
	s_add_u32 s100, s100, 0x385b6100
	s_addc_u32 s101, s101, 0
	s_movk_i32 s74, 0x4000
	s_and_b64 s[62:63], s[10:11], exec
	s_cselect_b32 s63, s99, s101
	s_cselect_b32 s62, s98, s100
	s_cselect_b32 s74, 0x2000, s74
	s_add_u32 s68, s62, s74
	s_addc_u32 s69, s63, 0
	s_lshl_b32 s74, s74, 1
	s_add_u32 s98, s29, s44
	s_addc_u32 s99, s30, s45
	s_add_u32 s98, s98, 0x36532500
	s_addc_u32 s99, s99, 0
	s_add_u32 s100, s29, s48
	s_addc_u32 s101, s30, s49
	s_add_u32 s100, s100, 0x385b6100
	s_addc_u32 s101, s101, 0
	s_movk_i32 s75, 0x4000
	s_and_b64 s[64:65], s[10:11], exec
	s_cselect_b32 s65, s99, s101
	s_cselect_b32 s64, s98, s100
	s_cselect_b32 s75, 0x2000, s75
	s_add_u32 s70, s64, s75
	s_addc_u32 s71, s65, 0
	s_lshl_b32 s75, s75, 1
	s_add_u32 s98, s29, s44
	s_addc_u32 s99, s30, s45
	s_add_u32 s98, s98, 0x36532900
	s_addc_u32 s99, s99, 0
	s_add_u32 s100, s29, s46
	s_addc_u32 s101, s30, s47
	s_add_u32 s100, s100, 0x385b6100
	s_addc_u32 s101, s101, 0
	s_movk_i32 s76, 0x4000
	s_and_b64 s[66:67], s[26:27], exec
	s_cselect_b32 s67, s99, s101
	s_cselect_b32 s66, s98, s100
	s_cselect_b32 s76, 0x2000, s76
	s_add_u32 s72, s66, s76
	s_addc_u32 s73, s67, 0
	s_lshl_b32 s76, s76, 1
	s_mov_b64 s[98:99], 0
	s_branch .LBB0_1300
.LBB0_1300:
	s_waitcnt vmcnt(0) lgkmcnt(0)
	s_barrier
	s_cmpk_gt_u32 s52, 0x7f
	s_cselect_b64 vcc, 0, exec
	s_mul_i32 s100, s55, 0x6000
	s_add_i32 s52, s52, 2
	s_xor_b32 s55, s55, 2
	v_add_u32_e32 v179, s100, v171
.LBB0_1299:
	ds_read_b128 v[204:207], v179
	ds_read_b128 v[208:211], v179 offset:1024
	ds_read_b128 v[212:215], v179 offset:2048
	ds_read_b128 v[216:219], v179 offset:3072
	s_cmp_lg_u64 s[98:99], 0
	s_cbranch_scc1 .Lslow_dif0_0
.Lback_dif0_0:
	v_cvt_pk_u8_f32 v196, v118, 0, 0
	v_cvt_pk_u8_f32 v197, v122, 0, 0
	v_cvt_pk_u8_f32 v198, v126, 0, 0
	v_cvt_pk_u8_f32 v199, v130, 0, 0
	v_cvt_pk_u8_f32 v196, v119, 1, v196
	v_cvt_pk_u8_f32 v197, v123, 1, v197
	v_cvt_pk_u8_f32 v198, v127, 1, v198
	v_cvt_pk_u8_f32 v199, v131, 1, v199
	s_waitcnt lgkmcnt(2)
	v_mfma_f32_32x32x64_f8f6f4 v[86:101], v[204:211], v[146:153], v[50:65]
	v_cvt_pk_u8_f32 v196, v120, 2, v196
	v_cvt_pk_u8_f32 v197, v124, 2, v197
	v_cvt_pk_u8_f32 v198, v128, 2, v198
	v_cvt_pk_u8_f32 v199, v132, 2, v199
	v_cvt_pk_u8_f32 v196, v121, 3, v196
	v_cvt_pk_u8_f32 v197, v125, 3, v197
	v_cvt_pk_u8_f32 v198, v129, 3, v198
	v_cvt_pk_u8_f32 v199, v133, 3, v199
	v_cvt_pk_u8_f32 v200, v180, 0, 0
	v_cvt_pk_u8_f32 v201, v184, 0, 0
	v_cvt_pk_u8_f32 v202, v188, 0, 0
	v_cvt_pk_u8_f32 v203, v192, 0, 0
	s_waitcnt lgkmcnt(0)
	v_mfma_f32_32x32x64_f8f6f4 v[102:117], v[212:219], v[146:153], v[50:65]
	v_cvt_pk_u8_f32 v200, v181, 1, v200
	v_cvt_pk_u8_f32 v201, v185, 1, v201
	v_cvt_pk_u8_f32 v202, v189, 1, v202
	v_cvt_pk_u8_f32 v203, v193, 1, v203
	v_cvt_pk_u8_f32 v200, v182, 2, v200
	v_cvt_pk_u8_f32 v201, v186, 2, v201
	v_cvt_pk_u8_f32 v202, v190, 2, v202
	v_cvt_pk_u8_f32 v203, v194, 2, v203
	v_cvt_pk_u8_f32 v200, v183, 3, v200
	v_cvt_pk_u8_f32 v201, v187, 3, v201
	v_cvt_pk_u8_f32 v202, v191, 3, v202
	v_cvt_pk_u8_f32 v203, v195, 3, v203
	s_nop 0
	s_nop 0
	v_mfma_f32_32x32x64_f8f6f4 v[66:81], v[220:227], v[196:203], v[66:81] blgp:1
	ds_read_b128 v[204:207], v179 offset:4096
	ds_read_b128 v[208:211], v179 offset:5120
	ds_read_b128 v[212:215], v179 offset:6144
	ds_read_b128 v[216:219], v179 offset:7168
	s_cbranch_vccz .Ldma_dif0_skip0
	s_mul_i32 s101, s55, 0x6000
	s_add_i32 s101, s101, s22
	s_mov_b32 m0, s101
	s_nop 0
	global_load_lds_dwordx4 v164, s[62:63]
.Ldma_dif0_skip0:
	v_mfma_f32_32x32x64_f8f6f4 v[34:49], v[228:235], v[196:203], v[34:49] blgp:1
	ds_read_b128 v[220:223], v179 offset:8192
	ds_read_b128 v[224:227], v179 offset:9216
	s_cbranch_vccz .Ldma_dif0_skip1
	s_add_i32 m0, s101, 0x400
	s_add_u32 s62, s62, s74
	s_addc_u32 s63, s63, 0
	global_load_lds_dwordx4 v164, s[64:65]
.Ldma_dif0_skip1:
	v_mfma_f32_32x32x64_f8f6f4 v[18:33], v[236:243], v[196:203], v[18:33] blgp:1
	ds_read_b128 v[228:231], v179 offset:10240
	ds_read_b128 v[232:235], v179 offset:11264
	v_max3_f32 v134, v86, v87, v88
	v_max3_f32 v134, v134, v89, v90
	v_max3_f32 v134, v134, v91, v92
	v_max3_f32 v134, v134, v93, v94
	v_max3_f32 v134, v134, v95, v96
	v_max3_f32 v134, v134, v97, v98
	v_max3_f32 v134, v134, v99, v100
	v_max3_f32 v134, v134, v101, v101
	v_mfma_f32_32x32x64_f8f6f4 v[2:17], v[244:251], v[196:203], v[2:17] blgp:1
	ds_read_b128 v[236:239], v179 offset:12288
	ds_read_b128 v[240:243], v179 offset:13312
	v_max3_f32 v134, v134, v102, v103
	v_max3_f32 v134, v134, v104, v105
	v_max3_f32 v134, v134, v106, v107
	v_max3_f32 v134, v134, v108, v109
	v_max3_f32 v134, v134, v110, v111
	v_max3_f32 v134, v134, v112, v113
	v_max3_f32 v134, v134, v114, v115
	v_max3_f32 v134, v134, v116, v117
	v_cmp_gt_f32_e64 s[98:99], v134, v178
	v_mfma_f32_16x16x128_f8f6f4 v[82:85], v[154:161], v[196:203], v[82:85] blgp:1
	ds_read_b128 v[244:247], v179 offset:14336
	ds_read_b128 v[248:251], v179 offset:15360
	s_cmp_lg_u64 s[98:99], 0
	s_cbranch_scc1 .Lslow_dif0_1
.Lback_dif0_1:
	v_cvt_pk_u8_f32 v196, v86, 0, 0
	v_cvt_pk_u8_f32 v197, v90, 0, 0
	v_cvt_pk_u8_f32 v198, v94, 0, 0
	v_cvt_pk_u8_f32 v199, v98, 0, 0
	v_cvt_pk_u8_f32 v196, v87, 1, v196
	v_cvt_pk_u8_f32 v197, v91, 1, v197
	v_cvt_pk_u8_f32 v198, v95, 1, v198
	v_cvt_pk_u8_f32 v199, v99, 1, v199
	s_waitcnt lgkmcnt(8)
	v_mfma_f32_32x32x64_f8f6f4 v[118:133], v[204:211], v[146:153], v[50:65]
	v_cvt_pk_u8_f32 v196, v88, 2, v196
	v_cvt_pk_u8_f32 v197, v92, 2, v197
	v_cvt_pk_u8_f32 v198, v96, 2, v198
	v_cvt_pk_u8_f32 v199, v100, 2, v199
	v_cvt_pk_u8_f32 v196, v89, 3, v196
	v_cvt_pk_u8_f32 v197, v93, 3, v197
	v_cvt_pk_u8_f32 v198, v97, 3, v198
	v_cvt_pk_u8_f32 v199, v101, 3, v199
	v_cvt_pk_u8_f32 v200, v102, 0, 0
	v_cvt_pk_u8_f32 v201, v106, 0, 0
	v_cvt_pk_u8_f32 v202, v110, 0, 0
	v_cvt_pk_u8_f32 v203, v114, 0, 0
	v_mfma_f32_32x32x64_f8f6f4 v[180:195], v[212:219], v[146:153], v[50:65]
	v_cvt_pk_u8_f32 v200, v103, 1, v200
	v_cvt_pk_u8_f32 v201, v107, 1, v201
	v_cvt_pk_u8_f32 v202, v111, 1, v202
	v_cvt_pk_u8_f32 v203, v115, 1, v203
	v_cvt_pk_u8_f32 v200, v104, 2, v200
	v_cvt_pk_u8_f32 v201, v108, 2, v201
	v_cvt_pk_u8_f32 v202, v112, 2, v202
	v_cvt_pk_u8_f32 v203, v116, 2, v203
	v_cvt_pk_u8_f32 v200, v105, 3, v200
	v_cvt_pk_u8_f32 v201, v109, 3, v201
	v_cvt_pk_u8_f32 v202, v113, 3, v202
	v_cvt_pk_u8_f32 v203, v117, 3, v203
	s_nop 0
	s_waitcnt lgkmcnt(0)
	v_mfma_f32_32x32x64_f8f6f4 v[66:81], v[220:227], v[196:203], v[66:81] blgp:1
	ds_read_b128 v[204:207], v179 offset:24576
	ds_read_b128 v[208:211], v179 offset:25600
	ds_read_b128 v[212:215], v179 offset:26624
	ds_read_b128 v[216:219], v179 offset:27648
	s_cbranch_vccz .Ldma_dif0_skip2
	s_add_i32 m0, s101, 0x800
	s_add_u32 s64, s64, s75
	s_addc_u32 s65, s65, 0
	global_load_lds_dwordx4 v164, s[66:67]
.Ldma_dif0_skip2:
	v_mfma_f32_32x32x64_f8f6f4 v[34:49], v[228:235], v[196:203], v[34:49] blgp:1
	ds_read_b128 v[220:223], v179 offset:16384
	ds_read_b128 v[224:227], v179 offset:17408
	s_cbranch_vccz .Ldma_dif0_skip3
	s_add_i32 m0, s101, 0x6000
	s_add_u32 s66, s66, s76
	s_addc_u32 s67, s67, 0
	global_load_lds_dwordx4 v164, s[68:69]
.Ldma_dif0_skip3:
	v_mfma_f32_32x32x64_f8f6f4 v[18:33], v[236:243], v[196:203], v[18:33] blgp:1
	ds_read_b128 v[228:231], v179 offset:18432
	ds_read_b128 v[232:235], v179 offset:19456
	v_max3_f32 v134, v118, v119, v120
	v_max3_f32 v134, v134, v121, v122
	v_max3_f32 v134, v134, v123, v124
	v_max3_f32 v134, v134, v125, v126
	v_max3_f32 v134, v134, v127, v128
	v_max3_f32 v134, v134, v129, v130
	v_max3_f32 v134, v134, v131, v132
	v_max3_f32 v134, v134, v133, v133
	v_mfma_f32_32x32x64_f8f6f4 v[2:17], v[244:251], v[196:203], v[2:17] blgp:1
	ds_read_b128 v[236:239], v179 offset:20480
	ds_read_b128 v[240:243], v179 offset:21504
	v_max3_f32 v134, v134, v180, v181
	v_max3_f32 v134, v134, v182, v183
	v_max3_f32 v134, v134, v184, v185
	v_max3_f32 v134, v134, v186, v187
	v_max3_f32 v134, v134, v188, v189
	v_max3_f32 v134, v134, v190, v191
	v_max3_f32 v134, v134, v192, v193
	v_max3_f32 v134, v134, v194, v195
	v_cmp_gt_f32_e64 s[98:99], v134, v178
	v_mfma_f32_16x16x128_f8f6f4 v[82:85], v[154:161], v[196:203], v[82:85] blgp:1
	ds_read_b128 v[244:247], v179 offset:22528
	ds_read_b128 v[248:251], v179 offset:23552
	s_cmp_lg_u64 s[98:99], 0
	s_cbranch_scc1 .Lslow_dif0_2
.Lback_dif0_2:
	v_cvt_pk_u8_f32 v196, v118, 0, 0
	v_cvt_pk_u8_f32 v197, v122, 0, 0
	v_cvt_pk_u8_f32 v198, v126, 0, 0
	v_cvt_pk_u8_f32 v199, v130, 0, 0
	v_cvt_pk_u8_f32 v196, v119, 1, v196
	v_cvt_pk_u8_f32 v197, v123, 1, v197
	v_cvt_pk_u8_f32 v198, v127, 1, v198
	v_cvt_pk_u8_f32 v199, v131, 1, v199
	s_waitcnt lgkmcnt(8)
	v_mfma_f32_32x32x64_f8f6f4 v[86:101], v[204:211], v[146:153], v[50:65]
	v_cvt_pk_u8_f32 v196, v120, 2, v196
	v_cvt_pk_u8_f32 v197, v124, 2, v197
	v_cvt_pk_u8_f32 v198, v128, 2, v198
	v_cvt_pk_u8_f32 v199, v132, 2, v199
	v_cvt_pk_u8_f32 v196, v121, 3, v196
	v_cvt_pk_u8_f32 v197, v125, 3, v197
	v_cvt_pk_u8_f32 v198, v129, 3, v198
	v_cvt_pk_u8_f32 v199, v133, 3, v199
	v_cvt_pk_u8_f32 v200, v180, 0, 0
	v_cvt_pk_u8_f32 v201, v184, 0, 0
	v_cvt_pk_u8_f32 v202, v188, 0, 0
	v_cvt_pk_u8_f32 v203, v192, 0, 0
	v_mfma_f32_32x32x64_f8f6f4 v[102:117], v[212:219], v[146:153], v[50:65]
	v_cvt_pk_u8_f32 v200, v181, 1, v200
	v_cvt_pk_u8_f32 v201, v185, 1, v201
	v_cvt_pk_u8_f32 v202, v189, 1, v202
	v_cvt_pk_u8_f32 v203, v193, 1, v203
	v_cvt_pk_u8_f32 v200, v182, 2, v200
	v_cvt_pk_u8_f32 v201, v186, 2, v201
	v_cvt_pk_u8_f32 v202, v190, 2, v202
	v_cvt_pk_u8_f32 v203, v194, 2, v203
	v_cvt_pk_u8_f32 v200, v183, 3, v200
	v_cvt_pk_u8_f32 v201, v187, 3, v201
	v_cvt_pk_u8_f32 v202, v191, 3, v202
	v_cvt_pk_u8_f32 v203, v195, 3, v203
	s_nop 0
	s_waitcnt lgkmcnt(0)
	v_mfma_f32_32x32x64_f8f6f4 v[66:81], v[220:227], v[196:203], v[66:81] blgp:1
	ds_read_b128 v[204:207], v179 offset:28672
	ds_read_b128 v[208:211], v179 offset:29696
	ds_read_b128 v[212:215], v179 offset:30720
	ds_read_b128 v[216:219], v179 offset:31744
	s_cbranch_vccz .Ldma_dif0_skip4
	s_add_i32 m0, s101, 0x6400
	s_add_u32 s68, s68, s74
	s_addc_u32 s69, s69, 0
	global_load_lds_dwordx4 v164, s[70:71]
.Ldma_dif0_skip4:
	v_mfma_f32_32x32x64_f8f6f4 v[34:49], v[228:235], v[196:203], v[34:49] blgp:1
	ds_read_b128 v[220:223], v179 offset:32768
	ds_read_b128 v[224:227], v179 offset:33792
	s_cbranch_vccz .Ldma_dif0_skip5
	s_add_i32 m0, s101, 0x6800
	s_add_u32 s70, s70, s75
	s_addc_u32 s71, s71, 0
	global_load_lds_dwordx4 v164, s[72:73]
	s_add_u32 s72, s72, s76
	s_addc_u32 s73, s73, 0
.Ldma_dif0_skip5:
	v_mfma_f32_32x32x64_f8f6f4 v[18:33], v[236:243], v[196:203], v[18:33] blgp:1
	ds_read_b128 v[228:231], v179 offset:34816
	ds_read_b128 v[232:235], v179 offset:35840
	v_max3_f32 v134, v86, v87, v88
	v_max3_f32 v134, v134, v89, v90
	v_max3_f32 v134, v134, v91, v92
	v_max3_f32 v134, v134, v93, v94
	v_max3_f32 v134, v134, v95, v96
	v_max3_f32 v134, v134, v97, v98
	v_max3_f32 v134, v134, v99, v100
	v_max3_f32 v134, v134, v101, v101
	v_mfma_f32_32x32x64_f8f6f4 v[2:17], v[244:251], v[196:203], v[2:17] blgp:1
	ds_read_b128 v[236:239], v179 offset:36864
	ds_read_b128 v[240:243], v179 offset:37888
	v_max3_f32 v134, v134, v102, v103
	v_max3_f32 v134, v134, v104, v105
	v_max3_f32 v134, v134, v106, v107
	v_max3_f32 v134, v134, v108, v109
	v_max3_f32 v134, v134, v110, v111
	v_max3_f32 v134, v134, v112, v113
	v_max3_f32 v134, v134, v114, v115
	v_max3_f32 v134, v134, v116, v117
	v_cmp_gt_f32_e64 s[98:99], v134, v178
	v_mfma_f32_16x16x128_f8f6f4 v[82:85], v[154:161], v[196:203], v[82:85] blgp:1
	ds_read_b128 v[244:247], v179 offset:38912
	ds_read_b128 v[248:251], v179 offset:39936
	s_cmp_lg_u64 s[98:99], 0
	s_cbranch_scc1 .Lslow_dif0_3
.Lback_dif0_3:
	v_cvt_pk_u8_f32 v196, v86, 0, 0
	v_cvt_pk_u8_f32 v197, v90, 0, 0
	v_cvt_pk_u8_f32 v198, v94, 0, 0
	v_cvt_pk_u8_f32 v199, v98, 0, 0
	v_cvt_pk_u8_f32 v196, v87, 1, v196
	v_cvt_pk_u8_f32 v197, v91, 1, v197
	v_cvt_pk_u8_f32 v198, v95, 1, v198
	v_cvt_pk_u8_f32 v199, v99, 1, v199
	s_waitcnt lgkmcnt(8)
	v_mfma_f32_32x32x64_f8f6f4 v[118:133], v[204:211], v[146:153], v[50:65]
	v_cvt_pk_u8_f32 v196, v88, 2, v196
	v_cvt_pk_u8_f32 v197, v92, 2, v197
	v_cvt_pk_u8_f32 v198, v96, 2, v198
	v_cvt_pk_u8_f32 v199, v100, 2, v199
	v_cvt_pk_u8_f32 v196, v89, 3, v196
	v_cvt_pk_u8_f32 v197, v93, 3, v197
	v_cvt_pk_u8_f32 v198, v97, 3, v198
	v_cvt_pk_u8_f32 v199, v101, 3, v199
	v_cvt_pk_u8_f32 v200, v102, 0, 0
	v_cvt_pk_u8_f32 v201, v106, 0, 0
	v_cvt_pk_u8_f32 v202, v110, 0, 0
	v_cvt_pk_u8_f32 v203, v114, 0, 0
	v_mfma_f32_32x32x64_f8f6f4 v[180:195], v[212:219], v[146:153], v[50:65]
	v_cvt_pk_u8_f32 v200, v103, 1, v200
	v_cvt_pk_u8_f32 v201, v107, 1, v201
	v_cvt_pk_u8_f32 v202, v111, 1, v202
	v_cvt_pk_u8_f32 v203, v115, 1, v203
	v_cvt_pk_u8_f32 v200, v104, 2, v200
	v_cvt_pk_u8_f32 v201, v108, 2, v201
	v_cvt_pk_u8_f32 v202, v112, 2, v202
	v_cvt_pk_u8_f32 v203, v116, 2, v203
	v_cvt_pk_u8_f32 v200, v105, 3, v200
	v_cvt_pk_u8_f32 v201, v109, 3, v201
	v_cvt_pk_u8_f32 v202, v113, 3, v202
	v_cvt_pk_u8_f32 v203, v117, 3, v203
	s_nop 0
	s_waitcnt lgkmcnt(0)
	v_mfma_f32_32x32x64_f8f6f4 v[66:81], v[220:227], v[196:203], v[66:81] blgp:1
	v_mfma_f32_32x32x64_f8f6f4 v[34:49], v[228:235], v[196:203], v[34:49] blgp:1
	ds_read_b128 v[220:223], v179 offset:40960
	ds_read_b128 v[224:227], v179 offset:41984
	v_mfma_f32_32x32x64_f8f6f4 v[18:33], v[236:243], v[196:203], v[18:33] blgp:1
	ds_read_b128 v[228:231], v179 offset:43008
	ds_read_b128 v[232:235], v179 offset:44032
	v_max3_f32 v134, v118, v119, v120
	v_max3_f32 v134, v134, v121, v122
	v_max3_f32 v134, v134, v123, v124
	v_max3_f32 v134, v134, v125, v126
	v_max3_f32 v134, v134, v127, v128
	v_max3_f32 v134, v134, v129, v130
	v_max3_f32 v134, v134, v131, v132
	v_max3_f32 v134, v134, v133, v133
	v_mfma_f32_32x32x64_f8f6f4 v[2:17], v[244:251], v[196:203], v[2:17] blgp:1
	ds_read_b128 v[236:239], v179 offset:45056
	ds_read_b128 v[240:243], v179 offset:46080
	v_max3_f32 v134, v134, v180, v181
	v_max3_f32 v134, v134, v182, v183
	v_max3_f32 v134, v134, v184, v185
	v_max3_f32 v134, v134, v186, v187
	v_max3_f32 v134, v134, v188, v189
	v_max3_f32 v134, v134, v190, v191
	v_max3_f32 v134, v134, v192, v193
	v_max3_f32 v134, v134, v194, v195
	v_cmp_gt_f32_e64 s[98:99], v134, v178
	v_mfma_f32_16x16x128_f8f6f4 v[82:85], v[154:161], v[196:203], v[82:85] blgp:1
	ds_read_b128 v[244:247], v179 offset:47104
	ds_read_b128 v[248:251], v179 offset:48128
	s_cbranch_vccnz .LBB0_1300
	s_waitcnt lgkmcnt(0)
	s_cmp_lg_u64 s[98:99], 0
	s_cbranch_scc1 .Lslow_dif0_4
.Lback_dif0_4:
	v_cvt_pk_u8_f32 v196, v118, 0, 0
	v_cvt_pk_u8_f32 v197, v122, 0, 0
	v_cvt_pk_u8_f32 v198, v126, 0, 0
	v_cvt_pk_u8_f32 v199, v130, 0, 0
	v_cvt_pk_u8_f32 v196, v119, 1, v196
	v_cvt_pk_u8_f32 v197, v123, 1, v197
	v_cvt_pk_u8_f32 v198, v127, 1, v198
	v_cvt_pk_u8_f32 v199, v131, 1, v199
	v_cvt_pk_u8_f32 v196, v120, 2, v196
	v_cvt_pk_u8_f32 v197, v124, 2, v197
	v_cvt_pk_u8_f32 v198, v128, 2, v198
	v_cvt_pk_u8_f32 v199, v132, 2, v199
	v_cvt_pk_u8_f32 v196, v121, 3, v196
	v_cvt_pk_u8_f32 v197, v125, 3, v197
	v_cvt_pk_u8_f32 v198, v129, 3, v198
	v_cvt_pk_u8_f32 v199, v133, 3, v199
	v_cvt_pk_u8_f32 v200, v180, 0, 0
	v_cvt_pk_u8_f32 v201, v184, 0, 0
	v_cvt_pk_u8_f32 v202, v188, 0, 0
	v_cvt_pk_u8_f32 v203, v192, 0, 0
	v_cvt_pk_u8_f32 v200, v181, 1, v200
	v_cvt_pk_u8_f32 v201, v185, 1, v201
	v_cvt_pk_u8_f32 v202, v189, 1, v202
	v_cvt_pk_u8_f32 v203, v193, 1, v203
	v_cvt_pk_u8_f32 v200, v182, 2, v200
	v_cvt_pk_u8_f32 v201, v186, 2, v201
	v_cvt_pk_u8_f32 v202, v190, 2, v202
	v_cvt_pk_u8_f32 v203, v194, 2, v203
	v_cvt_pk_u8_f32 v200, v183, 3, v200
	v_cvt_pk_u8_f32 v201, v187, 3, v201
	v_cvt_pk_u8_f32 v202, v191, 3, v202
	v_cvt_pk_u8_f32 v203, v195, 3, v203
	s_nop 0
	s_nop 0
	v_mfma_f32_32x32x64_f8f6f4 v[66:81], v[220:227], v[196:203], v[66:81] blgp:1
	v_mfma_f32_32x32x64_f8f6f4 v[34:49], v[228:235], v[196:203], v[34:49] blgp:1
	v_mfma_f32_32x32x64_f8f6f4 v[18:33], v[236:243], v[196:203], v[18:33] blgp:1
	v_mfma_f32_32x32x64_f8f6f4 v[2:17], v[244:251], v[196:203], v[2:17] blgp:1
	v_mfma_f32_16x16x128_f8f6f4 v[82:85], v[154:161], v[196:203], v[82:85] blgp:1
	v_mov_b32_e32 v210, v142
	v_mov_b32_e32 v211, v143
	v_mov_b32_e32 v218, v144
	v_mov_b32_e32 v219, v145
	s_branch .LBB0_1297
.Lslow_dif0_0:
	v_med3_f32 v118, v118, 0, v178
	v_med3_f32 v119, v119, 0, v178
	v_med3_f32 v120, v120, 0, v178
	v_med3_f32 v121, v121, 0, v178
	v_med3_f32 v122, v122, 0, v178
	v_med3_f32 v123, v123, 0, v178
	v_med3_f32 v124, v124, 0, v178
	v_med3_f32 v125, v125, 0, v178
	v_med3_f32 v126, v126, 0, v178
	v_med3_f32 v127, v127, 0, v178
	v_med3_f32 v128, v128, 0, v178
	v_med3_f32 v129, v129, 0, v178
	v_med3_f32 v130, v130, 0, v178
	v_med3_f32 v131, v131, 0, v178
	v_med3_f32 v132, v132, 0, v178
	v_med3_f32 v133, v133, 0, v178
	v_med3_f32 v180, v180, 0, v178
	v_med3_f32 v181, v181, 0, v178
	v_med3_f32 v182, v182, 0, v178
	v_med3_f32 v183, v183, 0, v178
	v_med3_f32 v184, v184, 0, v178
	v_med3_f32 v185, v185, 0, v178
	v_med3_f32 v186, v186, 0, v178
	v_med3_f32 v187, v187, 0, v178
	v_med3_f32 v188, v188, 0, v178
	v_med3_f32 v189, v189, 0, v178
	v_med3_f32 v190, v190, 0, v178
	v_med3_f32 v191, v191, 0, v178
	v_med3_f32 v192, v192, 0, v178
	v_med3_f32 v193, v193, 0, v178
	v_med3_f32 v194, v194, 0, v178
	v_med3_f32 v195, v195, 0, v178
	s_branch .Lback_dif0_0
.Lslow_dif0_1:
	v_med3_f32 v86, v86, 0, v178
	v_med3_f32 v87, v87, 0, v178
	v_med3_f32 v88, v88, 0, v178
	v_med3_f32 v89, v89, 0, v178
	v_med3_f32 v90, v90, 0, v178
	v_med3_f32 v91, v91, 0, v178
	v_med3_f32 v92, v92, 0, v178
	v_med3_f32 v93, v93, 0, v178
	v_med3_f32 v94, v94, 0, v178
	v_med3_f32 v95, v95, 0, v178
	v_med3_f32 v96, v96, 0, v178
	v_med3_f32 v97, v97, 0, v178
	v_med3_f32 v98, v98, 0, v178
	v_med3_f32 v99, v99, 0, v178
	v_med3_f32 v100, v100, 0, v178
	v_med3_f32 v101, v101, 0, v178
	v_med3_f32 v102, v102, 0, v178
	v_med3_f32 v103, v103, 0, v178
	v_med3_f32 v104, v104, 0, v178
	v_med3_f32 v105, v105, 0, v178
	v_med3_f32 v106, v106, 0, v178
	v_med3_f32 v107, v107, 0, v178
	v_med3_f32 v108, v108, 0, v178
	v_med3_f32 v109, v109, 0, v178
	v_med3_f32 v110, v110, 0, v178
	v_med3_f32 v111, v111, 0, v178
	v_med3_f32 v112, v112, 0, v178
	v_med3_f32 v113, v113, 0, v178
	v_med3_f32 v114, v114, 0, v178
	v_med3_f32 v115, v115, 0, v178
	v_med3_f32 v116, v116, 0, v178
	v_med3_f32 v117, v117, 0, v178
	s_branch .Lback_dif0_1

.LBB0_1304:
	s_ashr_i32 s10, s30, 3
	s_mul_i32 s11, s10, 0x4100
	v_add_u32_e32 v2, s11, v219
	v_ashrrev_i32_e32 v3, 31, v2
	s_and_b32 s37, s30, 7
	v_lshlrev_b64 v[4:5], 9, v[2:3]
	v_lshl_add_u64 v[4:5], s[14:15], 0, v[4:5]
	s_lshl_b32 s18, s37, 6
	v_lshlrev_b64 v[6:7], 5, v[2:3]
	v_lshl_add_u64 v[4:5], v[4:5], 0, s[18:19]
	v_lshl_add_u64 v[6:7], s[12:13], 0, v[6:7]
	s_lshl_b32 s18, s37, 2
	v_lshl_add_u64 v[6:7], v[6:7], 0, s[18:19]
	s_mul_i32 s18, s30, 0x104000
	s_mul_hi_i32 s11, s30, 0x104000
	s_add_u32 s31, s20, s18
	s_addc_u32 s34, s21, s11
	s_lshl_b32 s10, s10, 2
	s_bfe_u32 s11, s30, 0x20001
	s_or_b32 s10, s10, s11
	s_mul_hi_i32 s11, s10, 0x208000
	s_mul_i32 s10, s10, 0x208000
	s_add_u32 s35, s22, s10
	s_addc_u32 s36, s23, s11
	s_add_i32 s10, s30, 16
	s_ashr_i32 s11, s10, 31
	s_lshl_b64 s[10:11], s[10:11], 2
	s_add_u32 s10, s3, s10
	s_addc_u32 s11, s28, s11
	global_load_dword v6, v[6:7], off
	v_lshlrev_b64 v[2:3], 11, v[2:3]
	global_load_dword v7, v211, s[10:11]
	v_lshl_add_u64 v[2:3], s[16:17], 0, v[2:3]
	s_lshl_b32 s18, s37, 8
	v_lshl_add_u64 v[216:217], v[2:3], 0, s[18:19]
	v_lshl_add_u64 v[2:3], v[4:5], 0, v[210:211]
	global_load_dwordx4 v[158:161], v[2:3], off offset:16
	global_load_dwordx4 v[154:157], v[2:3], off
	v_readfirstlane_b32 s18, v1
	s_ashr_i32 s18, s18, 6
	v_mov_b32 v146, 0x38383838
	v_mov_b32 v147, 0x38383838
	v_mov_b32 v148, 0x38383838
	v_mov_b32 v149, 0x38383838
	v_mov_b32 v150, 0x38383838
	v_mov_b32 v151, 0x38383838
	v_mov_b32 v152, 0x38383838
	v_mov_b32 v153, 0x38383838
	v_readlane_b32 s2, v252, 8
	s_waitcnt vmcnt(0)
	v_cmp_gt_f32_e32 vcc, s26, v7
	v_mul_f32_e32 v2, 0x4f800000, v7
	s_nop 0
	v_cndmask_b32_e32 v2, v7, v2, vcc
	v_sqrt_f32_e32 v3, v2
	s_nop 0
	v_add_u32_e32 v4, -1, v3
	v_fma_f32 v5, -v4, v3, v2
	v_cmp_ge_f32_e64 s[10:11], 0, v5
	v_add_u32_e32 v5, 1, v3
	s_nop 0
	v_cndmask_b32_e64 v4, v3, v4, s[10:11]
	v_fma_f32 v3, -v5, v3, v2
	v_cmp_lt_f32_e64 s[10:11], 0, v3
	s_nop 1
	v_cndmask_b32_e64 v3, v4, v5, s[10:11]
	s_mul_i32 s10, s18, 0xc00
	s_add_i32 s11, s10, 0xffffe000
	s_add_u32 s37, s35, s11
	s_addc_u32 s38, s36, 0
	s_ashr_i32 s39, s10, 31
	s_add_u32 s40, s31, s10
	s_addc_u32 s41, s34, s39
	s_add_i32 s43, s10, 0x400
	s_add_i32 s42, s10, 0
	s_ashr_i32 s44, s43, 31
	s_add_u32 s45, s40, 0x400
	s_addc_u32 s46, s41, 0
	s_add_i32 s47, s10, 0xffffe400
	s_add_u32 s48, s35, s47
	s_addc_u32 s49, s36, 0
	s_add_i32 s51, s10, 0x800
	s_add_i32 s50, s42, 0x400
	s_ashr_i32 s52, s51, 31
	s_add_u32 s53, s40, 0x800
	s_addc_u32 s55, s41, 0
	s_add_i32 s62, s10, 0xffffe800
	s_add_u32 s63, s35, s62
	s_addc_u32 s64, s36, 0
	s_add_i32 s65, s42, 0x800
	s_add_u32 s66, s35, 0x4000
	s_addc_u32 s36, s36, 0
	s_add_u32 s31, s31, 0x2000
	s_addc_u32 s67, s34, 0
	s_add_u32 s34, s31, s10
	s_addc_u32 s35, s67, s39
	s_add_u32 s39, s66, s11
	s_addc_u32 s68, s36, 0
	s_add_i32 s69, s42, 0x6000
	s_add_u32 s43, s31, s43
	s_addc_u32 s44, s67, s44
	s_add_u32 s47, s66, s47
	v_mul_f32_e32 v4, 0x37800000, v3
	s_addc_u32 s70, s36, 0
	v_cndmask_b32_e32 v3, v3, v4, vcc
	v_cmp_class_f32_e32 vcc, v2, v221
	s_cmp_lt_i32 s18, 3
	s_cselect_b32 s11, s41, s38
	v_cndmask_b32_e32 v2, v3, v2, vcc
	s_cselect_b32 s10, s40, s37
	v_mul_f32_e32 v4, v6, v2
	v_lshl_add_u64 v[2:3], s[10:11], 0, v[212:213]
	s_mov_b32 m0, s42
	s_cselect_b32 s11, s46, s49
	s_cselect_b32 s10, s45, s48
	global_load_lds_dwordx4 v[2:3], off
	v_lshl_add_u64 v[2:3], s[10:11], 0, v[212:213]
	s_cselect_b32 s10, s34, s39
	s_cselect_b32 s11, s35, s68
	s_cselect_b32 s34, s43, s47
	s_cselect_b32 s35, s44, s70
	s_add_i32 s38, s42, 0x6400
	s_add_u32 s31, s31, s51
	s_addc_u32 s39, s67, s52
	s_add_u32 s40, s66, s62
	s_addc_u32 s41, s36, 0
	s_cmp_lt_i32 s18, 2
	s_mov_b32 m0, s50
	s_cselect_b32 s37, s55, s64
	s_cselect_b32 s36, s53, s63
	global_load_lds_dwordx4 v[2:3], off
	v_lshl_add_u64 v[2:3], s[36:37], 0, v[212:213]
	s_mov_b32 m0, s65
	v_fmamk_f32 v18, v4, 0x3f90a3d7, v222
	global_load_lds_dwordx4 v[2:3], off
	v_lshl_add_u64 v[2:3], s[10:11], 0, v[212:213]
	s_mov_b32 m0, s69
	s_cselect_b32 s11, s39, s41
	global_load_lds_dwordx4 v[2:3], off
	v_lshl_add_u64 v[2:3], s[34:35], 0, v[212:213]
	s_mov_b32 m0, s38
	s_cselect_b32 s10, s31, s40
	global_load_lds_dwordx4 v[2:3], off
	v_lshl_add_u64 v[2:3], s[10:11], 0, v[212:213]
	s_add_i32 m0, s42, 0x6800
	v_cmp_lt_i32_e32 vcc, v225, v226
	global_load_lds_dwordx4 v[2:3], off
	s_waitcnt vmcnt(3)
	s_barrier
	ds_read_b128 v[2:5], v220
	ds_read_b128 v[6:9], v220 offset:1024
	s_waitcnt lgkmcnt(0)
	v_mfma_f32_32x32x64_f8f6f4 v[2:17], v[2:9], v[154:161], 0
	s_add_i32 s30, s30, s2
	s_nop 15
	s_nop 2
	v_max3_f32 v2, v2, s27, v3
	v_max3_f32 v2, v2, v4, v5
	v_max3_f32 v2, v2, v6, v7
	v_max3_f32 v2, v2, v8, v9
	v_max3_f32 v2, v2, v10, v11
	v_max3_f32 v2, v2, v12, v13
	v_max3_f32 v2, v2, v14, v15
	v_max3_f32 v19, v2, v16, v17
	ds_read_b128 v[2:5], v220 offset:2048
	ds_read_b128 v[6:9], v220 offset:3072
	s_waitcnt lgkmcnt(0)
	v_mfma_f32_32x32x64_f8f6f4 v[2:17], v[2:9], v[154:161], 0
	s_nop 15
	s_nop 3
	v_max3_f32 v2, v19, v2, v3
	v_max3_f32 v2, v2, v4, v5
	v_max3_f32 v2, v2, v6, v7
	v_max3_f32 v2, v2, v8, v9
	v_max3_f32 v2, v2, v10, v11
	v_max3_f32 v2, v2, v12, v13
	v_max3_f32 v2, v2, v14, v15
	v_max3_f32 v19, v2, v16, v17
	ds_read_b128 v[2:5], v220 offset:4096
	ds_read_b128 v[6:9], v220 offset:5120
	s_waitcnt lgkmcnt(0)
	v_mfma_f32_32x32x64_f8f6f4 v[2:17], v[2:9], v[154:161], 0
	s_nop 15
	s_nop 3
	v_max3_f32 v2, v19, v2, v3
	v_max3_f32 v2, v2, v4, v5
	v_max3_f32 v2, v2, v6, v7
	v_max3_f32 v2, v2, v8, v9
	v_max3_f32 v2, v2, v10, v11
	v_max3_f32 v2, v2, v12, v13
	v_max3_f32 v2, v2, v14, v15
	v_max3_f32 v19, v2, v16, v17
	ds_read_b128 v[2:5], v220 offset:6144
	ds_read_b128 v[6:9], v220 offset:7168
	s_waitcnt lgkmcnt(0)
	v_mfma_f32_32x32x64_f8f6f4 v[2:17], v[2:9], v[154:161], 0
	s_waitcnt vmcnt(0)
	s_barrier
	s_nop 15
	s_nop 2
	v_max3_f32 v2, v19, v2, v3
	v_max3_f32 v2, v2, v4, v5
	v_max3_f32 v2, v2, v6, v7
	v_max3_f32 v2, v2, v8, v9
	v_max3_f32 v2, v2, v10, v11
	v_max3_f32 v2, v2, v12, v13
	v_max3_f32 v2, v2, v14, v15
	v_cndmask_b32_e32 v3, v224, v225, vcc
	v_max3_f32 v2, v2, v16, v17
	v_lshlrev_b32_e32 v3, 2, v3
	ds_bpermute_b32 v3, v3, v2
	s_waitcnt lgkmcnt(0)
	v_max_f32_e32 v3, v3, v3
	v_max_f32_e32 v2, v2, v3
	v_add_f32_e32 v2, 0x42800000, v2
	v_min_f32_e32 v2, v18, v2
	v_add_f32_e32 v2, 0xc2ec0000, v2
	v_xor_b32_e32 v2, 0x80000000, v2
	v_mov_b32_e32 v3, v2
	v_mov_b32_e32 v4, v2
	v_mov_b32_e32 v5, v2
	v_mov_b32_e32 v6, v2
	v_mov_b32_e32 v7, v2
	v_mov_b32_e32 v8, v2
	v_mov_b32_e32 v9, v2
	v_mov_b32_e32 v10, v2
	v_mov_b32_e32 v11, v2
	v_mov_b32_e32 v12, v2
	v_mov_b32_e32 v13, v2
	v_mov_b32_e32 v14, v2
	v_mov_b32_e32 v15, v2
	v_mov_b32_e32 v16, v2
	v_mov_b32_e32 v17, v2
	ds_read_b128 v[18:21], v220
	ds_read_b128 v[22:25], v220 offset:1024
	ds_read_b128 v[50:53], v220 offset:2048
	ds_read_b128 v[54:57], v220 offset:3072
	ds_read_b128 v[34:37], v220 offset:8192
	ds_read_b128 v[38:41], v220 offset:9216
	ds_read_b128 v[42:45], v220 offset:10240
	ds_read_b128 v[46:49], v220 offset:11264
	ds_read_b128 v[114:117], v220 offset:12288
	ds_read_b128 v[118:121], v220 offset:13312
	ds_read_b128 v[122:125], v220 offset:14336
	ds_read_b128 v[126:129], v220 offset:15360
	s_waitcnt lgkmcnt(0)
	v_mfma_f32_32x32x64_f8f6f4 v[18:33], v[18:25], v[154:161], v[2:17]
	ds_read_b128 v[66:69], v220 offset:4096
	ds_read_b128 v[70:73], v220 offset:5120
	ds_read_b128 v[58:61], v220 offset:6144
	ds_read_b128 v[62:65], v220 offset:7168
	s_nop 15
	v_med3_f32 v18, v18, 0, v227
	v_med3_f32 v19, v19, 0, v227
	v_cvt_pk_u8_f32 v18, v18, 0, 0
	v_med3_f32 v20, v20, 0, v227
	v_cvt_pk_u8_f32 v18, v19, 1, v18
	v_med3_f32 v21, v21, 0, v227
	v_cvt_pk_u8_f32 v18, v20, 2, v18
	v_cvt_pk_u8_f32 v130, v21, 3, v18
	v_med3_f32 v21, v22, 0, v227
	v_med3_f32 v20, v23, 0, v227
	v_cvt_pk_u8_f32 v21, v21, 0, 0
	v_med3_f32 v19, v24, 0, v227
	v_cvt_pk_u8_f32 v20, v20, 1, v21
	v_med3_f32 v21, v26, 0, v227
	v_med3_f32 v18, v25, 0, v227
	v_cvt_pk_u8_f32 v19, v19, 2, v20
	v_med3_f32 v20, v27, 0, v227
	v_cvt_pk_u8_f32 v21, v21, 0, 0
	v_cvt_pk_u8_f32 v131, v18, 3, v19
	v_med3_f32 v19, v28, 0, v227
	v_cvt_pk_u8_f32 v20, v20, 1, v21
	v_med3_f32 v21, v30, 0, v227
	v_med3_f32 v18, v29, 0, v227
	v_cvt_pk_u8_f32 v19, v19, 2, v20
	v_med3_f32 v20, v31, 0, v227
	v_cvt_pk_u8_f32 v21, v21, 0, 0
	v_cvt_pk_u8_f32 v132, v18, 3, v19
	v_med3_f32 v19, v32, 0, v227
	v_cvt_pk_u8_f32 v20, v20, 1, v21
	v_med3_f32 v18, v33, 0, v227
	v_cvt_pk_u8_f32 v19, v19, 2, v20
	v_cvt_pk_u8_f32 v133, v18, 3, v19
	v_mfma_f32_32x32x64_f8f6f4 v[18:33], v[50:57], v[154:161], v[2:17]
	s_waitcnt lgkmcnt(0)
	v_mfma_f32_32x32x64_f8f6f4 v[82:97], v[66:73], v[154:161], v[2:17]
	s_nop 15
	s_nop 1
	v_med3_f32 v18, v18, 0, v227
	v_med3_f32 v19, v19, 0, v227
	v_cvt_pk_u8_f32 v18, v18, 0, 0
	v_med3_f32 v20, v20, 0, v227
	v_cvt_pk_u8_f32 v18, v19, 1, v18
	v_med3_f32 v21, v21, 0, v227
	v_cvt_pk_u8_f32 v18, v20, 2, v18
	v_cvt_pk_u8_f32 v134, v21, 3, v18
	v_med3_f32 v21, v22, 0, v227
	v_med3_f32 v20, v23, 0, v227
	v_cvt_pk_u8_f32 v21, v21, 0, 0
	v_med3_f32 v19, v24, 0, v227
	v_cvt_pk_u8_f32 v20, v20, 1, v21
	v_med3_f32 v21, v26, 0, v227
	v_med3_f32 v18, v25, 0, v227
	v_mfma_f32_32x32x64_f8f6f4 v[98:113], v[58:65], v[154:161], v[2:17]
	v_med3_f32 v82, v82, 0, v227
	v_med3_f32 v83, v83, 0, v227
	v_cvt_pk_u8_f32 v82, v82, 0, 0
	v_med3_f32 v84, v84, 0, v227
	v_cvt_pk_u8_f32 v82, v83, 1, v82
	v_cvt_pk_u8_f32 v19, v19, 2, v20
	v_med3_f32 v20, v27, 0, v227
	v_cvt_pk_u8_f32 v21, v21, 0, 0
	v_med3_f32 v85, v85, 0, v227
	v_cvt_pk_u8_f32 v82, v84, 2, v82
	v_cvt_pk_u8_f32 v135, v18, 3, v19
	v_med3_f32 v19, v28, 0, v227
	v_cvt_pk_u8_f32 v20, v20, 1, v21
	v_med3_f32 v21, v30, 0, v227
	v_cvt_pk_u8_f32 v194, v85, 3, v82
	v_med3_f32 v85, v86, 0, v227
	v_med3_f32 v18, v29, 0, v227
	v_cvt_pk_u8_f32 v19, v19, 2, v20
	v_med3_f32 v20, v31, 0, v227
	v_cvt_pk_u8_f32 v21, v21, 0, 0
	v_med3_f32 v84, v87, 0, v227
	v_cvt_pk_u8_f32 v85, v85, 0, 0
	v_cvt_pk_u8_f32 v136, v18, 3, v19
	v_med3_f32 v19, v32, 0, v227
	v_cvt_pk_u8_f32 v20, v20, 1, v21
	v_med3_f32 v83, v88, 0, v227
	v_cvt_pk_u8_f32 v84, v84, 1, v85
	v_med3_f32 v85, v90, 0, v227
	v_med3_f32 v18, v33, 0, v227
	v_cvt_pk_u8_f32 v19, v19, 2, v20
	v_med3_f32 v82, v89, 0, v227
	v_cvt_pk_u8_f32 v83, v83, 2, v84
	v_med3_f32 v84, v91, 0, v227
	v_cvt_pk_u8_f32 v85, v85, 0, 0
	v_cvt_pk_u8_f32 v137, v18, 3, v19
	v_cvt_pk_u8_f32 v195, v82, 3, v83
	v_med3_f32 v83, v92, 0, v227
	v_cvt_pk_u8_f32 v84, v84, 1, v85
	v_med3_f32 v85, v94, 0, v227
	v_mfma_f32_32x32x64_f8f6f4 v[66:81], v[34:41], v[130:137], 0 blgp:1
	v_med3_f32 v82, v93, 0, v227
	v_cvt_pk_u8_f32 v83, v83, 2, v84
	v_med3_f32 v84, v95, 0, v227
	v_cvt_pk_u8_f32 v85, v85, 0, 0
	v_cvt_pk_u8_f32 v196, v82, 3, v83
	v_med3_f32 v83, v96, 0, v227
	v_cvt_pk_u8_f32 v84, v84, 1, v85
	v_med3_f32 v82, v97, 0, v227
	v_cvt_pk_u8_f32 v83, v83, 2, v84
	v_cvt_pk_u8_f32 v197, v82, 3, v83
	v_med3_f32 v98, v98, 0, v227
	v_med3_f32 v99, v99, 0, v227
	v_cvt_pk_u8_f32 v98, v98, 0, 0
	v_med3_f32 v100, v100, 0, v227
	v_cvt_pk_u8_f32 v98, v99, 1, v98
	v_mfma_f32_32x32x64_f8f6f4 v[50:65], v[42:49], v[130:137], 0 blgp:1
	v_med3_f32 v101, v101, 0, v227
	v_cvt_pk_u8_f32 v98, v100, 2, v98
	v_cvt_pk_u8_f32 v198, v101, 3, v98
	v_med3_f32 v101, v102, 0, v227
	v_med3_f32 v100, v103, 0, v227
	v_cvt_pk_u8_f32 v101, v101, 0, 0
	v_med3_f32 v99, v104, 0, v227
	v_cvt_pk_u8_f32 v100, v100, 1, v101
	v_med3_f32 v101, v106, 0, v227
	v_med3_f32 v98, v105, 0, v227
	v_cvt_pk_u8_f32 v99, v99, 2, v100
	v_med3_f32 v100, v107, 0, v227
	v_cvt_pk_u8_f32 v101, v101, 0, 0
	v_cvt_pk_u8_f32 v199, v98, 3, v99
	v_med3_f32 v99, v108, 0, v227
	v_mfma_f32_32x32x64_f8f6f4 v[34:49], v[114:121], v[130:137], 0 blgp:1
	ds_read_b128 v[162:165], v220 offset:16384
	ds_read_b128 v[166:169], v220 offset:17408
	ds_read_b128 v[170:173], v220 offset:18432
	ds_read_b128 v[174:177], v220 offset:19456
	ds_read_b128 v[178:181], v220 offset:20480
	ds_read_b128 v[182:185], v220 offset:21504
	ds_read_b128 v[186:189], v220 offset:22528
	ds_read_b128 v[190:193], v220 offset:23552
	ds_read_b128 v[114:117], v220 offset:24576
	ds_read_b128 v[118:121], v220 offset:25600
	ds_read_b128 v[138:141], v220 offset:26624
	ds_read_b128 v[142:145], v220 offset:27648
	v_cvt_pk_u8_f32 v100, v100, 1, v101
	v_med3_f32 v101, v110, 0, v227
	v_med3_f32 v98, v109, 0, v227
	v_cvt_pk_u8_f32 v99, v99, 2, v100
	v_med3_f32 v100, v111, 0, v227
	v_cvt_pk_u8_f32 v101, v101, 0, 0
	v_cvt_pk_u8_f32 v200, v98, 3, v99
	v_med3_f32 v99, v112, 0, v227
	v_cvt_pk_u8_f32 v100, v100, 1, v101
	v_med3_f32 v98, v113, 0, v227
	v_cvt_pk_u8_f32 v99, v99, 2, v100
	v_cvt_pk_u8_f32 v201, v98, 3, v99
	v_mfma_f32_32x32x64_f8f6f4 v[18:33], v[122:129], v[130:137], 0 blgp:1
	v_mfma_f32_32x32x64_f8f6f4 v[82:97], v[146:153], v[130:137], 0 blgp:1
	s_waitcnt lgkmcnt(0)
	v_mfma_f32_32x32x64_f8f6f4 v[114:129], v[114:121], v[154:161], v[2:17]
	v_mfma_f32_32x32x64_f8f6f4 v[130:145], v[138:145], v[154:161], v[2:17]
	s_nop 15
	s_nop 2
	v_med3_f32 v114, v114, 0, v227
	v_med3_f32 v115, v115, 0, v227
	v_cvt_pk_u8_f32 v114, v114, 0, 0
	v_med3_f32 v116, v116, 0, v227
	v_cvt_pk_u8_f32 v114, v115, 1, v114
	v_med3_f32 v117, v117, 0, v227
	v_cvt_pk_u8_f32 v114, v116, 2, v114
	v_med3_f32 v118, v118, 0, v227
	v_cvt_pk_u8_f32 v114, v117, 3, v114
	v_med3_f32 v117, v119, 0, v227
	v_cvt_pk_u8_f32 v118, v118, 0, 0
	v_med3_f32 v119, v122, 0, v227
	v_med3_f32 v116, v120, 0, v227
	v_cvt_pk_u8_f32 v117, v117, 1, v118
	v_med3_f32 v118, v123, 0, v227
	v_mfma_f32_32x32x64_f8f6f4 v[66:81], v[162:169], v[194:201], v[66:81] blgp:1
	v_cvt_pk_u8_f32 v119, v119, 0, 0
	v_med3_f32 v120, v126, 0, v227
	v_med3_f32 v115, v121, 0, v227
	v_cvt_pk_u8_f32 v116, v116, 2, v117
	v_med3_f32 v117, v124, 0, v227
	v_cvt_pk_u8_f32 v118, v118, 1, v119
	v_med3_f32 v119, v127, 0, v227
	v_cvt_pk_u8_f32 v120, v120, 0, 0
	v_med3_f32 v121, v130, 0, v227
	v_cvt_pk_u8_f32 v115, v115, 3, v116
	v_med3_f32 v116, v125, 0, v227
	v_cvt_pk_u8_f32 v117, v117, 2, v118
	v_med3_f32 v118, v128, 0, v227
	v_cvt_pk_u8_f32 v119, v119, 1, v120
	v_med3_f32 v120, v131, 0, v227
	v_mfma_f32_32x32x64_f8f6f4 v[50:65], v[170:177], v[194:201], v[50:65] blgp:1
	v_cvt_pk_u8_f32 v121, v121, 0, 0
	v_med3_f32 v122, v134, 0, v227
	v_cvt_pk_u8_f32 v116, v116, 3, v117
	v_med3_f32 v117, v129, 0, v227
	v_cvt_pk_u8_f32 v118, v118, 2, v119
	v_med3_f32 v119, v132, 0, v227
	v_cvt_pk_u8_f32 v120, v120, 1, v121
	v_med3_f32 v121, v135, 0, v227
	v_cvt_pk_u8_f32 v122, v122, 0, 0
	v_med3_f32 v123, v138, 0, v227
	v_cvt_pk_u8_f32 v117, v117, 3, v118
	v_med3_f32 v118, v133, 0, v227
	v_cvt_pk_u8_f32 v119, v119, 2, v120
	v_med3_f32 v120, v136, 0, v227
	v_cvt_pk_u8_f32 v121, v121, 1, v122
	v_mfma_f32_32x32x64_f8f6f4 v[34:49], v[178:185], v[194:201], v[34:49] blgp:1
	v_med3_f32 v122, v139, 0, v227
	v_cvt_pk_u8_f32 v123, v123, 0, 0
	v_med3_f32 v124, v142, 0, v227
	v_cvt_pk_u8_f32 v118, v118, 3, v119
	v_med3_f32 v119, v137, 0, v227
	v_cvt_pk_u8_f32 v120, v120, 2, v121
	v_med3_f32 v121, v140, 0, v227
	v_cvt_pk_u8_f32 v122, v122, 1, v123
	v_med3_f32 v123, v143, 0, v227
	v_cvt_pk_u8_f32 v124, v124, 0, 0
	v_cvt_pk_u8_f32 v119, v119, 3, v120
	v_med3_f32 v120, v141, 0, v227
	v_cvt_pk_u8_f32 v121, v121, 2, v122
	v_med3_f32 v122, v144, 0, v227
	v_cvt_pk_u8_f32 v123, v123, 1, v124
	v_mfma_f32_32x32x64_f8f6f4 v[18:33], v[186:193], v[194:201], v[18:33] blgp:1
	ds_read_b128 v[98:101], v220 offset:28672
	ds_read_b128 v[102:105], v220 offset:29696
	ds_read_b128 v[202:205], v220 offset:30720
	ds_read_b128 v[206:209], v220 offset:31744
	ds_read_b128 v[162:165], v220 offset:32768
	ds_read_b128 v[166:169], v220 offset:33792
	ds_read_b128 v[170:173], v220 offset:34816
	ds_read_b128 v[174:177], v220 offset:35840
	ds_read_b128 v[178:181], v220 offset:36864
	ds_read_b128 v[182:185], v220 offset:37888
	ds_read_b128 v[186:189], v220 offset:38912
	ds_read_b128 v[190:193], v220 offset:39936
	v_cvt_pk_u8_f32 v120, v120, 3, v121
	v_med3_f32 v121, v145, 0, v227
	v_cvt_pk_u8_f32 v122, v122, 2, v123
	v_cvt_pk_u8_f32 v121, v121, 3, v122
	s_waitcnt lgkmcnt(0)
	v_mfma_f32_32x32x64_f8f6f4 v[98:113], v[98:105], v[154:161], v[2:17]
	v_mfma_f32_32x32x64_f8f6f4 v[82:97], v[146:153], v[194:201], v[82:97] blgp:1
	s_nop 15
	s_nop 2
	v_med3_f32 v98, v98, 0, v227
	v_med3_f32 v99, v99, 0, v227
	v_cvt_pk_u8_f32 v98, v98, 0, 0
	v_med3_f32 v100, v100, 0, v227
	v_cvt_pk_u8_f32 v98, v99, 1, v98
	v_med3_f32 v101, v101, 0, v227
	v_cvt_pk_u8_f32 v98, v100, 2, v98
	v_med3_f32 v102, v102, 0, v227
	v_cvt_pk_u8_f32 v98, v101, 3, v98
	v_med3_f32 v101, v103, 0, v227
	v_cvt_pk_u8_f32 v102, v102, 0, 0
	v_med3_f32 v103, v106, 0, v227
	v_med3_f32 v100, v104, 0, v227
	v_cvt_pk_u8_f32 v101, v101, 1, v102
	v_med3_f32 v102, v107, 0, v227
	v_mfma_f32_32x32x64_f8f6f4 v[2:17], v[202:209], v[154:161], v[2:17]
	v_cvt_pk_u8_f32 v103, v103, 0, 0
	v_med3_f32 v104, v110, 0, v227
	v_med3_f32 v99, v105, 0, v227
	v_cvt_pk_u8_f32 v100, v100, 2, v101
	v_med3_f32 v101, v108, 0, v227
	v_cvt_pk_u8_f32 v102, v102, 1, v103
	v_med3_f32 v103, v111, 0, v227
	v_cvt_pk_u8_f32 v104, v104, 0, 0
	v_cvt_pk_u8_f32 v99, v99, 3, v100
	v_med3_f32 v100, v109, 0, v227
	v_cvt_pk_u8_f32 v101, v101, 2, v102
	v_med3_f32 v102, v112, 0, v227
	v_cvt_pk_u8_f32 v103, v103, 1, v104
	v_cvt_pk_u8_f32 v100, v100, 3, v101
	v_med3_f32 v101, v113, 0, v227
	v_mfma_f32_32x32x64_f8f6f4 v[82:97], v[146:153], v[114:121], v[82:97] blgp:1
	s_nop 3
	v_med3_f32 v2, v2, 0, v227
	v_med3_f32 v3, v3, 0, v227
	v_cvt_pk_u8_f32 v2, v2, 0, 0
	v_med3_f32 v4, v4, 0, v227
	v_cvt_pk_u8_f32 v2, v3, 1, v2
	v_cvt_pk_u8_f32 v102, v102, 2, v103
	v_med3_f32 v5, v5, 0, v227
	v_cvt_pk_u8_f32 v2, v4, 2, v2
	v_cvt_pk_u8_f32 v101, v101, 3, v102
	v_cvt_pk_u8_f32 v102, v5, 3, v2
	v_med3_f32 v5, v6, 0, v227
	v_med3_f32 v4, v7, 0, v227
	v_cvt_pk_u8_f32 v5, v5, 0, 0
	v_med3_f32 v3, v8, 0, v227
	v_cvt_pk_u8_f32 v4, v4, 1, v5
	v_med3_f32 v5, v10, 0, v227
	v_med3_f32 v2, v9, 0, v227
	v_cvt_pk_u8_f32 v3, v3, 2, v4
	v_med3_f32 v4, v11, 0, v227
	v_cvt_pk_u8_f32 v5, v5, 0, 0
	v_cvt_pk_u8_f32 v103, v2, 3, v3
	v_med3_f32 v3, v12, 0, v227
	v_cvt_pk_u8_f32 v4, v4, 1, v5
	v_med3_f32 v5, v14, 0, v227
	v_med3_f32 v2, v13, 0, v227
	v_cvt_pk_u8_f32 v3, v3, 2, v4
	v_med3_f32 v4, v15, 0, v227
	v_cvt_pk_u8_f32 v5, v5, 0, 0
	v_cvt_pk_u8_f32 v104, v2, 3, v3
	v_med3_f32 v3, v16, 0, v227
	v_cvt_pk_u8_f32 v4, v4, 1, v5
	v_mfma_f32_32x32x64_f8f6f4 v[66:81], v[162:169], v[114:121], v[66:81] blgp:1
	v_med3_f32 v2, v17, 0, v227
	v_cvt_pk_u8_f32 v3, v3, 2, v4
	v_cvt_pk_u8_f32 v105, v2, 3, v3
	ds_read_b128 v[154:157], v220 offset:40960
	ds_read_b128 v[158:161], v220 offset:41984
	ds_read_b128 v[138:141], v220 offset:43008
	ds_read_b128 v[142:145], v220 offset:44032
	ds_read_b128 v[130:133], v220 offset:45056
	ds_read_b128 v[134:137], v220 offset:46080
	ds_read_b128 v[122:125], v220 offset:47104
	ds_read_b128 v[126:129], v220 offset:48128
	v_mfma_f32_32x32x64_f8f6f4 v[82:97], v[146:153], v[98:105], v[82:97] blgp:1
	v_mfma_f32_32x32x64_f8f6f4 v[50:65], v[170:177], v[114:121], v[50:65] blgp:1
	s_nop 15
	s_nop 2
	v_div_scale_f32 v2, s[34:35], v82, v82, 1.0
	v_rcp_f32_e32 v3, v2
	v_cmp_nlt_f32_e32 vcc, 0, v82
	v_cmp_ngt_f32_e64 s[10:11], s29, v82
	s_or_b64 s[10:11], vcc, s[10:11]
	v_fma_f32 v4, -v2, v3, 1.0
	v_fmac_f32_e32 v3, v4, v3
	v_div_scale_f32 v4, vcc, 1.0, v82, 1.0
	v_mul_f32_e32 v5, v4, v3
	v_fma_f32 v6, -v2, v5, v4
	v_fmac_f32_e32 v5, v6, v3
	v_fma_f32 v2, -v2, v5, v4
	v_div_fmas_f32 v2, v2, v3, v5
	v_mfma_f32_32x32x64_f8f6f4 v[34:49], v[178:185], v[114:121], v[34:49] blgp:1
	v_div_fixup_f32 v2, v2, v82, 1.0
	v_cndmask_b32_e64 v4, v2, 0, s[10:11]
	v_lshl_add_u64 v[2:3], v[216:217], 0, v[214:215]
	s_cmp_gt_i32 s30, 15
	s_waitcnt lgkmcnt(0)
	v_mfma_f32_32x32x64_f8f6f4 v[66:81], v[154:161], v[98:105], v[66:81] blgp:1
	v_mfma_f32_32x32x64_f8f6f4 v[18:33], v[186:193], v[114:121], v[18:33] blgp:1
	s_nop 15
	s_nop 2
	v_mul_f32_e64 v6, v66, v4
	v_mul_f32_e64 v7, v67, v4
	v_mul_f32_e64 v8, v68, v4
	v_mul_f32_e64 v9, v69, v4
	v_cvt_pk_bf16_f32 v6, v6, v7
	v_cvt_pk_bf16_f32 v7, v8, v9
	global_store_dwordx2 v[2:3], v[6:7], off
	v_mul_f32_e64 v6, v70, v4
	v_mul_f32_e64 v7, v71, v4
	v_mul_f32_e64 v8, v72, v4
	v_mul_f32_e64 v9, v73, v4
	v_cvt_pk_bf16_f32 v6, v6, v7
	v_cvt_pk_bf16_f32 v7, v8, v9
	global_store_dwordx2 v[2:3], v[6:7], off offset:16
	v_pk_mul_f32 v[6:7], v[74:75], v[4:5] op_sel_hi:[1,0]
	v_pk_mul_f32 v[8:9], v[76:77], v[4:5] op_sel_hi:[1,0]
	v_cvt_pk_bf16_f32 v6, v6, v7
	v_cvt_pk_bf16_f32 v7, v8, v9
	global_store_dwordx2 v[2:3], v[6:7], off offset:32
	v_mfma_f32_32x32x64_f8f6f4 v[50:65], v[138:145], v[98:105], v[50:65] blgp:1
	v_mul_f32_e64 v6, v78, v4
	v_mul_f32_e64 v7, v79, v4
	v_mul_f32_e64 v8, v80, v4
	v_mul_f32_e64 v9, v81, v4
	v_cvt_pk_bf16_f32 v6, v6, v7
	v_cvt_pk_bf16_f32 v7, v8, v9
	global_store_dwordx2 v[2:3], v[6:7], off offset:48
	s_nop 12
	v_pk_mul_f32 v[6:7], v[50:51], v[4:5] op_sel_hi:[1,0]
	v_mfma_f32_32x32x64_f8f6f4 v[34:49], v[130:137], v[98:105], v[34:49] blgp:1
	v_mul_f32_e64 v8, v52, v4
	v_mul_f32_e64 v9, v53, v4
	v_cvt_pk_bf16_f32 v6, v6, v7
	v_cvt_pk_bf16_f32 v7, v8, v9
	global_store_dwordx2 v[2:3], v[6:7], off offset:64
	v_mul_f32_e64 v6, v54, v4
	v_mul_f32_e64 v7, v55, v4
	v_mul_f32_e64 v8, v56, v4
	v_mul_f32_e64 v9, v57, v4
	v_cvt_pk_bf16_f32 v6, v6, v7
	v_cvt_pk_bf16_f32 v7, v8, v9
	global_store_dwordx2 v[2:3], v[6:7], off offset:80
	v_mul_f32_e64 v6, v58, v4
	v_mul_f32_e64 v7, v59, v4
	v_pk_mul_f32 v[8:9], v[60:61], v[4:5] op_sel_hi:[1,0]
	v_cvt_pk_bf16_f32 v6, v6, v7
	v_cvt_pk_bf16_f32 v7, v8, v9
	global_store_dwordx2 v[2:3], v[6:7], off offset:96
	v_pk_mul_f32 v[6:7], v[62:63], v[4:5] op_sel_hi:[1,0]
	v_mfma_f32_32x32x64_f8f6f4 v[18:33], v[122:129], v[98:105], v[18:33] blgp:1
	v_mul_f32_e64 v8, v64, v4
	v_mul_f32_e64 v9, v65, v4
	v_cvt_pk_bf16_f32 v6, v6, v7
	v_cvt_pk_bf16_f32 v7, v8, v9
	global_store_dwordx2 v[2:3], v[6:7], off offset:112
	v_mul_f32_e64 v6, v34, v4
	v_mul_f32_e64 v7, v35, v4
	v_mul_f32_e64 v8, v36, v4
	v_mul_f32_e64 v9, v37, v4
	v_cvt_pk_bf16_f32 v6, v6, v7
	v_cvt_pk_bf16_f32 v7, v8, v9
	global_store_dwordx2 v[2:3], v[6:7], off offset:128
	v_mul_f32_e64 v6, v38, v4
	v_mul_f32_e64 v7, v39, v4
	v_pk_mul_f32 v[8:9], v[40:41], v[4:5] op_sel_hi:[1,0]
	v_cvt_pk_bf16_f32 v6, v6, v7
	v_cvt_pk_bf16_f32 v7, v8, v9
	global_store_dwordx2 v[2:3], v[6:7], off offset:144
	v_pk_mul_f32 v[6:7], v[42:43], v[4:5] op_sel_hi:[1,0]
	v_pk_mul_f32 v[8:9], v[44:45], v[4:5] op_sel_hi:[1,0]
	v_cvt_pk_bf16_f32 v6, v6, v7
	v_cvt_pk_bf16_f32 v7, v8, v9
	global_store_dwordx2 v[2:3], v[6:7], off offset:160
	v_pk_mul_f32 v[6:7], v[46:47], v[4:5] op_sel_hi:[1,0]
	v_pk_mul_f32 v[8:9], v[48:49], v[4:5] op_sel_hi:[1,0]
	v_cvt_pk_bf16_f32 v6, v6, v7
	v_cvt_pk_bf16_f32 v7, v8, v9
	global_store_dwordx2 v[2:3], v[6:7], off offset:176
	v_pk_mul_f32 v[6:7], v[18:19], v[4:5] op_sel_hi:[1,0]
	v_pk_mul_f32 v[8:9], v[20:21], v[4:5] op_sel_hi:[1,0]
	v_cvt_pk_bf16_f32 v6, v6, v7
	v_cvt_pk_bf16_f32 v7, v8, v9
	global_store_dwordx2 v[2:3], v[6:7], off offset:192
	v_pk_mul_f32 v[6:7], v[22:23], v[4:5] op_sel_hi:[1,0]
	v_pk_mul_f32 v[8:9], v[24:25], v[4:5] op_sel_hi:[1,0]
	v_cvt_pk_bf16_f32 v6, v6, v7
	v_cvt_pk_bf16_f32 v7, v8, v9
	global_store_dwordx2 v[2:3], v[6:7], off offset:208
	v_pk_mul_f32 v[6:7], v[26:27], v[4:5] op_sel_hi:[1,0]
	v_pk_mul_f32 v[8:9], v[28:29], v[4:5] op_sel_hi:[1,0]
	v_cvt_pk_bf16_f32 v6, v6, v7
	v_cvt_pk_bf16_f32 v7, v8, v9
	global_store_dwordx2 v[2:3], v[6:7], off offset:224
	v_pk_mul_f32 v[6:7], v[30:31], v[4:5] op_sel_hi:[1,0]
	v_pk_mul_f32 v[4:5], v[32:33], v[4:5] op_sel_hi:[1,0]
	v_cvt_pk_bf16_f32 v6, v6, v7
	v_cvt_pk_bf16_f32 v7, v4, v5
	global_store_dwordx2 v[2:3], v[6:7], off offset:240
	s_barrier
	s_cbranch_scc0 .LBB0_1304

.LBB0_1542:
	s_waitcnt vmcnt(20)
	s_nop 0
	v_mfma_f32_32x32x64_f8f6f4 v[2:17], v[106:113], v[66:73], v[2:17]
	s_and_b64 s[38:39], s[28:29], exec
	s_mov_b32 s39, s23
	s_cselect_b32 s22, s30, 0x380
	s_cselect_b32 s38, s31, 0x380
	s_mov_b32 s41, s23
	s_cselect_b32 s40, s34, 0x380
	v_lshl_add_u64 v[194:195], v[186:187], 0, s[40:41]
	v_lshl_add_u64 v[196:197], v[188:189], 0, s[40:41]
	v_cndmask_b32_e64 v193, 0, 1, s[28:29]
	v_cmp_ne_u32_e32 vcc, 1, v193
	s_mov_b64 s[28:29], 0
	s_and_b64 vcc, exec, vcc
	s_waitcnt vmcnt(16)
	v_mfma_f32_32x32x64_f8f6f4 v[2:17], v[90:97], v[50:57], v[2:17]
	s_waitcnt vmcnt(12)
	v_mfma_f32_32x32x64_f8f6f4 v[2:17], v[114:121], v[74:81], v[2:17]
	s_waitcnt vmcnt(8)
	v_mfma_f32_32x32x64_f8f6f4 v[2:17], v[82:89], v[34:41], v[2:17]
	v_lshl_add_u64 v[34:35], v[186:187], 0, s[22:23]
	v_lshl_add_u64 v[36:37], v[188:189], 0, s[22:23]
	v_lshl_add_u64 v[38:39], v[186:187], 0, s[38:39]
	v_lshl_add_u64 v[86:87], v[188:189], 0, s[38:39]
	global_load_dwordx4 v[66:69], v[34:35], off
	global_load_dwordx4 v[70:73], v[34:35], off offset:16
	global_load_dwordx4 v[106:109], v[36:37], off
	global_load_dwordx4 v[110:113], v[36:37], off offset:16
	global_load_dwordx4 v[50:53], v[34:35], off offset:32
	s_waitcnt vmcnt(9)
	v_mfma_f32_32x32x64_f8f6f4 v[2:17], v[130:137], v[42:49], v[2:17]
	global_load_dwordx4 v[54:57], v[34:35], off offset:48
	global_load_dwordx4 v[90:93], v[36:37], off offset:32
	global_load_dwordx4 v[94:97], v[36:37], off offset:48
	global_load_dwordx4 v[74:77], v[38:39], off
	global_load_dwordx4 v[78:81], v[38:39], off offset:16
	global_load_dwordx4 v[114:117], v[86:87], off
	global_load_dwordx4 v[118:121], v[86:87], off offset:16
	s_nop 0
	global_load_dwordx4 v[34:37], v[38:39], off offset:32
	s_nop 0
	global_load_dwordx4 v[38:41], v[38:39], off offset:48
	s_nop 0
	global_load_dwordx4 v[82:85], v[86:87], off offset:32
	s_nop 0
	global_load_dwordx4 v[86:89], v[86:87], off offset:48
	s_nop 0
	global_load_dwordx4 v[42:45], v[194:195], off
	global_load_dwordx4 v[46:49], v[194:195], off offset:16
	global_load_dwordx4 v[130:133], v[196:197], off
	global_load_dwordx4 v[134:137], v[196:197], off offset:16
	s_waitcnt vmcnt(20)
	v_mfma_f32_32x32x64_f8f6f4 v[2:17], v[26:33], v[18:25], v[2:17]
	global_load_dwordx4 v[18:21], v[194:195], off offset:32
	global_load_dwordx4 v[22:25], v[194:195], off offset:48
	global_load_dwordx4 v[26:29], v[196:197], off offset:32
	global_load_dwordx4 v[30:33], v[196:197], off offset:48
	s_waitcnt vmcnt(32)
	v_mfma_f32_32x32x64_f8f6f4 v[2:17], v[138:145], v[98:105], v[2:17]
	s_waitcnt vmcnt(29)
	v_mov_b32_e32 v98, v154
	v_mov_b32_e32 v99, v155
	v_mov_b32_e32 v100, v156
	v_mov_b32_e32 v101, v157
	s_waitcnt vmcnt(28)
	v_mov_b32_e32 v102, v158
	v_mov_b32_e32 v103, v159
	v_mov_b32_e32 v104, v160
	v_mov_b32_e32 v105, v161
	s_waitcnt vmcnt(25)
	v_mov_b32_e32 v138, v170
	v_mov_b32_e32 v139, v171
	v_mov_b32_e32 v140, v172
	v_mov_b32_e32 v141, v173
	s_waitcnt vmcnt(24)
	v_mov_b32_e32 v142, v174
	v_mov_b32_e32 v143, v175
	v_mov_b32_e32 v144, v176
	v_mfma_f32_32x32x64_f8f6f4 v[2:17], v[122:129], v[58:65], v[2:17]
	v_mov_b32_e32 v145, v177
	v_mov_b32_e32 v58, v146
	v_mov_b32_e32 v59, v147
	v_mov_b32_e32 v60, v148
	v_mov_b32_e32 v61, v149
	v_mov_b32_e32 v62, v150
	v_mov_b32_e32 v63, v151
	v_mov_b32_e32 v64, v152
	v_mov_b32_e32 v65, v153
	v_mov_b32_e32 v122, v162
	v_mov_b32_e32 v123, v163
	v_mov_b32_e32 v124, v164
	v_mov_b32_e32 v125, v165
	v_mov_b32_e32 v126, v166
	v_mov_b32_e32 v127, v167
	v_mov_b32_e32 v128, v168
	v_mov_b32_e32 v129, v169
	s_cbranch_vccz .LBB0_1542
	s_waitcnt vmcnt(2)
	v_or_b32_e32 v22, v185, v178
	v_ashrrev_i32_e32 v23, 31, v22
	s_waitcnt lgkmcnt(0)
	v_lshl_add_u64 v[24:25], v[22:23], 2, s[16:17]
	global_load_dwordx4 v[18:21], v[24:25], off
	s_waitcnt vmcnt(2)
	v_mov_b64_e32 v[26:27], s[14:15]
	v_add_u32_e32 v1, s54, v1
	v_cmp_lt_i32_e32 vcc, s36, v1
	s_or_b64 s[20:21], vcc, s[20:21]
	s_waitcnt vmcnt(0)
	v_pk_fma_f32 v[4:5], v[4:5], s[26:27], v[20:21] op_sel_hi:[1,0,1]
	v_pk_fma_f32 v[2:3], v[2:3], s[26:27], v[18:19] op_sel_hi:[1,0,1]
	v_mul_f32_e32 v4, 0xbfb8aa3b, v4
	v_mul_f32_e32 v2, 0xbfb8aa3b, v2
	v_mul_f32_e32 v3, 0xbfb8aa3b, v3
	v_mul_f32_e32 v5, 0xbfb8aa3b, v5
	v_exp_f32_e32 v2, v2
	v_exp_f32_e32 v3, v3
	v_exp_f32_e32 v4, v4
	v_exp_f32_e32 v5, v5
	v_add_f32_e32 v2, 1.0, v2
	v_add_f32_e32 v3, 1.0, v3
	v_add_f32_e32 v4, 1.0, v4
	v_add_f32_e32 v5, 1.0, v5
	v_rcp_f32_e32 v20, v2
	v_rcp_f32_e32 v21, v3
	v_rcp_f32_e32 v4, v4
	v_rcp_f32_e32 v5, v5
	v_mad_i64_i32 v[2:3], s[28:29], v184, s35, v[26:27]
	v_lshl_add_u64 v[18:19], v[22:23], 1, v[2:3]
	v_cvt_pk_bf16_f32 v2, v20, v21
	v_cvt_pk_bf16_f32 v3, v4, v5
	global_store_dwordx2 v[18:19], v[2:3], off
	global_load_dwordx4 v[2:5], v[24:25], off offset:32
	s_waitcnt vmcnt(0)
	v_pk_fma_f32 v[4:5], v[8:9], s[26:27], v[4:5] op_sel_hi:[1,0,1]
	v_pk_fma_f32 v[2:3], v[6:7], s[26:27], v[2:3] op_sel_hi:[1,0,1]
	v_mul_f32_e32 v4, 0xbfb8aa3b, v4
	v_mul_f32_e32 v2, 0xbfb8aa3b, v2
	v_mul_f32_e32 v3, 0xbfb8aa3b, v3
	v_mul_f32_e32 v5, 0xbfb8aa3b, v5
	v_exp_f32_e32 v2, v2
	v_exp_f32_e32 v3, v3
	v_exp_f32_e32 v4, v4
	v_exp_f32_e32 v5, v5
	v_add_f32_e32 v2, 1.0, v2
	v_add_f32_e32 v3, 1.0, v3
	v_add_f32_e32 v4, 1.0, v4
	v_add_f32_e32 v5, 1.0, v5
	v_rcp_f32_e32 v2, v2
	v_rcp_f32_e32 v3, v3
	v_rcp_f32_e32 v4, v4
	v_rcp_f32_e32 v5, v5
	v_cvt_pk_bf16_f32 v2, v2, v3
	v_cvt_pk_bf16_f32 v3, v4, v5
	global_store_dwordx2 v[18:19], v[2:3], off offset:16
	global_load_dwordx4 v[2:5], v[24:25], off offset:64
	s_waitcnt vmcnt(0)
	v_pk_fma_f32 v[4:5], v[12:13], s[26:27], v[4:5] op_sel_hi:[1,0,1]
	v_pk_fma_f32 v[2:3], v[10:11], s[26:27], v[2:3] op_sel_hi:[1,0,1]
	v_mul_f32_e32 v4, 0xbfb8aa3b, v4
	v_mul_f32_e32 v2, 0xbfb8aa3b, v2
	v_mul_f32_e32 v3, 0xbfb8aa3b, v3
	v_mul_f32_e32 v5, 0xbfb8aa3b, v5
	v_exp_f32_e32 v2, v2
	v_exp_f32_e32 v3, v3
	v_exp_f32_e32 v4, v4
	v_exp_f32_e32 v5, v5
	v_add_f32_e32 v2, 1.0, v2
	v_add_f32_e32 v3, 1.0, v3
	v_add_f32_e32 v4, 1.0, v4
	v_add_f32_e32 v5, 1.0, v5
	v_rcp_f32_e32 v2, v2
	v_rcp_f32_e32 v3, v3
	v_rcp_f32_e32 v4, v4
	v_rcp_f32_e32 v5, v5
	v_cvt_pk_bf16_f32 v2, v2, v3
	v_cvt_pk_bf16_f32 v3, v4, v5
	global_store_dwordx2 v[18:19], v[2:3], off offset:32
	global_load_dwordx4 v[2:5], v[24:25], off offset:96
	s_waitcnt vmcnt(0)
	v_pk_fma_f32 v[4:5], v[16:17], s[26:27], v[4:5] op_sel_hi:[1,0,1]
	v_pk_fma_f32 v[2:3], v[14:15], s[26:27], v[2:3] op_sel_hi:[1,0,1]
	v_mul_f32_e32 v4, 0xbfb8aa3b, v4
	v_mul_f32_e32 v2, 0xbfb8aa3b, v2
	v_mul_f32_e32 v3, 0xbfb8aa3b, v3
	v_mul_f32_e32 v5, 0xbfb8aa3b, v5
	v_exp_f32_e32 v2, v2
	v_exp_f32_e32 v3, v3
	v_exp_f32_e32 v4, v4
	v_exp_f32_e32 v5, v5
	v_add_f32_e32 v2, 1.0, v2
	v_add_f32_e32 v3, 1.0, v3
	v_add_f32_e32 v4, 1.0, v4
	v_add_f32_e32 v5, 1.0, v5
	v_rcp_f32_e32 v2, v2
	v_rcp_f32_e32 v3, v3
	v_rcp_f32_e32 v4, v4
	v_rcp_f32_e32 v5, v5
	v_cvt_pk_bf16_f32 v2, v2, v3
	v_cvt_pk_bf16_f32 v3, v4, v5
	global_store_dwordx2 v[18:19], v[2:3], off offset:48
	s_andn2_b64 exec, exec, s[20:21]
	s_cbranch_execnz .LBB0_1541

.LBB0_1551:
	ds_read_b128 v[2:5], v167
	ds_read_b128 v[6:9], v171
	ds_read_b128 v[10:13], v172
	ds_read_b128 v[14:17], v173
	s_add_u32 s40, s38, 0xfffe0080
	s_addc_u32 s41, s39, -1
	s_cmp_eq_u32 s77, 4
	s_cselect_b32 s43, s29, s41
	s_cselect_b32 s42, s73, s40
	s_cselect_b32 s41, s27, s76
	s_cselect_b32 s40, s74, s75
	v_lshl_add_u64 v[158:159], s[38:39], 0, v[152:153]
	s_add_i32 m0, s37, 0xc000
	ds_read_b128 v[186:189], v184
	ds_read_b128 v[190:193], v184 offset:1024
	ds_read_b128 v[194:197], v184 offset:2048
	ds_read_b128 v[198:201], v184 offset:3072
	ds_read_b128 v[202:205], v184 offset:4096
	ds_read_b128 v[206:209], v184 offset:5120
	ds_read_b128 v[210:213], v184 offset:6144
	ds_read_b128 v[214:217], v184 offset:7168
	global_load_lds_dwordx4 v[158:159], off
	v_lshl_add_u64 v[158:159], s[38:39], 0, v[150:151]
	s_add_i32 m0, s37, 0xe000
	s_nop 0
	global_load_lds_dwordx4 v[158:159], off
	s_waitcnt lgkmcnt(8)
	s_barrier
	s_waitcnt lgkmcnt(0)
	s_setprio 1
	s_waitcnt lgkmcnt(0)
	v_mfma_f32_16x16x128_f8f6f4 v[142:145], v[2:9], v[186:193], v[142:145]
	v_mfma_f32_16x16x128_f8f6f4 v[138:141], v[10:17], v[186:193], v[138:141]
	v_mfma_f32_16x16x128_f8f6f4 v[126:129], v[2:9], v[194:201], v[126:129]
	v_mfma_f32_16x16x128_f8f6f4 v[122:125], v[10:17], v[194:201], v[122:125]
	v_mfma_f32_16x16x128_f8f6f4 v[110:113], v[2:9], v[202:209], v[110:113]
	v_mfma_f32_16x16x128_f8f6f4 v[106:109], v[10:17], v[202:209], v[106:109]
	v_mfma_f32_16x16x128_f8f6f4 v[94:97], v[2:9], v[210:217], v[94:97]
	v_mfma_f32_16x16x128_f8f6f4 v[90:93], v[10:17], v[210:217], v[90:93]
	s_setprio 0
	s_barrier
	s_mov_b32 m0, s45
	v_lshl_add_u64 v[158:159], s[40:41], 0, v[148:149]
	ds_read_b128 v[220:223], v168
	ds_read_b128 v[224:227], v174
	ds_read_b128 v[228:231], v175
	ds_read_b128 v[232:235], v176
	global_load_lds_dwordx4 v[158:159], off
	v_lshl_add_u64 v[160:161], s[40:41], 0, v[146:147]
	s_mov_b32 m0, s46
	s_nop 0
	global_load_lds_dwordx4 v[160:161], off
	s_barrier
	s_waitcnt lgkmcnt(0)
	s_setprio 1
	s_waitcnt lgkmcnt(0)
	v_mfma_f32_16x16x128_f8f6f4 v[134:137], v[220:227], v[186:193], v[134:137]
	v_mfma_f32_16x16x128_f8f6f4 v[130:133], v[228:235], v[186:193], v[130:133]
	v_mfma_f32_16x16x128_f8f6f4 v[118:121], v[220:227], v[194:201], v[118:121]
	v_mfma_f32_16x16x128_f8f6f4 v[114:117], v[228:235], v[194:201], v[114:117]
	v_mfma_f32_16x16x128_f8f6f4 v[102:105], v[220:227], v[202:209], v[102:105]
	v_mfma_f32_16x16x128_f8f6f4 v[98:101], v[228:235], v[202:209], v[98:101]
	v_mfma_f32_16x16x128_f8f6f4 v[86:89], v[220:227], v[210:217], v[86:89]
	v_mfma_f32_16x16x128_f8f6f4 v[82:85], v[228:235], v[210:217], v[82:85]
	s_setprio 0
	s_mov_b32 m0, s37
	v_lshl_add_u64 v[162:163], s[42:43], 0, v[148:149]
	s_barrier
	ds_read_b128 v[186:189], v184 offset:16384
	ds_read_b128 v[190:193], v184 offset:17408
	ds_read_b128 v[194:197], v184 offset:18432
	ds_read_b128 v[198:201], v184 offset:19456
	ds_read_b128 v[202:205], v184 offset:20480
	ds_read_b128 v[206:209], v184 offset:21504
	ds_read_b128 v[210:213], v184 offset:22528
	ds_read_b128 v[214:217], v184 offset:23552
	global_load_lds_dwordx4 v[162:163], off
	v_lshl_add_u64 v[164:165], s[42:43], 0, v[146:147]
	s_mov_b32 m0, s47
	s_nop 0
	global_load_lds_dwordx4 v[164:165], off
	s_barrier
	s_waitcnt lgkmcnt(0)
	s_setprio 1
	s_waitcnt lgkmcnt(0)
	v_mfma_f32_16x16x128_f8f6f4 v[78:81], v[2:9], v[186:193], v[78:81]
	v_mfma_f32_16x16x128_f8f6f4 v[74:77], v[10:17], v[186:193], v[74:77]
	v_mfma_f32_16x16x128_f8f6f4 v[62:65], v[2:9], v[194:201], v[62:65]
	v_mfma_f32_16x16x128_f8f6f4 v[58:61], v[10:17], v[194:201], v[58:61]
	v_mfma_f32_16x16x128_f8f6f4 v[46:49], v[2:9], v[202:209], v[46:49]
	v_mfma_f32_16x16x128_f8f6f4 v[42:45], v[10:17], v[202:209], v[42:45]
	v_mfma_f32_16x16x128_f8f6f4 v[30:33], v[2:9], v[210:217], v[30:33]
	v_mfma_f32_16x16x128_f8f6f4 v[26:29], v[10:17], v[210:217], v[26:29]
	s_setprio 0
	s_barrier
	s_add_u32 s66, s40, 0x20000
	s_addc_u32 s67, s41, 0
	s_mov_b32 m0, s48
	v_lshl_add_u64 v[2:3], s[66:67], 0, v[148:149]
	global_load_lds_dwordx4 v[2:3], off
	v_lshl_add_u64 v[2:3], s[66:67], 0, v[146:147]
	s_mov_b32 m0, s49
	s_nop 0
	global_load_lds_dwordx4 v[2:3], off
	s_waitcnt vmcnt(6)
	s_barrier
	s_setprio 1
	v_mfma_f32_16x16x128_f8f6f4 v[70:73], v[220:227], v[186:193], v[70:73]
	v_mfma_f32_16x16x128_f8f6f4 v[66:69], v[228:235], v[186:193], v[66:69]
	v_mfma_f32_16x16x128_f8f6f4 v[54:57], v[220:227], v[194:201], v[54:57]
	v_mfma_f32_16x16x128_f8f6f4 v[50:53], v[228:235], v[194:201], v[50:53]
	v_mfma_f32_16x16x128_f8f6f4 v[38:41], v[220:227], v[202:209], v[38:41]
	v_mfma_f32_16x16x128_f8f6f4 v[34:37], v[228:235], v[202:209], v[34:37]
	v_mfma_f32_16x16x128_f8f6f4 v[22:25], v[220:227], v[210:217], v[22:25]
	v_mfma_f32_16x16x128_f8f6f4 v[18:21], v[228:235], v[210:217], v[18:21]
	s_setprio 0
	s_barrier
	ds_read_b128 v[2:5], v169
	ds_read_b128 v[6:9], v177
	ds_read_b128 v[10:13], v178
	ds_read_b128 v[14:17], v179
	s_add_u32 s42, s42, 0x20000
	s_addc_u32 s43, s43, 0
	s_mov_b32 m0, s50
	v_lshl_add_u64 v[220:221], s[42:43], 0, v[148:149]
	ds_read_b128 v[186:189], v184 offset:32768
	ds_read_b128 v[190:193], v184 offset:33792
	ds_read_b128 v[194:197], v184 offset:34816
	ds_read_b128 v[198:201], v184 offset:35840
	ds_read_b128 v[202:205], v184 offset:36864
	ds_read_b128 v[206:209], v184 offset:37888
	ds_read_b128 v[210:213], v184 offset:38912
	ds_read_b128 v[214:217], v184 offset:39936
	global_load_lds_dwordx4 v[220:221], off
	v_lshl_add_u64 v[220:221], s[42:43], 0, v[146:147]
	s_mov_b32 m0, s51
	s_nop 0
	global_load_lds_dwordx4 v[220:221], off
	s_waitcnt lgkmcnt(8)
	s_barrier
	s_waitcnt lgkmcnt(0)
	s_setprio 1
	s_waitcnt lgkmcnt(0)
	v_mfma_f32_16x16x128_f8f6f4 v[142:145], v[2:9], v[186:193], v[142:145]
	v_mfma_f32_16x16x128_f8f6f4 v[138:141], v[10:17], v[186:193], v[138:141]
	v_mfma_f32_16x16x128_f8f6f4 v[126:129], v[2:9], v[194:201], v[126:129]
	v_mfma_f32_16x16x128_f8f6f4 v[122:125], v[10:17], v[194:201], v[122:125]
	v_mfma_f32_16x16x128_f8f6f4 v[110:113], v[2:9], v[202:209], v[110:113]
	v_mfma_f32_16x16x128_f8f6f4 v[106:109], v[10:17], v[202:209], v[106:109]
	v_mfma_f32_16x16x128_f8f6f4 v[94:97], v[2:9], v[210:217], v[94:97]
	v_mfma_f32_16x16x128_f8f6f4 v[90:93], v[10:17], v[210:217], v[90:93]
	s_setprio 0
	s_barrier
	s_mov_b32 m0, s53
	v_lshl_add_u64 v[158:159], v[158:159], 0, s[20:21]
	ds_read_b128 v[220:223], v170
	ds_read_b128 v[224:227], v180
	ds_read_b128 v[228:231], v181
	ds_read_b128 v[232:235], v182
	global_load_lds_dwordx4 v[158:159], off
	v_lshl_add_u64 v[158:159], v[160:161], 0, s[20:21]
	s_mov_b32 m0, s55
	s_nop 0
	global_load_lds_dwordx4 v[158:159], off
	s_barrier
	s_waitcnt lgkmcnt(0)
	s_setprio 1
	s_waitcnt lgkmcnt(0)
	v_mfma_f32_16x16x128_f8f6f4 v[134:137], v[220:227], v[186:193], v[134:137]
	v_mfma_f32_16x16x128_f8f6f4 v[130:133], v[228:235], v[186:193], v[130:133]
	v_mfma_f32_16x16x128_f8f6f4 v[118:121], v[220:227], v[194:201], v[118:121]
	v_mfma_f32_16x16x128_f8f6f4 v[114:117], v[228:235], v[194:201], v[114:117]
	v_mfma_f32_16x16x128_f8f6f4 v[102:105], v[220:227], v[202:209], v[102:105]
	v_mfma_f32_16x16x128_f8f6f4 v[98:101], v[228:235], v[202:209], v[98:101]
	v_mfma_f32_16x16x128_f8f6f4 v[86:89], v[220:227], v[210:217], v[86:89]
	v_mfma_f32_16x16x128_f8f6f4 v[82:85], v[228:235], v[210:217], v[82:85]
	s_setprio 0
	s_mov_b32 m0, s64
	v_lshl_add_u64 v[158:159], v[162:163], 0, s[20:21]
	s_barrier
	ds_read_b128 v[186:189], v184 offset:49152
	ds_read_b128 v[190:193], v184 offset:50176
	ds_read_b128 v[194:197], v184 offset:51200
	ds_read_b128 v[198:201], v184 offset:52224
	ds_read_b128 v[202:205], v184 offset:53248
	ds_read_b128 v[206:209], v184 offset:54272
	ds_read_b128 v[210:213], v184 offset:55296
	ds_read_b128 v[214:217], v184 offset:56320
	global_load_lds_dwordx4 v[158:159], off
	v_lshl_add_u64 v[158:159], v[164:165], 0, s[20:21]
	s_mov_b32 m0, s65
	s_nop 0
	global_load_lds_dwordx4 v[158:159], off
	s_barrier
	s_waitcnt lgkmcnt(0)
	s_setprio 1
	s_waitcnt lgkmcnt(0)
	v_mfma_f32_16x16x128_f8f6f4 v[78:81], v[2:9], v[186:193], v[78:81]
	v_mfma_f32_16x16x128_f8f6f4 v[74:77], v[10:17], v[186:193], v[74:77]
	v_mfma_f32_16x16x128_f8f6f4 v[62:65], v[2:9], v[194:201], v[62:65]
	v_mfma_f32_16x16x128_f8f6f4 v[58:61], v[10:17], v[194:201], v[58:61]
	v_mfma_f32_16x16x128_f8f6f4 v[46:49], v[2:9], v[202:209], v[46:49]
	v_mfma_f32_16x16x128_f8f6f4 v[42:45], v[10:17], v[202:209], v[42:45]
	v_mfma_f32_16x16x128_f8f6f4 v[30:33], v[2:9], v[210:217], v[30:33]
	v_mfma_f32_16x16x128_f8f6f4 v[26:29], v[10:17], v[210:217], v[26:29]
	s_setprio 0
	s_barrier
	s_add_u32 s40, s40, 0x20080
	s_addc_u32 s41, s41, 0
	s_mov_b32 m0, s68
	v_lshl_add_u64 v[2:3], s[40:41], 0, v[148:149]
	global_load_lds_dwordx4 v[2:3], off
	v_lshl_add_u64 v[2:3], s[40:41], 0, v[146:147]
	s_mov_b32 m0, s69
	s_nop 0
	global_load_lds_dwordx4 v[2:3], off
	s_waitcnt vmcnt(6)
	s_barrier
	s_setprio 1
	v_mfma_f32_16x16x128_f8f6f4 v[70:73], v[220:227], v[186:193], v[70:73]
	v_mfma_f32_16x16x128_f8f6f4 v[66:69], v[228:235], v[186:193], v[66:69]
	v_mfma_f32_16x16x128_f8f6f4 v[54:57], v[220:227], v[194:201], v[54:57]
	v_mfma_f32_16x16x128_f8f6f4 v[50:53], v[228:235], v[194:201], v[50:53]
	v_mfma_f32_16x16x128_f8f6f4 v[38:41], v[220:227], v[202:209], v[38:41]
	v_mfma_f32_16x16x128_f8f6f4 v[34:37], v[228:235], v[202:209], v[34:37]
	v_mfma_f32_16x16x128_f8f6f4 v[22:25], v[220:227], v[210:217], v[22:25]
	v_mfma_f32_16x16x128_f8f6f4 v[18:21], v[228:235], v[210:217], v[18:21]
	s_setprio 0
	s_add_i32 s77, s77, 2
	s_add_u32 s75, s75, 0x100
	s_addc_u32 s76, s76, 0
	s_add_u32 s38, s38, 0x100
	s_addc_u32 s39, s39, 0
	s_cmp_gt_u32 s77, 5
	s_barrier
	s_cbranch_scc0 .LBB0_1551
	v_lshl_or_b32 v10, s72, 8, v183
	v_ashrrev_i32_e32 v11, 31, v10
	s_nop 15
	s_nop 15
	v_lshl_add_u64 v[14:15], v[10:11], 2, s[16:17]
	global_load_dwordx4 v[158:161], v[14:15], off
	global_load_dwordx4 v[162:165], v[14:15], off offset:64
	global_load_dwordx4 v[6:9], v[14:15], off offset:512
	global_load_dwordx4 v[2:5], v[14:15], off offset:576
	v_lshl_add_u32 v16, s36, 8, v166
	v_mov_b64_e32 v[12:13], s[14:15]
	v_mad_i64_i32 v[186:187], s[38:39], v16, s71, v[12:13]
	v_lshlrev_b64 v[10:11], 1, v[10:11]
	v_lshl_add_u64 v[186:187], v[186:187], 0, v[10:11]
	s_and_b64 vcc, exec, s[10:11]
	s_mov_b32 s72, s26
	s_mov_b32 s36, s28
	s_mov_b64 s[40:41], s[30:31]
	s_waitcnt vmcnt(0)
	v_pk_fma_f32 v[144:145], v[144:145], s[22:23], v[160:161] op_sel_hi:[1,0,1]
	v_pk_fma_f32 v[142:143], v[142:143], s[22:23], v[158:159] op_sel_hi:[1,0,1]
	v_pk_fma_f32 v[140:141], v[140:141], s[22:23], v[164:165] op_sel_hi:[1,0,1]
	v_pk_fma_f32 v[138:139], v[138:139], s[22:23], v[162:163] op_sel_hi:[1,0,1]
	v_pk_fma_f32 v[136:137], v[136:137], s[22:23], v[8:9] op_sel_hi:[1,0,1]
	v_pk_fma_f32 v[134:135], v[134:135], s[22:23], v[6:7] op_sel_hi:[1,0,1]
	v_mul_f32_e32 v17, 0xbfb8aa3b, v142
	v_mul_f32_e32 v142, 0xbfb8aa3b, v143
	v_mul_f32_e32 v143, 0xbfb8aa3b, v144
	v_mul_f32_e32 v144, 0xbfb8aa3b, v145
	v_mul_f32_e32 v138, 0xbfb8aa3b, v138
	v_mul_f32_e32 v139, 0xbfb8aa3b, v139
	v_mul_f32_e32 v140, 0xbfb8aa3b, v140
	v_mul_f32_e32 v141, 0xbfb8aa3b, v141
	v_mul_f32_e32 v134, 0xbfb8aa3b, v134
	v_mul_f32_e32 v135, 0xbfb8aa3b, v135
	v_mul_f32_e32 v136, 0xbfb8aa3b, v136
	v_mul_f32_e32 v137, 0xbfb8aa3b, v137
	v_exp_f32_e32 v17, v17
	v_exp_f32_e32 v142, v142
	v_exp_f32_e32 v143, v143
	v_exp_f32_e32 v144, v144
	v_exp_f32_e32 v138, v138
	v_exp_f32_e32 v139, v139
	v_exp_f32_e32 v140, v140
	v_exp_f32_e32 v141, v141
	v_exp_f32_e32 v134, v134
	v_exp_f32_e32 v135, v135
	v_exp_f32_e32 v136, v136
	v_exp_f32_e32 v137, v137
	v_pk_fma_f32 v[130:131], v[130:131], s[22:23], v[2:3] op_sel_hi:[1,0,1]
	v_pk_fma_f32 v[132:133], v[132:133], s[22:23], v[4:5] op_sel_hi:[1,0,1]
	v_mul_f32_e32 v130, 0xbfb8aa3b, v130
	v_mul_f32_e32 v131, 0xbfb8aa3b, v131
	v_mul_f32_e32 v132, 0xbfb8aa3b, v132
	v_mul_f32_e32 v133, 0xbfb8aa3b, v133
	v_exp_f32_e32 v130, v130
	v_exp_f32_e32 v131, v131
	v_add_f32_e32 v17, 1.0, v17
	v_add_f32_e32 v142, 1.0, v142
	v_add_f32_e32 v143, 1.0, v143
	v_add_f32_e32 v144, 1.0, v144
	v_exp_f32_e32 v132, v132
	v_exp_f32_e32 v133, v133
	v_add_f32_e32 v138, 1.0, v138
	v_add_f32_e32 v139, 1.0, v139
	v_add_f32_e32 v140, 1.0, v140
	v_add_f32_e32 v141, 1.0, v141
	v_add_f32_e32 v134, 1.0, v134
	v_add_f32_e32 v135, 1.0, v135
	v_add_f32_e32 v136, 1.0, v136
	v_add_f32_e32 v137, 1.0, v137
	v_rcp_f32_e32 v17, v17
	v_rcp_f32_e32 v142, v142
	v_rcp_f32_e32 v143, v143
	v_rcp_f32_e32 v144, v144
	v_rcp_f32_e32 v138, v138
	v_rcp_f32_e32 v139, v139
	v_rcp_f32_e32 v140, v140
	v_rcp_f32_e32 v141, v141
	v_rcp_f32_e32 v134, v134
	v_rcp_f32_e32 v135, v135
	v_rcp_f32_e32 v136, v136
	v_rcp_f32_e32 v137, v137
	v_add_f32_e32 v130, 1.0, v130
	v_add_f32_e32 v131, 1.0, v131
	v_pk_fma_f32 v[126:127], v[126:127], s[22:23], v[158:159] op_sel_hi:[1,0,1]
	v_add_f32_e32 v132, 1.0, v132
	v_add_f32_e32 v133, 1.0, v133
	v_rcp_f32_e32 v145, v130
	v_rcp_f32_e32 v185, v131
	v_cvt_pk_bf16_f32 v130, v17, v142
	v_cvt_pk_bf16_f32 v131, v143, v144
	v_mul_f32_e32 v17, 0xbfb8aa3b, v126
	v_mul_f32_e32 v126, 0xbfb8aa3b, v127
	v_rcp_f32_e32 v188, v132
	v_rcp_f32_e32 v189, v133
	v_cvt_pk_bf16_f32 v132, v138, v139
	v_cvt_pk_bf16_f32 v133, v140, v141
	v_cvt_pk_bf16_f32 v134, v134, v135
	v_cvt_pk_bf16_f32 v135, v136, v137
	global_store_dwordx2 v[186:187], v[130:131], off
	global_store_dwordx2 v[186:187], v[132:133], off offset:32
	global_store_dwordx2 v[186:187], v[134:135], off offset:256
	v_exp_f32_e32 v130, v126
	v_pk_fma_f32 v[126:127], v[128:129], s[22:23], v[160:161] op_sel_hi:[1,0,1]
	v_exp_f32_e32 v17, v17
	v_mul_f32_e32 v126, 0xbfb8aa3b, v126
	v_exp_f32_e32 v126, v126
	v_mul_f32_e32 v127, 0xbfb8aa3b, v127
	v_exp_f32_e32 v127, v127
	v_add_f32_e32 v17, 1.0, v17
	v_add_f32_e32 v128, 1.0, v130
	v_add_f32_e32 v126, 1.0, v126
	v_rcp_f32_e32 v17, v17
	v_rcp_f32_e32 v128, v128
	v_rcp_f32_e32 v129, v126
	v_add_f32_e32 v126, 1.0, v127
	v_rcp_f32_e32 v127, v126
	v_pk_fma_f32 v[122:123], v[122:123], s[22:23], v[162:163] op_sel_hi:[1,0,1]
	v_or_b32_e32 v130, 16, v16
	v_cvt_pk_bf16_f32 v126, v17, v128
	v_mul_f32_e32 v17, 0xbfb8aa3b, v122
	v_mul_f32_e32 v122, 0xbfb8aa3b, v123
	v_cvt_pk_bf16_f32 v127, v129, v127
	v_mad_i64_i32 v[128:129], s[38:39], v130, s71, v[12:13]
	v_exp_f32_e32 v17, v17
	v_exp_f32_e32 v130, v122
	v_pk_fma_f32 v[122:123], v[124:125], s[22:23], v[164:165] op_sel_hi:[1,0,1]
	v_pk_fma_f32 v[6:7], v[118:119], s[22:23], v[6:7] op_sel_hi:[1,0,1]
	v_add_f32_e32 v17, 1.0, v17
	v_add_f32_e32 v124, 1.0, v130
	v_rcp_f32_e32 v17, v17
	v_rcp_f32_e32 v124, v124
	v_mul_f32_e32 v6, 0xbfb8aa3b, v6
	v_pk_fma_f32 v[2:3], v[114:115], s[22:23], v[2:3] op_sel_hi:[1,0,1]
	v_mul_f32_e32 v122, 0xbfb8aa3b, v122
	v_cvt_pk_bf16_f32 v124, v17, v124
	v_exp_f32_e32 v17, v6
	v_mul_f32_e32 v6, 0xbfb8aa3b, v7
	v_exp_f32_e32 v118, v6
	v_pk_fma_f32 v[6:7], v[120:121], s[22:23], v[8:9] op_sel_hi:[1,0,1]
	v_add_f32_e32 v8, 1.0, v17
	v_rcp_f32_e32 v8, v8
	v_add_f32_e32 v9, 1.0, v118
	v_rcp_f32_e32 v9, v9
	v_mul_f32_e32 v6, 0xbfb8aa3b, v6
	v_exp_f32_e32 v17, v6
	v_mul_f32_e32 v6, 0xbfb8aa3b, v7
	v_mul_f32_e32 v2, 0xbfb8aa3b, v2
	v_exp_f32_e32 v7, v6
	v_cvt_pk_bf16_f32 v6, v8, v9
	v_exp_f32_e32 v9, v2
	v_mul_f32_e32 v2, 0xbfb8aa3b, v3
	v_add_f32_e32 v8, 1.0, v17
	v_exp_f32_e32 v17, v2
	v_pk_fma_f32 v[2:3], v[116:117], s[22:23], v[4:5] op_sel_hi:[1,0,1]
	v_exp_f32_e32 v122, v122
	v_mul_f32_e32 v2, 0xbfb8aa3b, v2
	v_mul_f32_e32 v123, 0xbfb8aa3b, v123
	v_exp_f32_e32 v2, v2
	v_mul_f32_e32 v3, 0xbfb8aa3b, v3
	v_exp_f32_e32 v123, v123
	v_exp_f32_e32 v3, v3
	v_add_f32_e32 v122, 1.0, v122
	v_add_f32_e32 v2, 1.0, v2
	v_rcp_f32_e32 v125, v122
	v_add_f32_e32 v122, 1.0, v123
	v_add_f32_e32 v7, 1.0, v7
	v_add_f32_e32 v4, 1.0, v9
	v_add_f32_e32 v5, 1.0, v17
	v_rcp_f32_e32 v9, v2
	v_add_f32_e32 v2, 1.0, v3
	v_rcp_f32_e32 v130, v122
	v_rcp_f32_e32 v8, v8
	v_rcp_f32_e32 v7, v7
	v_rcp_f32_e32 v4, v4
	v_rcp_f32_e32 v5, v5
	v_rcp_f32_e32 v3, v2
	v_cvt_pk_bf16_f32 v136, v145, v185
	v_cvt_pk_bf16_f32 v137, v188, v189
	v_lshl_add_u64 v[122:123], v[128:129], 0, v[10:11]
	v_cvt_pk_bf16_f32 v125, v125, v130
	v_cvt_pk_bf16_f32 v7, v8, v7
	v_cvt_pk_bf16_f32 v2, v4, v5
	v_cvt_pk_bf16_f32 v3, v9, v3
	global_store_dwordx2 v[186:187], v[136:137], off offset:288
	global_store_dwordx2 v[122:123], v[126:127], off
	global_store_dwordx2 v[122:123], v[124:125], off offset:32
	global_store_dwordx2 v[122:123], v[6:7], off offset:256
	global_store_dwordx2 v[122:123], v[2:3], off offset:288
	global_load_dwordx4 v[6:9], v[14:15], off
	s_nop 0
	global_load_dwordx4 v[114:117], v[14:15], off offset:64
	global_load_dwordx4 v[118:121], v[14:15], off offset:512
	global_load_dwordx4 v[2:5], v[14:15], off offset:576
	s_waitcnt vmcnt(0)
	v_pk_fma_f32 v[110:111], v[110:111], s[22:23], v[6:7] op_sel_hi:[1,0,1]
	s_nop 0
	v_mul_f32_e32 v17, 0xbfb8aa3b, v110
	v_mul_f32_e32 v110, 0xbfb8aa3b, v111
	v_exp_f32_e32 v122, v110
	v_pk_fma_f32 v[110:111], v[112:113], s[22:23], v[8:9] op_sel_hi:[1,0,1]
	v_exp_f32_e32 v17, v17
	v_mul_f32_e32 v110, 0xbfb8aa3b, v110
	v_exp_f32_e32 v110, v110
	v_mul_f32_e32 v111, 0xbfb8aa3b, v111
	v_exp_f32_e32 v111, v111
	v_add_f32_e32 v17, 1.0, v17
	v_add_f32_e32 v112, 1.0, v122
	v_add_f32_e32 v110, 1.0, v110
	v_rcp_f32_e32 v17, v17
	v_rcp_f32_e32 v112, v112
	v_rcp_f32_e32 v113, v110
	v_add_f32_e32 v110, 1.0, v111
	v_rcp_f32_e32 v111, v110
	v_pk_fma_f32 v[106:107], v[106:107], s[22:23], v[114:115] op_sel_hi:[1,0,1]
	v_or_b32_e32 v122, 32, v16
	v_cvt_pk_bf16_f32 v110, v17, v112
	v_mul_f32_e32 v17, 0xbfb8aa3b, v106
	v_mul_f32_e32 v106, 0xbfb8aa3b, v107
	v_cvt_pk_bf16_f32 v111, v113, v111
	v_mad_i64_i32 v[112:113], s[38:39], v122, s71, v[12:13]
	v_exp_f32_e32 v122, v106
	v_pk_fma_f32 v[106:107], v[108:109], s[22:23], v[116:117] op_sel_hi:[1,0,1]
	v_exp_f32_e32 v17, v17
	v_mul_f32_e32 v106, 0xbfb8aa3b, v106
	v_exp_f32_e32 v106, v106
	v_mul_f32_e32 v107, 0xbfb8aa3b, v107
	v_exp_f32_e32 v107, v107
	v_add_f32_e32 v17, 1.0, v17
	v_add_f32_e32 v106, 1.0, v106
	v_add_f32_e32 v108, 1.0, v122
	v_rcp_f32_e32 v109, v106
	v_add_f32_e32 v106, 1.0, v107
	v_rcp_f32_e32 v17, v17
	v_rcp_f32_e32 v108, v108
	v_rcp_f32_e32 v122, v106
	v_pk_fma_f32 v[102:103], v[102:103], s[22:23], v[118:119] op_sel_hi:[1,0,1]
	v_lshl_add_u64 v[106:107], v[112:113], 0, v[10:11]
	v_cvt_pk_bf16_f32 v108, v17, v108
	v_cvt_pk_bf16_f32 v109, v109, v122
	v_mul_f32_e32 v17, 0xbfb8aa3b, v102
	v_mul_f32_e32 v102, 0xbfb8aa3b, v103
	global_store_dwordx2 v[106:107], v[108:109], off offset:32
	v_exp_f32_e32 v17, v17
	v_exp_f32_e32 v108, v102
	v_pk_fma_f32 v[102:103], v[104:105], s[22:23], v[120:121] op_sel_hi:[1,0,1]
	v_pk_fma_f32 v[6:7], v[94:95], s[22:23], v[6:7] op_sel_hi:[1,0,1]
	v_mul_f32_e32 v102, 0xbfb8aa3b, v102
	v_add_f32_e32 v17, 1.0, v17
	v_add_f32_e32 v104, 1.0, v108
	v_exp_f32_e32 v105, v102
	v_mul_f32_e32 v102, 0xbfb8aa3b, v103
	v_rcp_f32_e32 v17, v17
	v_rcp_f32_e32 v104, v104
	v_exp_f32_e32 v103, v102
	v_mul_f32_e32 v6, 0xbfb8aa3b, v6
	v_pk_fma_f32 v[90:91], v[90:91], s[22:23], v[114:115] op_sel_hi:[1,0,1]
	v_cvt_pk_bf16_f32 v102, v17, v104
	v_add_f32_e32 v17, 1.0, v105
	v_add_f32_e32 v103, 1.0, v103
	v_rcp_f32_e32 v17, v17
	v_rcp_f32_e32 v103, v103
	v_pk_fma_f32 v[98:99], v[98:99], s[22:23], v[2:3] op_sel_hi:[1,0,1]
	v_pk_fma_f32 v[2:3], v[82:83], s[22:23], v[2:3] op_sel_hi:[1,0,1]
	v_mul_f32_e32 v98, 0xbfb8aa3b, v98
	v_cvt_pk_bf16_f32 v103, v17, v103
	v_exp_f32_e32 v17, v6
	v_mul_f32_e32 v6, 0xbfb8aa3b, v7
	v_exp_f32_e32 v94, v6
	v_pk_fma_f32 v[6:7], v[96:97], s[22:23], v[8:9] op_sel_hi:[1,0,1]
	v_add_f32_e32 v8, 1.0, v17
	v_mul_f32_e32 v6, 0xbfb8aa3b, v6
	v_exp_f32_e32 v6, v6
	v_mul_f32_e32 v7, 0xbfb8aa3b, v7
	v_exp_f32_e32 v7, v7
	v_add_f32_e32 v9, 1.0, v94
	v_add_f32_e32 v6, 1.0, v6
	v_rcp_f32_e32 v17, v6
	v_add_f32_e32 v6, 1.0, v7
	v_rcp_f32_e32 v7, v6
	v_rcp_f32_e32 v8, v8
	v_rcp_f32_e32 v9, v9
	v_or_b32_e32 v94, 48, v16
	v_cvt_pk_bf16_f32 v7, v17, v7
	v_mul_f32_e32 v17, 0xbfb8aa3b, v90
	v_mul_f32_e32 v90, 0xbfb8aa3b, v91
	v_cvt_pk_bf16_f32 v6, v8, v9
	v_mad_i64_i32 v[8:9], s[38:39], v94, s71, v[12:13]
	v_exp_f32_e32 v94, v90
	v_pk_fma_f32 v[90:91], v[92:93], s[22:23], v[116:117] op_sel_hi:[1,0,1]
	v_exp_f32_e32 v17, v17
	v_mul_f32_e32 v90, 0xbfb8aa3b, v90
	v_mul_f32_e32 v91, 0xbfb8aa3b, v91
	v_exp_f32_e32 v90, v90
	v_exp_f32_e32 v91, v91
	v_add_f32_e32 v17, 1.0, v17
	v_add_f32_e32 v92, 1.0, v94
	v_add_f32_e32 v90, 1.0, v90
	v_add_f32_e32 v91, 1.0, v91
	v_rcp_f32_e32 v17, v17
	v_rcp_f32_e32 v92, v92
	v_rcp_f32_e32 v90, v90
	v_rcp_f32_e32 v91, v91
	v_lshl_add_u64 v[8:9], v[8:9], 0, v[10:11]
	global_store_dwordx2 v[8:9], v[6:7], off
	v_cvt_pk_bf16_f32 v6, v17, v92
	v_cvt_pk_bf16_f32 v7, v90, v91
	global_store_dwordx2 v[8:9], v[6:7], off offset:32
	v_pk_fma_f32 v[6:7], v[86:87], s[22:23], v[118:119] op_sel_hi:[1,0,1]
	v_mul_f32_e32 v2, 0xbfb8aa3b, v2
	v_mul_f32_e32 v6, 0xbfb8aa3b, v6
	v_exp_f32_e32 v17, v6
	v_mul_f32_e32 v6, 0xbfb8aa3b, v7
	v_exp_f32_e32 v86, v6
	v_exp_f32_e32 v104, v98
	v_mul_f32_e32 v98, 0xbfb8aa3b, v99
	v_exp_f32_e32 v82, v2
	v_mul_f32_e32 v2, 0xbfb8aa3b, v3
	v_exp_f32_e32 v105, v98
	v_pk_fma_f32 v[98:99], v[100:101], s[22:23], v[4:5] op_sel_hi:[1,0,1]
	v_pk_fma_f32 v[6:7], v[88:89], s[22:23], v[120:121] op_sel_hi:[1,0,1]
	v_exp_f32_e32 v83, v2
	v_pk_fma_f32 v[2:3], v[84:85], s[22:23], v[4:5] op_sel_hi:[1,0,1]
	v_mul_f32_e32 v98, 0xbfb8aa3b, v98
	v_mul_f32_e32 v6, 0xbfb8aa3b, v6
	v_mul_f32_e32 v2, 0xbfb8aa3b, v2
	v_exp_f32_e32 v98, v98
	v_mul_f32_e32 v99, 0xbfb8aa3b, v99
	v_add_f32_e32 v17, 1.0, v17
	v_add_f32_e32 v86, 1.0, v86
	v_exp_f32_e32 v87, v6
	v_mul_f32_e32 v6, 0xbfb8aa3b, v7
	v_exp_f32_e32 v2, v2
	v_mul_f32_e32 v3, 0xbfb8aa3b, v3
	v_exp_f32_e32 v99, v99
	v_rcp_f32_e32 v17, v17
	v_rcp_f32_e32 v86, v86
	v_exp_f32_e32 v7, v6
	v_exp_f32_e32 v3, v3
	v_add_f32_e32 v98, 1.0, v98
	v_add_f32_e32 v2, 1.0, v2
	v_add_f32_e32 v100, 1.0, v104
	v_add_f32_e32 v101, 1.0, v105
	v_rcp_f32_e32 v104, v98
	v_add_f32_e32 v98, 1.0, v99
	v_cvt_pk_bf16_f32 v6, v17, v86
	v_add_f32_e32 v17, 1.0, v87
	v_add_f32_e32 v7, 1.0, v7
	v_add_f32_e32 v4, 1.0, v82
	v_add_f32_e32 v5, 1.0, v83
	v_rcp_f32_e32 v82, v2
	v_add_f32_e32 v2, 1.0, v3
	v_rcp_f32_e32 v100, v100
	v_rcp_f32_e32 v101, v101
	v_rcp_f32_e32 v99, v98
	v_rcp_f32_e32 v17, v17
	v_rcp_f32_e32 v7, v7
	v_rcp_f32_e32 v4, v4
	v_rcp_f32_e32 v5, v5
	v_rcp_f32_e32 v3, v2
	v_cvt_pk_bf16_f32 v98, v100, v101
	v_cvt_pk_bf16_f32 v99, v104, v99
	v_cvt_pk_bf16_f32 v7, v17, v7
	v_cvt_pk_bf16_f32 v2, v4, v5
	v_cvt_pk_bf16_f32 v3, v82, v3
	global_store_dwordx2 v[106:107], v[110:111], off
	global_store_dwordx2 v[106:107], v[102:103], off offset:256
	global_store_dwordx2 v[106:107], v[98:99], off offset:288
	global_store_dwordx2 v[8:9], v[6:7], off offset:256
	global_store_dwordx2 v[8:9], v[2:3], off offset:288
	global_load_dwordx4 v[6:9], v[14:15], off
	s_nop 0
	global_load_dwordx4 v[82:85], v[14:15], off offset:64
	global_load_dwordx4 v[86:89], v[14:15], off offset:512
	global_load_dwordx4 v[2:5], v[14:15], off offset:576
	s_waitcnt vmcnt(0)
	v_pk_fma_f32 v[78:79], v[78:79], s[22:23], v[6:7] op_sel_hi:[1,0,1]
	s_nop 0
	v_mul_f32_e32 v17, 0xbfb8aa3b, v78
	v_mul_f32_e32 v78, 0xbfb8aa3b, v79
	v_exp_f32_e32 v90, v78
	v_pk_fma_f32 v[78:79], v[80:81], s[22:23], v[8:9] op_sel_hi:[1,0,1]
	v_exp_f32_e32 v17, v17
	v_mul_f32_e32 v78, 0xbfb8aa3b, v78
	v_exp_f32_e32 v78, v78
	v_mul_f32_e32 v79, 0xbfb8aa3b, v79
	v_exp_f32_e32 v79, v79
	v_add_f32_e32 v17, 1.0, v17
	v_add_f32_e32 v80, 1.0, v90
	v_add_f32_e32 v78, 1.0, v78
	v_rcp_f32_e32 v17, v17
	v_rcp_f32_e32 v80, v80
	v_rcp_f32_e32 v81, v78
	v_add_f32_e32 v78, 1.0, v79
	v_rcp_f32_e32 v79, v78
	v_pk_fma_f32 v[74:75], v[74:75], s[22:23], v[82:83] op_sel_hi:[1,0,1]
	v_add_u32_e32 v90, 0x80, v16
	v_cvt_pk_bf16_f32 v78, v17, v80
	v_mul_f32_e32 v17, 0xbfb8aa3b, v74
	v_mul_f32_e32 v74, 0xbfb8aa3b, v75
	v_cvt_pk_bf16_f32 v79, v81, v79
	v_mad_i64_i32 v[80:81], s[38:39], v90, s71, v[12:13]
	v_exp_f32_e32 v90, v74
	v_pk_fma_f32 v[74:75], v[76:77], s[22:23], v[84:85] op_sel_hi:[1,0,1]
	v_exp_f32_e32 v17, v17
	v_mul_f32_e32 v74, 0xbfb8aa3b, v74
	v_exp_f32_e32 v74, v74
	v_mul_f32_e32 v75, 0xbfb8aa3b, v75
	v_exp_f32_e32 v75, v75
	v_add_f32_e32 v17, 1.0, v17
	v_add_f32_e32 v74, 1.0, v74
	v_add_f32_e32 v76, 1.0, v90
	v_rcp_f32_e32 v77, v74
	v_add_f32_e32 v74, 1.0, v75
	v_rcp_f32_e32 v17, v17
	v_rcp_f32_e32 v76, v76
	v_rcp_f32_e32 v90, v74
	v_pk_fma_f32 v[70:71], v[70:71], s[22:23], v[86:87] op_sel_hi:[1,0,1]
	v_lshl_add_u64 v[74:75], v[80:81], 0, v[10:11]
	v_cvt_pk_bf16_f32 v76, v17, v76
	v_cvt_pk_bf16_f32 v77, v77, v90
	v_mul_f32_e32 v17, 0xbfb8aa3b, v70
	v_mul_f32_e32 v70, 0xbfb8aa3b, v71
	global_store_dwordx2 v[74:75], v[76:77], off offset:32
	v_exp_f32_e32 v17, v17
	v_exp_f32_e32 v76, v70
	v_pk_fma_f32 v[70:71], v[72:73], s[22:23], v[88:89] op_sel_hi:[1,0,1]
	v_pk_fma_f32 v[6:7], v[62:63], s[22:23], v[6:7] op_sel_hi:[1,0,1]
	v_mul_f32_e32 v70, 0xbfb8aa3b, v70
	v_add_f32_e32 v17, 1.0, v17
	v_add_f32_e32 v72, 1.0, v76
	v_exp_f32_e32 v73, v70
	v_mul_f32_e32 v70, 0xbfb8aa3b, v71
	v_rcp_f32_e32 v17, v17
	v_rcp_f32_e32 v72, v72
	v_exp_f32_e32 v71, v70
	v_mul_f32_e32 v6, 0xbfb8aa3b, v6
	v_pk_fma_f32 v[58:59], v[58:59], s[22:23], v[82:83] op_sel_hi:[1,0,1]
	v_cvt_pk_bf16_f32 v70, v17, v72
	v_add_f32_e32 v17, 1.0, v73
	v_add_f32_e32 v71, 1.0, v71
	v_rcp_f32_e32 v17, v17
	v_rcp_f32_e32 v71, v71
	v_pk_fma_f32 v[66:67], v[66:67], s[22:23], v[2:3] op_sel_hi:[1,0,1]
	v_pk_fma_f32 v[2:3], v[50:51], s[22:23], v[2:3] op_sel_hi:[1,0,1]
	v_mul_f32_e32 v66, 0xbfb8aa3b, v66
	v_cvt_pk_bf16_f32 v71, v17, v71
	v_exp_f32_e32 v17, v6
	v_mul_f32_e32 v6, 0xbfb8aa3b, v7
	v_exp_f32_e32 v62, v6
	v_pk_fma_f32 v[6:7], v[64:65], s[22:23], v[8:9] op_sel_hi:[1,0,1]
	v_add_f32_e32 v8, 1.0, v17
	v_mul_f32_e32 v6, 0xbfb8aa3b, v6
	v_exp_f32_e32 v6, v6
	v_mul_f32_e32 v7, 0xbfb8aa3b, v7
	v_exp_f32_e32 v7, v7
	v_add_f32_e32 v9, 1.0, v62
	v_add_f32_e32 v6, 1.0, v6
	v_rcp_f32_e32 v17, v6
	v_add_f32_e32 v6, 1.0, v7
	v_rcp_f32_e32 v7, v6
	v_rcp_f32_e32 v8, v8
	v_rcp_f32_e32 v9, v9
	v_add_u32_e32 v62, 0x90, v16
	v_cvt_pk_bf16_f32 v7, v17, v7
	v_mul_f32_e32 v17, 0xbfb8aa3b, v58
	v_mul_f32_e32 v58, 0xbfb8aa3b, v59
	v_cvt_pk_bf16_f32 v6, v8, v9
	v_mad_i64_i32 v[8:9], s[38:39], v62, s71, v[12:13]
	v_exp_f32_e32 v62, v58
	v_pk_fma_f32 v[58:59], v[60:61], s[22:23], v[84:85] op_sel_hi:[1,0,1]
	v_exp_f32_e32 v17, v17
	v_mul_f32_e32 v58, 0xbfb8aa3b, v58
	v_mul_f32_e32 v59, 0xbfb8aa3b, v59
	v_exp_f32_e32 v58, v58
	v_exp_f32_e32 v59, v59
	v_add_f32_e32 v17, 1.0, v17
	v_add_f32_e32 v60, 1.0, v62
	v_add_f32_e32 v58, 1.0, v58
	v_add_f32_e32 v59, 1.0, v59
	v_rcp_f32_e32 v17, v17
	v_rcp_f32_e32 v60, v60
	v_rcp_f32_e32 v58, v58
	v_rcp_f32_e32 v59, v59
	v_lshl_add_u64 v[8:9], v[8:9], 0, v[10:11]
	global_store_dwordx2 v[8:9], v[6:7], off
	v_cvt_pk_bf16_f32 v6, v17, v60
	v_cvt_pk_bf16_f32 v7, v58, v59
	global_store_dwordx2 v[8:9], v[6:7], off offset:32
	v_pk_fma_f32 v[6:7], v[54:55], s[22:23], v[86:87] op_sel_hi:[1,0,1]
	v_mul_f32_e32 v2, 0xbfb8aa3b, v2
	v_mul_f32_e32 v6, 0xbfb8aa3b, v6
	v_exp_f32_e32 v17, v6
	v_mul_f32_e32 v6, 0xbfb8aa3b, v7
	v_exp_f32_e32 v54, v6
	v_exp_f32_e32 v72, v66
	v_mul_f32_e32 v66, 0xbfb8aa3b, v67
	v_exp_f32_e32 v50, v2
	v_mul_f32_e32 v2, 0xbfb8aa3b, v3
	v_exp_f32_e32 v73, v66
	v_pk_fma_f32 v[66:67], v[68:69], s[22:23], v[4:5] op_sel_hi:[1,0,1]
	v_pk_fma_f32 v[6:7], v[56:57], s[22:23], v[88:89] op_sel_hi:[1,0,1]
	v_exp_f32_e32 v51, v2
	v_pk_fma_f32 v[2:3], v[52:53], s[22:23], v[4:5] op_sel_hi:[1,0,1]
	v_mul_f32_e32 v66, 0xbfb8aa3b, v66
	v_mul_f32_e32 v6, 0xbfb8aa3b, v6
	v_mul_f32_e32 v2, 0xbfb8aa3b, v2
	v_exp_f32_e32 v66, v66
	v_mul_f32_e32 v67, 0xbfb8aa3b, v67
	v_add_f32_e32 v17, 1.0, v17
	v_add_f32_e32 v54, 1.0, v54
	v_exp_f32_e32 v55, v6
	v_mul_f32_e32 v6, 0xbfb8aa3b, v7
	v_exp_f32_e32 v2, v2
	v_mul_f32_e32 v3, 0xbfb8aa3b, v3
	v_exp_f32_e32 v67, v67
	v_rcp_f32_e32 v17, v17
	v_rcp_f32_e32 v54, v54
	v_exp_f32_e32 v7, v6
	v_exp_f32_e32 v3, v3
	v_add_f32_e32 v66, 1.0, v66
	v_add_f32_e32 v2, 1.0, v2
	v_add_f32_e32 v68, 1.0, v72
	v_add_f32_e32 v69, 1.0, v73
	v_rcp_f32_e32 v72, v66
	v_add_f32_e32 v66, 1.0, v67
	v_cvt_pk_bf16_f32 v6, v17, v54
	v_add_f32_e32 v17, 1.0, v55
	v_add_f32_e32 v7, 1.0, v7
	v_add_f32_e32 v4, 1.0, v50
	v_add_f32_e32 v5, 1.0, v51
	v_rcp_f32_e32 v50, v2
	v_add_f32_e32 v2, 1.0, v3
	v_rcp_f32_e32 v68, v68
	v_rcp_f32_e32 v69, v69
	v_rcp_f32_e32 v67, v66
	v_rcp_f32_e32 v17, v17
	v_rcp_f32_e32 v7, v7
	v_rcp_f32_e32 v4, v4
	v_rcp_f32_e32 v5, v5
	v_rcp_f32_e32 v3, v2
	v_cvt_pk_bf16_f32 v66, v68, v69
	v_cvt_pk_bf16_f32 v67, v72, v67
	v_cvt_pk_bf16_f32 v7, v17, v7
	v_cvt_pk_bf16_f32 v2, v4, v5
	v_cvt_pk_bf16_f32 v3, v50, v3
	global_store_dwordx2 v[74:75], v[78:79], off
	global_store_dwordx2 v[74:75], v[70:71], off offset:256
	global_store_dwordx2 v[74:75], v[66:67], off offset:288
	global_store_dwordx2 v[8:9], v[6:7], off offset:256
	global_store_dwordx2 v[8:9], v[2:3], off offset:288
	global_load_dwordx4 v[6:9], v[14:15], off
	s_nop 0
	global_load_dwordx4 v[50:53], v[14:15], off offset:64
	global_load_dwordx4 v[54:57], v[14:15], off offset:512
	global_load_dwordx4 v[2:5], v[14:15], off offset:576
	s_waitcnt vmcnt(0)
	v_pk_fma_f32 v[14:15], v[46:47], s[22:23], v[6:7] op_sel_hi:[1,0,1]
	s_nop 0
	v_mul_f32_e32 v14, 0xbfb8aa3b, v14
	v_exp_f32_e32 v17, v14
	v_mul_f32_e32 v14, 0xbfb8aa3b, v15
	v_exp_f32_e32 v46, v14
	v_pk_fma_f32 v[14:15], v[48:49], s[22:23], v[8:9] op_sel_hi:[1,0,1]
	v_add_f32_e32 v17, 1.0, v17
	v_mul_f32_e32 v14, 0xbfb8aa3b, v14
	v_exp_f32_e32 v14, v14
	v_mul_f32_e32 v15, 0xbfb8aa3b, v15
	v_exp_f32_e32 v15, v15
	v_add_f32_e32 v46, 1.0, v46
	v_add_f32_e32 v14, 1.0, v14
	v_rcp_f32_e32 v17, v17
	v_rcp_f32_e32 v46, v46
	v_rcp_f32_e32 v47, v14
	v_add_f32_e32 v14, 1.0, v15
	v_rcp_f32_e32 v15, v14
	v_pk_fma_f32 v[42:43], v[42:43], s[22:23], v[50:51] op_sel_hi:[1,0,1]
	v_add_u32_e32 v48, 0xa0, v16
	v_cvt_pk_bf16_f32 v14, v17, v46
	v_mul_f32_e32 v17, 0xbfb8aa3b, v42
	v_mul_f32_e32 v42, 0xbfb8aa3b, v43
	v_cvt_pk_bf16_f32 v15, v47, v15
	v_mad_i64_i32 v[46:47], s[38:39], v48, s71, v[12:13]
	v_exp_f32_e32 v48, v42
	v_pk_fma_f32 v[42:43], v[44:45], s[22:23], v[52:53] op_sel_hi:[1,0,1]
	v_exp_f32_e32 v17, v17
	v_mul_f32_e32 v42, 0xbfb8aa3b, v42
	v_exp_f32_e32 v42, v42
	v_mul_f32_e32 v43, 0xbfb8aa3b, v43
	v_exp_f32_e32 v43, v43
	v_add_f32_e32 v17, 1.0, v17
	v_add_f32_e32 v42, 1.0, v42
	v_add_f32_e32 v44, 1.0, v48
	v_rcp_f32_e32 v45, v42
	v_add_f32_e32 v42, 1.0, v43
	v_rcp_f32_e32 v17, v17
	v_rcp_f32_e32 v44, v44
	v_rcp_f32_e32 v48, v42
	v_lshl_add_u64 v[42:43], v[46:47], 0, v[10:11]
	global_store_dwordx2 v[42:43], v[14:15], off
	v_cvt_pk_bf16_f32 v14, v17, v44
	v_cvt_pk_bf16_f32 v15, v45, v48
	global_store_dwordx2 v[42:43], v[14:15], off offset:32
	v_pk_fma_f32 v[14:15], v[38:39], s[22:23], v[54:55] op_sel_hi:[1,0,1]
	v_pk_fma_f32 v[34:35], v[34:35], s[22:23], v[2:3] op_sel_hi:[1,0,1]
	v_mul_f32_e32 v14, 0xbfb8aa3b, v14
	v_exp_f32_e32 v17, v14
	v_mul_f32_e32 v14, 0xbfb8aa3b, v15
	v_exp_f32_e32 v38, v14
	v_pk_fma_f32 v[14:15], v[40:41], s[22:23], v[56:57] op_sel_hi:[1,0,1]
	v_add_f32_e32 v17, 1.0, v17
	v_mul_f32_e32 v14, 0xbfb8aa3b, v14
	v_add_f32_e32 v38, 1.0, v38
	v_exp_f32_e32 v39, v14
	v_mul_f32_e32 v14, 0xbfb8aa3b, v15
	v_rcp_f32_e32 v17, v17
	v_rcp_f32_e32 v38, v38
	v_exp_f32_e32 v15, v14
	v_mul_f32_e32 v34, 0xbfb8aa3b, v34
	v_pk_fma_f32 v[6:7], v[30:31], s[22:23], v[6:7] op_sel_hi:[1,0,1]
	v_cvt_pk_bf16_f32 v14, v17, v38
	v_add_f32_e32 v17, 1.0, v39
	v_add_f32_e32 v15, 1.0, v15
	v_rcp_f32_e32 v17, v17
	v_rcp_f32_e32 v15, v15
	v_exp_f32_e32 v38, v34
	v_mul_f32_e32 v34, 0xbfb8aa3b, v35
	v_exp_f32_e32 v39, v34
	v_pk_fma_f32 v[34:35], v[36:37], s[22:23], v[4:5] op_sel_hi:[1,0,1]
	v_mul_f32_e32 v6, 0xbfb8aa3b, v6
	v_mul_f32_e32 v34, 0xbfb8aa3b, v34
	v_mul_f32_e32 v35, 0xbfb8aa3b, v35
	v_exp_f32_e32 v34, v34
	v_exp_f32_e32 v35, v35
	v_cvt_pk_bf16_f32 v15, v17, v15
	v_exp_f32_e32 v17, v6
	v_mul_f32_e32 v6, 0xbfb8aa3b, v7
	v_exp_f32_e32 v30, v6
	v_pk_fma_f32 v[6:7], v[32:33], s[22:23], v[8:9] op_sel_hi:[1,0,1]
	v_add_f32_e32 v36, 1.0, v38
	v_add_f32_e32 v37, 1.0, v39
	v_add_f32_e32 v34, 1.0, v34
	v_add_f32_e32 v35, 1.0, v35
	v_mul_f32_e32 v6, 0xbfb8aa3b, v6
	v_rcp_f32_e32 v36, v36
	v_rcp_f32_e32 v37, v37
	v_rcp_f32_e32 v34, v34
	v_rcp_f32_e32 v35, v35
	v_exp_f32_e32 v6, v6
	v_mul_f32_e32 v7, 0xbfb8aa3b, v7
	v_add_f32_e32 v8, 1.0, v17
	v_add_f32_e32 v9, 1.0, v30
	v_exp_f32_e32 v7, v7
	v_rcp_f32_e32 v8, v8
	v_rcp_f32_e32 v9, v9
	global_store_dwordx2 v[42:43], v[14:15], off offset:256
	v_cvt_pk_bf16_f32 v14, v36, v37
	v_cvt_pk_bf16_f32 v15, v34, v35
	v_add_f32_e32 v6, 1.0, v6
	v_rcp_f32_e32 v17, v6
	v_add_f32_e32 v6, 1.0, v7
	global_store_dwordx2 v[42:43], v[14:15], off offset:288
	v_add_u32_e32 v14, 0xb0, v16
	v_rcp_f32_e32 v7, v6
	v_cvt_pk_bf16_f32 v6, v8, v9
	v_mad_i64_i32 v[8:9], s[38:39], v14, s71, v[12:13]
	v_pk_fma_f32 v[12:13], v[26:27], s[22:23], v[50:51] op_sel_hi:[1,0,1]
	v_cvt_pk_bf16_f32 v7, v17, v7
	v_mul_f32_e32 v12, 0xbfb8aa3b, v12
	v_exp_f32_e32 v14, v12
	v_mul_f32_e32 v12, 0xbfb8aa3b, v13
	v_exp_f32_e32 v15, v12
	v_pk_fma_f32 v[12:13], v[28:29], s[22:23], v[52:53] op_sel_hi:[1,0,1]
	v_add_f32_e32 v14, 1.0, v14
	v_mul_f32_e32 v12, 0xbfb8aa3b, v12
	v_mul_f32_e32 v13, 0xbfb8aa3b, v13
	v_exp_f32_e32 v12, v12
	v_exp_f32_e32 v13, v13
	v_add_f32_e32 v15, 1.0, v15
	v_rcp_f32_e32 v14, v14
	v_add_f32_e32 v12, 1.0, v12
	v_add_f32_e32 v13, 1.0, v13
	v_rcp_f32_e32 v15, v15
	v_rcp_f32_e32 v12, v12
	v_rcp_f32_e32 v13, v13
	v_lshl_add_u64 v[8:9], v[8:9], 0, v[10:11]
	global_store_dwordx2 v[8:9], v[6:7], off
	v_cvt_pk_bf16_f32 v6, v14, v15
	v_cvt_pk_bf16_f32 v7, v12, v13
	global_store_dwordx2 v[8:9], v[6:7], off offset:32
	v_pk_fma_f32 v[6:7], v[22:23], s[22:23], v[54:55] op_sel_hi:[1,0,1]
	v_pk_fma_f32 v[2:3], v[18:19], s[22:23], v[2:3] op_sel_hi:[1,0,1]
	v_mul_f32_e32 v6, 0xbfb8aa3b, v6
	v_exp_f32_e32 v10, v6
	v_mul_f32_e32 v6, 0xbfb8aa3b, v7
	v_exp_f32_e32 v11, v6
	v_pk_fma_f32 v[6:7], v[24:25], s[22:23], v[56:57] op_sel_hi:[1,0,1]
	v_add_f32_e32 v10, 1.0, v10
	v_rcp_f32_e32 v10, v10
	v_add_f32_e32 v11, 1.0, v11
	v_rcp_f32_e32 v11, v11
	v_mul_f32_e32 v6, 0xbfb8aa3b, v6
	v_exp_f32_e32 v12, v6
	v_mul_f32_e32 v6, 0xbfb8aa3b, v7
	v_mul_f32_e32 v2, 0xbfb8aa3b, v2
	v_exp_f32_e32 v7, v6
	v_cvt_pk_bf16_f32 v6, v10, v11
	v_exp_f32_e32 v11, v2
	v_mul_f32_e32 v2, 0xbfb8aa3b, v3
	v_add_f32_e32 v10, 1.0, v12
	v_exp_f32_e32 v12, v2
	v_pk_fma_f32 v[2:3], v[20:21], s[22:23], v[4:5] op_sel_hi:[1,0,1]
	v_add_f32_e32 v7, 1.0, v7
	v_mul_f32_e32 v2, 0xbfb8aa3b, v2
	v_exp_f32_e32 v2, v2
	v_mul_f32_e32 v3, 0xbfb8aa3b, v3
	v_exp_f32_e32 v3, v3
	v_add_f32_e32 v4, 1.0, v11
	v_add_f32_e32 v2, 1.0, v2
	v_add_f32_e32 v5, 1.0, v12
	v_rcp_f32_e32 v11, v2
	v_add_f32_e32 v2, 1.0, v3
	v_rcp_f32_e32 v10, v10
	v_rcp_f32_e32 v7, v7
	v_rcp_f32_e32 v4, v4
	v_rcp_f32_e32 v5, v5
	v_rcp_f32_e32 v3, v2
	v_cvt_pk_bf16_f32 v7, v10, v7
	s_mov_b64 s[38:39], s[34:35]
	v_cvt_pk_bf16_f32 v2, v4, v5
	v_cvt_pk_bf16_f32 v3, v11, v3
	global_store_dwordx2 v[8:9], v[6:7], off offset:256
	global_store_dwordx2 v[8:9], v[2:3], off offset:288
	s_cbranch_vccz .LBB0_1548
	s_waitcnt vmcnt(0)
	s_cmpk_gt_u32 s3, 0xff
	s_cbranch_scc1 .LBB0_1555
	s_barrier

.LBB0_2869:
	s_waitcnt vmcnt(20)
	s_nop 0
	v_mfma_f32_32x32x64_f8f6f4 v[2:17], v[106:113], v[66:73], v[2:17]
	s_and_b64 s[42:43], s[26:27], exec
	s_mov_b32 s43, s25
	s_cselect_b32 s24, s34, 0x380
	s_cselect_b32 s42, s35, 0x380
	s_mov_b32 s45, s25
	s_cselect_b32 s44, s36, 0x380
	v_lshl_add_u64 v[194:195], v[186:187], 0, s[44:45]
	v_lshl_add_u64 v[196:197], v[188:189], 0, s[44:45]
	s_waitcnt vmcnt(16)
	v_mfma_f32_32x32x64_f8f6f4 v[2:17], v[90:97], v[50:57], v[2:17]
	s_waitcnt vmcnt(12)
	v_mfma_f32_32x32x64_f8f6f4 v[2:17], v[114:121], v[74:81], v[2:17]
	s_waitcnt vmcnt(8)
	v_mfma_f32_32x32x64_f8f6f4 v[2:17], v[82:89], v[34:41], v[2:17]
	v_lshl_add_u64 v[34:35], v[186:187], 0, s[24:25]
	v_lshl_add_u64 v[36:37], v[188:189], 0, s[24:25]
	v_lshl_add_u64 v[38:39], v[186:187], 0, s[42:43]
	v_lshl_add_u64 v[86:87], v[188:189], 0, s[42:43]
	global_load_dwordx4 v[66:69], v[34:35], off
	global_load_dwordx4 v[70:73], v[34:35], off offset:16
	global_load_dwordx4 v[106:109], v[36:37], off
	global_load_dwordx4 v[110:113], v[36:37], off offset:16
	global_load_dwordx4 v[50:53], v[34:35], off offset:32
	s_waitcnt vmcnt(9)
	v_mfma_f32_32x32x64_f8f6f4 v[2:17], v[130:137], v[42:49], v[2:17]
	global_load_dwordx4 v[54:57], v[34:35], off offset:48
	global_load_dwordx4 v[90:93], v[36:37], off offset:32
	global_load_dwordx4 v[94:97], v[36:37], off offset:48
	global_load_dwordx4 v[74:77], v[38:39], off
	global_load_dwordx4 v[78:81], v[38:39], off offset:16
	global_load_dwordx4 v[114:117], v[86:87], off
	global_load_dwordx4 v[118:121], v[86:87], off offset:16
	s_nop 0
	global_load_dwordx4 v[34:37], v[38:39], off offset:32
	s_nop 0
	global_load_dwordx4 v[38:41], v[38:39], off offset:48
	s_nop 0
	global_load_dwordx4 v[82:85], v[86:87], off offset:32
	s_nop 0
	global_load_dwordx4 v[86:89], v[86:87], off offset:48
	s_nop 0
	global_load_dwordx4 v[42:45], v[194:195], off
	global_load_dwordx4 v[46:49], v[194:195], off offset:16
	global_load_dwordx4 v[130:133], v[196:197], off
	global_load_dwordx4 v[134:137], v[196:197], off offset:16
	s_waitcnt vmcnt(20)
	v_mfma_f32_32x32x64_f8f6f4 v[2:17], v[26:33], v[18:25], v[2:17]
	global_load_dwordx4 v[18:21], v[194:195], off offset:32
	global_load_dwordx4 v[22:25], v[194:195], off offset:48
	global_load_dwordx4 v[26:29], v[196:197], off offset:32
	global_load_dwordx4 v[30:33], v[196:197], off offset:48
	v_cndmask_b32_e64 v194, 0, 1, s[26:27]
	v_cmp_ne_u32_e32 vcc, 1, v194
	s_mov_b64 s[26:27], 0
	s_and_b64 vcc, exec, vcc
	s_waitcnt vmcnt(32)
	v_mfma_f32_32x32x64_f8f6f4 v[2:17], v[138:145], v[98:105], v[2:17]
	s_waitcnt vmcnt(29)
	v_mov_b32_e32 v98, v154
	v_mov_b32_e32 v99, v155
	v_mov_b32_e32 v100, v156
	v_mov_b32_e32 v101, v157
	s_waitcnt vmcnt(28)
	v_mov_b32_e32 v102, v158
	v_mov_b32_e32 v103, v159
	v_mov_b32_e32 v104, v160
	v_mov_b32_e32 v105, v161
	s_waitcnt vmcnt(25)
	v_mov_b32_e32 v138, v170
	v_mov_b32_e32 v139, v171
	v_mov_b32_e32 v140, v172
	v_mov_b32_e32 v141, v173
	s_waitcnt vmcnt(24)
	v_mov_b32_e32 v142, v174
	v_mov_b32_e32 v143, v175
	v_mov_b32_e32 v144, v176
	v_mfma_f32_32x32x64_f8f6f4 v[2:17], v[122:129], v[58:65], v[2:17]
	v_mov_b32_e32 v145, v177
	v_mov_b32_e32 v58, v146
	v_mov_b32_e32 v59, v147
	v_mov_b32_e32 v60, v148
	v_mov_b32_e32 v61, v149
	v_mov_b32_e32 v62, v150
	v_mov_b32_e32 v63, v151
	v_mov_b32_e32 v64, v152
	v_mov_b32_e32 v65, v153
	v_mov_b32_e32 v122, v162
	v_mov_b32_e32 v123, v163
	v_mov_b32_e32 v124, v164
	v_mov_b32_e32 v125, v165
	v_mov_b32_e32 v126, v166
	v_mov_b32_e32 v127, v167
	v_mov_b32_e32 v128, v168
	v_mov_b32_e32 v129, v169
	s_cbranch_vccz .LBB0_2869
	s_nop 1
	v_mul_f32_e32 v2, 0x3d000000, v2
	s_waitcnt vmcnt(3)
	v_mul_f32_e32 v19, 0xbfb8aa3b, v2
	v_exp_f32_e32 v19, v19
	v_mul_f32_e32 v3, 0x3d000000, v3
	s_waitcnt vmcnt(2)
	v_mul_f32_e32 v22, 0xbfb8aa3b, v3
	v_exp_f32_e32 v22, v22
	v_add_f32_e32 v19, 1.0, v19
	v_rcp_f32_e32 v19, v19
	v_mul_f32_e32 v10, 0x3d000000, v10
	v_mul_f32_e32 v4, 0x3d000000, v4
	v_mul_f32_e32 v5, 0x3d000000, v5
	v_mul_f32_e32 v2, v2, v19
	v_mul_f32_e32 v2, v10, v2
	v_add_f32_e32 v10, 1.0, v22
	v_rcp_f32_e32 v10, v10
	v_mul_f32_e32 v2, 4.0, v2
	v_med3_f32 v22, v2, s39, v193
	v_mul_f32_e32 v2, 0x3d000000, v11
	v_mul_f32_e32 v3, v3, v10
	v_mul_f32_e32 v10, 0xbfb8aa3b, v4
	v_exp_f32_e32 v10, v10
	v_mul_f32_e32 v2, v2, v3
	v_mul_f32_e32 v2, 4.0, v2
	v_med3_f32 v2, v2, s39, v193
	v_add_f32_e32 v3, 1.0, v10
	v_mul_f32_e32 v10, 0xbfb8aa3b, v5
	v_rcp_f32_e32 v3, v3
	v_exp_f32_e32 v10, v10
	v_mul_f32_e32 v11, 0x3d000000, v12
	v_cvt_pk_fp8_f32 v22, v22, v2
	v_mul_f32_e32 v3, v4, v3
	v_add_f32_e32 v4, 1.0, v10
	v_rcp_f32_e32 v4, v4
	v_mul_f32_e32 v10, 0x3d000000, v13
	v_mul_f32_e32 v3, v11, v3
	v_mul_f32_e32 v3, 4.0, v3
	v_mul_f32_e32 v4, v5, v4
	v_mul_f32_e32 v2, v10, v4
	v_mul_f32_e32 v2, 4.0, v2
	v_med3_f32 v3, v3, s39, v193
	v_med3_f32 v2, v2, s39, v193
	v_mul_f32_e32 v4, 0x3d000000, v6
	v_cvt_pk_fp8_f32 v22, v3, v2 op_sel:[0,0,1]
	v_mul_f32_e32 v2, 0xbfb8aa3b, v4
	v_exp_f32_e32 v5, v2
	v_mul_f32_e32 v6, 0x3d000000, v7
	v_mul_f32_e32 v7, 0xbfb8aa3b, v6
	v_exp_f32_e32 v7, v7
	v_add_f32_e32 v5, 1.0, v5
	v_rcp_f32_e32 v5, v5
	v_mul_f32_e32 v10, 0x3d000000, v14
	v_lshl_or_b32 v18, v185, 4, v191
	v_mov_b64_e32 v[20:21], s[14:15]
	v_mul_f32_e32 v4, v4, v5
	v_add_f32_e32 v5, 1.0, v7
	v_rcp_f32_e32 v5, v5
	v_mul_f32_e32 v7, 0x3d000000, v15
	v_mul_f32_e32 v4, v10, v4
	v_mul_f32_e32 v4, 4.0, v4
	v_mul_f32_e32 v5, v6, v5
	v_mul_f32_e32 v6, 0x3d000000, v8
	v_mul_f32_e32 v8, 0xbfb8aa3b, v6
	v_exp_f32_e32 v8, v8
	v_mul_f32_e32 v5, v7, v5
	v_mul_f32_e32 v5, 4.0, v5
	v_med3_f32 v4, v4, s39, v193
	v_add_f32_e32 v7, 1.0, v8
	v_mul_f32_e32 v8, 0x3d000000, v9
	v_mul_f32_e32 v9, 0xbfb8aa3b, v8
	v_rcp_f32_e32 v7, v7
	v_exp_f32_e32 v9, v9
	v_med3_f32 v5, v5, s39, v193
	v_mul_f32_e32 v10, 0x3d000000, v16
	v_mul_f32_e32 v6, v6, v7
	v_add_f32_e32 v7, 1.0, v9
	v_rcp_f32_e32 v7, v7
	v_mul_f32_e32 v9, 0x3d000000, v17
	v_cvt_pk_fp8_f32 v4, v4, v5
	v_mul_f32_e32 v6, v10, v6
	v_mul_f32_e32 v7, v8, v7
	v_mul_f32_e32 v5, v9, v7
	v_mul_f32_e32 v6, 4.0, v6
	v_mul_f32_e32 v5, 4.0, v5
	v_med3_f32 v6, v6, s39, v193
	v_med3_f32 v5, v5, s39, v193
	v_cvt_pk_fp8_f32 v4, v6, v5 op_sel:[0,0,1]
	v_add_u32_e32 v1, s54, v1
	v_mad_i64_i32 v[20:21], s[26:27], v184, s37, v[20:21]
	v_ashrrev_i32_e32 v19, 31, v18
	v_cmp_lt_i32_e32 vcc, s40, v1
	v_lshl_add_u64 v[2:3], v[20:21], 0, v[18:19]
	s_or_b64 s[22:23], vcc, s[22:23]
	global_store_dword v[2:3], v22, off
	global_store_dword v[2:3], v4, off offset:8
	s_andn2_b64 exec, exec, s[22:23]
	s_cbranch_execnz .LBB0_2864

.LBB0_2878:
	ds_read2_b32 v[2:3], v178 offset1:16
	s_add_u32 s0, s3, s30
	s_addc_u32 s1, s38, s31
	s_add_u32 s0, s0, 0x1b3c3200
	ds_read2_b32 v[168:169], v178 offset0:32 offset1:48
	s_waitcnt lgkmcnt(0)
	v_lshl_add_u32 v161, v2, 10, v1
	v_lshl_add_u32 v163, v3, 10, v176
	ds_read_b128 v[2:5], v179
	ds_read_b128 v[6:9], v184
	ds_read_b128 v[10:13], v185
	ds_read_b128 v[14:17], v186
	s_addc_u32 s1, s1, 0
	s_add_u32 s2, s76, s30
	s_addc_u32 s4, s77, s31
	s_cmpk_eq_i32 s30, 0x300
	s_cselect_b64 vcc, -1, 0
	s_and_b64 s[34:35], vcc, exec
	v_lshl_add_u32 v198, v168, 10, v1
	v_lshl_add_u32 v199, v169, 10, v176
	v_cndmask_b32_e32 v150, v200, v161, vcc
	s_cselect_b32 s37, s17, s1
	s_cselect_b32 s36, s16, s0
	v_cndmask_b32_e32 v172, v158, v163, vcc
	v_cndmask_b32_e32 v201, v160, v198, vcc
	s_cselect_b32 s35, s25, s4
	s_cselect_b32 s34, s75, s2
	v_cndmask_b32_e32 v219, v162, v199, vcc
	v_lshl_add_u64 v[168:169], v[166:167], 0, s[30:31]
	s_add_i32 m0, s42, 0xc000
	ds_read_b128 v[202:205], v196
	ds_read_b128 v[206:209], v196 offset:1024
	ds_read_b128 v[210:213], v196 offset:2048
	ds_read_b128 v[214:217], v196 offset:3072
	ds_read_b128 v[220:223], v196 offset:4096
	ds_read_b128 v[224:227], v196 offset:5120
	ds_read_b128 v[228:231], v196 offset:6144
	ds_read_b128 v[232:235], v196 offset:7168
	global_load_lds_dwordx4 v[168:169], off
	v_lshl_add_u64 v[168:169], v[164:165], 0, s[30:31]
	s_add_i32 m0, s42, 0xe000
	s_nop 0
	global_load_lds_dwordx4 v[168:169], off
	s_waitcnt lgkmcnt(8)
	s_barrier
	s_waitcnt lgkmcnt(0)
	s_setprio 1
	s_waitcnt lgkmcnt(0)
	v_mfma_f32_16x16x128_f8f6f4 v[142:145], v[2:9], v[202:209], v[142:145]
	v_mfma_f32_16x16x128_f8f6f4 v[138:141], v[10:17], v[202:209], v[138:141]
	v_mfma_f32_16x16x128_f8f6f4 v[126:129], v[2:9], v[210:217], v[126:129]
	v_mfma_f32_16x16x128_f8f6f4 v[122:125], v[10:17], v[210:217], v[122:125]
	v_mfma_f32_16x16x128_f8f6f4 v[110:113], v[2:9], v[220:227], v[110:113]
	v_mfma_f32_16x16x128_f8f6f4 v[106:109], v[10:17], v[220:227], v[106:109]
	v_mfma_f32_16x16x128_f8f6f4 v[94:97], v[2:9], v[228:235], v[94:97]
	v_mfma_f32_16x16x128_f8f6f4 v[90:93], v[10:17], v[228:235], v[90:93]
	s_setprio 0
	s_barrier
	s_mov_b32 m0, s43
	v_lshl_add_u64 v[168:169], s[34:35], 0, v[148:149]
	ds_read_b128 v[236:239], v180
	ds_read_b128 v[240:243], v187
	ds_read_b128 v[244:247], v188
	ds_read_b128 v[248:251], v189
	global_load_lds_dwordx4 v[168:169], off
	v_lshl_add_u64 v[170:171], s[34:35], 0, v[146:147]
	s_mov_b32 m0, s44
	s_nop 0
	global_load_lds_dwordx4 v[170:171], off
	s_barrier
	s_waitcnt lgkmcnt(0)
	s_setprio 1
	s_waitcnt lgkmcnt(0)
	v_mfma_f32_16x16x128_f8f6f4 v[134:137], v[236:243], v[202:209], v[134:137]
	v_mfma_f32_16x16x128_f8f6f4 v[130:133], v[244:251], v[202:209], v[130:133]
	v_mfma_f32_16x16x128_f8f6f4 v[118:121], v[236:243], v[210:217], v[118:121]
	v_mfma_f32_16x16x128_f8f6f4 v[114:117], v[244:251], v[210:217], v[114:117]
	v_mfma_f32_16x16x128_f8f6f4 v[102:105], v[236:243], v[220:227], v[102:105]
	v_mfma_f32_16x16x128_f8f6f4 v[98:101], v[244:251], v[220:227], v[98:101]
	v_mfma_f32_16x16x128_f8f6f4 v[86:89], v[236:243], v[228:235], v[86:89]
	v_mfma_f32_16x16x128_f8f6f4 v[82:85], v[244:251], v[228:235], v[82:85]
	s_setprio 0
	s_mov_b32 m0, s42
	s_barrier
	ds_read_b128 v[202:205], v196 offset:16384
	ds_read_b128 v[206:209], v196 offset:17408
	ds_read_b128 v[210:213], v196 offset:18432
	ds_read_b128 v[214:217], v196 offset:19456
	ds_read_b128 v[220:223], v196 offset:20480
	ds_read_b128 v[224:227], v196 offset:21504
	ds_read_b128 v[228:231], v196 offset:22528
	ds_read_b128 v[232:235], v196 offset:23552
	global_load_lds_dwordx4 v150, s[36:37]
	s_mov_b32 m0, s45
	v_mov_b32_e32 v173, v151
	global_load_lds_dwordx4 v172, s[36:37]
	s_barrier
	s_waitcnt lgkmcnt(0)
	v_lshl_add_u64 v[174:175], s[36:37], 0, v[150:151]
	v_lshl_add_u64 v[172:173], s[36:37], 0, v[172:173]
	s_setprio 1
	s_waitcnt lgkmcnt(0)
	v_mfma_f32_16x16x128_f8f6f4 v[78:81], v[2:9], v[202:209], v[78:81]
	v_mfma_f32_16x16x128_f8f6f4 v[74:77], v[10:17], v[202:209], v[74:77]
	v_mfma_f32_16x16x128_f8f6f4 v[62:65], v[2:9], v[210:217], v[62:65]
	v_mfma_f32_16x16x128_f8f6f4 v[58:61], v[10:17], v[210:217], v[58:61]
	v_mfma_f32_16x16x128_f8f6f4 v[46:49], v[2:9], v[220:227], v[46:49]
	v_mfma_f32_16x16x128_f8f6f4 v[42:45], v[10:17], v[220:227], v[42:45]
	v_mfma_f32_16x16x128_f8f6f4 v[30:33], v[2:9], v[228:235], v[30:33]
	v_mfma_f32_16x16x128_f8f6f4 v[26:29], v[10:17], v[228:235], v[26:29]
	s_setprio 0
	s_barrier
	s_add_u32 s66, s34, 0x20000
	s_addc_u32 s67, s35, 0
	s_mov_b32 m0, s46
	v_lshl_add_u64 v[2:3], s[66:67], 0, v[148:149]
	global_load_lds_dwordx4 v[2:3], off
	v_lshl_add_u64 v[2:3], s[66:67], 0, v[146:147]
	s_mov_b32 m0, s47
	s_nop 0
	global_load_lds_dwordx4 v[2:3], off
	s_waitcnt vmcnt(6)
	s_barrier
	s_setprio 1
	v_mfma_f32_16x16x128_f8f6f4 v[70:73], v[236:243], v[202:209], v[70:73]
	v_mfma_f32_16x16x128_f8f6f4 v[66:69], v[244:251], v[202:209], v[66:69]
	v_mfma_f32_16x16x128_f8f6f4 v[54:57], v[236:243], v[210:217], v[54:57]
	v_mfma_f32_16x16x128_f8f6f4 v[50:53], v[244:251], v[210:217], v[50:53]
	v_mfma_f32_16x16x128_f8f6f4 v[38:41], v[236:243], v[220:227], v[38:41]
	v_mfma_f32_16x16x128_f8f6f4 v[34:37], v[244:251], v[220:227], v[34:37]
	v_mfma_f32_16x16x128_f8f6f4 v[22:25], v[236:243], v[228:235], v[22:25]
	v_mfma_f32_16x16x128_f8f6f4 v[18:21], v[244:251], v[228:235], v[18:21]
	s_setprio 0
	s_barrier
	ds_read_b128 v[2:5], v181
	ds_read_b128 v[6:9], v190
	ds_read_b128 v[10:13], v191
	ds_read_b128 v[14:17], v192
	s_mov_b32 m0, s48
	ds_read_b128 v[202:205], v196 offset:32768
	ds_read_b128 v[206:209], v196 offset:33792
	ds_read_b128 v[210:213], v196 offset:34816
	ds_read_b128 v[214:217], v196 offset:35840
	ds_read_b128 v[220:223], v196 offset:36864
	ds_read_b128 v[224:227], v196 offset:37888
	ds_read_b128 v[228:231], v196 offset:38912
	ds_read_b128 v[232:235], v196 offset:39936
	global_load_lds_dwordx4 v201, s[36:37]
	s_mov_b32 m0, s49
	s_nop 0
	global_load_lds_dwordx4 v219, s[36:37]
	s_waitcnt lgkmcnt(8)
	s_barrier
	s_waitcnt lgkmcnt(0)
	s_setprio 1
	s_waitcnt lgkmcnt(0)
	v_mfma_f32_16x16x128_f8f6f4 v[142:145], v[2:9], v[202:209], v[142:145]
	v_mfma_f32_16x16x128_f8f6f4 v[138:141], v[10:17], v[202:209], v[138:141]
	v_mfma_f32_16x16x128_f8f6f4 v[126:129], v[2:9], v[210:217], v[126:129]
	v_mfma_f32_16x16x128_f8f6f4 v[122:125], v[10:17], v[210:217], v[122:125]
	v_mfma_f32_16x16x128_f8f6f4 v[110:113], v[2:9], v[220:227], v[110:113]
	v_mfma_f32_16x16x128_f8f6f4 v[106:109], v[10:17], v[220:227], v[106:109]
	v_mfma_f32_16x16x128_f8f6f4 v[94:97], v[2:9], v[228:235], v[94:97]
	v_mfma_f32_16x16x128_f8f6f4 v[90:93], v[10:17], v[228:235], v[90:93]
	s_setprio 0
	s_barrier
	s_mov_b32 m0, s53
	v_lshl_add_u64 v[168:169], v[168:169], 0, s[20:21]
	ds_read_b128 v[236:239], v182
	ds_read_b128 v[240:243], v193
	ds_read_b128 v[244:247], v194
	ds_read_b128 v[248:251], v195
	global_load_lds_dwordx4 v[168:169], off
	v_lshl_add_u64 v[168:169], v[170:171], 0, s[20:21]
	s_mov_b32 m0, s55
	s_nop 0
	global_load_lds_dwordx4 v[168:169], off
	s_barrier
	s_waitcnt lgkmcnt(0)
	s_setprio 1
	s_waitcnt lgkmcnt(0)
	v_mfma_f32_16x16x128_f8f6f4 v[134:137], v[236:243], v[202:209], v[134:137]
	v_mfma_f32_16x16x128_f8f6f4 v[130:133], v[244:251], v[202:209], v[130:133]
	v_mfma_f32_16x16x128_f8f6f4 v[118:121], v[236:243], v[210:217], v[118:121]
	v_mfma_f32_16x16x128_f8f6f4 v[114:117], v[244:251], v[210:217], v[114:117]
	v_mfma_f32_16x16x128_f8f6f4 v[102:105], v[236:243], v[220:227], v[102:105]
	v_mfma_f32_16x16x128_f8f6f4 v[98:101], v[244:251], v[220:227], v[98:101]
	v_mfma_f32_16x16x128_f8f6f4 v[86:89], v[236:243], v[228:235], v[86:89]
	v_mfma_f32_16x16x128_f8f6f4 v[82:85], v[244:251], v[228:235], v[82:85]
	s_setprio 0
	s_mov_b32 m0, s64
	v_lshl_add_u64 v[168:169], v[174:175], 0, s[20:21]
	s_barrier
	ds_read_b128 v[202:205], v196 offset:49152
	ds_read_b128 v[206:209], v196 offset:50176
	ds_read_b128 v[210:213], v196 offset:51200
	ds_read_b128 v[214:217], v196 offset:52224
	ds_read_b128 v[220:223], v196 offset:53248
	ds_read_b128 v[224:227], v196 offset:54272
	ds_read_b128 v[228:231], v196 offset:55296
	ds_read_b128 v[232:235], v196 offset:56320
	global_load_lds_dwordx4 v[168:169], off
	v_lshl_add_u64 v[168:169], v[172:173], 0, s[20:21]
	s_mov_b32 m0, s65
	s_nop 0
	global_load_lds_dwordx4 v[168:169], off
	s_barrier
	s_waitcnt lgkmcnt(0)
	s_setprio 1
	s_waitcnt lgkmcnt(0)
	v_mfma_f32_16x16x128_f8f6f4 v[78:81], v[2:9], v[202:209], v[78:81]
	v_mfma_f32_16x16x128_f8f6f4 v[74:77], v[10:17], v[202:209], v[74:77]
	v_mfma_f32_16x16x128_f8f6f4 v[62:65], v[2:9], v[210:217], v[62:65]
	v_mfma_f32_16x16x128_f8f6f4 v[58:61], v[10:17], v[210:217], v[58:61]
	v_mfma_f32_16x16x128_f8f6f4 v[46:49], v[2:9], v[220:227], v[46:49]
	v_mfma_f32_16x16x128_f8f6f4 v[42:45], v[10:17], v[220:227], v[42:45]
	v_mfma_f32_16x16x128_f8f6f4 v[30:33], v[2:9], v[228:235], v[30:33]
	v_mfma_f32_16x16x128_f8f6f4 v[26:29], v[10:17], v[228:235], v[26:29]
	s_setprio 0
	s_barrier
	s_add_u32 s34, s34, 0x20080
	s_addc_u32 s35, s35, 0
	s_mov_b32 m0, s68
	v_lshl_add_u64 v[2:3], s[34:35], 0, v[148:149]
	global_load_lds_dwordx4 v[2:3], off
	v_lshl_add_u64 v[2:3], s[34:35], 0, v[146:147]
	s_mov_b32 m0, s69
	s_nop 0
	global_load_lds_dwordx4 v[2:3], off
	s_waitcnt vmcnt(6)
	s_barrier
	s_setprio 1
	v_mfma_f32_16x16x128_f8f6f4 v[70:73], v[236:243], v[202:209], v[70:73]
	v_mfma_f32_16x16x128_f8f6f4 v[66:69], v[244:251], v[202:209], v[66:69]
	v_mfma_f32_16x16x128_f8f6f4 v[54:57], v[236:243], v[210:217], v[54:57]
	v_mfma_f32_16x16x128_f8f6f4 v[50:53], v[244:251], v[210:217], v[50:53]
	v_mfma_f32_16x16x128_f8f6f4 v[38:41], v[236:243], v[220:227], v[38:41]
	v_mfma_f32_16x16x128_f8f6f4 v[34:37], v[244:251], v[220:227], v[34:37]
	v_mfma_f32_16x16x128_f8f6f4 v[22:25], v[236:243], v[228:235], v[22:25]
	v_mfma_f32_16x16x128_f8f6f4 v[18:21], v[244:251], v[228:235], v[18:21]
	s_setprio 0
	s_add_i32 s78, s78, 2
	s_add_u32 s30, s30, 0x100
	s_addc_u32 s31, s31, 0
	s_cmp_gt_u32 s78, 5
	s_barrier
	s_cbranch_scc0 .LBB0_2878
	v_mul_f32_e32 v3, 0x3d000000, v142
	v_mul_f32_e32 v2, 0xbfb8aa3b, v3
	v_exp_f32_e32 v4, v2
	v_mul_f32_e32 v5, 0x3d000000, v143
	v_mul_f32_e32 v7, 0xbfb8aa3b, v5
	v_exp_f32_e32 v7, v7
	v_add_f32_e32 v4, 1.0, v4
	v_rcp_f32_e32 v4, v4
	v_mul_f32_e32 v8, 0x3d000000, v138
	v_mul_f32_e32 v10, 0x3d000000, v140
	v_mul_f32_e32 v12, 0x3d000000, v135
	v_mul_f32_e32 v3, v3, v4
	v_add_f32_e32 v4, 1.0, v7
	v_rcp_f32_e32 v4, v4
	v_mul_f32_e32 v3, v8, v3
	v_mul_f32_e32 v3, 4.0, v3
	v_med3_f32 v7, v3, s71, v197
	v_mul_f32_e32 v4, v5, v4
	v_mul_f32_e32 v5, 0x3d000000, v144
	v_mul_f32_e32 v8, 0xbfb8aa3b, v5
	v_exp_f32_e32 v8, v8
	v_mul_f32_e32 v3, 0x3d000000, v139
	v_mul_f32_e32 v3, v3, v4
	v_mul_f32_e32 v3, 4.0, v3
	v_add_f32_e32 v4, 1.0, v8
	v_mul_f32_e32 v8, 0x3d000000, v145
	v_mul_f32_e32 v9, 0xbfb8aa3b, v8
	v_rcp_f32_e32 v4, v4
	v_exp_f32_e32 v9, v9
	v_med3_f32 v3, v3, s71, v197
	v_cvt_pk_fp8_f32 v7, v7, v3
	v_mul_f32_e32 v4, v5, v4
	v_add_f32_e32 v5, 1.0, v9
	v_rcp_f32_e32 v5, v5
	v_mul_f32_e32 v9, 0x3d000000, v141
	v_mul_f32_e32 v4, v10, v4
	v_mul_f32_e32 v4, 4.0, v4
	v_mul_f32_e32 v5, v8, v5
	v_mul_f32_e32 v3, v9, v5
	v_mul_f32_e32 v3, 4.0, v3
	v_med3_f32 v4, v4, s71, v197
	v_med3_f32 v3, v3, s71, v197
	v_mul_f32_e32 v10, 0x3d000000, v134
	v_cvt_pk_fp8_f32 v7, v4, v3 op_sel:[0,0,1]
	v_mul_f32_e32 v3, 0xbfb8aa3b, v10
	v_exp_f32_e32 v11, v3
	v_mul_f32_e32 v13, 0xbfb8aa3b, v12
	v_exp_f32_e32 v13, v13
	v_mul_f32_e32 v14, 0x3d000000, v130
	v_add_f32_e32 v11, 1.0, v11
	v_rcp_f32_e32 v11, v11
	s_mul_hi_i32 s0, s28, 0x2e8ba2e9
	s_lshr_b32 s1, s0, 31
	s_lshr_b32 s0, s0, 2
	v_mul_f32_e32 v10, v10, v11
	v_add_f32_e32 v11, 1.0, v13
	v_rcp_f32_e32 v11, v11
	v_mul_f32_e32 v10, v14, v10
	v_mul_f32_e32 v13, 0x3d000000, v131
	v_mul_f32_e32 v10, 4.0, v10
	v_mul_f32_e32 v11, v12, v11
	v_mul_f32_e32 v12, 0x3d000000, v136
	v_mul_f32_e32 v14, 0xbfb8aa3b, v12
	v_exp_f32_e32 v14, v14
	v_mul_f32_e32 v11, v13, v11
	v_mul_f32_e32 v11, 4.0, v11
	v_med3_f32 v10, v10, s71, v197
	v_add_f32_e32 v13, 1.0, v14
	v_mul_f32_e32 v14, 0x3d000000, v137
	v_mul_f32_e32 v15, 0xbfb8aa3b, v14
	v_rcp_f32_e32 v13, v13
	v_exp_f32_e32 v15, v15
	v_med3_f32 v11, v11, s71, v197
	v_mul_f32_e32 v16, 0x3d000000, v132
	v_mul_f32_e32 v12, v12, v13
	v_add_f32_e32 v13, 1.0, v15
	v_rcp_f32_e32 v13, v13
	v_mul_f32_e32 v15, 0x3d000000, v133
	v_cvt_pk_fp8_f32 v10, v10, v11
	s_add_i32 s0, s0, s1
	v_mul_f32_e32 v13, v14, v13
	v_mul_f32_e32 v12, v16, v12
	v_mul_f32_e32 v11, v15, v13
	s_mul_i32 s0, s0, 22
	v_mul_f32_e32 v12, 4.0, v12
	v_mul_f32_e32 v11, 4.0, v11
	s_sub_i32 s0, s28, s0
	v_med3_f32 v12, v12, s71, v197
	v_med3_f32 v11, v11, s71, v197
	v_lshl_add_u32 v6, s74, 8, v159
	v_lshl_or_b32 v2, s0, 7, v183
	v_mov_b64_e32 v[4:5], s[14:15]
	v_cvt_pk_fp8_f32 v10, v12, v11 op_sel:[0,0,1]
	v_mad_i64_i32 v[8:9], s[30:31], v6, s72, v[4:5]
	v_ashrrev_i32_e32 v3, 31, v2
	v_lshl_add_u64 v[8:9], v[8:9], 0, v[2:3]
	s_nop 15
	s_nop 15
	v_mul_f32_e32 v11, 0x3d000000, v126
	global_store_dword v[8:9], v7, off
	global_store_dword v[8:9], v10, off offset:64
	v_mul_f32_e32 v9, 0x3d000000, v127
	v_mul_f32_e32 v12, 0xbfb8aa3b, v11
	v_mul_f32_e32 v10, 0xbfb8aa3b, v9
	v_exp_f32_e32 v12, v12
	v_exp_f32_e32 v10, v10
	v_mul_f32_e32 v14, 0x3d000000, v124
	v_or_b32_e32 v7, 16, v6
	v_add_f32_e32 v8, 1.0, v12
	v_add_f32_e32 v10, 1.0, v10
	v_rcp_f32_e32 v8, v8
	v_rcp_f32_e32 v10, v10
	v_mul_f32_e32 v12, 0x3d000000, v122
	v_mul_f32_e32 v16, 0x3d000000, v116
	v_mul_f32_e32 v8, v11, v8
	v_mul_f32_e32 v9, v9, v10
	v_mul_f32_e32 v10, 0x3d000000, v128
	v_mul_f32_e32 v8, v12, v8
	v_mul_f32_e32 v12, 0xbfb8aa3b, v10
	v_exp_f32_e32 v12, v12
	v_mul_f32_e32 v8, 4.0, v8
	v_med3_f32 v11, v8, s71, v197
	v_mul_f32_e32 v8, 0x3d000000, v123
	v_mul_f32_e32 v8, v8, v9
	v_add_f32_e32 v9, 1.0, v12
	v_mul_f32_e32 v12, 0x3d000000, v129
	v_mul_f32_e32 v13, 0xbfb8aa3b, v12
	v_rcp_f32_e32 v9, v9
	v_exp_f32_e32 v13, v13
	v_mul_f32_e32 v8, 4.0, v8
	v_med3_f32 v8, v8, s71, v197
	v_mul_f32_e32 v9, v10, v9
	v_add_f32_e32 v10, 1.0, v13
	v_rcp_f32_e32 v10, v10
	v_mul_f32_e32 v13, 0x3d000000, v125
	v_cvt_pk_fp8_f32 v11, v11, v8
	v_mul_f32_e32 v9, v14, v9
	v_mul_f32_e32 v10, v12, v10
	v_mul_f32_e32 v8, v13, v10
	v_mul_f32_e32 v9, 4.0, v9
	v_mul_f32_e32 v8, 4.0, v8
	v_med3_f32 v9, v9, s71, v197
	v_med3_f32 v8, v8, s71, v197
	v_mul_f32_e32 v10, 0x3d000000, v118
	v_cvt_pk_fp8_f32 v11, v9, v8 op_sel:[0,0,1]
	v_mul_f32_e32 v8, 0xbfb8aa3b, v10
	v_exp_f32_e32 v12, v8
	v_mad_i64_i32 v[8:9], s[30:31], v7, s72, v[4:5]
	v_mul_f32_e32 v14, 0x3d000000, v114
	v_add_f32_e32 v7, 1.0, v12
	v_mul_f32_e32 v12, 0x3d000000, v119
	v_mul_f32_e32 v13, 0xbfb8aa3b, v12
	v_rcp_f32_e32 v7, v7
	v_exp_f32_e32 v13, v13
	v_lshl_add_u64 v[8:9], v[8:9], 0, v[2:3]
	s_and_b64 vcc, exec, s[12:13]
	v_mul_f32_e32 v7, v10, v7
	v_add_f32_e32 v10, 1.0, v13
	v_rcp_f32_e32 v10, v10
	v_mul_f32_e32 v7, v14, v7
	v_mul_f32_e32 v13, 0x3d000000, v115
	v_mul_f32_e32 v7, 4.0, v7
	v_mul_f32_e32 v10, v12, v10
	v_mul_f32_e32 v12, 0x3d000000, v120
	v_mul_f32_e32 v14, 0xbfb8aa3b, v12
	v_exp_f32_e32 v14, v14
	v_mul_f32_e32 v10, v13, v10
	v_mul_f32_e32 v10, 4.0, v10
	v_med3_f32 v7, v7, s71, v197
	v_add_f32_e32 v13, 1.0, v14
	v_mul_f32_e32 v14, 0x3d000000, v121
	v_mul_f32_e32 v15, 0xbfb8aa3b, v14
	v_rcp_f32_e32 v13, v13
	v_exp_f32_e32 v15, v15
	v_med3_f32 v10, v10, s71, v197
	v_cvt_pk_fp8_f32 v7, v7, v10
	v_mul_f32_e32 v12, v12, v13
	v_add_f32_e32 v13, 1.0, v15
	v_rcp_f32_e32 v13, v13
	v_mul_f32_e32 v15, 0x3d000000, v117
	v_mul_f32_e32 v12, v16, v12
	v_mul_f32_e32 v12, 4.0, v12
	v_mul_f32_e32 v13, v14, v13
	v_mul_f32_e32 v10, v15, v13
	v_mul_f32_e32 v10, 4.0, v10
	v_med3_f32 v12, v12, s71, v197
	v_med3_f32 v10, v10, s71, v197
	v_cvt_pk_fp8_f32 v7, v12, v10 op_sel:[0,0,1]
	v_mul_f32_e32 v10, 0x3d000000, v110
	v_mul_f32_e32 v12, 0xbfb8aa3b, v10
	v_exp_f32_e32 v12, v12
	global_store_dword v[8:9], v11, off
	global_store_dword v[8:9], v7, off offset:64
	v_mul_f32_e32 v9, 0x3d000000, v111
	v_mul_f32_e32 v11, 0xbfb8aa3b, v9
	v_add_f32_e32 v8, 1.0, v12
	v_rcp_f32_e32 v8, v8
	v_exp_f32_e32 v11, v11
	v_mul_f32_e32 v12, 0x3d000000, v106
	v_mul_f32_e32 v14, 0x3d000000, v108
	v_mul_f32_e32 v8, v10, v8
	v_add_f32_e32 v10, 1.0, v11
	v_rcp_f32_e32 v10, v10
	v_mul_f32_e32 v8, v12, v8
	v_mul_f32_e32 v8, 4.0, v8
	v_med3_f32 v11, v8, s71, v197
	v_mul_f32_e32 v9, v9, v10
	v_mul_f32_e32 v10, 0x3d000000, v112
	v_mul_f32_e32 v12, 0xbfb8aa3b, v10
	v_exp_f32_e32 v12, v12
	v_mul_f32_e32 v8, 0x3d000000, v107
	v_mul_f32_e32 v8, v8, v9
	v_mul_f32_e32 v8, 4.0, v8
	v_add_f32_e32 v9, 1.0, v12
	v_mul_f32_e32 v12, 0x3d000000, v113
	v_mul_f32_e32 v13, 0xbfb8aa3b, v12
	v_rcp_f32_e32 v9, v9
	v_exp_f32_e32 v13, v13
	v_med3_f32 v8, v8, s71, v197
	v_cvt_pk_fp8_f32 v11, v11, v8
	v_mul_f32_e32 v9, v10, v9
	v_add_f32_e32 v10, 1.0, v13
	v_rcp_f32_e32 v10, v10
	v_mul_f32_e32 v13, 0x3d000000, v109
	v_mul_f32_e32 v9, v14, v9
	v_mul_f32_e32 v9, 4.0, v9
	v_mul_f32_e32 v10, v12, v10
	v_mul_f32_e32 v8, v13, v10
	v_mul_f32_e32 v8, 4.0, v8
	v_med3_f32 v9, v9, s71, v197
	v_med3_f32 v8, v8, s71, v197
	v_mul_f32_e32 v10, 0x3d000000, v102
	v_cvt_pk_fp8_f32 v11, v9, v8 op_sel:[0,0,1]
	v_mul_f32_e32 v8, 0xbfb8aa3b, v10
	v_exp_f32_e32 v12, v8
	v_or_b32_e32 v7, 32, v6
	v_mad_i64_i32 v[8:9], s[30:31], v7, s72, v[4:5]
	v_add_f32_e32 v7, 1.0, v12
	v_mul_f32_e32 v12, 0x3d000000, v103
	v_mul_f32_e32 v13, 0xbfb8aa3b, v12
	v_rcp_f32_e32 v7, v7
	v_exp_f32_e32 v13, v13
	v_mul_f32_e32 v14, 0x3d000000, v98
	v_mul_f32_e32 v16, 0x3d000000, v100
	v_mul_f32_e32 v7, v10, v7
	v_add_f32_e32 v10, 1.0, v13
	v_rcp_f32_e32 v10, v10
	v_mul_f32_e32 v7, v14, v7
	v_mul_f32_e32 v13, 0x3d000000, v99
	v_mul_f32_e32 v7, 4.0, v7
	v_mul_f32_e32 v10, v12, v10
	v_mul_f32_e32 v12, 0x3d000000, v104
	v_mul_f32_e32 v14, 0xbfb8aa3b, v12
	v_exp_f32_e32 v14, v14
	v_mul_f32_e32 v10, v13, v10
	v_mul_f32_e32 v10, 4.0, v10
	v_med3_f32 v7, v7, s71, v197
	v_add_f32_e32 v13, 1.0, v14
	v_mul_f32_e32 v14, 0x3d000000, v105
	v_mul_f32_e32 v15, 0xbfb8aa3b, v14
	v_rcp_f32_e32 v13, v13
	v_exp_f32_e32 v15, v15
	v_med3_f32 v10, v10, s71, v197
	v_cvt_pk_fp8_f32 v7, v7, v10
	v_mul_f32_e32 v12, v12, v13
	v_add_f32_e32 v13, 1.0, v15
	v_rcp_f32_e32 v13, v13
	v_mul_f32_e32 v15, 0x3d000000, v101
	v_mul_f32_e32 v12, v16, v12
	v_mul_f32_e32 v12, 4.0, v12
	v_mul_f32_e32 v13, v14, v13
	v_mul_f32_e32 v10, v15, v13
	v_mul_f32_e32 v10, 4.0, v10
	v_med3_f32 v12, v12, s71, v197
	v_med3_f32 v10, v10, s71, v197
	v_cvt_pk_fp8_f32 v7, v12, v10 op_sel:[0,0,1]
	v_mul_f32_e32 v10, 0x3d000000, v94
	v_mul_f32_e32 v12, 0xbfb8aa3b, v10
	v_exp_f32_e32 v12, v12
	v_lshl_add_u64 v[8:9], v[8:9], 0, v[2:3]
	global_store_dword v[8:9], v11, off
	global_store_dword v[8:9], v7, off offset:64
	v_mul_f32_e32 v9, 0x3d000000, v95
	v_add_f32_e32 v8, 1.0, v12
	v_mul_f32_e32 v11, 0xbfb8aa3b, v9
	v_rcp_f32_e32 v8, v8
	v_exp_f32_e32 v11, v11
	v_mul_f32_e32 v12, 0x3d000000, v90
	v_mul_f32_e32 v14, 0x3d000000, v92
	v_mul_f32_e32 v8, v10, v8
	v_add_f32_e32 v10, 1.0, v11
	v_rcp_f32_e32 v10, v10
	v_mul_f32_e32 v8, v12, v8
	v_mul_f32_e32 v8, 4.0, v8
	v_med3_f32 v11, v8, s71, v197
	v_mul_f32_e32 v9, v9, v10
	v_mul_f32_e32 v10, 0x3d000000, v96
	v_mul_f32_e32 v12, 0xbfb8aa3b, v10
	v_exp_f32_e32 v12, v12
	v_mul_f32_e32 v8, 0x3d000000, v91
	v_mul_f32_e32 v8, v8, v9
	v_mul_f32_e32 v8, 4.0, v8
	v_add_f32_e32 v9, 1.0, v12
	v_mul_f32_e32 v12, 0x3d000000, v97
	v_mul_f32_e32 v13, 0xbfb8aa3b, v12
	v_rcp_f32_e32 v9, v9
	v_exp_f32_e32 v13, v13
	v_med3_f32 v8, v8, s71, v197
	v_cvt_pk_fp8_f32 v11, v11, v8
	v_mul_f32_e32 v9, v10, v9
	v_add_f32_e32 v10, 1.0, v13
	v_rcp_f32_e32 v10, v10
	v_mul_f32_e32 v13, 0x3d000000, v93
	v_mul_f32_e32 v9, v14, v9
	v_mul_f32_e32 v9, 4.0, v9
	v_mul_f32_e32 v10, v12, v10
	v_mul_f32_e32 v8, v13, v10
	v_mul_f32_e32 v8, 4.0, v8
	v_med3_f32 v9, v9, s71, v197
	v_med3_f32 v8, v8, s71, v197
	v_mul_f32_e32 v10, 0x3d000000, v86
	v_cvt_pk_fp8_f32 v11, v9, v8 op_sel:[0,0,1]
	v_mul_f32_e32 v8, 0xbfb8aa3b, v10
	v_exp_f32_e32 v12, v8
	v_or_b32_e32 v7, 48, v6
	v_mad_i64_i32 v[8:9], s[30:31], v7, s72, v[4:5]
	v_add_f32_e32 v7, 1.0, v12
	v_mul_f32_e32 v12, 0x3d000000, v87
	v_mul_f32_e32 v13, 0xbfb8aa3b, v12
	v_rcp_f32_e32 v7, v7
	v_exp_f32_e32 v13, v13
	v_mul_f32_e32 v14, 0x3d000000, v82
	v_mul_f32_e32 v16, 0x3d000000, v84
	v_mul_f32_e32 v7, v10, v7
	v_add_f32_e32 v10, 1.0, v13
	v_rcp_f32_e32 v10, v10
	v_mul_f32_e32 v7, v14, v7
	v_mul_f32_e32 v13, 0x3d000000, v83
	v_mul_f32_e32 v7, 4.0, v7
	v_mul_f32_e32 v10, v12, v10
	v_mul_f32_e32 v12, 0x3d000000, v88
	v_mul_f32_e32 v14, 0xbfb8aa3b, v12
	v_exp_f32_e32 v14, v14
	v_mul_f32_e32 v10, v13, v10
	v_mul_f32_e32 v10, 4.0, v10
	v_med3_f32 v7, v7, s71, v197
	v_add_f32_e32 v13, 1.0, v14
	v_mul_f32_e32 v14, 0x3d000000, v89
	v_mul_f32_e32 v15, 0xbfb8aa3b, v14
	v_rcp_f32_e32 v13, v13
	v_exp_f32_e32 v15, v15
	v_med3_f32 v10, v10, s71, v197
	v_cvt_pk_fp8_f32 v7, v7, v10
	v_mul_f32_e32 v12, v12, v13
	v_add_f32_e32 v13, 1.0, v15
	v_rcp_f32_e32 v13, v13
	v_mul_f32_e32 v15, 0x3d000000, v85
	v_mul_f32_e32 v12, v16, v12
	v_mul_f32_e32 v12, 4.0, v12
	v_mul_f32_e32 v13, v14, v13
	v_mul_f32_e32 v10, v15, v13
	v_mul_f32_e32 v10, 4.0, v10
	v_med3_f32 v12, v12, s71, v197
	v_med3_f32 v10, v10, s71, v197
	v_cvt_pk_fp8_f32 v7, v12, v10 op_sel:[0,0,1]
	v_mul_f32_e32 v10, 0x3d000000, v78
	v_mul_f32_e32 v12, 0xbfb8aa3b, v10
	v_exp_f32_e32 v12, v12
	v_lshl_add_u64 v[8:9], v[8:9], 0, v[2:3]
	global_store_dword v[8:9], v11, off
	global_store_dword v[8:9], v7, off offset:64
	v_mul_f32_e32 v9, 0x3d000000, v79
	v_add_f32_e32 v8, 1.0, v12
	v_mul_f32_e32 v11, 0xbfb8aa3b, v9
	v_rcp_f32_e32 v8, v8
	v_exp_f32_e32 v11, v11
	v_mul_f32_e32 v12, 0x3d000000, v74
	v_mul_f32_e32 v14, 0x3d000000, v76
	v_mul_f32_e32 v8, v10, v8
	v_add_f32_e32 v10, 1.0, v11
	v_rcp_f32_e32 v10, v10
	v_mul_f32_e32 v8, v12, v8
	v_mul_f32_e32 v8, 4.0, v8
	v_med3_f32 v11, v8, s71, v197
	v_mul_f32_e32 v9, v9, v10
	v_mul_f32_e32 v10, 0x3d000000, v80
	v_mul_f32_e32 v12, 0xbfb8aa3b, v10
	v_exp_f32_e32 v12, v12
	v_mul_f32_e32 v8, 0x3d000000, v75
	v_mul_f32_e32 v8, v8, v9
	v_mul_f32_e32 v8, 4.0, v8
	v_add_f32_e32 v9, 1.0, v12
	v_mul_f32_e32 v12, 0x3d000000, v81
	v_mul_f32_e32 v13, 0xbfb8aa3b, v12
	v_rcp_f32_e32 v9, v9
	v_exp_f32_e32 v13, v13
	v_med3_f32 v8, v8, s71, v197
	v_cvt_pk_fp8_f32 v11, v11, v8
	v_mul_f32_e32 v9, v10, v9
	v_add_f32_e32 v10, 1.0, v13
	v_rcp_f32_e32 v10, v10
	v_mul_f32_e32 v13, 0x3d000000, v77
	v_mul_f32_e32 v9, v14, v9
	v_mul_f32_e32 v9, 4.0, v9
	v_mul_f32_e32 v10, v12, v10
	v_mul_f32_e32 v8, v13, v10
	v_mul_f32_e32 v8, 4.0, v8
	v_med3_f32 v9, v9, s71, v197
	v_med3_f32 v8, v8, s71, v197
	v_mul_f32_e32 v10, 0x3d000000, v70
	v_cvt_pk_fp8_f32 v11, v9, v8 op_sel:[0,0,1]
	v_mul_f32_e32 v8, 0xbfb8aa3b, v10
	v_exp_f32_e32 v12, v8
	v_add_u32_e32 v7, 0x80, v6
	v_mad_i64_i32 v[8:9], s[30:31], v7, s72, v[4:5]
	v_add_f32_e32 v7, 1.0, v12
	v_mul_f32_e32 v12, 0x3d000000, v71
	v_mul_f32_e32 v13, 0xbfb8aa3b, v12
	v_rcp_f32_e32 v7, v7
	v_exp_f32_e32 v13, v13
	v_mul_f32_e32 v14, 0x3d000000, v66
	v_mul_f32_e32 v16, 0x3d000000, v68
	v_mul_f32_e32 v7, v10, v7
	v_add_f32_e32 v10, 1.0, v13
	v_rcp_f32_e32 v10, v10
	v_mul_f32_e32 v7, v14, v7
	v_mul_f32_e32 v13, 0x3d000000, v67
	v_mul_f32_e32 v7, 4.0, v7
	v_mul_f32_e32 v10, v12, v10
	v_mul_f32_e32 v12, 0x3d000000, v72
	v_mul_f32_e32 v14, 0xbfb8aa3b, v12
	v_exp_f32_e32 v14, v14
	v_mul_f32_e32 v10, v13, v10
	v_mul_f32_e32 v10, 4.0, v10
	v_med3_f32 v7, v7, s71, v197
	v_add_f32_e32 v13, 1.0, v14
	v_mul_f32_e32 v14, 0x3d000000, v73
	v_mul_f32_e32 v15, 0xbfb8aa3b, v14
	v_rcp_f32_e32 v13, v13
	v_exp_f32_e32 v15, v15
	v_med3_f32 v10, v10, s71, v197
	v_cvt_pk_fp8_f32 v7, v7, v10
	v_mul_f32_e32 v12, v12, v13
	v_add_f32_e32 v13, 1.0, v15
	v_rcp_f32_e32 v13, v13
	v_mul_f32_e32 v15, 0x3d000000, v69
	v_mul_f32_e32 v12, v16, v12
	v_mul_f32_e32 v12, 4.0, v12
	v_mul_f32_e32 v13, v14, v13
	v_mul_f32_e32 v10, v15, v13
	v_mul_f32_e32 v10, 4.0, v10
	v_med3_f32 v12, v12, s71, v197
	v_med3_f32 v10, v10, s71, v197
	v_cvt_pk_fp8_f32 v7, v12, v10 op_sel:[0,0,1]
	v_mul_f32_e32 v10, 0x3d000000, v62
	v_mul_f32_e32 v12, 0xbfb8aa3b, v10
	v_exp_f32_e32 v12, v12
	v_lshl_add_u64 v[8:9], v[8:9], 0, v[2:3]
	global_store_dword v[8:9], v11, off
	global_store_dword v[8:9], v7, off offset:64
	v_mul_f32_e32 v9, 0x3d000000, v63
	v_add_f32_e32 v8, 1.0, v12
	v_mul_f32_e32 v11, 0xbfb8aa3b, v9
	v_rcp_f32_e32 v8, v8
	v_exp_f32_e32 v11, v11
	v_mul_f32_e32 v12, 0x3d000000, v58
	v_mul_f32_e32 v14, 0x3d000000, v60
	v_mul_f32_e32 v8, v10, v8
	v_add_f32_e32 v10, 1.0, v11
	v_rcp_f32_e32 v10, v10
	v_mul_f32_e32 v8, v12, v8
	v_mul_f32_e32 v8, 4.0, v8
	v_med3_f32 v11, v8, s71, v197
	v_mul_f32_e32 v9, v9, v10
	v_mul_f32_e32 v10, 0x3d000000, v64
	v_mul_f32_e32 v12, 0xbfb8aa3b, v10
	v_exp_f32_e32 v12, v12
	v_mul_f32_e32 v8, 0x3d000000, v59
	v_mul_f32_e32 v8, v8, v9
	v_mul_f32_e32 v8, 4.0, v8
	v_add_f32_e32 v9, 1.0, v12
	v_mul_f32_e32 v12, 0x3d000000, v65
	v_mul_f32_e32 v13, 0xbfb8aa3b, v12
	v_rcp_f32_e32 v9, v9
	v_exp_f32_e32 v13, v13
	v_med3_f32 v8, v8, s71, v197
	v_cvt_pk_fp8_f32 v11, v11, v8
	v_mul_f32_e32 v9, v10, v9
	v_add_f32_e32 v10, 1.0, v13
	v_rcp_f32_e32 v10, v10
	v_mul_f32_e32 v13, 0x3d000000, v61
	v_mul_f32_e32 v9, v14, v9
	v_mul_f32_e32 v9, 4.0, v9
	v_mul_f32_e32 v10, v12, v10
	v_mul_f32_e32 v8, v13, v10
	v_mul_f32_e32 v8, 4.0, v8
	v_med3_f32 v9, v9, s71, v197
	v_med3_f32 v8, v8, s71, v197
	v_mul_f32_e32 v10, 0x3d000000, v54
	v_cvt_pk_fp8_f32 v11, v9, v8 op_sel:[0,0,1]
	v_mul_f32_e32 v8, 0xbfb8aa3b, v10
	v_exp_f32_e32 v12, v8
	v_add_u32_e32 v7, 0x90, v6
	v_mad_i64_i32 v[8:9], s[30:31], v7, s72, v[4:5]
	v_add_f32_e32 v7, 1.0, v12
	v_mul_f32_e32 v12, 0x3d000000, v55
	v_mul_f32_e32 v13, 0xbfb8aa3b, v12
	v_rcp_f32_e32 v7, v7
	v_exp_f32_e32 v13, v13
	v_mul_f32_e32 v14, 0x3d000000, v50
	v_mul_f32_e32 v16, 0x3d000000, v52
	v_mul_f32_e32 v7, v10, v7
	v_add_f32_e32 v10, 1.0, v13
	v_rcp_f32_e32 v10, v10
	v_mul_f32_e32 v7, v14, v7
	v_mul_f32_e32 v13, 0x3d000000, v51
	v_mul_f32_e32 v7, 4.0, v7
	v_mul_f32_e32 v10, v12, v10
	v_mul_f32_e32 v12, 0x3d000000, v56
	v_mul_f32_e32 v14, 0xbfb8aa3b, v12
	v_exp_f32_e32 v14, v14
	v_mul_f32_e32 v10, v13, v10
	v_mul_f32_e32 v10, 4.0, v10
	v_med3_f32 v7, v7, s71, v197
	v_add_f32_e32 v13, 1.0, v14
	v_mul_f32_e32 v14, 0x3d000000, v57
	v_mul_f32_e32 v15, 0xbfb8aa3b, v14
	v_rcp_f32_e32 v13, v13
	v_exp_f32_e32 v15, v15
	v_med3_f32 v10, v10, s71, v197
	v_cvt_pk_fp8_f32 v7, v7, v10
	v_mul_f32_e32 v12, v12, v13
	v_add_f32_e32 v13, 1.0, v15
	v_rcp_f32_e32 v13, v13
	v_mul_f32_e32 v15, 0x3d000000, v53
	v_mul_f32_e32 v12, v16, v12
	v_mul_f32_e32 v12, 4.0, v12
	v_mul_f32_e32 v13, v14, v13
	v_mul_f32_e32 v10, v15, v13
	v_mul_f32_e32 v10, 4.0, v10
	v_med3_f32 v12, v12, s71, v197
	v_med3_f32 v10, v10, s71, v197
	v_cvt_pk_fp8_f32 v7, v12, v10 op_sel:[0,0,1]
	v_mul_f32_e32 v10, 0x3d000000, v46
	v_mul_f32_e32 v12, 0xbfb8aa3b, v10
	v_exp_f32_e32 v12, v12
	v_lshl_add_u64 v[8:9], v[8:9], 0, v[2:3]
	global_store_dword v[8:9], v11, off
	global_store_dword v[8:9], v7, off offset:64
	v_mul_f32_e32 v9, 0x3d000000, v47
	v_add_f32_e32 v8, 1.0, v12
	v_mul_f32_e32 v11, 0xbfb8aa3b, v9
	v_rcp_f32_e32 v8, v8
	v_exp_f32_e32 v11, v11
	v_mul_f32_e32 v12, 0x3d000000, v42
	v_mul_f32_e32 v14, 0x3d000000, v44
	v_mul_f32_e32 v8, v10, v8
	v_add_f32_e32 v10, 1.0, v11
	v_rcp_f32_e32 v10, v10
	v_mul_f32_e32 v8, v12, v8
	v_mul_f32_e32 v8, 4.0, v8
	v_med3_f32 v11, v8, s71, v197
	v_mul_f32_e32 v9, v9, v10
	v_mul_f32_e32 v10, 0x3d000000, v48
	v_mul_f32_e32 v12, 0xbfb8aa3b, v10
	v_exp_f32_e32 v12, v12
	v_mul_f32_e32 v8, 0x3d000000, v43
	v_mul_f32_e32 v8, v8, v9
	v_mul_f32_e32 v8, 4.0, v8
	v_add_f32_e32 v9, 1.0, v12
	v_mul_f32_e32 v12, 0x3d000000, v49
	v_mul_f32_e32 v13, 0xbfb8aa3b, v12
	v_rcp_f32_e32 v9, v9
	v_exp_f32_e32 v13, v13
	v_med3_f32 v8, v8, s71, v197
	v_cvt_pk_fp8_f32 v11, v11, v8
	v_mul_f32_e32 v9, v10, v9
	v_add_f32_e32 v10, 1.0, v13
	v_rcp_f32_e32 v10, v10
	v_mul_f32_e32 v13, 0x3d000000, v45
	v_mul_f32_e32 v9, v14, v9
	v_mul_f32_e32 v9, 4.0, v9
	v_mul_f32_e32 v10, v12, v10
	v_mul_f32_e32 v8, v13, v10
	v_mul_f32_e32 v8, 4.0, v8
	v_med3_f32 v9, v9, s71, v197
	v_med3_f32 v8, v8, s71, v197
	v_mul_f32_e32 v10, 0x3d000000, v38
	v_cvt_pk_fp8_f32 v11, v9, v8 op_sel:[0,0,1]
	v_mul_f32_e32 v8, 0xbfb8aa3b, v10
	v_exp_f32_e32 v12, v8
	v_add_u32_e32 v7, 0xa0, v6
	v_mad_i64_i32 v[8:9], s[30:31], v7, s72, v[4:5]
	v_add_f32_e32 v7, 1.0, v12
	v_mul_f32_e32 v12, 0x3d000000, v39
	v_mul_f32_e32 v13, 0xbfb8aa3b, v12
	v_rcp_f32_e32 v7, v7
	v_exp_f32_e32 v13, v13
	v_mul_f32_e32 v14, 0x3d000000, v34
	v_mul_f32_e32 v16, 0x3d000000, v36
	v_mul_f32_e32 v7, v10, v7
	v_add_f32_e32 v10, 1.0, v13
	v_rcp_f32_e32 v10, v10
	v_mul_f32_e32 v7, v14, v7
	v_mul_f32_e32 v13, 0x3d000000, v35
	v_mul_f32_e32 v7, 4.0, v7
	v_mul_f32_e32 v10, v12, v10
	v_mul_f32_e32 v12, 0x3d000000, v40
	v_mul_f32_e32 v14, 0xbfb8aa3b, v12
	v_exp_f32_e32 v14, v14
	v_mul_f32_e32 v10, v13, v10
	v_mul_f32_e32 v10, 4.0, v10
	v_med3_f32 v7, v7, s71, v197
	v_add_f32_e32 v13, 1.0, v14
	v_mul_f32_e32 v14, 0x3d000000, v41
	v_mul_f32_e32 v15, 0xbfb8aa3b, v14
	v_rcp_f32_e32 v13, v13
	v_exp_f32_e32 v15, v15
	v_med3_f32 v10, v10, s71, v197
	v_cvt_pk_fp8_f32 v7, v7, v10
	v_mul_f32_e32 v12, v12, v13
	v_add_f32_e32 v13, 1.0, v15
	v_rcp_f32_e32 v13, v13
	v_mul_f32_e32 v15, 0x3d000000, v37
	v_mul_f32_e32 v12, v16, v12
	v_mul_f32_e32 v12, 4.0, v12
	v_mul_f32_e32 v13, v14, v13
	v_mul_f32_e32 v10, v15, v13
	v_mul_f32_e32 v10, 4.0, v10
	v_med3_f32 v12, v12, s71, v197
	v_med3_f32 v10, v10, s71, v197
	v_cvt_pk_fp8_f32 v7, v12, v10 op_sel:[0,0,1]
	v_lshl_add_u64 v[8:9], v[8:9], 0, v[2:3]
	v_mul_f32_e32 v10, 0x3d000000, v30
	global_store_dword v[8:9], v11, off
	global_store_dword v[8:9], v7, off offset:64
	v_mul_f32_e32 v8, 0x3d000000, v31
	v_mul_f32_e32 v12, 0xbfb8aa3b, v10
	v_mul_f32_e32 v9, 0xbfb8aa3b, v8
	v_exp_f32_e32 v12, v12
	v_exp_f32_e32 v9, v9
	v_mul_f32_e32 v11, 0x3d000000, v26
	v_mul_f32_e32 v13, 0x3d000000, v28
	v_add_f32_e32 v7, 1.0, v12
	v_add_f32_e32 v9, 1.0, v9
	v_rcp_f32_e32 v7, v7
	v_rcp_f32_e32 v9, v9
	v_mul_f32_e32 v14, 0x3d000000, v20
	v_add_u32_e32 v6, 0xb0, v6
	v_mul_f32_e32 v7, v10, v7
	v_mul_f32_e32 v8, v8, v9
	v_mul_f32_e32 v9, 0x3d000000, v32
	v_mul_f32_e32 v7, v11, v7
	v_mul_f32_e32 v11, 0xbfb8aa3b, v9
	v_exp_f32_e32 v11, v11
	v_mul_f32_e32 v10, 0x3d000000, v27
	v_mul_f32_e32 v8, v10, v8
	v_mul_f32_e32 v7, 4.0, v7
	v_add_f32_e32 v10, 1.0, v11
	v_mul_f32_e32 v11, 0x3d000000, v33
	v_mul_f32_e32 v12, 0xbfb8aa3b, v11
	v_rcp_f32_e32 v10, v10
	v_exp_f32_e32 v12, v12
	v_mul_f32_e32 v8, 4.0, v8
	v_med3_f32 v7, v7, s71, v197
	v_mul_f32_e32 v9, v9, v10
	v_add_f32_e32 v10, 1.0, v12
	v_rcp_f32_e32 v10, v10
	v_med3_f32 v8, v8, s71, v197
	v_cvt_pk_fp8_f32 v7, v7, v8
	v_mul_f32_e32 v8, 0x3d000000, v22
	v_mul_f32_e32 v12, 0x3d000000, v29
	v_mul_f32_e32 v10, v11, v10
	v_mul_f32_e32 v11, 0xbfb8aa3b, v8
	v_mul_f32_e32 v9, v13, v9
	v_mul_f32_e32 v10, v12, v10
	v_exp_f32_e32 v11, v11
	v_mul_f32_e32 v9, 4.0, v9
	v_mul_f32_e32 v10, 4.0, v10
	v_med3_f32 v9, v9, s71, v197
	v_med3_f32 v10, v10, s71, v197
	v_cvt_pk_fp8_f32 v7, v9, v10 op_sel:[0,0,1]
	v_mul_f32_e32 v10, 0x3d000000, v23
	v_add_f32_e32 v9, 1.0, v11
	v_mul_f32_e32 v11, 0xbfb8aa3b, v10
	v_rcp_f32_e32 v9, v9
	v_exp_f32_e32 v11, v11
	v_mul_f32_e32 v12, 0x3d000000, v18
	v_mad_i64_i32 v[4:5], s[30:31], v6, s72, v[4:5]
	v_mul_f32_e32 v8, v8, v9
	v_add_f32_e32 v9, 1.0, v11
	v_rcp_f32_e32 v9, v9
	v_mul_f32_e32 v8, v12, v8
	v_mul_f32_e32 v11, 0x3d000000, v19
	v_mul_f32_e32 v8, 4.0, v8
	v_mul_f32_e32 v9, v10, v9
	v_mul_f32_e32 v10, 0x3d000000, v24
	v_mul_f32_e32 v12, 0xbfb8aa3b, v10
	v_exp_f32_e32 v12, v12
	v_mul_f32_e32 v9, v11, v9
	v_mul_f32_e32 v9, 4.0, v9
	v_med3_f32 v8, v8, s71, v197
	v_add_f32_e32 v11, 1.0, v12
	v_mul_f32_e32 v12, 0x3d000000, v25
	v_mul_f32_e32 v13, 0xbfb8aa3b, v12
	v_rcp_f32_e32 v11, v11
	v_exp_f32_e32 v13, v13
	v_med3_f32 v9, v9, s71, v197
	v_cvt_pk_fp8_f32 v8, v8, v9
	v_mul_f32_e32 v10, v10, v11
	v_add_f32_e32 v11, 1.0, v13
	v_rcp_f32_e32 v11, v11
	v_mul_f32_e32 v13, 0x3d000000, v21
	v_mul_f32_e32 v10, v14, v10
	v_mul_f32_e32 v10, 4.0, v10
	v_mul_f32_e32 v11, v12, v11
	v_mul_f32_e32 v9, v13, v11
	v_mul_f32_e32 v9, 4.0, v9
	v_med3_f32 v10, v10, s71, v197
	v_med3_f32 v9, v9, s71, v197
	v_cvt_pk_fp8_f32 v8, v10, v9 op_sel:[0,0,1]
	v_lshl_add_u64 v[2:3], v[4:5], 0, v[2:3]
	v_mov_b32_e32 v200, v161
	v_mov_b32_e32 v158, v163
	v_mov_b32_e32 v160, v198
	v_mov_b32_e32 v162, v199
	s_mov_b32 s28, s24
	s_mov_b32 s74, s73
	s_mov_b64 s[30:31], s[26:27]
	global_store_dword v[2:3], v7, off
	global_store_dword v[2:3], v8, off offset:64
	s_cbranch_vccz .LBB0_2875
	s_waitcnt vmcnt(0)
	s_cmpk_gt_u32 s39, 0xff
	s_cbranch_scc1 .LBB0_2882
	s_barrier

.LBB0_3100:
	s_waitcnt vmcnt(8)
	v_mov_b32_e32 v164, v128
	v_mov_b32_e32 v165, v129
	v_mov_b32_e32 v166, v130
	v_mov_b32_e32 v167, v131
	s_waitcnt vmcnt(24)
	v_mov_b32_e32 v168, v124
	v_mov_b32_e32 v169, v125
	v_mov_b32_e32 v170, v126
	v_mov_b32_e32 v171, v127
	v_mov_b32_e32 v128, v108
	v_mov_b32_e32 v129, v109
	v_mov_b32_e32 v130, v110
	v_mov_b32_e32 v131, v111
	v_mov_b32_e32 v108, v100
	v_mov_b32_e32 v109, v101
	v_mov_b32_e32 v110, v102
	v_mov_b32_e32 v111, v103
	v_mov_b32_e32 v124, v112
	v_mov_b32_e32 v125, v113
	v_mfma_f32_32x32x64_f8f6f4 v[4:19], v[164:171], v[104:111], v[4:19]
	v_mov_b32_e32 v126, v114
	v_mov_b32_e32 v127, v115
	s_waitcnt vmcnt(2)
	v_mov_b32_e32 v180, v136
	v_mov_b32_e32 v181, v137
	v_mov_b32_e32 v182, v138
	v_mov_b32_e32 v183, v139
	s_waitcnt vmcnt(18)
	v_mov_b32_e32 v184, v132
	v_mov_b32_e32 v185, v133
	v_mov_b32_e32 v186, v134
	v_mov_b32_e32 v187, v135
	v_mov_b32_e32 v132, v88
	v_mov_b32_e32 v133, v89
	v_mov_b32_e32 v134, v90
	v_mov_b32_e32 v135, v91
	v_mov_b32_e32 v136, v84
	v_mov_b32_e32 v137, v85
	v_mov_b32_e32 v138, v86
	v_mov_b32_e32 v139, v87
	s_cmp_gt_u32 s38, 17
	s_cselect_b64 s[28:29], -1, 0
	v_mfma_f32_32x32x64_f8f6f4 v[4:19], v[124:131], v[132:139], v[4:19]
	s_cmp_lt_u32 s38, 18
	s_cselect_b32 s26, s39, 0x540
	s_min_u32 s0, s38, 16
	s_lshl_b64 s[30:31], s[26:27], 1
	s_lshl_b32 s26, s0, 7
	s_waitcnt vmcnt(0)
	v_mov_b32_e32 v172, v144
	v_mov_b32_e32 v173, v145
	v_mov_b32_e32 v174, v146
	v_mov_b32_e32 v175, v147
	s_waitcnt vmcnt(16)
	v_mov_b32_e32 v176, v140
	v_mov_b32_e32 v177, v141
	v_mov_b32_e32 v178, v142
	v_mov_b32_e32 v179, v143
	v_mov_b32_e32 v140, v120
	v_mov_b32_e32 v141, v121
	v_mov_b32_e32 v192, v92
	v_mov_b32_e32 v193, v93
	v_mov_b32_e32 v194, v94
	v_mov_b32_e32 v195, v95
	v_lshl_add_u64 v[92:93], v[156:157], 0, s[30:31]
	v_lshl_add_u64 v[94:95], v[158:159], 0, s[30:31]
	v_lshl_add_u64 v[120:121], v[156:157], 0, s[26:27]
	v_mov_b32_e32 v142, v122
	v_mov_b32_e32 v143, v123
	v_mov_b32_e32 v144, v116
	v_mov_b32_e32 v145, v117
	v_mov_b32_e32 v146, v118
	v_mov_b32_e32 v147, v119
	v_mov_b32_e32 v188, v96
	v_mov_b32_e32 v189, v97
	v_mov_b32_e32 v190, v98
	v_mov_b32_e32 v191, v99
	global_load_dwordx4 v[84:87], v[92:93], off offset:48
	global_load_dwordx4 v[88:91], v[92:93], off offset:32
	global_load_dwordx4 v[100:103], v[92:93], off offset:16
	global_load_dwordx4 v[104:107], v[92:93], off
	global_load_dwordx4 v[108:111], v[94:95], off offset:48
	global_load_dwordx4 v[112:115], v[94:95], off offset:32
	global_load_dwordx4 v[124:127], v[94:95], off offset:16
	global_load_dwordx4 v[128:131], v[94:95], off
	v_lshl_add_u64 v[164:165], v[158:159], 0, s[26:27]
	global_load_dwordx4 v[92:95], v[120:121], off offset:688
	global_load_dwordx4 v[96:99], v[120:121], off offset:672
	global_load_dwordx4 v[116:119], v[120:121], off offset:656
	s_nop 0
	global_load_dwordx4 v[120:123], v[120:121], off offset:640
	s_nop 0
	global_load_dwordx4 v[132:135], v[164:165], off offset:688
	global_load_dwordx4 v[136:139], v[164:165], off offset:672
	v_mfma_f32_32x32x64_f8f6f4 v[4:19], v[172:179], v[140:147], v[4:19]
	global_load_dwordx4 v[140:143], v[164:165], off offset:656
	global_load_dwordx4 v[144:147], v[164:165], off offset:640
	s_add_i32 s0, s38, 2
	s_cmp_lt_u32 s0, 22
	s_cselect_b64 s[30:31], -1, 0
	s_cmp_gt_u32 s0, 21
	v_mfma_f32_32x32x64_f8f6f4 v[4:19], v[180:187], v[188:195], v[4:19]
	s_cbranch_scc0 .LBB0_3102
	s_andn2_b64 vcc, exec, s[30:31]
	s_cbranch_vccnz .LBB0_3099
	s_branch .LBB0_3103
.LBB0_3102:
	s_min_u32 s0, s38, 15
	s_lshl_b32 s26, s0, 7
	v_lshl_add_u64 v[176:177], v[156:157], 0, s[26:27]
	v_lshl_add_u64 v[192:193], v[158:159], 0, s[26:27]
	global_load_dwordx4 v[164:167], v[176:177], off offset:800
	global_load_dwordx4 v[168:171], v[176:177], off offset:816
	global_load_dwordx4 v[172:175], v[176:177], off offset:768
	s_nop 0
	global_load_dwordx4 v[176:179], v[176:177], off offset:784
	s_nop 0
	global_load_dwordx4 v[180:183], v[192:193], off offset:800
	global_load_dwordx4 v[184:187], v[192:193], off offset:816
	global_load_dwordx4 v[188:191], v[192:193], off offset:768
	s_waitcnt vmcnt(31)
	v_mfma_f32_32x32x64_f8f6f4 v[4:19], v[52:59], v[28:35], v[4:19]
	global_load_dwordx4 v[56:59], v[192:193], off offset:784
	s_waitcnt vmcnt(5)
	v_mov_b32_e32 v28, v172
	v_mfma_f32_32x32x64_f8f6f4 v[4:19], v[36:43], v[20:27], v[4:19]
	v_mov_b32_e32 v20, v164
	v_mov_b32_e32 v21, v165
	v_mov_b32_e32 v22, v166
	v_mov_b32_e32 v23, v167
	v_mov_b32_e32 v24, v168
	v_mov_b32_e32 v25, v169
	v_mov_b32_e32 v26, v170
	v_mov_b32_e32 v27, v171
	v_mov_b32_e32 v29, v173
	v_mov_b32_e32 v30, v174
	v_mov_b32_e32 v31, v175
	s_waitcnt vmcnt(4)
	v_mov_b32_e32 v32, v176
	v_mov_b32_e32 v33, v177
	v_mov_b32_e32 v34, v178
	v_mov_b32_e32 v35, v179
	s_waitcnt vmcnt(3)
	v_mov_b32_e32 v36, v180
	v_mov_b32_e32 v37, v181
	v_mov_b32_e32 v38, v182
	v_mov_b32_e32 v39, v183
	s_waitcnt vmcnt(2)
	v_mov_b32_e32 v40, v184
	v_mov_b32_e32 v41, v185
	v_mov_b32_e32 v42, v186
	v_mov_b32_e32 v43, v187
	s_waitcnt vmcnt(1)
	v_mov_b32_e32 v52, v188
	v_mov_b32_e32 v53, v189
	v_mov_b32_e32 v54, v190
	v_mov_b32_e32 v55, v191
	s_andn2_b64 vcc, exec, s[30:31]
	s_cbranch_vccnz .LBB0_3099
.LBB0_3103:
	s_min_u32 s0, s38, 14
	s_lshl_b32 s26, s0, 7
	v_lshl_add_u64 v[176:177], v[156:157], 0, s[26:27]
	v_lshl_add_u64 v[192:193], v[158:159], 0, s[26:27]
	global_load_dwordx4 v[164:167], v[176:177], off offset:928
	global_load_dwordx4 v[168:171], v[176:177], off offset:944
	global_load_dwordx4 v[172:175], v[176:177], off offset:896
	s_nop 0
	global_load_dwordx4 v[176:179], v[176:177], off offset:912
	s_nop 0
	global_load_dwordx4 v[180:183], v[192:193], off offset:928
	global_load_dwordx4 v[184:187], v[192:193], off offset:944
	global_load_dwordx4 v[188:191], v[192:193], off offset:896
	s_waitcnt vmcnt(23)
	v_mfma_f32_32x32x64_f8f6f4 v[4:19], v[76:83], v[60:67], v[4:19]
	global_load_dwordx4 v[80:83], v[192:193], off offset:912
	s_waitcnt vmcnt(5)
	v_mov_b32_e32 v60, v172
	v_mfma_f32_32x32x64_f8f6f4 v[4:19], v[68:75], v[44:51], v[4:19]
	v_mov_b32_e32 v44, v164
	v_mov_b32_e32 v45, v165
	v_mov_b32_e32 v46, v166
	v_mov_b32_e32 v47, v167
	v_mov_b32_e32 v48, v168
	v_mov_b32_e32 v49, v169
	v_mov_b32_e32 v50, v170
	v_mov_b32_e32 v51, v171
	v_mov_b32_e32 v61, v173
	v_mov_b32_e32 v62, v174
	v_mov_b32_e32 v63, v175
	s_waitcnt vmcnt(4)
	v_mov_b32_e32 v64, v176
	v_mov_b32_e32 v65, v177
	v_mov_b32_e32 v66, v178
	v_mov_b32_e32 v67, v179
	s_waitcnt vmcnt(3)
	v_mov_b32_e32 v68, v180
	v_mov_b32_e32 v69, v181
	v_mov_b32_e32 v70, v182
	v_mov_b32_e32 v71, v183
	s_waitcnt vmcnt(2)
	v_mov_b32_e32 v72, v184
	v_mov_b32_e32 v73, v185
	v_mov_b32_e32 v74, v186
	v_mov_b32_e32 v75, v187
	s_waitcnt vmcnt(1)
	v_mov_b32_e32 v76, v188
	v_mov_b32_e32 v77, v189
	v_mov_b32_e32 v78, v190
	v_mov_b32_e32 v79, v191
	s_branch .LBB0_3099

.LBB0_3123:
	ds_read_b128 v[2:5], v167
	ds_read_b128 v[6:9], v171
	ds_read_b128 v[10:13], v172
	ds_read_b128 v[14:17], v173
	s_add_u32 s40, s38, 0x100
	s_addc_u32 s41, s39, 0
	s_cmp_eq_u32 s86, 18
	s_cselect_b32 s45, s15, s41
	s_cselect_b32 s44, s14, s40
	s_cselect_b32 s43, s17, s85
	s_cselect_b32 s42, s16, s84
	v_lshl_add_u64 v[158:159], s[38:39], 0, v[152:153]
	s_add_i32 m0, s47, 0xc000
	ds_read_b128 v[186:189], v184
	ds_read_b128 v[190:193], v184 offset:1024
	ds_read_b128 v[194:197], v184 offset:2048
	ds_read_b128 v[198:201], v184 offset:3072
	ds_read_b128 v[202:205], v184 offset:4096
	ds_read_b128 v[206:209], v184 offset:5120
	ds_read_b128 v[210:213], v184 offset:6144
	ds_read_b128 v[214:217], v184 offset:7168
	global_load_lds_dwordx4 v[158:159], off
	v_lshl_add_u64 v[158:159], s[38:39], 0, v[150:151]
	s_add_i32 m0, s47, 0xe000
	s_nop 0
	global_load_lds_dwordx4 v[158:159], off
	s_waitcnt lgkmcnt(8)
	s_barrier
	s_waitcnt lgkmcnt(0)
	s_setprio 1
	s_waitcnt lgkmcnt(0)
	v_mfma_f32_16x16x128_f8f6f4 v[142:145], v[2:9], v[186:193], v[142:145]
	v_mfma_f32_16x16x128_f8f6f4 v[138:141], v[10:17], v[186:193], v[138:141]
	v_mfma_f32_16x16x128_f8f6f4 v[134:137], v[2:9], v[194:201], v[134:137]
	v_mfma_f32_16x16x128_f8f6f4 v[130:133], v[10:17], v[194:201], v[130:133]
	v_mfma_f32_16x16x128_f8f6f4 v[110:113], v[2:9], v[202:209], v[110:113]
	v_mfma_f32_16x16x128_f8f6f4 v[106:109], v[10:17], v[202:209], v[106:109]
	v_mfma_f32_16x16x128_f8f6f4 v[102:105], v[2:9], v[210:217], v[102:105]
	v_mfma_f32_16x16x128_f8f6f4 v[98:101], v[10:17], v[210:217], v[98:101]
	s_setprio 0
	s_barrier
	s_mov_b32 m0, s48
	v_lshl_add_u64 v[158:159], s[42:43], 0, v[146:147]
	ds_read_b128 v[220:223], v168
	ds_read_b128 v[224:227], v174
	ds_read_b128 v[228:231], v175
	ds_read_b128 v[232:235], v176
	global_load_lds_dwordx4 v[158:159], off
	v_lshl_add_u64 v[160:161], s[42:43], 0, v[148:149]
	s_mov_b32 m0, s49
	s_nop 0
	global_load_lds_dwordx4 v[160:161], off
	s_barrier
	s_waitcnt lgkmcnt(0)
	s_setprio 1
	s_waitcnt lgkmcnt(0)
	v_mfma_f32_16x16x128_f8f6f4 v[126:129], v[220:227], v[186:193], v[126:129]
	v_mfma_f32_16x16x128_f8f6f4 v[122:125], v[228:235], v[186:193], v[122:125]
	v_mfma_f32_16x16x128_f8f6f4 v[118:121], v[220:227], v[194:201], v[118:121]
	v_mfma_f32_16x16x128_f8f6f4 v[114:117], v[228:235], v[194:201], v[114:117]
	v_mfma_f32_16x16x128_f8f6f4 v[94:97], v[220:227], v[202:209], v[94:97]
	v_mfma_f32_16x16x128_f8f6f4 v[90:93], v[228:235], v[202:209], v[90:93]
	v_mfma_f32_16x16x128_f8f6f4 v[86:89], v[220:227], v[210:217], v[86:89]
	v_mfma_f32_16x16x128_f8f6f4 v[82:85], v[228:235], v[210:217], v[82:85]
	s_setprio 0
	s_mov_b32 m0, s47
	v_lshl_add_u64 v[162:163], s[44:45], 0, v[146:147]
	s_barrier
	ds_read_b128 v[186:189], v184 offset:16384
	ds_read_b128 v[190:193], v184 offset:17408
	ds_read_b128 v[194:197], v184 offset:18432
	ds_read_b128 v[198:201], v184 offset:19456
	ds_read_b128 v[202:205], v184 offset:20480
	ds_read_b128 v[206:209], v184 offset:21504
	ds_read_b128 v[210:213], v184 offset:22528
	ds_read_b128 v[214:217], v184 offset:23552
	global_load_lds_dwordx4 v[162:163], off
	v_lshl_add_u64 v[164:165], s[44:45], 0, v[148:149]
	s_mov_b32 m0, s52
	s_nop 0
	global_load_lds_dwordx4 v[164:165], off
	s_barrier
	s_waitcnt lgkmcnt(0)
	s_setprio 1
	s_waitcnt lgkmcnt(0)
	v_mfma_f32_16x16x128_f8f6f4 v[78:81], v[2:9], v[186:193], v[78:81]
	v_mfma_f32_16x16x128_f8f6f4 v[74:77], v[10:17], v[186:193], v[74:77]
	v_mfma_f32_16x16x128_f8f6f4 v[70:73], v[2:9], v[194:201], v[70:73]
	v_mfma_f32_16x16x128_f8f6f4 v[66:69], v[10:17], v[194:201], v[66:69]
	v_mfma_f32_16x16x128_f8f6f4 v[46:49], v[2:9], v[202:209], v[46:49]
	v_mfma_f32_16x16x128_f8f6f4 v[42:45], v[10:17], v[202:209], v[42:45]
	v_mfma_f32_16x16x128_f8f6f4 v[38:41], v[2:9], v[210:217], v[38:41]
	v_mfma_f32_16x16x128_f8f6f4 v[34:37], v[10:17], v[210:217], v[34:37]
	s_setprio 0
	s_barrier
	s_add_u32 s38, s42, 0x58000
	s_addc_u32 s39, s43, 0
	s_mov_b32 m0, s53
	v_lshl_add_u64 v[2:3], s[38:39], 0, v[146:147]
	global_load_lds_dwordx4 v[2:3], off
	v_lshl_add_u64 v[2:3], s[38:39], 0, v[148:149]
	s_mov_b32 m0, s55
	s_nop 0
	global_load_lds_dwordx4 v[2:3], off
	s_waitcnt vmcnt(6)
	s_barrier
	s_setprio 1
	v_mfma_f32_16x16x128_f8f6f4 v[62:65], v[220:227], v[186:193], v[62:65]
	v_mfma_f32_16x16x128_f8f6f4 v[58:61], v[228:235], v[186:193], v[58:61]
	v_mfma_f32_16x16x128_f8f6f4 v[54:57], v[220:227], v[194:201], v[54:57]
	v_mfma_f32_16x16x128_f8f6f4 v[50:53], v[228:235], v[194:201], v[50:53]
	v_mfma_f32_16x16x128_f8f6f4 v[30:33], v[220:227], v[202:209], v[30:33]
	v_mfma_f32_16x16x128_f8f6f4 v[26:29], v[228:235], v[202:209], v[26:29]
	v_mfma_f32_16x16x128_f8f6f4 v[22:25], v[220:227], v[210:217], v[22:25]
	v_mfma_f32_16x16x128_f8f6f4 v[18:21], v[228:235], v[210:217], v[18:21]
	s_setprio 0
	s_barrier
	ds_read_b128 v[2:5], v169
	ds_read_b128 v[6:9], v177
	ds_read_b128 v[10:13], v178
	ds_read_b128 v[14:17], v179
	s_add_u32 s38, s44, 0x58000
	s_addc_u32 s39, s45, 0
	s_mov_b32 m0, s64
	v_lshl_add_u64 v[220:221], s[38:39], 0, v[146:147]
	ds_read_b128 v[186:189], v184 offset:32768
	ds_read_b128 v[190:193], v184 offset:33792
	ds_read_b128 v[194:197], v184 offset:34816
	ds_read_b128 v[198:201], v184 offset:35840
	ds_read_b128 v[202:205], v184 offset:36864
	ds_read_b128 v[206:209], v184 offset:37888
	ds_read_b128 v[210:213], v184 offset:38912
	ds_read_b128 v[214:217], v184 offset:39936
	global_load_lds_dwordx4 v[220:221], off
	v_lshl_add_u64 v[220:221], s[38:39], 0, v[148:149]
	s_mov_b32 m0, s65
	s_nop 0
	global_load_lds_dwordx4 v[220:221], off
	s_waitcnt lgkmcnt(8)
	s_barrier
	s_waitcnt lgkmcnt(0)
	s_setprio 1
	s_waitcnt lgkmcnt(0)
	v_mfma_f32_16x16x128_f8f6f4 v[142:145], v[2:9], v[186:193], v[142:145]
	v_mfma_f32_16x16x128_f8f6f4 v[138:141], v[10:17], v[186:193], v[138:141]
	v_mfma_f32_16x16x128_f8f6f4 v[134:137], v[2:9], v[194:201], v[134:137]
	v_mfma_f32_16x16x128_f8f6f4 v[130:133], v[10:17], v[194:201], v[130:133]
	v_mfma_f32_16x16x128_f8f6f4 v[110:113], v[2:9], v[202:209], v[110:113]
	v_mfma_f32_16x16x128_f8f6f4 v[106:109], v[10:17], v[202:209], v[106:109]
	v_mfma_f32_16x16x128_f8f6f4 v[102:105], v[2:9], v[210:217], v[102:105]
	v_mfma_f32_16x16x128_f8f6f4 v[98:101], v[10:17], v[210:217], v[98:101]
	s_setprio 0
	s_barrier
	s_mov_b32 m0, s69
	v_lshl_add_u64 v[158:159], v[158:159], 0, s[28:29]
	ds_read_b128 v[220:223], v170
	ds_read_b128 v[224:227], v180
	ds_read_b128 v[228:231], v181
	ds_read_b128 v[232:235], v182
	global_load_lds_dwordx4 v[158:159], off
	v_lshl_add_u64 v[158:159], v[160:161], 0, s[28:29]
	s_mov_b32 m0, s70
	s_nop 0
	global_load_lds_dwordx4 v[158:159], off
	s_barrier
	s_waitcnt lgkmcnt(0)
	s_setprio 1
	s_waitcnt lgkmcnt(0)
	v_mfma_f32_16x16x128_f8f6f4 v[126:129], v[220:227], v[186:193], v[126:129]
	v_mfma_f32_16x16x128_f8f6f4 v[122:125], v[228:235], v[186:193], v[122:125]
	v_mfma_f32_16x16x128_f8f6f4 v[118:121], v[220:227], v[194:201], v[118:121]
	v_mfma_f32_16x16x128_f8f6f4 v[114:117], v[228:235], v[194:201], v[114:117]
	v_mfma_f32_16x16x128_f8f6f4 v[94:97], v[220:227], v[202:209], v[94:97]
	v_mfma_f32_16x16x128_f8f6f4 v[90:93], v[228:235], v[202:209], v[90:93]
	v_mfma_f32_16x16x128_f8f6f4 v[86:89], v[220:227], v[210:217], v[86:89]
	v_mfma_f32_16x16x128_f8f6f4 v[82:85], v[228:235], v[210:217], v[82:85]
	s_setprio 0
	s_mov_b32 m0, s71
	v_lshl_add_u64 v[158:159], v[162:163], 0, s[28:29]
	s_barrier
	ds_read_b128 v[186:189], v184 offset:49152
	ds_read_b128 v[190:193], v184 offset:50176
	ds_read_b128 v[194:197], v184 offset:51200
	ds_read_b128 v[198:201], v184 offset:52224
	ds_read_b128 v[202:205], v184 offset:53248
	ds_read_b128 v[206:209], v184 offset:54272
	ds_read_b128 v[210:213], v184 offset:55296
	ds_read_b128 v[214:217], v184 offset:56320
	global_load_lds_dwordx4 v[158:159], off
	v_lshl_add_u64 v[158:159], v[164:165], 0, s[28:29]
	s_mov_b32 m0, s72
	s_nop 0
	global_load_lds_dwordx4 v[158:159], off
	s_barrier
	s_waitcnt lgkmcnt(0)
	s_setprio 1
	s_waitcnt lgkmcnt(0)
	v_mfma_f32_16x16x128_f8f6f4 v[78:81], v[2:9], v[186:193], v[78:81]
	v_mfma_f32_16x16x128_f8f6f4 v[74:77], v[10:17], v[186:193], v[74:77]
	v_mfma_f32_16x16x128_f8f6f4 v[70:73], v[2:9], v[194:201], v[70:73]
	v_mfma_f32_16x16x128_f8f6f4 v[66:69], v[10:17], v[194:201], v[66:69]
	v_mfma_f32_16x16x128_f8f6f4 v[46:49], v[2:9], v[202:209], v[46:49]
	v_mfma_f32_16x16x128_f8f6f4 v[42:45], v[10:17], v[202:209], v[42:45]
	v_mfma_f32_16x16x128_f8f6f4 v[38:41], v[2:9], v[210:217], v[38:41]
	v_mfma_f32_16x16x128_f8f6f4 v[34:37], v[10:17], v[210:217], v[34:37]
	s_setprio 0
	s_barrier
	s_add_u32 s38, s42, 0x58080
	s_addc_u32 s39, s43, 0
	s_mov_b32 m0, s73
	v_lshl_add_u64 v[2:3], s[38:39], 0, v[146:147]
	global_load_lds_dwordx4 v[2:3], off
	v_lshl_add_u64 v[2:3], s[38:39], 0, v[148:149]
	s_mov_b32 m0, s74
	s_nop 0
	global_load_lds_dwordx4 v[2:3], off
	s_waitcnt vmcnt(6)
	s_barrier
	s_setprio 1
	v_mfma_f32_16x16x128_f8f6f4 v[62:65], v[220:227], v[186:193], v[62:65]
	v_mfma_f32_16x16x128_f8f6f4 v[58:61], v[228:235], v[186:193], v[58:61]
	v_mfma_f32_16x16x128_f8f6f4 v[54:57], v[220:227], v[194:201], v[54:57]
	v_mfma_f32_16x16x128_f8f6f4 v[50:53], v[228:235], v[194:201], v[50:53]
	v_mfma_f32_16x16x128_f8f6f4 v[30:33], v[220:227], v[202:209], v[30:33]
	v_mfma_f32_16x16x128_f8f6f4 v[26:29], v[228:235], v[202:209], v[26:29]
	v_mfma_f32_16x16x128_f8f6f4 v[22:25], v[220:227], v[210:217], v[22:25]
	v_mfma_f32_16x16x128_f8f6f4 v[18:21], v[228:235], v[210:217], v[18:21]
	s_setprio 0
	s_add_i32 s86, s86, 2
	s_add_u32 s84, s84, 0x100
	s_addc_u32 s85, s85, 0
	s_cmp_gt_u32 s86, 19
	s_mov_b64 s[38:39], s[40:41]
	s_barrier
	s_cbranch_scc0 .LBB0_3123
	v_lshl_add_u32 v6, s83, 8, v166
	v_ashrrev_i32_e32 v7, 31, v6
	v_or_b32_e32 v4, 16, v6
	s_nop 15
	s_nop 15
	v_lshl_add_u64 v[2:3], v[6:7], 2, s[20:21]
	v_ashrrev_i32_e32 v5, 31, v4
	global_load_dword v158, v[2:3], off
	v_lshl_add_u64 v[8:9], v[4:5], 2, s[20:21]
	global_load_dword v159, v[8:9], off
	s_ashr_i32 s0, s82, 31
	s_lshr_b32 s0, s0, 30
	s_add_i32 s0, s82, s0
	s_and_b32 s0, s0, 0xfffffc
	v_lshlrev_b64 v[4:5], 11, v[4:5]
	s_sub_i32 s0, s82, s0
	v_lshl_add_u64 v[14:15], s[18:19], 0, v[4:5]
	v_lshl_or_b32 v4, s0, 8, v183
	v_lshlrev_b64 v[10:11], 11, v[6:7]
	v_ashrrev_i32_e32 v5, 31, v4
	v_lshl_add_u64 v[10:11], s[18:19], 0, v[10:11]
	v_lshlrev_b64 v[16:17], 1, v[4:5]
	v_lshl_add_u64 v[4:5], v[10:11], 0, v[16:17]
	v_lshl_add_u64 v[10:11], v[14:15], 0, v[16:17]
	v_or_b32_e32 v8, 32, v6
	v_ashrrev_i32_e32 v9, 31, v8
	v_lshl_add_u64 v[12:13], v[8:9], 2, s[20:21]
	v_or_b32_e32 v6, 48, v6
	v_ashrrev_i32_e32 v7, 31, v6
	v_lshlrev_b64 v[8:9], 11, v[8:9]
	v_lshlrev_b64 v[6:7], 11, v[6:7]
	v_lshl_add_u64 v[8:9], s[18:19], 0, v[8:9]
	v_lshl_add_u64 v[6:7], s[18:19], 0, v[6:7]
	v_lshl_add_u64 v[8:9], v[8:9], 0, v[16:17]
	v_lshl_add_u64 v[6:7], v[6:7], 0, v[16:17]
	s_mov_b32 s83, s80
	s_mov_b64 s[40:41], s[16:17]
	s_mov_b64 s[38:39], s[14:15]
	s_mov_b32 s82, s81
	s_waitcnt vmcnt(0)
	v_mul_f32_e32 v14, 0x3b800000, v158
	v_pk_mul_f32 v[142:143], v[142:143], v[14:15] op_sel_hi:[1,0]
	v_pk_mul_f32 v[144:145], v[144:145], v[14:15] op_sel_hi:[1,0]
	v_pk_mul_f32 v[138:139], v[138:139], v[14:15] op_sel_hi:[1,0]
	v_pk_mul_f32 v[140:141], v[140:141], v[14:15] op_sel_hi:[1,0]
	v_pk_mul_f32 v[126:127], v[126:127], v[14:15] op_sel_hi:[1,0]
	v_pk_mul_f32 v[128:129], v[128:129], v[14:15] op_sel_hi:[1,0]
	v_pk_mul_f32 v[122:123], v[122:123], v[14:15] op_sel_hi:[1,0]
	v_pk_mul_f32 v[14:15], v[124:125], v[14:15] op_sel_hi:[1,0]
	v_mul_f32_e32 v124, 0x3b800000, v159
	v_cvt_pk_bf16_f32 v126, v126, v127
	v_cvt_pk_bf16_f32 v127, v128, v129
	v_cvt_pk_bf16_f32 v122, v122, v123
	v_cvt_pk_bf16_f32 v123, v14, v15
	v_pk_mul_f32 v[14:15], v[134:135], v[124:125] op_sel_hi:[1,0]
	v_pk_mul_f32 v[128:129], v[136:137], v[124:125] op_sel_hi:[1,0]
	v_cvt_pk_bf16_f32 v142, v142, v143
	v_cvt_pk_bf16_f32 v143, v144, v145
	v_pk_mul_f32 v[130:131], v[130:131], v[124:125] op_sel_hi:[1,0]
	v_pk_mul_f32 v[132:133], v[132:133], v[124:125] op_sel_hi:[1,0]
	v_pk_mul_f32 v[118:119], v[118:119], v[124:125] op_sel_hi:[1,0]
	v_pk_mul_f32 v[120:121], v[120:121], v[124:125] op_sel_hi:[1,0]
	v_pk_mul_f32 v[114:115], v[114:115], v[124:125] op_sel_hi:[1,0]
	v_pk_mul_f32 v[116:117], v[116:117], v[124:125] op_sel_hi:[1,0]
	v_cvt_pk_bf16_f32 v14, v14, v15
	v_cvt_pk_bf16_f32 v15, v128, v129
	v_cvt_pk_bf16_f32 v138, v138, v139
	v_cvt_pk_bf16_f32 v139, v140, v141
	global_store_dwordx2 v[4:5], v[142:143], off
	global_store_dwordx2 v[4:5], v[138:139], off offset:32
	global_store_dwordx2 v[4:5], v[126:127], off offset:256
	global_store_dwordx2 v[4:5], v[122:123], off offset:288
	v_cvt_pk_bf16_f32 v122, v130, v131
	v_cvt_pk_bf16_f32 v123, v132, v133
	v_cvt_pk_bf16_f32 v118, v118, v119
	v_cvt_pk_bf16_f32 v119, v120, v121
	v_cvt_pk_bf16_f32 v114, v114, v115
	v_cvt_pk_bf16_f32 v115, v116, v117
	global_store_dwordx2 v[10:11], v[14:15], off
	global_store_dwordx2 v[10:11], v[122:123], off offset:32
	global_store_dwordx2 v[10:11], v[118:119], off offset:256
	global_store_dwordx2 v[10:11], v[114:115], off offset:288
	global_load_dword v10, v[12:13], off
	s_nop 0
	global_load_dword v11, v[2:3], off offset:192
	s_waitcnt vmcnt(0)
	v_mul_f32_e32 v10, 0x3b800000, v10
	v_mul_f32_e32 v12, 0x3b800000, v11
	v_pk_mul_f32 v[14:15], v[110:111], v[10:11] op_sel_hi:[1,0]
	v_pk_mul_f32 v[16:17], v[112:113], v[10:11] op_sel_hi:[1,0]
	v_pk_mul_f32 v[106:107], v[106:107], v[10:11] op_sel_hi:[1,0]
	v_pk_mul_f32 v[108:109], v[108:109], v[10:11] op_sel_hi:[1,0]
	v_pk_mul_f32 v[94:95], v[94:95], v[10:11] op_sel_hi:[1,0]
	v_pk_mul_f32 v[96:97], v[96:97], v[10:11] op_sel_hi:[1,0]
	v_pk_mul_f32 v[90:91], v[90:91], v[10:11] op_sel_hi:[1,0]
	v_pk_mul_f32 v[10:11], v[92:93], v[10:11] op_sel_hi:[1,0]
	v_pk_mul_f32 v[92:93], v[102:103], v[12:13] op_sel_hi:[1,0]
	v_pk_mul_f32 v[102:103], v[104:105], v[12:13] op_sel_hi:[1,0]
	v_pk_mul_f32 v[98:99], v[98:99], v[12:13] op_sel_hi:[1,0]
	v_pk_mul_f32 v[100:101], v[100:101], v[12:13] op_sel_hi:[1,0]
	v_pk_mul_f32 v[86:87], v[86:87], v[12:13] op_sel_hi:[1,0]
	v_pk_mul_f32 v[88:89], v[88:89], v[12:13] op_sel_hi:[1,0]
	v_pk_mul_f32 v[82:83], v[82:83], v[12:13] op_sel_hi:[1,0]
	v_pk_mul_f32 v[12:13], v[84:85], v[12:13] op_sel_hi:[1,0]
	v_cvt_pk_bf16_f32 v14, v14, v15
	v_cvt_pk_bf16_f32 v15, v16, v17
	v_cvt_pk_bf16_f32 v16, v106, v107
	v_cvt_pk_bf16_f32 v17, v108, v109
	v_cvt_pk_bf16_f32 v84, v94, v95
	v_cvt_pk_bf16_f32 v85, v96, v97
	v_cvt_pk_bf16_f32 v90, v90, v91
	v_cvt_pk_bf16_f32 v91, v10, v11
	v_cvt_pk_bf16_f32 v10, v92, v93
	v_cvt_pk_bf16_f32 v11, v102, v103
	v_cvt_pk_bf16_f32 v92, v98, v99
	v_cvt_pk_bf16_f32 v93, v100, v101
	v_cvt_pk_bf16_f32 v86, v86, v87
	v_cvt_pk_bf16_f32 v87, v88, v89
	v_cvt_pk_bf16_f32 v82, v82, v83
	v_cvt_pk_bf16_f32 v83, v12, v13
	global_store_dwordx2 v[8:9], v[14:15], off
	global_store_dwordx2 v[8:9], v[16:17], off offset:32
	global_store_dwordx2 v[8:9], v[84:85], off offset:256
	global_store_dwordx2 v[8:9], v[90:91], off offset:288
	global_store_dwordx2 v[6:7], v[10:11], off
	global_store_dwordx2 v[6:7], v[92:93], off offset:32
	global_store_dwordx2 v[6:7], v[86:87], off offset:256
	global_store_dwordx2 v[6:7], v[82:83], off offset:288
	global_load_dword v14, v[2:3], off offset:512
	global_load_dword v15, v[2:3], off offset:576
	v_add_co_u32_e32 v8, vcc, s76, v4
	v_lshl_add_u64 v[6:7], v[4:5], 0, s[30:31]
	s_nop 0
	v_addc_co_u32_e32 v9, vcc, 0, v5, vcc
	v_add_co_u32_e32 v12, vcc, s77, v4
	v_lshl_add_u64 v[10:11], v[4:5], 0, s[34:35]
	s_nop 0
	v_addc_co_u32_e32 v13, vcc, 0, v5, vcc
	s_and_b64 vcc, exec, s[12:13]
	s_waitcnt vmcnt(0)
	v_mul_f32_e32 v14, 0x3b800000, v14
	v_mul_f32_e32 v16, 0x3b800000, v15
	v_pk_mul_f32 v[78:79], v[78:79], v[14:15] op_sel_hi:[1,0]
	v_pk_mul_f32 v[80:81], v[80:81], v[14:15] op_sel_hi:[1,0]
	v_pk_mul_f32 v[74:75], v[74:75], v[14:15] op_sel_hi:[1,0]
	v_pk_mul_f32 v[76:77], v[76:77], v[14:15] op_sel_hi:[1,0]
	v_pk_mul_f32 v[62:63], v[62:63], v[14:15] op_sel_hi:[1,0]
	v_pk_mul_f32 v[64:65], v[64:65], v[14:15] op_sel_hi:[1,0]
	v_pk_mul_f32 v[58:59], v[58:59], v[14:15] op_sel_hi:[1,0]
	v_pk_mul_f32 v[14:15], v[60:61], v[14:15] op_sel_hi:[1,0]
	v_pk_mul_f32 v[60:61], v[70:71], v[16:17] op_sel_hi:[1,0]
	v_pk_mul_f32 v[70:71], v[72:73], v[16:17] op_sel_hi:[1,0]
	v_pk_mul_f32 v[66:67], v[66:67], v[16:17] op_sel_hi:[1,0]
	v_pk_mul_f32 v[68:69], v[68:69], v[16:17] op_sel_hi:[1,0]
	v_pk_mul_f32 v[54:55], v[54:55], v[16:17] op_sel_hi:[1,0]
	v_pk_mul_f32 v[56:57], v[56:57], v[16:17] op_sel_hi:[1,0]
	v_pk_mul_f32 v[50:51], v[50:51], v[16:17] op_sel_hi:[1,0]
	v_pk_mul_f32 v[16:17], v[52:53], v[16:17] op_sel_hi:[1,0]
	v_cvt_pk_bf16_f32 v52, v78, v79
	v_cvt_pk_bf16_f32 v53, v80, v81
	v_cvt_pk_bf16_f32 v72, v74, v75
	v_cvt_pk_bf16_f32 v73, v76, v77
	v_cvt_pk_bf16_f32 v62, v62, v63
	v_cvt_pk_bf16_f32 v63, v64, v65
	v_cvt_pk_bf16_f32 v58, v58, v59
	v_cvt_pk_bf16_f32 v59, v14, v15
	v_cvt_pk_bf16_f32 v14, v60, v61
	v_cvt_pk_bf16_f32 v15, v70, v71
	v_cvt_pk_bf16_f32 v60, v66, v67
	v_cvt_pk_bf16_f32 v61, v68, v69
	v_cvt_pk_bf16_f32 v54, v54, v55
	v_cvt_pk_bf16_f32 v55, v56, v57
	v_cvt_pk_bf16_f32 v50, v50, v51
	v_cvt_pk_bf16_f32 v51, v16, v17
	global_store_dwordx2 v[8:9], v[52:53], off
	global_store_dwordx2 v[6:7], v[72:73], off offset:32
	global_store_dwordx2 v[6:7], v[62:63], off offset:256
	global_store_dwordx2 v[6:7], v[58:59], off offset:288
	global_store_dwordx2 v[12:13], v[14:15], off
	global_store_dwordx2 v[10:11], v[60:61], off offset:32
	global_store_dwordx2 v[10:11], v[54:55], off offset:256
	global_store_dwordx2 v[10:11], v[50:51], off offset:288
	global_load_dword v10, v[2:3], off offset:640
	s_nop 0
	global_load_dword v11, v[2:3], off offset:704
	v_add_co_u32_e64 v6, s[12:13], s78, v4
	v_lshl_add_u64 v[2:3], v[4:5], 0, s[36:37]
	s_nop 0
	v_addc_co_u32_e64 v7, s[12:13], 0, v5, s[12:13]
	v_lshl_add_u64 v[8:9], v[4:5], 0, s[26:27]
	v_add_co_u32_e64 v4, s[12:13], s79, v4
	s_waitcnt vmcnt(0)
	v_mul_f32_e32 v10, 0x3b800000, v10
	v_mul_f32_e32 v12, 0x3b800000, v11
	v_pk_mul_f32 v[14:15], v[46:47], v[10:11] op_sel_hi:[1,0]
	v_pk_mul_f32 v[16:17], v[48:49], v[10:11] op_sel_hi:[1,0]
	v_pk_mul_f32 v[42:43], v[42:43], v[10:11] op_sel_hi:[1,0]
	v_pk_mul_f32 v[44:45], v[44:45], v[10:11] op_sel_hi:[1,0]
	v_pk_mul_f32 v[30:31], v[30:31], v[10:11] op_sel_hi:[1,0]
	v_pk_mul_f32 v[32:33], v[32:33], v[10:11] op_sel_hi:[1,0]
	v_pk_mul_f32 v[26:27], v[26:27], v[10:11] op_sel_hi:[1,0]
	v_pk_mul_f32 v[10:11], v[28:29], v[10:11] op_sel_hi:[1,0]
	v_pk_mul_f32 v[28:29], v[38:39], v[12:13] op_sel_hi:[1,0]
	v_pk_mul_f32 v[38:39], v[40:41], v[12:13] op_sel_hi:[1,0]
	v_pk_mul_f32 v[34:35], v[34:35], v[12:13] op_sel_hi:[1,0]
	v_pk_mul_f32 v[36:37], v[36:37], v[12:13] op_sel_hi:[1,0]
	v_pk_mul_f32 v[22:23], v[22:23], v[12:13] op_sel_hi:[1,0]
	v_pk_mul_f32 v[24:25], v[24:25], v[12:13] op_sel_hi:[1,0]
	v_pk_mul_f32 v[18:19], v[18:19], v[12:13] op_sel_hi:[1,0]
	v_pk_mul_f32 v[12:13], v[20:21], v[12:13] op_sel_hi:[1,0]
	v_cvt_pk_bf16_f32 v14, v14, v15
	v_cvt_pk_bf16_f32 v15, v16, v17
	v_addc_co_u32_e64 v5, s[12:13], 0, v5, s[12:13]
	v_cvt_pk_bf16_f32 v16, v42, v43
	v_cvt_pk_bf16_f32 v17, v44, v45
	v_cvt_pk_bf16_f32 v20, v30, v31
	v_cvt_pk_bf16_f32 v21, v32, v33
	v_cvt_pk_bf16_f32 v26, v26, v27
	v_cvt_pk_bf16_f32 v27, v10, v11
	v_cvt_pk_bf16_f32 v10, v28, v29
	v_cvt_pk_bf16_f32 v11, v38, v39
	v_cvt_pk_bf16_f32 v28, v34, v35
	v_cvt_pk_bf16_f32 v29, v36, v37
	v_cvt_pk_bf16_f32 v22, v22, v23
	v_cvt_pk_bf16_f32 v23, v24, v25
	v_cvt_pk_bf16_f32 v18, v18, v19
	v_cvt_pk_bf16_f32 v19, v12, v13
	global_store_dwordx2 v[6:7], v[14:15], off
	global_store_dwordx2 v[2:3], v[16:17], off offset:32
	global_store_dwordx2 v[2:3], v[20:21], off offset:256
	global_store_dwordx2 v[2:3], v[26:27], off offset:288
	global_store_dwordx2 v[4:5], v[10:11], off
	global_store_dwordx2 v[8:9], v[28:29], off offset:32
	global_store_dwordx2 v[8:9], v[22:23], off offset:256
	global_store_dwordx2 v[8:9], v[18:19], off offset:288
	s_cbranch_vccz .LBB0_3112
	s_waitcnt vmcnt(0)
	s_cmpk_gt_u32 s3, 0xff
	s_cbranch_scc1 .LBB0_3127
	s_barrier

.LBB0_3411:
	s_waitcnt vmcnt(20)
	s_nop 0
	v_mfma_f32_32x32x64_f8f6f4 v[2:17], v[106:113], v[66:73], v[2:17]
	s_and_b64 s[36:37], s[26:27], exec
	s_mov_b32 s37, s23
	s_cselect_b32 s22, s28, 0x380
	s_cselect_b32 s36, s29, 0x380
	s_mov_b32 s39, s23
	s_cselect_b32 s38, s30, 0x380
	v_lshl_add_u64 v[194:195], v[186:187], 0, s[38:39]
	v_lshl_add_u64 v[196:197], v[188:189], 0, s[38:39]
	v_cndmask_b32_e64 v193, 0, 1, s[26:27]
	v_cmp_ne_u32_e32 vcc, 1, v193
	s_mov_b64 s[26:27], 0
	s_and_b64 vcc, exec, vcc
	s_waitcnt vmcnt(16)
	v_mfma_f32_32x32x64_f8f6f4 v[2:17], v[90:97], v[50:57], v[2:17]
	s_waitcnt vmcnt(12)
	v_mfma_f32_32x32x64_f8f6f4 v[2:17], v[114:121], v[74:81], v[2:17]
	s_waitcnt vmcnt(8)
	v_mfma_f32_32x32x64_f8f6f4 v[2:17], v[82:89], v[34:41], v[2:17]
	v_lshl_add_u64 v[34:35], v[186:187], 0, s[22:23]
	v_lshl_add_u64 v[36:37], v[188:189], 0, s[22:23]
	v_lshl_add_u64 v[38:39], v[186:187], 0, s[36:37]
	v_lshl_add_u64 v[86:87], v[188:189], 0, s[36:37]
	global_load_dwordx4 v[66:69], v[34:35], off
	global_load_dwordx4 v[70:73], v[34:35], off offset:16
	global_load_dwordx4 v[106:109], v[36:37], off
	global_load_dwordx4 v[110:113], v[36:37], off offset:16
	global_load_dwordx4 v[50:53], v[34:35], off offset:32
	s_waitcnt vmcnt(9)
	v_mfma_f32_32x32x64_f8f6f4 v[2:17], v[130:137], v[42:49], v[2:17]
	global_load_dwordx4 v[54:57], v[34:35], off offset:48
	global_load_dwordx4 v[90:93], v[36:37], off offset:32
	global_load_dwordx4 v[94:97], v[36:37], off offset:48
	global_load_dwordx4 v[74:77], v[38:39], off
	global_load_dwordx4 v[78:81], v[38:39], off offset:16
	global_load_dwordx4 v[114:117], v[86:87], off
	global_load_dwordx4 v[118:121], v[86:87], off offset:16
	s_nop 0
	global_load_dwordx4 v[34:37], v[38:39], off offset:32
	s_nop 0
	global_load_dwordx4 v[38:41], v[38:39], off offset:48
	s_nop 0
	global_load_dwordx4 v[82:85], v[86:87], off offset:32
	s_nop 0
	global_load_dwordx4 v[86:89], v[86:87], off offset:48
	s_nop 0
	global_load_dwordx4 v[42:45], v[194:195], off
	global_load_dwordx4 v[46:49], v[194:195], off offset:16
	global_load_dwordx4 v[130:133], v[196:197], off
	global_load_dwordx4 v[134:137], v[196:197], off offset:16
	s_waitcnt vmcnt(20)
	v_mfma_f32_32x32x64_f8f6f4 v[2:17], v[26:33], v[18:25], v[2:17]
	global_load_dwordx4 v[18:21], v[194:195], off offset:32
	global_load_dwordx4 v[22:25], v[194:195], off offset:48
	global_load_dwordx4 v[26:29], v[196:197], off offset:32
	global_load_dwordx4 v[30:33], v[196:197], off offset:48
	s_waitcnt vmcnt(32)
	v_mfma_f32_32x32x64_f8f6f4 v[2:17], v[138:145], v[98:105], v[2:17]
	s_waitcnt vmcnt(29)
	v_mov_b32_e32 v98, v154
	v_mov_b32_e32 v99, v155
	v_mov_b32_e32 v100, v156
	v_mov_b32_e32 v101, v157
	s_waitcnt vmcnt(28)
	v_mov_b32_e32 v102, v158
	v_mov_b32_e32 v103, v159
	v_mov_b32_e32 v104, v160
	v_mov_b32_e32 v105, v161
	s_waitcnt vmcnt(25)
	v_mov_b32_e32 v138, v170
	v_mov_b32_e32 v139, v171
	v_mov_b32_e32 v140, v172
	v_mov_b32_e32 v141, v173
	s_waitcnt vmcnt(24)
	v_mov_b32_e32 v142, v174
	v_mov_b32_e32 v143, v175
	v_mov_b32_e32 v144, v176
	v_mfma_f32_32x32x64_f8f6f4 v[2:17], v[122:129], v[58:65], v[2:17]
	v_mov_b32_e32 v145, v177
	v_mov_b32_e32 v58, v146
	v_mov_b32_e32 v59, v147
	v_mov_b32_e32 v60, v148
	v_mov_b32_e32 v61, v149
	v_mov_b32_e32 v62, v150
	v_mov_b32_e32 v63, v151
	v_mov_b32_e32 v64, v152
	v_mov_b32_e32 v65, v153
	v_mov_b32_e32 v122, v162
	v_mov_b32_e32 v123, v163
	v_mov_b32_e32 v124, v164
	v_mov_b32_e32 v125, v165
	v_mov_b32_e32 v126, v166
	v_mov_b32_e32 v127, v167
	v_mov_b32_e32 v128, v168
	v_mov_b32_e32 v129, v169
	s_cbranch_vccz .LBB0_3411
	s_nop 1
	v_pk_mul_f32 v[4:5], v[4:5], s[24:25] op_sel_hi:[1,0]
	v_pk_mul_f32 v[2:3], v[2:3], s[24:25] op_sel_hi:[1,0]
	s_waitcnt vmcnt(3)
	v_or_b32_e32 v18, v185, v178
	v_cvt_pk_bf16_f32 v2, v2, v3
	v_cvt_pk_bf16_f32 v3, v4, v5
	v_mov_b64_e32 v[4:5], s[16:17]
	v_mad_i64_i32 v[4:5], s[26:27], v184, s31, v[4:5]
	v_ashrrev_i32_e32 v19, 31, v18
	v_lshl_add_u64 v[4:5], v[18:19], 1, v[4:5]
	global_store_dwordx2 v[4:5], v[2:3], off
	v_pk_mul_f32 v[2:3], v[8:9], s[24:25] op_sel_hi:[1,0]
	v_pk_mul_f32 v[6:7], v[6:7], s[24:25] op_sel_hi:[1,0]
	v_add_u32_e32 v1, s54, v1
	v_cvt_pk_bf16_f32 v6, v6, v7
	v_cvt_pk_bf16_f32 v7, v2, v3
	global_store_dwordx2 v[4:5], v[6:7], off offset:16
	v_pk_mul_f32 v[2:3], v[12:13], s[24:25] op_sel_hi:[1,0]
	v_pk_mul_f32 v[6:7], v[10:11], s[24:25] op_sel_hi:[1,0]
	v_cmp_lt_i32_e32 vcc, s34, v1
	v_cvt_pk_bf16_f32 v6, v6, v7
	v_cvt_pk_bf16_f32 v7, v2, v3
	global_store_dwordx2 v[4:5], v[6:7], off offset:32
	v_pk_mul_f32 v[2:3], v[16:17], s[24:25] op_sel_hi:[1,0]
	v_pk_mul_f32 v[6:7], v[14:15], s[24:25] op_sel_hi:[1,0]
	s_or_b64 s[20:21], vcc, s[20:21]
	v_cvt_pk_bf16_f32 v6, v6, v7
	v_cvt_pk_bf16_f32 v7, v2, v3
	global_store_dwordx2 v[4:5], v[6:7], off offset:48
	s_andn2_b64 exec, exec, s[20:21]
	s_cbranch_execnz .LBB0_3410

.LBB0_3420:
	ds_read_b128 v[2:5], v167
	ds_read_b128 v[6:9], v171
	ds_read_b128 v[10:13], v172
	ds_read_b128 v[14:17], v173
	s_add_u32 s0, s36, 0xfffe0080
	s_addc_u32 s1, s37, -1
	s_cmp_eq_u32 s76, 4
	s_cselect_b32 s41, s27, s1
	s_cselect_b32 s40, s72, s0
	s_cselect_b32 s39, s25, s75
	s_cselect_b32 s38, s73, s74
	v_lshl_add_u64 v[158:159], s[36:37], 0, v[152:153]
	s_add_i32 m0, s35, 0xc000
	ds_read_b128 v[186:189], v184
	ds_read_b128 v[190:193], v184 offset:1024
	ds_read_b128 v[194:197], v184 offset:2048
	ds_read_b128 v[198:201], v184 offset:3072
	ds_read_b128 v[202:205], v184 offset:4096
	ds_read_b128 v[206:209], v184 offset:5120
	ds_read_b128 v[210:213], v184 offset:6144
	ds_read_b128 v[214:217], v184 offset:7168
	global_load_lds_dwordx4 v[158:159], off
	v_lshl_add_u64 v[158:159], s[36:37], 0, v[150:151]
	s_add_i32 m0, s35, 0xe000
	s_nop 0
	global_load_lds_dwordx4 v[158:159], off
	s_waitcnt lgkmcnt(8)
	s_barrier
	s_waitcnt lgkmcnt(0)
	s_setprio 1
	s_waitcnt lgkmcnt(0)
	v_mfma_f32_16x16x128_f8f6f4 v[142:145], v[2:9], v[186:193], v[142:145]
	v_mfma_f32_16x16x128_f8f6f4 v[138:141], v[10:17], v[186:193], v[138:141]
	v_mfma_f32_16x16x128_f8f6f4 v[134:137], v[2:9], v[194:201], v[134:137]
	v_mfma_f32_16x16x128_f8f6f4 v[126:129], v[10:17], v[194:201], v[126:129]
	v_mfma_f32_16x16x128_f8f6f4 v[118:121], v[2:9], v[202:209], v[118:121]
	v_mfma_f32_16x16x128_f8f6f4 v[110:113], v[10:17], v[202:209], v[110:113]
	v_mfma_f32_16x16x128_f8f6f4 v[102:105], v[2:9], v[210:217], v[102:105]
	v_mfma_f32_16x16x128_f8f6f4 v[94:97], v[10:17], v[210:217], v[94:97]
	s_setprio 0
	s_barrier
	s_mov_b32 m0, s43
	v_lshl_add_u64 v[158:159], s[38:39], 0, v[148:149]
	ds_read_b128 v[220:223], v168
	ds_read_b128 v[224:227], v174
	ds_read_b128 v[228:231], v175
	ds_read_b128 v[232:235], v176
	global_load_lds_dwordx4 v[158:159], off
	v_lshl_add_u64 v[160:161], s[38:39], 0, v[146:147]
	s_mov_b32 m0, s44
	s_nop 0
	global_load_lds_dwordx4 v[160:161], off
	s_barrier
	s_waitcnt lgkmcnt(0)
	s_setprio 1
	s_waitcnt lgkmcnt(0)
	v_mfma_f32_16x16x128_f8f6f4 v[130:133], v[220:227], v[186:193], v[130:133]
	v_mfma_f32_16x16x128_f8f6f4 v[122:125], v[228:235], v[186:193], v[122:125]
	v_mfma_f32_16x16x128_f8f6f4 v[114:117], v[220:227], v[194:201], v[114:117]
	v_mfma_f32_16x16x128_f8f6f4 v[106:109], v[228:235], v[194:201], v[106:109]
	v_mfma_f32_16x16x128_f8f6f4 v[98:101], v[220:227], v[202:209], v[98:101]
	v_mfma_f32_16x16x128_f8f6f4 v[90:93], v[228:235], v[202:209], v[90:93]
	v_mfma_f32_16x16x128_f8f6f4 v[86:89], v[220:227], v[210:217], v[86:89]
	v_mfma_f32_16x16x128_f8f6f4 v[82:85], v[228:235], v[210:217], v[82:85]
	s_setprio 0
	s_mov_b32 m0, s35
	v_lshl_add_u64 v[162:163], s[40:41], 0, v[148:149]
	s_barrier
	ds_read_b128 v[186:189], v184 offset:16384
	ds_read_b128 v[190:193], v184 offset:17408
	ds_read_b128 v[194:197], v184 offset:18432
	ds_read_b128 v[198:201], v184 offset:19456
	ds_read_b128 v[202:205], v184 offset:20480
	ds_read_b128 v[206:209], v184 offset:21504
	ds_read_b128 v[210:213], v184 offset:22528
	ds_read_b128 v[214:217], v184 offset:23552
	global_load_lds_dwordx4 v[162:163], off
	v_lshl_add_u64 v[164:165], s[40:41], 0, v[146:147]
	s_mov_b32 m0, s45
	s_nop 0
	global_load_lds_dwordx4 v[164:165], off
	s_barrier
	s_waitcnt lgkmcnt(0)
	s_setprio 1
	s_waitcnt lgkmcnt(0)
	v_mfma_f32_16x16x128_f8f6f4 v[78:81], v[2:9], v[186:193], v[78:81]
	v_mfma_f32_16x16x128_f8f6f4 v[74:77], v[10:17], v[186:193], v[74:77]
	v_mfma_f32_16x16x128_f8f6f4 v[70:73], v[2:9], v[194:201], v[70:73]
	v_mfma_f32_16x16x128_f8f6f4 v[62:65], v[10:17], v[194:201], v[62:65]
	v_mfma_f32_16x16x128_f8f6f4 v[54:57], v[2:9], v[202:209], v[54:57]
	v_mfma_f32_16x16x128_f8f6f4 v[46:49], v[10:17], v[202:209], v[46:49]
	v_mfma_f32_16x16x128_f8f6f4 v[38:41], v[2:9], v[210:217], v[38:41]
	v_mfma_f32_16x16x128_f8f6f4 v[30:33], v[10:17], v[210:217], v[30:33]
	s_setprio 0
	s_barrier
	s_add_u32 s78, s38, 0x20000
	s_addc_u32 s79, s39, 0
	s_mov_b32 m0, s46
	v_lshl_add_u64 v[2:3], s[78:79], 0, v[148:149]
	global_load_lds_dwordx4 v[2:3], off
	v_lshl_add_u64 v[2:3], s[78:79], 0, v[146:147]
	s_mov_b32 m0, s47
	s_nop 0
	global_load_lds_dwordx4 v[2:3], off
	s_waitcnt vmcnt(6)
	s_barrier
	s_setprio 1
	v_mfma_f32_16x16x128_f8f6f4 v[66:69], v[220:227], v[186:193], v[66:69]
	v_mfma_f32_16x16x128_f8f6f4 v[58:61], v[228:235], v[186:193], v[58:61]
	v_mfma_f32_16x16x128_f8f6f4 v[50:53], v[220:227], v[194:201], v[50:53]
	v_mfma_f32_16x16x128_f8f6f4 v[42:45], v[228:235], v[194:201], v[42:45]
	v_mfma_f32_16x16x128_f8f6f4 v[34:37], v[220:227], v[202:209], v[34:37]
	v_mfma_f32_16x16x128_f8f6f4 v[26:29], v[228:235], v[202:209], v[26:29]
	v_mfma_f32_16x16x128_f8f6f4 v[22:25], v[220:227], v[210:217], v[22:25]
	v_mfma_f32_16x16x128_f8f6f4 v[18:21], v[228:235], v[210:217], v[18:21]
	s_setprio 0
	s_barrier
	ds_read_b128 v[2:5], v169
	ds_read_b128 v[6:9], v177
	ds_read_b128 v[10:13], v178
	ds_read_b128 v[14:17], v179
	s_add_u32 s40, s40, 0x20000
	s_addc_u32 s41, s41, 0
	s_mov_b32 m0, s48
	v_lshl_add_u64 v[220:221], s[40:41], 0, v[148:149]
	ds_read_b128 v[186:189], v184 offset:32768
	ds_read_b128 v[190:193], v184 offset:33792
	ds_read_b128 v[194:197], v184 offset:34816
	ds_read_b128 v[198:201], v184 offset:35840
	ds_read_b128 v[202:205], v184 offset:36864
	ds_read_b128 v[206:209], v184 offset:37888
	ds_read_b128 v[210:213], v184 offset:38912
	ds_read_b128 v[214:217], v184 offset:39936
	global_load_lds_dwordx4 v[220:221], off
	v_lshl_add_u64 v[220:221], s[40:41], 0, v[146:147]
	s_mov_b32 m0, s49
	s_nop 0
	global_load_lds_dwordx4 v[220:221], off
	s_waitcnt lgkmcnt(8)
	s_barrier
	s_waitcnt lgkmcnt(0)
	s_setprio 1
	s_waitcnt lgkmcnt(0)
	v_mfma_f32_16x16x128_f8f6f4 v[142:145], v[2:9], v[186:193], v[142:145]
	v_mfma_f32_16x16x128_f8f6f4 v[138:141], v[10:17], v[186:193], v[138:141]
	v_mfma_f32_16x16x128_f8f6f4 v[134:137], v[2:9], v[194:201], v[134:137]
	v_mfma_f32_16x16x128_f8f6f4 v[126:129], v[10:17], v[194:201], v[126:129]
	v_mfma_f32_16x16x128_f8f6f4 v[118:121], v[2:9], v[202:209], v[118:121]
	v_mfma_f32_16x16x128_f8f6f4 v[110:113], v[10:17], v[202:209], v[110:113]
	v_mfma_f32_16x16x128_f8f6f4 v[102:105], v[2:9], v[210:217], v[102:105]
	v_mfma_f32_16x16x128_f8f6f4 v[94:97], v[10:17], v[210:217], v[94:97]
	s_setprio 0
	s_barrier
	s_mov_b32 m0, s55
	v_lshl_add_u64 v[158:159], v[158:159], 0, s[20:21]
	ds_read_b128 v[220:223], v170
	ds_read_b128 v[224:227], v180
	ds_read_b128 v[228:231], v181
	ds_read_b128 v[232:235], v182
	global_load_lds_dwordx4 v[158:159], off
	v_lshl_add_u64 v[158:159], v[160:161], 0, s[20:21]
	s_mov_b32 m0, s64
	s_nop 0
	global_load_lds_dwordx4 v[158:159], off
	s_barrier
	s_waitcnt lgkmcnt(0)
	s_setprio 1
	s_waitcnt lgkmcnt(0)
	v_mfma_f32_16x16x128_f8f6f4 v[130:133], v[220:227], v[186:193], v[130:133]
	v_mfma_f32_16x16x128_f8f6f4 v[122:125], v[228:235], v[186:193], v[122:125]
	v_mfma_f32_16x16x128_f8f6f4 v[114:117], v[220:227], v[194:201], v[114:117]
	v_mfma_f32_16x16x128_f8f6f4 v[106:109], v[228:235], v[194:201], v[106:109]
	v_mfma_f32_16x16x128_f8f6f4 v[98:101], v[220:227], v[202:209], v[98:101]
	v_mfma_f32_16x16x128_f8f6f4 v[90:93], v[228:235], v[202:209], v[90:93]
	v_mfma_f32_16x16x128_f8f6f4 v[86:89], v[220:227], v[210:217], v[86:89]
	v_mfma_f32_16x16x128_f8f6f4 v[82:85], v[228:235], v[210:217], v[82:85]
	s_setprio 0
	s_mov_b32 m0, s65
	v_lshl_add_u64 v[158:159], v[162:163], 0, s[20:21]
	s_barrier
	ds_read_b128 v[186:189], v184 offset:49152
	ds_read_b128 v[190:193], v184 offset:50176
	ds_read_b128 v[194:197], v184 offset:51200
	ds_read_b128 v[198:201], v184 offset:52224
	ds_read_b128 v[202:205], v184 offset:53248
	ds_read_b128 v[206:209], v184 offset:54272
	ds_read_b128 v[210:213], v184 offset:55296
	ds_read_b128 v[214:217], v184 offset:56320
	global_load_lds_dwordx4 v[158:159], off
	v_lshl_add_u64 v[158:159], v[164:165], 0, s[20:21]
	s_mov_b32 m0, s66
	s_nop 0
	global_load_lds_dwordx4 v[158:159], off
	s_barrier
	s_waitcnt lgkmcnt(0)
	s_setprio 1
	s_waitcnt lgkmcnt(0)
	v_mfma_f32_16x16x128_f8f6f4 v[78:81], v[2:9], v[186:193], v[78:81]
	v_mfma_f32_16x16x128_f8f6f4 v[74:77], v[10:17], v[186:193], v[74:77]
	v_mfma_f32_16x16x128_f8f6f4 v[70:73], v[2:9], v[194:201], v[70:73]
	v_mfma_f32_16x16x128_f8f6f4 v[62:65], v[10:17], v[194:201], v[62:65]
	v_mfma_f32_16x16x128_f8f6f4 v[54:57], v[2:9], v[202:209], v[54:57]
	v_mfma_f32_16x16x128_f8f6f4 v[46:49], v[10:17], v[202:209], v[46:49]
	v_mfma_f32_16x16x128_f8f6f4 v[38:41], v[2:9], v[210:217], v[38:41]
	v_mfma_f32_16x16x128_f8f6f4 v[30:33], v[10:17], v[210:217], v[30:33]
	s_setprio 0
	s_barrier
	s_add_u32 s38, s38, 0x20080
	s_addc_u32 s39, s39, 0
	s_mov_b32 m0, s67
	v_lshl_add_u64 v[2:3], s[38:39], 0, v[148:149]
	global_load_lds_dwordx4 v[2:3], off
	v_lshl_add_u64 v[2:3], s[38:39], 0, v[146:147]
	s_mov_b32 m0, s68
	s_nop 0
	global_load_lds_dwordx4 v[2:3], off
	s_waitcnt vmcnt(6)
	s_barrier
	s_setprio 1
	v_mfma_f32_16x16x128_f8f6f4 v[66:69], v[220:227], v[186:193], v[66:69]
	v_mfma_f32_16x16x128_f8f6f4 v[58:61], v[228:235], v[186:193], v[58:61]
	v_mfma_f32_16x16x128_f8f6f4 v[50:53], v[220:227], v[194:201], v[50:53]
	v_mfma_f32_16x16x128_f8f6f4 v[42:45], v[228:235], v[194:201], v[42:45]
	v_mfma_f32_16x16x128_f8f6f4 v[34:37], v[220:227], v[202:209], v[34:37]
	v_mfma_f32_16x16x128_f8f6f4 v[26:29], v[228:235], v[202:209], v[26:29]
	v_mfma_f32_16x16x128_f8f6f4 v[22:25], v[220:227], v[210:217], v[22:25]
	v_mfma_f32_16x16x128_f8f6f4 v[18:21], v[228:235], v[210:217], v[18:21]
	s_setprio 0
	s_add_i32 s76, s76, 2
	s_add_u32 s74, s74, 0x100
	s_addc_u32 s75, s75, 0
	s_add_u32 s36, s36, 0x100
	s_addc_u32 s37, s37, 0
	s_cmp_gt_u32 s76, 5
	s_barrier
	s_cbranch_scc0 .LBB0_3420
	v_lshl_or_b32 v4, s71, 8, v183
	v_pk_mul_f32 v[2:3], v[144:145], s[22:23] op_sel_hi:[1,0]
	v_pk_mul_f32 v[6:7], v[142:143], s[22:23] op_sel_hi:[1,0]
	v_lshl_add_u32 v12, s34, 8, v166
	v_cvt_pk_bf16_f32 v6, v6, v7
	v_cvt_pk_bf16_f32 v7, v2, v3
	v_mov_b64_e32 v[2:3], s[16:17]
	v_ashrrev_i32_e32 v5, 31, v4
	v_mad_i64_i32 v[8:9], s[36:37], v12, s70, v[2:3]
	v_lshlrev_b64 v[4:5], 1, v[4:5]
	v_lshl_add_u64 v[8:9], v[8:9], 0, v[4:5]
	s_nop 15
	s_nop 15
	global_store_dwordx2 v[8:9], v[6:7], off
	v_pk_mul_f32 v[6:7], v[140:141], s[22:23] op_sel_hi:[1,0]
	v_pk_mul_f32 v[10:11], v[138:139], s[22:23] op_sel_hi:[1,0]
	s_and_b64 vcc, exec, s[12:13]
	v_cvt_pk_bf16_f32 v10, v10, v11
	v_cvt_pk_bf16_f32 v11, v6, v7
	global_store_dwordx2 v[8:9], v[10:11], off offset:32
	v_pk_mul_f32 v[6:7], v[132:133], s[22:23] op_sel_hi:[1,0]
	v_pk_mul_f32 v[10:11], v[130:131], s[22:23] op_sel_hi:[1,0]
	s_mov_b32 s71, s24
	v_cvt_pk_bf16_f32 v10, v10, v11
	v_cvt_pk_bf16_f32 v11, v6, v7
	global_store_dwordx2 v[8:9], v[10:11], off offset:256
	v_pk_mul_f32 v[6:7], v[124:125], s[22:23] op_sel_hi:[1,0]
	v_pk_mul_f32 v[10:11], v[122:123], s[22:23] op_sel_hi:[1,0]
	s_mov_b32 s34, s26
	v_cvt_pk_bf16_f32 v10, v10, v11
	v_cvt_pk_bf16_f32 v11, v6, v7
	global_store_dwordx2 v[8:9], v[10:11], off offset:288
	v_or_b32_e32 v10, 16, v12
	v_pk_mul_f32 v[6:7], v[136:137], s[22:23] op_sel_hi:[1,0]
	v_pk_mul_f32 v[8:9], v[134:135], s[22:23] op_sel_hi:[1,0]
	s_mov_b64 s[38:39], s[28:29]
	v_cvt_pk_bf16_f32 v8, v8, v9
	v_cvt_pk_bf16_f32 v9, v6, v7
	v_mad_i64_i32 v[6:7], s[36:37], v10, s70, v[2:3]
	v_lshl_add_u64 v[6:7], v[6:7], 0, v[4:5]
	global_store_dwordx2 v[6:7], v[8:9], off
	v_pk_mul_f32 v[8:9], v[128:129], s[22:23] op_sel_hi:[1,0]
	v_pk_mul_f32 v[10:11], v[126:127], s[22:23] op_sel_hi:[1,0]
	s_nop 0
	v_cvt_pk_bf16_f32 v10, v10, v11
	v_cvt_pk_bf16_f32 v11, v8, v9
	global_store_dwordx2 v[6:7], v[10:11], off offset:32
	v_pk_mul_f32 v[8:9], v[116:117], s[22:23] op_sel_hi:[1,0]
	v_pk_mul_f32 v[10:11], v[114:115], s[22:23] op_sel_hi:[1,0]
	s_nop 0
	v_cvt_pk_bf16_f32 v10, v10, v11
	v_cvt_pk_bf16_f32 v11, v8, v9
	global_store_dwordx2 v[6:7], v[10:11], off offset:256
	v_pk_mul_f32 v[8:9], v[108:109], s[22:23] op_sel_hi:[1,0]
	v_pk_mul_f32 v[10:11], v[106:107], s[22:23] op_sel_hi:[1,0]
	s_nop 0
	v_cvt_pk_bf16_f32 v10, v10, v11
	v_cvt_pk_bf16_f32 v11, v8, v9
	global_store_dwordx2 v[6:7], v[10:11], off offset:288
	v_or_b32_e32 v10, 32, v12
	v_pk_mul_f32 v[6:7], v[120:121], s[22:23] op_sel_hi:[1,0]
	v_pk_mul_f32 v[8:9], v[118:119], s[22:23] op_sel_hi:[1,0]
	s_nop 0
	v_cvt_pk_bf16_f32 v8, v8, v9
	v_cvt_pk_bf16_f32 v9, v6, v7
	v_mad_i64_i32 v[6:7], s[36:37], v10, s70, v[2:3]
	v_lshl_add_u64 v[6:7], v[6:7], 0, v[4:5]
	global_store_dwordx2 v[6:7], v[8:9], off
	v_pk_mul_f32 v[8:9], v[112:113], s[22:23] op_sel_hi:[1,0]
	v_pk_mul_f32 v[10:11], v[110:111], s[22:23] op_sel_hi:[1,0]
	s_nop 0
	v_cvt_pk_bf16_f32 v10, v10, v11
	v_cvt_pk_bf16_f32 v11, v8, v9
	global_store_dwordx2 v[6:7], v[10:11], off offset:32
	v_pk_mul_f32 v[8:9], v[100:101], s[22:23] op_sel_hi:[1,0]
	v_pk_mul_f32 v[10:11], v[98:99], s[22:23] op_sel_hi:[1,0]
	s_nop 0
	v_cvt_pk_bf16_f32 v10, v10, v11
	v_cvt_pk_bf16_f32 v11, v8, v9
	global_store_dwordx2 v[6:7], v[10:11], off offset:256
	v_pk_mul_f32 v[8:9], v[92:93], s[22:23] op_sel_hi:[1,0]
	v_pk_mul_f32 v[10:11], v[90:91], s[22:23] op_sel_hi:[1,0]
	s_nop 0
	v_cvt_pk_bf16_f32 v10, v10, v11
	v_cvt_pk_bf16_f32 v11, v8, v9
	global_store_dwordx2 v[6:7], v[10:11], off offset:288
	v_or_b32_e32 v10, 48, v12
	v_pk_mul_f32 v[6:7], v[104:105], s[22:23] op_sel_hi:[1,0]
	v_pk_mul_f32 v[8:9], v[102:103], s[22:23] op_sel_hi:[1,0]
	s_nop 0
	v_cvt_pk_bf16_f32 v8, v8, v9
	v_cvt_pk_bf16_f32 v9, v6, v7
	v_mad_i64_i32 v[6:7], s[36:37], v10, s70, v[2:3]
	v_lshl_add_u64 v[6:7], v[6:7], 0, v[4:5]
	global_store_dwordx2 v[6:7], v[8:9], off
	v_pk_mul_f32 v[8:9], v[96:97], s[22:23] op_sel_hi:[1,0]
	v_pk_mul_f32 v[10:11], v[94:95], s[22:23] op_sel_hi:[1,0]
	s_nop 0
	v_cvt_pk_bf16_f32 v10, v10, v11
	v_cvt_pk_bf16_f32 v11, v8, v9
	global_store_dwordx2 v[6:7], v[10:11], off offset:32
	v_pk_mul_f32 v[8:9], v[88:89], s[22:23] op_sel_hi:[1,0]
	v_pk_mul_f32 v[10:11], v[86:87], s[22:23] op_sel_hi:[1,0]
	s_nop 0
	v_cvt_pk_bf16_f32 v10, v10, v11
	v_cvt_pk_bf16_f32 v11, v8, v9
	global_store_dwordx2 v[6:7], v[10:11], off offset:256
	v_pk_mul_f32 v[8:9], v[84:85], s[22:23] op_sel_hi:[1,0]
	v_pk_mul_f32 v[10:11], v[82:83], s[22:23] op_sel_hi:[1,0]
	s_nop 0
	v_cvt_pk_bf16_f32 v10, v10, v11
	v_cvt_pk_bf16_f32 v11, v8, v9
	global_store_dwordx2 v[6:7], v[10:11], off offset:288
	v_add_u32_e32 v10, 0x80, v12
	v_pk_mul_f32 v[6:7], v[80:81], s[22:23] op_sel_hi:[1,0]
	v_pk_mul_f32 v[8:9], v[78:79], s[22:23] op_sel_hi:[1,0]
	s_nop 0
	v_cvt_pk_bf16_f32 v8, v8, v9
	v_cvt_pk_bf16_f32 v9, v6, v7
	v_mad_i64_i32 v[6:7], s[36:37], v10, s70, v[2:3]
	v_lshl_add_u64 v[6:7], v[6:7], 0, v[4:5]
	global_store_dwordx2 v[6:7], v[8:9], off
	v_pk_mul_f32 v[8:9], v[76:77], s[22:23] op_sel_hi:[1,0]
	v_pk_mul_f32 v[10:11], v[74:75], s[22:23] op_sel_hi:[1,0]
	s_nop 0
	v_cvt_pk_bf16_f32 v10, v10, v11
	v_cvt_pk_bf16_f32 v11, v8, v9
	global_store_dwordx2 v[6:7], v[10:11], off offset:32
	v_pk_mul_f32 v[8:9], v[68:69], s[22:23] op_sel_hi:[1,0]
	v_pk_mul_f32 v[10:11], v[66:67], s[22:23] op_sel_hi:[1,0]
	s_nop 0
	v_cvt_pk_bf16_f32 v10, v10, v11
	v_cvt_pk_bf16_f32 v11, v8, v9
	global_store_dwordx2 v[6:7], v[10:11], off offset:256
	v_pk_mul_f32 v[8:9], v[60:61], s[22:23] op_sel_hi:[1,0]
	v_pk_mul_f32 v[10:11], v[58:59], s[22:23] op_sel_hi:[1,0]
	s_nop 0
	v_cvt_pk_bf16_f32 v10, v10, v11
	v_cvt_pk_bf16_f32 v11, v8, v9
	global_store_dwordx2 v[6:7], v[10:11], off offset:288
	v_add_u32_e32 v10, 0x90, v12
	v_pk_mul_f32 v[6:7], v[72:73], s[22:23] op_sel_hi:[1,0]
	v_pk_mul_f32 v[8:9], v[70:71], s[22:23] op_sel_hi:[1,0]
	s_nop 0
	v_cvt_pk_bf16_f32 v8, v8, v9
	v_cvt_pk_bf16_f32 v9, v6, v7
	v_mad_i64_i32 v[6:7], s[36:37], v10, s70, v[2:3]
	v_lshl_add_u64 v[6:7], v[6:7], 0, v[4:5]
	global_store_dwordx2 v[6:7], v[8:9], off
	v_pk_mul_f32 v[8:9], v[64:65], s[22:23] op_sel_hi:[1,0]
	v_pk_mul_f32 v[10:11], v[62:63], s[22:23] op_sel_hi:[1,0]
	s_nop 0
	v_cvt_pk_bf16_f32 v10, v10, v11
	v_cvt_pk_bf16_f32 v11, v8, v9
	global_store_dwordx2 v[6:7], v[10:11], off offset:32
	v_pk_mul_f32 v[8:9], v[52:53], s[22:23] op_sel_hi:[1,0]
	v_pk_mul_f32 v[10:11], v[50:51], s[22:23] op_sel_hi:[1,0]
	s_nop 0
	v_cvt_pk_bf16_f32 v10, v10, v11
	v_cvt_pk_bf16_f32 v11, v8, v9
	global_store_dwordx2 v[6:7], v[10:11], off offset:256
	v_pk_mul_f32 v[8:9], v[44:45], s[22:23] op_sel_hi:[1,0]
	v_pk_mul_f32 v[10:11], v[42:43], s[22:23] op_sel_hi:[1,0]
	s_nop 0
	v_cvt_pk_bf16_f32 v10, v10, v11
	v_cvt_pk_bf16_f32 v11, v8, v9
	global_store_dwordx2 v[6:7], v[10:11], off offset:288
	v_add_u32_e32 v10, 0xa0, v12
	v_pk_mul_f32 v[6:7], v[56:57], s[22:23] op_sel_hi:[1,0]
	v_pk_mul_f32 v[8:9], v[54:55], s[22:23] op_sel_hi:[1,0]
	s_nop 0
	v_cvt_pk_bf16_f32 v8, v8, v9
	v_cvt_pk_bf16_f32 v9, v6, v7
	v_mad_i64_i32 v[6:7], s[36:37], v10, s70, v[2:3]
	v_lshl_add_u64 v[6:7], v[6:7], 0, v[4:5]
	global_store_dwordx2 v[6:7], v[8:9], off
	v_pk_mul_f32 v[8:9], v[48:49], s[22:23] op_sel_hi:[1,0]
	v_pk_mul_f32 v[10:11], v[46:47], s[22:23] op_sel_hi:[1,0]
	s_nop 0
	v_cvt_pk_bf16_f32 v10, v10, v11
	v_cvt_pk_bf16_f32 v11, v8, v9
	global_store_dwordx2 v[6:7], v[10:11], off offset:32
	v_pk_mul_f32 v[8:9], v[36:37], s[22:23] op_sel_hi:[1,0]
	v_pk_mul_f32 v[10:11], v[34:35], s[22:23] op_sel_hi:[1,0]
	s_nop 0
	v_cvt_pk_bf16_f32 v10, v10, v11
	v_cvt_pk_bf16_f32 v11, v8, v9
	global_store_dwordx2 v[6:7], v[10:11], off offset:256
	v_pk_mul_f32 v[8:9], v[28:29], s[22:23] op_sel_hi:[1,0]
	v_pk_mul_f32 v[10:11], v[26:27], s[22:23] op_sel_hi:[1,0]
	s_nop 0
	v_cvt_pk_bf16_f32 v10, v10, v11
	v_cvt_pk_bf16_f32 v11, v8, v9
	global_store_dwordx2 v[6:7], v[10:11], off offset:288
	v_add_u32_e32 v10, 0xb0, v12
	v_pk_mul_f32 v[6:7], v[40:41], s[22:23] op_sel_hi:[1,0]
	v_pk_mul_f32 v[8:9], v[38:39], s[22:23] op_sel_hi:[1,0]
	v_mad_i64_i32 v[2:3], s[36:37], v10, s70, v[2:3]
	v_cvt_pk_bf16_f32 v8, v8, v9
	v_cvt_pk_bf16_f32 v9, v6, v7
	v_lshl_add_u64 v[2:3], v[2:3], 0, v[4:5]
	v_pk_mul_f32 v[4:5], v[32:33], s[22:23] op_sel_hi:[1,0]
	v_pk_mul_f32 v[6:7], v[30:31], s[22:23] op_sel_hi:[1,0]
	s_mov_b64 s[36:37], s[30:31]
	v_cvt_pk_bf16_f32 v6, v6, v7
	v_cvt_pk_bf16_f32 v7, v4, v5
	global_store_dwordx2 v[2:3], v[6:7], off offset:32
	v_pk_mul_f32 v[4:5], v[24:25], s[22:23] op_sel_hi:[1,0]
	v_pk_mul_f32 v[6:7], v[22:23], s[22:23] op_sel_hi:[1,0]
	global_store_dwordx2 v[2:3], v[8:9], off
	v_cvt_pk_bf16_f32 v6, v6, v7
	v_cvt_pk_bf16_f32 v7, v4, v5
	global_store_dwordx2 v[2:3], v[6:7], off offset:256
	v_pk_mul_f32 v[4:5], v[20:21], s[22:23] op_sel_hi:[1,0]
	v_pk_mul_f32 v[6:7], v[18:19], s[22:23] op_sel_hi:[1,0]
	s_nop 0
	v_cvt_pk_bf16_f32 v6, v6, v7
	v_cvt_pk_bf16_f32 v7, v4, v5
	global_store_dwordx2 v[2:3], v[6:7], off offset:288
	s_cbranch_vccz .LBB0_3417
	s_waitcnt vmcnt(0)
	s_cmpk_gt_u32 s3, 0xff
	v_readlane_b32 s4, v252, 8
	s_cbranch_scc1 .LBB0_3424
	s_barrier

.LBB0_4060:
	s_lshl_b32 s4, s44, 5
	s_lshr_b32 s2, s44, 1
	s_and_b32 s4, s4, 32
	s_ashr_i32 s0, s12, 6
	s_and_b32 s1, s12, 63
	s_add_i32 s2, s2, s34
	s_add_i32 s4, s4, s31
	s_and_b64 s[12:13], s[18:19], exec
	s_cselect_b32 s0, s2, s0
	s_cselect_b32 s1, s4, s1
	s_lshr_b32 s2, s0, 3
	s_mulk_i32 s2, 0x4100
	s_lshl_b32 s1, s1, 8
	s_and_b32 s4, s0, 7
	s_add_i32 s2, s2, s1
	v_add_u32_e32 v166, s2, v170
	s_lshl_b32 s24, s4, 7
	s_lshl_b32 s12, s4, 2
	s_mul_i32 s46, s0, 0x208000
	v_ashrrev_i32_e32 v167, 31, v166
	s_mul_hi_i32 s47, s0, 0x208000
	s_add_u32 s1, s35, s46
	v_lshlrev_b64 v[4:5], 5, v[166:167]
	s_addc_u32 s2, s36, s47
	s_mul_i32 s55, s0, 0x104000
	v_lshl_add_u64 v[4:5], s[16:17], 0, v[4:5]
	s_mov_b32 s13, s25
	s_mul_hi_i32 s64, s0, 0x104000
	s_add_u32 s4, s37, s55
	v_lshl_add_u64 v[4:5], v[4:5], 0, s[12:13]
	s_addc_u32 s5, s38, s64
	s_add_i32 s12, s0, 32
	v_lshlrev_b64 v[2:3], 10, v[166:167]
	s_ashr_i32 s13, s12, 31
	v_lshl_add_u64 v[2:3], s[22:23], 0, v[2:3]
	s_lshl_b64 s[12:13], s[12:13], 2
	v_lshl_add_u64 v[2:3], v[2:3], 0, s[24:25]
	s_add_u32 s12, s3, s12
	s_addc_u32 s13, s30, s13
	v_lshl_add_u64 v[2:3], v[2:3], 0, v[178:179]
	global_load_dword v58, v[4:5], off
	global_load_dword v50, v163, s[12:13]
	global_load_dwordx4 v[142:145], v[2:3], off offset:16
	global_load_dwordx4 v[138:141], v[2:3], off
	global_load_dwordx4 v[150:153], v[2:3], off offset:80
	global_load_dwordx4 v[146:149], v[2:3], off offset:64
	v_readfirstlane_b32 s0, v1
	s_ashr_i32 s0, s0, 6
	s_cmp_lt_i32 s0, 6
	s_mul_i32 s48, s0, 0xc00
	s_cselect_b64 s[14:15], -1, 0
	s_add_i32 s65, s48, 0xffffc000
	s_add_u32 s6, s4, s65
	s_addc_u32 s7, s5, 0
	s_ashr_i32 s49, s48, 31
	s_add_u32 s8, s1, s48
	s_addc_u32 s9, s2, s49
	s_and_b64 s[12:13], s[14:15], exec
	s_cselect_b32 s13, s9, s7
	s_cselect_b32 s12, s8, s6
	s_add_i32 s45, s48, 0
	s_cmp_lt_i32 s0, 5
	s_cselect_b64 s[28:29], -1, 0
	s_add_i32 s0, s48, 0x400
	s_ashr_i32 s6, s0, 31
	s_add_u32 s7, s8, 0x400
	s_addc_u32 s10, s9, 0
	s_add_i32 s52, s48, 0xffffc400
	s_add_u32 s11, s4, s52
	s_addc_u32 s33, s5, 0
	v_lshl_add_u64 v[2:3], s[12:13], 0, v[164:165]
	s_and_b64 s[12:13], s[28:29], exec
	s_mov_b32 m0, s45
	s_cselect_b32 s13, s10, s33
	s_cselect_b32 s12, s7, s11
	s_add_i32 s7, s48, 0x800
	v_lshrrev_b32 v154, 2, v0
	v_xor_b32 v154, v154, v0
	v_bfe_u32 v154, v154, 2, 1
	v_add_u32 v154, -1, v154
	v_and_b32 v154, 0x38383838, v154
	v_mov_b32 v155, v154
	v_mov_b32 v156, v154
	v_mov_b32 v157, v154
	v_mov_b32 v158, v154
	v_mov_b32 v159, v154
	v_mov_b32 v160, v154
	v_mov_b32 v161, v154
	global_load_lds_dwordx4 v[2:3], off
	s_add_i32 m0, s45, 0x400
	s_ashr_i32 s10, s7, 31
	s_add_u32 s8, s8, 0x800
	s_addc_u32 s9, s9, 0
	s_add_i32 s53, s48, 0xffffc800
	s_add_u32 s11, s4, s53
	s_addc_u32 s33, s5, 0
	v_lshl_add_u64 v[2:3], s[12:13], 0, v[164:165]
	s_and_b64 s[12:13], s[28:29], exec
	global_load_lds_dwordx4 v[2:3], off
	s_cselect_b32 s13, s9, s33
	s_cselect_b32 s12, s8, s11
	s_add_i32 m0, s45, 0x800
	s_add_u32 s4, s4, 0x2000
	s_addc_u32 s5, s5, 0
	s_add_u32 s1, s1, 0x4000
	s_addc_u32 s2, s2, 0
	s_add_u32 s8, s1, s48
	s_addc_u32 s9, s2, s49
	s_add_u32 s11, s4, s65
	s_addc_u32 s33, s5, 0
	v_lshl_add_u64 v[2:3], s[12:13], 0, v[164:165]
	s_and_b64 s[12:13], s[14:15], exec
	global_load_lds_dwordx4 v[2:3], off
	s_cselect_b32 s13, s9, s33
	s_cselect_b32 s12, s8, s11
	s_add_i32 m0, s45, 0x6000
	s_add_u32 s0, s1, s0
	s_addc_u32 s6, s2, s6
	s_add_u32 s8, s4, s52
	s_addc_u32 s9, s5, 0
	v_lshl_add_u64 v[2:3], s[12:13], 0, v[164:165]
	s_and_b64 s[12:13], s[28:29], exec
	global_load_lds_dwordx4 v[2:3], off
	s_cselect_b32 s13, s6, s9
	s_cselect_b32 s12, s0, s8
	s_add_i32 m0, s45, 0x6400
	s_add_u32 s0, s1, s7
	s_addc_u32 s1, s2, s10
	s_add_u32 s2, s4, s53
	s_addc_u32 s4, s5, 0
	v_lshl_add_u64 v[2:3], s[12:13], 0, v[164:165]
	s_and_b64 s[12:13], s[28:29], exec
	s_cselect_b32 s13, s1, s4
	s_cselect_b32 s12, s0, s2
	global_load_lds_dwordx4 v[2:3], off
	v_lshl_add_u64 v[2:3], s[12:13], 0, v[164:165]
	s_add_i32 m0, s45, 0x6800
	s_waitcnt vmcnt(0)
	v_mul_f32_e32 v51, 0x4f800000, v50
	global_load_lds_dwordx4 v[2:3], off
	s_waitcnt vmcnt(3)
	s_barrier
	ds_read_b128 v[2:5], v171
	ds_read_b128 v[6:9], v171 offset:1024
	s_waitcnt lgkmcnt(0)
	v_mfma_f32_32x32x64_f8f6f4 v[2:17], v[2:9], v[138:145], 0
	ds_read_b128 v[18:21], v171 offset:2048
	ds_read_b128 v[22:25], v171 offset:3072
	v_cmp_gt_f32_e32 vcc, s39, v50
	s_add_u32 s46, s46, s48
	s_addc_u32 s47, s47, s49
	v_cndmask_b32_e32 v59, v50, v51, vcc
	v_sqrt_f32_e32 v60, v59
	s_add_u32 s48, s55, s53
	s_addc_u32 s49, s64, 0
	s_add_u32 s52, s55, s52
	v_add_u32_e32 v61, -1, v60
	v_fma_f32 v62, -v61, v60, v59
	v_cmp_ge_f32_e64 s[12:13], 0, v62
	v_add_u32_e32 v62, 1, v60
	s_addc_u32 s53, s64, 0
	v_cndmask_b32_e64 v61, v60, v61, s[12:13]
	s_waitcnt lgkmcnt(0)
	v_mfma_f32_32x32x64_f8f6f4 v[2:17], v[18:25], v[146:153], v[2:17]
	ds_read_b128 v[18:21], v171 offset:4096
	ds_read_b128 v[22:25], v171 offset:5120
	ds_read_b128 v[34:37], v171 offset:6144
	ds_read_b128 v[38:41], v171 offset:7168
	v_fma_f32 v60, -v62, v60, v59
	v_cmp_lt_f32_e64 s[12:13], 0, v60
	s_add_u32 s55, s55, s65
	s_addc_u32 s64, s64, 0
	v_cndmask_b32_e64 v60, v61, v62, s[12:13]
	s_mov_b32 s67, 0
	s_mov_b32 s65, 0
	v_mov_b32_e32 v61, v163
	v_mov_b32_e32 v62, v163
	v_mov_b32_e32 v63, v163
	v_mov_b32_e32 v64, v163
	v_mov_b32_e32 v65, v163
	s_nop 3
	v_max3_f32 v2, v2, s41, v3
	s_waitcnt lgkmcnt(0)
	v_mfma_f32_32x32x64_f8f6f4 v[18:33], v[18:25], v[138:145], 0
	v_max3_f32 v2, v2, v4, v5
	v_max3_f32 v2, v2, v6, v7
	v_max3_f32 v2, v2, v8, v9
	v_max3_f32 v2, v2, v10, v11
	v_max3_f32 v2, v2, v12, v13
	v_max3_f32 v2, v2, v14, v15
	v_max3_f32 v2, v2, v16, v17
	v_mfma_f32_32x32x64_f8f6f4 v[18:33], v[34:41], v[146:153], v[18:33]
	ds_read_b128 v[34:37], v171 offset:8192
	ds_read_b128 v[38:41], v171 offset:9216
	ds_read_b128 v[50:53], v171 offset:10240
	ds_read_b128 v[54:57], v171 offset:11264
	s_waitcnt lgkmcnt(0)
	v_mfma_f32_32x32x64_f8f6f4 v[34:49], v[34:41], v[138:145], 0
	s_nop 13
	v_max3_f32 v2, v2, v18, v19
	v_max3_f32 v2, v2, v20, v21
	v_max3_f32 v18, v2, v22, v23
	v_max3_f32 v18, v18, v24, v25
	v_max3_f32 v18, v18, v26, v27
	v_max3_f32 v18, v18, v28, v29
	v_max3_f32 v18, v18, v30, v31
	v_max3_f32 v26, v18, v32, v33
	v_mov_b32_e32 v27, v163
	v_mov_b32_e32 v28, v163
	v_mov_b32_e32 v29, v163
	v_mov_b32_e32 v30, v163
	v_mov_b32_e32 v31, v163
	v_mov_b32_e32 v32, v163
	v_mov_b32_e32 v33, v163
	v_mfma_f32_32x32x64_f8f6f4 v[34:49], v[50:57], v[146:153], v[34:49]
	v_mul_f32_e32 v50, 0x37800000, v60
	v_cndmask_b32_e32 v60, v60, v50, vcc
	ds_read_b128 v[50:53], v171 offset:12288
	ds_read_b128 v[54:57], v171 offset:13312
	ds_read_b128 v[18:21], v171 offset:14336
	ds_read_b128 v[22:25], v171 offset:15360
	v_cmp_lt_i32_e32 vcc, v176, v177
	s_nop 12
	v_max3_f32 v26, v26, v34, v35
	s_waitcnt lgkmcnt(0)
	v_mfma_f32_32x32x64_f8f6f4 v[2:17], v[50:57], v[138:145], 0
	v_max3_f32 v26, v26, v36, v37
	v_max3_f32 v26, v26, v38, v39
	v_max3_f32 v26, v26, v40, v41
	v_max3_f32 v26, v26, v42, v43
	v_max3_f32 v26, v26, v44, v45
	v_max3_f32 v26, v26, v46, v47
	v_max3_f32 v26, v26, v48, v49
	v_mov_b32_e32 v50, 0
	v_mov_b32_e32 v51, v163
	v_mov_b32_e32 v52, v163
	v_mov_b32_e32 v53, v163
	v_mov_b32_e32 v54, v163
	v_mov_b32_e32 v55, v163
	v_mov_b32_e32 v56, v163
	v_mov_b32_e32 v57, v163
	v_mfma_f32_32x32x64_f8f6f4 v[2:17], v[18:25], v[146:153], v[2:17]
	v_mov_b32_e32 v18, 0
	v_mov_b32_e32 v19, v163
	v_mov_b32_e32 v20, v163
	v_mov_b32_e32 v21, v163
	v_mov_b32_e32 v22, v163
	v_mov_b32_e32 v23, v163
	v_mov_b32_e32 v24, v163
	v_mov_b32_e32 v25, v163
	s_nop 11
	v_max3_f32 v2, v26, v2, v3
	v_max3_f32 v2, v2, v4, v5
	v_max3_f32 v2, v2, v6, v7
	v_max3_f32 v2, v2, v8, v9
	v_max3_f32 v2, v2, v10, v11
	v_max3_f32 v2, v2, v12, v13
	v_max3_f32 v2, v2, v14, v15
	v_cndmask_b32_e32 v3, v175, v176, vcc
	v_max3_f32 v2, v2, v16, v17
	v_lshlrev_b32_e32 v3, 2, v3
	ds_bpermute_b32 v3, v3, v2
	v_cmp_class_f32_e32 vcc, v59, v172
	v_mov_b32_e32 v26, v163
	v_mov_b32_e32 v5, v163
	v_cndmask_b32_e32 v4, v60, v59, vcc
	s_waitcnt lgkmcnt(0)
	v_max_f32_e32 v3, v3, v3
	v_mul_f32_e32 v4, v58, v4
	v_max_f32_e32 v2, v2, v3
	v_fmamk_f32 v4, v4, 0x3f90a3d7, v173
	v_add_f32_e32 v2, 0x42800000, v2
	v_min_f32_e32 v2, v4, v2
	v_add_f32_e32 v2, 0xc2ec0000, v2
	v_xor_b32_e32 v34, 0x80000000, v2
	v_mov_b32_e32 v35, v34
	v_mov_b32_e32 v36, v34
	v_mov_b32_e32 v37, v34
	v_mov_b32_e32 v38, v34
	v_mov_b32_e32 v39, v34
	v_mov_b32_e32 v40, v34
	v_mov_b32_e32 v41, v34
	v_mov_b32_e32 v42, v34
	v_mov_b32_e32 v43, v34
	v_mov_b32_e32 v44, v34
	v_mov_b32_e32 v45, v34
	v_mov_b32_e32 v46, v34
	v_mov_b32_e32 v47, v34
	v_mov_b32_e32 v48, v34
	v_mov_b32_e32 v49, v34
	v_mov_b32_e32 v58, v163
	v_mov_b32_e32 v59, v163
	v_mov_b32_e32 v60, v163
	v_mov_b32_e32 v2, 0
	v_mov_b32_e32 v3, v163
	v_mov_b32_e32 v4, v163
	v_mov_b32_e32 v6, v163
	v_mov_b32_e32 v7, v163
	v_mov_b32_e32 v8, v163
	v_mov_b32_e32 v9, v163
	v_mov_b32_e32 v10, v163
	v_mov_b32_e32 v11, v163
	v_mov_b32_e32 v12, v163
	v_mov_b32_e32 v13, v163
	v_mov_b32_e32 v14, v163
	v_mov_b32_e32 v15, v163
	v_mov_b32_e32 v16, v163
	v_mov_b32_e32 v17, v163
	v_mov_b32_e32 v86, v163
	v_mov_b32_e32 v87, v163
	v_mov_b32_e32 v88, v163
	v_mov_b32_e32 v89, v163
	v_mov_b32_e32 v90, v163
	v_mov_b32_e32 v91, v163
	v_mov_b32_e32 v92, v163
	v_mov_b32_e32 v93, v163
	v_mov_b32_e32 v94, v163
	v_mov_b32_e32 v95, v163
	v_mov_b32_e32 v96, v163
	v_mov_b32_e32 v97, v163
	v_mov_b32_e32 v98, v163
	v_mov_b32_e32 v99, v163
	v_mov_b32_e32 v100, v163
	v_mov_b32_e32 v101, v163
	v_mov_b32_e32 v102, v163
	v_mov_b32_e32 v103, v163
	v_mov_b32_e32 v104, v163
	v_mov_b32_e32 v105, v163
	v_mov_b32_e32 v106, v163
	v_mov_b32_e32 v107, v163
	v_mov_b32_e32 v108, v163
	v_mov_b32_e32 v109, v163
	v_mov_b32_e32 v110, v163
	v_mov_b32_e32 v111, v163
	v_mov_b32_e32 v112, v163
	v_mov_b32_e32 v113, v163
	v_mov_b32_e32 v114, v163
	v_mov_b32_e32 v115, v163
	v_mov_b32_e32 v116, v163
	v_mov_b32_e32 v117, v163
	v_mov_b32_e32 v228, v163
	v_mov_b32_e32 v229, v163
	v_mov_b32_e32 v230, v163
	v_mov_b32_e32 v231, v163
	v_mov_b32_e32 v232, v163
	v_mov_b32_e32 v233, v163
	v_mov_b32_e32 v234, v163
	v_mov_b32_e32 v235, v163
	v_mov_b32_e32 v236, v163
	v_mov_b32_e32 v237, v163
	v_mov_b32_e32 v238, v163
	v_mov_b32_e32 v239, v163
	v_mov_b32_e32 v240, v163
	v_mov_b32_e32 v241, v163
	v_mov_b32_e32 v242, v163
	v_mov_b32_e32 v243, v163
	s_add_u32 s98, s20, s46
	s_addc_u32 s99, s21, s47
	s_add_u32 s98, s98, 0x23076100
	s_addc_u32 s99, s99, 0
	s_add_u32 s100, s20, s55
	s_addc_u32 s101, s21, s64
	s_add_u32 s100, s100, 0x26132100
	s_addc_u32 s101, s101, 0
	s_movk_i32 s2, 0x2000
	s_and_b64 s[0:1], s[14:15], exec
	s_cselect_b32 s1, s99, s101
	s_cselect_b32 s0, s98, s100
	s_cselect_b32 s2, 0x4000, s2
	s_add_u32 s8, s0, s2
	s_addc_u32 s9, s1, 0
	s_lshl_b32 s2, s2, 1
	s_add_u32 s98, s20, s46
	s_addc_u32 s99, s21, s47
	s_add_u32 s98, s98, 0x23076500
	s_addc_u32 s99, s99, 0
	s_add_u32 s100, s20, s52
	s_addc_u32 s101, s21, s53
	s_add_u32 s100, s100, 0x26132100
	s_addc_u32 s101, s101, 0
	s_movk_i32 s33, 0x2000
	s_and_b64 s[4:5], s[28:29], exec
	s_cselect_b32 s5, s99, s101
	s_cselect_b32 s4, s98, s100
	s_cselect_b32 s33, 0x4000, s33
	s_add_u32 s10, s4, s33
	s_addc_u32 s11, s5, 0
	s_lshl_b32 s33, s33, 1
	s_add_u32 s98, s20, s46
	s_addc_u32 s99, s21, s47
	s_add_u32 s98, s98, 0x23076900
	s_addc_u32 s99, s99, 0
	s_add_u32 s100, s20, s48
	s_addc_u32 s101, s21, s49
	s_add_u32 s100, s100, 0x26132100
	s_addc_u32 s101, s101, 0
	s_movk_i32 s50, 0x2000
	s_and_b64 s[6:7], s[28:29], exec
	s_cselect_b32 s7, s99, s101
	s_cselect_b32 s6, s98, s100
	s_cselect_b32 s50, 0x4000, s50
	s_add_u32 s68, s6, s50
	s_addc_u32 s69, s7, 0
	s_lshl_b32 s50, s50, 1
	s_mov_b64 s[98:99], 0
	s_branch .LBB0_4062
.LBB0_4062:
	s_waitcnt vmcnt(0) lgkmcnt(0)
	s_barrier
	s_cmpk_gt_u32 s65, 0x7f
	s_cselect_b64 vcc, 0, exec
	s_mul_i32 s100, s67, 0x6000
	s_add_i32 s65, s65, 2
	s_xor_b32 s67, s67, 2
	v_add_u32_e32 v167, s100, v171

.Lback_mla1_0:
	v_cvt_pk_u8_f32 v118, v86, 0, 0
	v_cvt_pk_u8_f32 v119, v90, 0, 0
	v_cvt_pk_u8_f32 v120, v94, 0, 0
	v_cvt_pk_u8_f32 v121, v98, 0, 0
	v_cvt_pk_u8_f32 v118, v87, 1, v118
	v_cvt_pk_u8_f32 v119, v91, 1, v119
	v_cvt_pk_u8_f32 v120, v95, 1, v120
	v_cvt_pk_u8_f32 v121, v99, 1, v121
	s_waitcnt lgkmcnt(6)
	v_mfma_f32_32x32x64_f8f6f4 v[54:69], v[190:197], v[138:145], v[34:49]
	v_cvt_pk_u8_f32 v118, v88, 2, v118
	v_cvt_pk_u8_f32 v119, v92, 2, v119
	v_cvt_pk_u8_f32 v120, v96, 2, v120
	v_cvt_pk_u8_f32 v121, v100, 2, v121
	v_cvt_pk_u8_f32 v118, v89, 3, v118
	v_cvt_pk_u8_f32 v119, v93, 3, v119
	v_cvt_pk_u8_f32 v120, v97, 3, v120
	v_cvt_pk_u8_f32 v121, v101, 3, v121
	s_waitcnt lgkmcnt(4)
	v_mfma_f32_32x32x64_f8f6f4 v[54:69], v[198:205], v[146:153], v[54:69]
	v_cvt_pk_u8_f32 v122, v102, 0, 0
	v_cvt_pk_u8_f32 v123, v106, 0, 0
	v_cvt_pk_u8_f32 v124, v110, 0, 0
	v_cvt_pk_u8_f32 v125, v114, 0, 0
	v_cvt_pk_u8_f32 v122, v103, 1, v122
	v_cvt_pk_u8_f32 v123, v107, 1, v123
	v_cvt_pk_u8_f32 v124, v111, 1, v124
	v_cvt_pk_u8_f32 v125, v115, 1, v125
	s_waitcnt lgkmcnt(2)
	v_mfma_f32_32x32x64_f8f6f4 v[70:85], v[206:213], v[138:145], v[34:49]
	v_cvt_pk_u8_f32 v122, v104, 2, v122
	v_cvt_pk_u8_f32 v123, v108, 2, v123
	v_cvt_pk_u8_f32 v124, v112, 2, v124
	v_cvt_pk_u8_f32 v125, v116, 2, v125
	v_cvt_pk_u8_f32 v122, v105, 3, v122
	v_cvt_pk_u8_f32 v123, v109, 3, v123
	v_cvt_pk_u8_f32 v124, v113, 3, v124
	v_cvt_pk_u8_f32 v125, v117, 3, v125
	s_waitcnt lgkmcnt(0)
	v_mfma_f32_32x32x64_f8f6f4 v[70:85], v[220:227], v[146:153], v[70:85]
	s_nop 0
	s_nop 0
	v_mfma_f32_32x32x64_f8f6f4 v[18:33], v[228:235], v[118:125], v[18:33] blgp:1
	ds_read_b128 v[190:193], v167 offset:8192
	ds_read_b128 v[194:197], v167 offset:9216
	ds_read_b128 v[198:201], v167 offset:10240
	ds_read_b128 v[202:205], v167 offset:11264
	s_cbranch_vccz .Ldma_mla1_skip0
	s_mul_i32 s101, s67, 0x6000
	s_add_i32 s101, s101, s45
	s_mov_b32 m0, s101
	s_nop 0
	global_load_lds_dwordx4 v164, s[0:1]
.Ldma_mla1_skip0:
	v_mfma_f32_32x32x64_f8f6f4 v[2:17], v[236:243], v[118:125], v[2:17] blgp:1
	ds_read_b128 v[206:209], v167 offset:12288
	ds_read_b128 v[210:213], v167 offset:13312
	ds_read_b128 v[220:223], v167 offset:14336
	ds_read_b128 v[224:227], v167 offset:15360
	v_max3_f32 v126, v54, v55, v56
	v_max3_f32 v126, v126, v57, v58
	v_max3_f32 v126, v126, v59, v60
	v_max3_f32 v126, v126, v61, v62
	v_max3_f32 v126, v126, v63, v64
	v_max3_f32 v126, v126, v65, v66
	v_max3_f32 v126, v126, v67, v68
	v_max3_f32 v126, v126, v69, v69
	s_cbranch_vccz .Ldma_mla1_skip1
	s_add_i32 m0, s101, 0x400
	s_add_u32 s0, s0, s2
	s_addc_u32 s1, s1, 0
	global_load_lds_dwordx4 v164, s[4:5]

.Lback_mla1_1:
	v_cvt_pk_u8_f32 v118, v54, 0, 0
	v_cvt_pk_u8_f32 v119, v58, 0, 0
	v_cvt_pk_u8_f32 v120, v62, 0, 0
	v_cvt_pk_u8_f32 v121, v66, 0, 0
	v_cvt_pk_u8_f32 v118, v55, 1, v118
	v_cvt_pk_u8_f32 v119, v59, 1, v119
	v_cvt_pk_u8_f32 v120, v63, 1, v120
	v_cvt_pk_u8_f32 v121, v67, 1, v121
	s_waitcnt lgkmcnt(4)
	v_mfma_f32_32x32x64_f8f6f4 v[86:101], v[190:197], v[138:145], v[34:49]
	v_cvt_pk_u8_f32 v118, v56, 2, v118
	v_cvt_pk_u8_f32 v119, v60, 2, v119
	v_cvt_pk_u8_f32 v120, v64, 2, v120
	v_cvt_pk_u8_f32 v121, v68, 2, v121
	v_cvt_pk_u8_f32 v118, v57, 3, v118
	v_cvt_pk_u8_f32 v119, v61, 3, v119
	v_cvt_pk_u8_f32 v120, v65, 3, v120
	v_cvt_pk_u8_f32 v121, v69, 3, v121
	v_mfma_f32_32x32x64_f8f6f4 v[86:101], v[198:205], v[146:153], v[86:101]
	v_cvt_pk_u8_f32 v122, v70, 0, 0
	v_cvt_pk_u8_f32 v123, v74, 0, 0
	v_cvt_pk_u8_f32 v124, v78, 0, 0
	v_cvt_pk_u8_f32 v125, v82, 0, 0
	v_cvt_pk_u8_f32 v122, v71, 1, v122
	v_cvt_pk_u8_f32 v123, v75, 1, v123
	v_cvt_pk_u8_f32 v124, v79, 1, v124
	v_cvt_pk_u8_f32 v125, v83, 1, v125
	v_mfma_f32_32x32x64_f8f6f4 v[102:117], v[206:213], v[138:145], v[34:49]
	v_cvt_pk_u8_f32 v122, v72, 2, v122
	v_cvt_pk_u8_f32 v123, v76, 2, v123
	v_cvt_pk_u8_f32 v124, v80, 2, v124
	v_cvt_pk_u8_f32 v125, v84, 2, v125
	v_cvt_pk_u8_f32 v122, v73, 3, v122
	v_cvt_pk_u8_f32 v123, v77, 3, v123
	v_cvt_pk_u8_f32 v124, v81, 3, v124
	v_cvt_pk_u8_f32 v125, v85, 3, v125
	v_mfma_f32_32x32x64_f8f6f4 v[102:117], v[220:227], v[146:153], v[102:117]
	s_nop 0
	s_waitcnt lgkmcnt(0)
	v_mfma_f32_32x32x64_f8f6f4 v[18:33], v[228:235], v[118:125], v[18:33] blgp:1
	ds_read_b128 v[190:193], v167 offset:24576
	ds_read_b128 v[194:197], v167 offset:25600
	ds_read_b128 v[198:201], v167 offset:26624
	ds_read_b128 v[202:205], v167 offset:27648
	s_cbranch_vccz .Ldma_mla1_skip2
	s_add_i32 m0, s101, 0x800
	s_add_u32 s4, s4, s33
	s_addc_u32 s5, s5, 0
	global_load_lds_dwordx4 v164, s[6:7]
.Ldma_mla1_skip2:
	v_mfma_f32_32x32x64_f8f6f4 v[2:17], v[236:243], v[118:125], v[2:17] blgp:1
	ds_read_b128 v[206:209], v167 offset:28672
	ds_read_b128 v[210:213], v167 offset:29696
	ds_read_b128 v[220:223], v167 offset:30720
	ds_read_b128 v[224:227], v167 offset:31744
	v_max3_f32 v126, v86, v87, v88
	v_max3_f32 v126, v126, v89, v90
	v_max3_f32 v126, v126, v91, v92
	v_max3_f32 v126, v126, v93, v94
	v_max3_f32 v126, v126, v95, v96
	v_max3_f32 v126, v126, v97, v98
	v_max3_f32 v126, v126, v99, v100
	v_max3_f32 v126, v126, v101, v101
	s_cbranch_vccz .Ldma_mla1_skip3
	s_add_i32 m0, s101, 0x6000
	s_add_u32 s6, s6, s50
	s_addc_u32 s7, s7, 0
	global_load_lds_dwordx4 v164, s[8:9]

.Lback_mla1_2:
	v_cvt_pk_u8_f32 v118, v86, 0, 0
	v_cvt_pk_u8_f32 v119, v90, 0, 0
	v_cvt_pk_u8_f32 v120, v94, 0, 0
	v_cvt_pk_u8_f32 v121, v98, 0, 0
	v_cvt_pk_u8_f32 v118, v87, 1, v118
	v_cvt_pk_u8_f32 v119, v91, 1, v119
	v_cvt_pk_u8_f32 v120, v95, 1, v120
	v_cvt_pk_u8_f32 v121, v99, 1, v121
	s_waitcnt lgkmcnt(4)
	v_mfma_f32_32x32x64_f8f6f4 v[54:69], v[190:197], v[138:145], v[34:49]
	v_cvt_pk_u8_f32 v118, v88, 2, v118
	v_cvt_pk_u8_f32 v119, v92, 2, v119
	v_cvt_pk_u8_f32 v120, v96, 2, v120
	v_cvt_pk_u8_f32 v121, v100, 2, v121
	v_cvt_pk_u8_f32 v118, v89, 3, v118
	v_cvt_pk_u8_f32 v119, v93, 3, v119
	v_cvt_pk_u8_f32 v120, v97, 3, v120
	v_cvt_pk_u8_f32 v121, v101, 3, v121
	v_mfma_f32_32x32x64_f8f6f4 v[54:69], v[198:205], v[146:153], v[54:69]
	v_cvt_pk_u8_f32 v122, v102, 0, 0
	v_cvt_pk_u8_f32 v123, v106, 0, 0
	v_cvt_pk_u8_f32 v124, v110, 0, 0
	v_cvt_pk_u8_f32 v125, v114, 0, 0
	v_cvt_pk_u8_f32 v122, v103, 1, v122
	v_cvt_pk_u8_f32 v123, v107, 1, v123
	v_cvt_pk_u8_f32 v124, v111, 1, v124
	v_cvt_pk_u8_f32 v125, v115, 1, v125
	v_mfma_f32_32x32x64_f8f6f4 v[70:85], v[206:213], v[138:145], v[34:49]
	v_cvt_pk_u8_f32 v122, v104, 2, v122
	v_cvt_pk_u8_f32 v123, v108, 2, v123
	v_cvt_pk_u8_f32 v124, v112, 2, v124
	v_cvt_pk_u8_f32 v125, v116, 2, v125
	v_cvt_pk_u8_f32 v122, v105, 3, v122
	v_cvt_pk_u8_f32 v123, v109, 3, v123
	v_cvt_pk_u8_f32 v124, v113, 3, v124
	v_cvt_pk_u8_f32 v125, v117, 3, v125
	v_mfma_f32_32x32x64_f8f6f4 v[70:85], v[220:227], v[146:153], v[70:85]
	s_nop 0
	s_waitcnt lgkmcnt(0)
	v_mfma_f32_32x32x64_f8f6f4 v[18:33], v[228:235], v[118:125], v[18:33] blgp:1
	ds_read_b128 v[190:193], v167 offset:32768
	ds_read_b128 v[194:197], v167 offset:33792
	ds_read_b128 v[198:201], v167 offset:34816
	ds_read_b128 v[202:205], v167 offset:35840
	s_cbranch_vccz .Ldma_mla1_skip4
	s_add_i32 m0, s101, 0x6400
	s_add_u32 s8, s8, s2
	s_addc_u32 s9, s9, 0
	global_load_lds_dwordx4 v164, s[10:11]
.Ldma_mla1_skip4:
	v_mfma_f32_32x32x64_f8f6f4 v[2:17], v[236:243], v[118:125], v[2:17] blgp:1
	ds_read_b128 v[206:209], v167 offset:36864
	ds_read_b128 v[210:213], v167 offset:37888
	ds_read_b128 v[220:223], v167 offset:38912
	ds_read_b128 v[224:227], v167 offset:39936
	v_max3_f32 v126, v54, v55, v56
	v_max3_f32 v126, v126, v57, v58
	v_max3_f32 v126, v126, v59, v60
	v_max3_f32 v126, v126, v61, v62
	v_max3_f32 v126, v126, v63, v64
	v_max3_f32 v126, v126, v65, v66
	v_max3_f32 v126, v126, v67, v68
	v_max3_f32 v126, v126, v69, v69
	s_cbranch_vccz .Ldma_mla1_skip5
	s_add_i32 m0, s101, 0x6800
	s_add_u32 s10, s10, s33
	s_addc_u32 s11, s11, 0
	global_load_lds_dwordx4 v164, s[68:69]
	s_add_u32 s68, s68, s50
	s_addc_u32 s69, s69, 0

.LBB0_4066:
	s_lshr_b32 s0, s34, 3
	s_and_b32 s1, s34, 7
	s_mulk_i32 s0, 0x4100
	v_add_u32_e32 v2, s0, v188
	s_lshl_b32 s18, s1, 7
	s_lshl_b32 s12, s1, 2
	s_mul_i32 s1, s34, 0x208000
	v_ashrrev_i32_e32 v3, 31, v2
	s_mul_hi_i32 s0, s34, 0x208000
	s_add_u32 s35, s22, s1
	v_lshlrev_b64 v[6:7], 5, v[2:3]
	s_addc_u32 s36, s23, s0
	s_mul_i32 s1, s34, 0x104000
	v_lshl_add_u64 v[6:7], s[16:17], 0, v[6:7]
	s_mov_b32 s13, s19
	s_mul_hi_i32 s0, s34, 0x104000
	s_add_u32 s37, s24, s1
	v_lshl_add_u64 v[6:7], v[6:7], 0, s[12:13]
	s_addc_u32 s38, s25, s0
	s_add_i32 s12, s34, 32
	s_ashr_i32 s13, s12, 31
	s_lshl_b64 s[12:13], s[12:13], 2
	s_add_u32 s12, s3, s12
	s_addc_u32 s13, s30, s13
	global_load_dword v6, v[6:7], off
	v_lshlrev_b64 v[4:5], 10, v[2:3]
	global_load_dword v7, v179, s[12:13]
	v_lshl_add_u64 v[4:5], s[14:15], 0, v[4:5]
	v_lshl_add_u64 v[4:5], v[4:5], 0, s[18:19]
	v_mad_i64_i32 v[2:3], s[12:13], v2, s26, v[182:183]
	v_lshl_add_u64 v[186:187], v[2:3], 0, s[18:19]
	v_lshl_add_u64 v[2:3], v[4:5], 0, v[178:179]
	global_load_dwordx4 v[126:129], v[2:3], off offset:16
	global_load_dwordx4 v[122:125], v[2:3], off
	global_load_dwordx4 v[134:137], v[2:3], off offset:80
	global_load_dwordx4 v[130:133], v[2:3], off offset:64
	v_readfirstlane_b32 s0, v1
	s_ashr_i32 s0, s0, 6
	s_mul_i32 s1, s0, 0xc00
	s_add_i32 s2, s1, 0xffffc000
	s_add_u32 s4, s37, s2
	s_addc_u32 s5, s38, 0
	s_ashr_i32 s6, s1, 31
	s_add_u32 s7, s35, s1
	s_addc_u32 s8, s36, s6
	s_add_i32 s9, s1, 0x400
	s_ashr_i32 s10, s9, 31
	v_mov_b32 v114, 0x38383838
	v_mov_b32 v115, 0x38383838
	v_mov_b32 v116, 0x38383838
	v_mov_b32 v117, 0x38383838
	v_mov_b32 v118, 0x38383838
	v_mov_b32 v119, 0x38383838
	v_mov_b32 v120, 0x38383838
	v_mov_b32 v121, 0x38383838
	s_waitcnt vmcnt(0)
	v_cmp_gt_f32_e32 vcc, s27, v7
	v_mul_f32_e32 v2, 0x4f800000, v7
	s_nop 0
	v_cndmask_b32_e32 v2, v7, v2, vcc
	v_sqrt_f32_e32 v3, v2
	s_nop 0
	v_add_u32_e32 v4, -1, v3
	v_fma_f32 v5, -v4, v3, v2
	v_cmp_ge_f32_e64 s[12:13], 0, v5
	v_add_u32_e32 v5, 1, v3
	s_nop 0
	v_cndmask_b32_e64 v4, v3, v4, s[12:13]
	v_fma_f32 v3, -v5, v3, v2
	v_cmp_lt_f32_e64 s[12:13], 0, v3
	s_nop 1
	v_cndmask_b32_e64 v3, v4, v5, s[12:13]
	s_add_i32 s12, s1, 0
	s_add_u32 s11, s7, 0x400
	s_addc_u32 s13, s8, 0
	s_add_i32 s18, s1, 0xffffc400
	s_add_u32 s33, s37, s18
	s_addc_u32 s39, s38, 0
	s_add_i32 s41, s1, 0x800
	s_add_i32 s40, s12, 0x400
	s_ashr_i32 s42, s41, 31
	s_add_u32 s43, s7, 0x800
	s_addc_u32 s44, s8, 0
	s_add_i32 s45, s1, 0xffffc800
	s_add_u32 s46, s37, s45
	s_addc_u32 s47, s38, 0
	s_add_i32 s48, s12, 0x800
	s_add_u32 s49, s37, 0x2000
	s_addc_u32 s38, s38, 0
	s_add_u32 s35, s35, 0x4000
	s_addc_u32 s50, s36, 0
	s_add_u32 s1, s35, s1
	s_addc_u32 s6, s50, s6
	s_add_u32 s2, s49, s2
	v_mul_f32_e32 v4, 0x37800000, v3
	s_addc_u32 s51, s38, 0
	v_cndmask_b32_e32 v3, v3, v4, vcc
	v_cmp_class_f32_e32 vcc, v2, v190
	s_cmp_lt_i32 s0, 6
	s_cselect_b32 s37, s8, s5
	v_cndmask_b32_e32 v2, v3, v2, vcc
	s_cselect_b32 s36, s7, s4
	v_mul_f32_e32 v4, v6, v2
	v_lshl_add_u64 v[2:3], s[36:37], 0, v[180:181]
	s_cselect_b32 s36, s1, s2
	s_cselect_b32 s37, s6, s51
	s_add_i32 s1, s12, 0x6000
	s_add_u32 s2, s35, s9
	s_addc_u32 s4, s50, s10
	s_add_u32 s5, s49, s18
	s_addc_u32 s6, s38, 0
	s_add_i32 s7, s12, 0x6400
	s_add_u32 s8, s35, s41
	s_addc_u32 s9, s50, s42
	s_add_u32 s10, s49, s45
	s_addc_u32 s18, s38, 0
	s_cmp_lt_i32 s0, 5
	s_mov_b32 m0, s12
	s_cselect_b32 s39, s13, s39
	s_cselect_b32 s38, s11, s33
	global_load_lds_dwordx4 v[2:3], off
	v_lshl_add_u64 v[2:3], s[38:39], 0, v[180:181]
	s_mov_b32 m0, s40
	s_cselect_b32 s39, s44, s47
	s_cselect_b32 s38, s43, s46
	global_load_lds_dwordx4 v[2:3], off
	v_lshl_add_u64 v[2:3], s[38:39], 0, v[180:181]
	s_mov_b32 m0, s48
	v_fmamk_f32 v26, v4, 0x3f90a3d7, v191
	global_load_lds_dwordx4 v[2:3], off
	v_lshl_add_u64 v[2:3], s[36:37], 0, v[180:181]
	s_mov_b32 m0, s1
	s_cselect_b32 s37, s4, s6
	s_cselect_b32 s36, s2, s5
	global_load_lds_dwordx4 v[2:3], off
	v_lshl_add_u64 v[2:3], s[36:37], 0, v[180:181]
	s_mov_b32 m0, s7
	s_cselect_b32 s37, s9, s18
	s_cselect_b32 s36, s8, s10
	global_load_lds_dwordx4 v[2:3], off
	v_lshl_add_u64 v[2:3], s[36:37], 0, v[180:181]
	s_add_i32 m0, s12, 0x6800
	v_cmp_lt_i32_e32 vcc, v194, v195
	global_load_lds_dwordx4 v[2:3], off
	s_waitcnt vmcnt(3)
	s_barrier
	ds_read_b128 v[2:5], v189
	ds_read_b128 v[6:9], v189 offset:1024
	s_waitcnt lgkmcnt(0)
	v_mfma_f32_32x32x64_f8f6f4 v[2:17], v[2:9], v[122:129], 0
	ds_read_b128 v[18:21], v189 offset:2048
	ds_read_b128 v[22:25], v189 offset:3072
	s_add_i32 s34, s34, s52
	s_waitcnt lgkmcnt(0)
	v_mfma_f32_32x32x64_f8f6f4 v[2:17], v[18:25], v[130:137], v[2:17]
	s_nop 15
	s_nop 3
	v_max3_f32 v2, v2, s28, v3
	v_max3_f32 v2, v2, v4, v5
	v_max3_f32 v2, v2, v6, v7
	v_max3_f32 v2, v2, v8, v9
	v_max3_f32 v2, v2, v10, v11
	v_max3_f32 v2, v2, v12, v13
	v_max3_f32 v2, v2, v14, v15
	v_max3_f32 v27, v2, v16, v17
	ds_read_b128 v[2:5], v189 offset:4096
	ds_read_b128 v[6:9], v189 offset:5120
	s_waitcnt lgkmcnt(0)
	v_mfma_f32_32x32x64_f8f6f4 v[2:17], v[2:9], v[122:129], 0
	ds_read_b128 v[18:21], v189 offset:6144
	ds_read_b128 v[22:25], v189 offset:7168
	s_waitcnt lgkmcnt(0)
	v_mfma_f32_32x32x64_f8f6f4 v[2:17], v[18:25], v[130:137], v[2:17]
	s_nop 15
	s_nop 3
	v_max3_f32 v2, v27, v2, v3
	v_max3_f32 v2, v2, v4, v5
	v_max3_f32 v2, v2, v6, v7
	v_max3_f32 v2, v2, v8, v9
	v_max3_f32 v2, v2, v10, v11
	v_max3_f32 v2, v2, v12, v13
	v_max3_f32 v2, v2, v14, v15
	v_max3_f32 v27, v2, v16, v17
	ds_read_b128 v[2:5], v189 offset:8192
	ds_read_b128 v[6:9], v189 offset:9216
	s_waitcnt lgkmcnt(0)
	v_mfma_f32_32x32x64_f8f6f4 v[2:17], v[2:9], v[122:129], 0
	ds_read_b128 v[18:21], v189 offset:10240
	ds_read_b128 v[22:25], v189 offset:11264
	s_waitcnt lgkmcnt(0)
	v_mfma_f32_32x32x64_f8f6f4 v[2:17], v[18:25], v[130:137], v[2:17]
	s_nop 15
	s_nop 3
	v_max3_f32 v2, v27, v2, v3
	v_max3_f32 v2, v2, v4, v5
	v_max3_f32 v2, v2, v6, v7
	v_max3_f32 v2, v2, v8, v9
	v_max3_f32 v2, v2, v10, v11
	v_max3_f32 v2, v2, v12, v13
	v_max3_f32 v2, v2, v14, v15
	v_max3_f32 v27, v2, v16, v17
	ds_read_b128 v[2:5], v189 offset:12288
	ds_read_b128 v[6:9], v189 offset:13312
	s_waitcnt lgkmcnt(0)
	v_mfma_f32_32x32x64_f8f6f4 v[2:17], v[2:9], v[122:129], 0
	ds_read_b128 v[18:21], v189 offset:14336
	ds_read_b128 v[22:25], v189 offset:15360
	s_waitcnt vmcnt(0)
	s_barrier
	s_waitcnt lgkmcnt(0)
	v_mfma_f32_32x32x64_f8f6f4 v[2:17], v[18:25], v[130:137], v[2:17]
	ds_read_b128 v[34:37], v189
	ds_read_b128 v[38:41], v189 offset:1024
	ds_read_b128 v[50:53], v189 offset:2048
	ds_read_b128 v[54:57], v189 offset:3072
	ds_read_b128 v[18:21], v189 offset:4096
	ds_read_b128 v[22:25], v189 offset:5120
	ds_read_b128 v[42:45], v189 offset:6144
	ds_read_b128 v[46:49], v189 offset:7168
	ds_read_b128 v[82:85], v189 offset:16384
	ds_read_b128 v[86:89], v189 offset:17408
	ds_read_b128 v[90:93], v189 offset:18432
	ds_read_b128 v[94:97], v189 offset:19456
	s_nop 7
	v_max3_f32 v2, v27, v2, v3
	v_max3_f32 v2, v2, v4, v5
	v_max3_f32 v2, v2, v6, v7
	v_max3_f32 v2, v2, v8, v9
	v_max3_f32 v2, v2, v10, v11
	v_max3_f32 v2, v2, v12, v13
	v_max3_f32 v2, v2, v14, v15
	v_cndmask_b32_e32 v3, v193, v194, vcc
	v_max3_f32 v2, v2, v16, v17
	v_lshlrev_b32_e32 v3, 2, v3
	ds_bpermute_b32 v3, v3, v2
	s_waitcnt lgkmcnt(0)
	v_max_f32_e32 v3, v3, v3
	v_max_f32_e32 v2, v2, v3
	v_add_f32_e32 v2, 0x42800000, v2
	v_min_f32_e32 v2, v26, v2
	v_add_f32_e32 v2, 0xc2ec0000, v2
	v_xor_b32_e32 v2, 0x80000000, v2
	v_mov_b32_e32 v3, v2
	v_mov_b32_e32 v4, v2
	v_mov_b32_e32 v5, v2
	v_mov_b32_e32 v6, v2
	v_mov_b32_e32 v7, v2
	v_mov_b32_e32 v8, v2
	v_mov_b32_e32 v9, v2
	v_mov_b32_e32 v10, v2
	v_mov_b32_e32 v11, v2
	v_mov_b32_e32 v12, v2
	v_mov_b32_e32 v13, v2
	v_mov_b32_e32 v14, v2
	v_mov_b32_e32 v15, v2
	v_mov_b32_e32 v16, v2
	v_mov_b32_e32 v17, v2
	s_nop 1
	v_mfma_f32_32x32x64_f8f6f4 v[18:33], v[18:25], v[122:129], v[2:17]
	ds_read_b128 v[66:69], v189 offset:8192
	ds_read_b128 v[70:73], v189 offset:9216
	ds_read_b128 v[98:101], v189 offset:10240
	ds_read_b128 v[102:105], v189 offset:11264
	ds_read_b128 v[58:61], v189 offset:12288
	ds_read_b128 v[62:65], v189 offset:13312
	ds_read_b128 v[74:77], v189 offset:14336
	ds_read_b128 v[78:81], v189 offset:15360
	v_mfma_f32_32x32x64_f8f6f4 v[18:33], v[42:49], v[130:137], v[18:33]
	v_mfma_f32_32x32x64_f8f6f4 v[34:49], v[34:41], v[122:129], v[2:17]
	s_nop 15
	s_nop 2
	v_med3_f32 v18, v18, 0, v196
	v_med3_f32 v19, v19, 0, v196
	v_cvt_pk_u8_f32 v18, v18, 0, 0
	v_med3_f32 v20, v20, 0, v196
	v_cvt_pk_u8_f32 v18, v19, 1, v18
	v_med3_f32 v21, v21, 0, v196
	v_cvt_pk_u8_f32 v18, v20, 2, v18
	v_cvt_pk_u8_f32 v166, v21, 3, v18
	v_med3_f32 v21, v22, 0, v196
	v_med3_f32 v20, v23, 0, v196
	v_cvt_pk_u8_f32 v21, v21, 0, 0
	v_med3_f32 v19, v24, 0, v196
	v_cvt_pk_u8_f32 v20, v20, 1, v21
	v_med3_f32 v21, v26, 0, v196
	v_mfma_f32_32x32x64_f8f6f4 v[34:49], v[50:57], v[130:137], v[34:49]
	v_med3_f32 v18, v25, 0, v196
	v_cvt_pk_u8_f32 v19, v19, 2, v20
	v_med3_f32 v20, v27, 0, v196
	v_cvt_pk_u8_f32 v21, v21, 0, 0
	v_cvt_pk_u8_f32 v167, v18, 3, v19
	v_med3_f32 v19, v28, 0, v196
	v_cvt_pk_u8_f32 v20, v20, 1, v21
	v_med3_f32 v21, v30, 0, v196
	v_med3_f32 v18, v29, 0, v196
	v_cvt_pk_u8_f32 v19, v19, 2, v20
	v_med3_f32 v20, v31, 0, v196
	v_cvt_pk_u8_f32 v21, v21, 0, 0
	v_cvt_pk_u8_f32 v168, v18, 3, v19
	v_med3_f32 v19, v32, 0, v196
	v_cvt_pk_u8_f32 v20, v20, 1, v21
	s_waitcnt lgkmcnt(0)
	v_mfma_f32_32x32x64_f8f6f4 v[50:65], v[58:65], v[122:129], v[2:17]
	ds_read_b128 v[138:141], v189 offset:20480
	ds_read_b128 v[142:145], v189 offset:21504
	ds_read_b128 v[146:149], v189 offset:22528
	ds_read_b128 v[150:153], v189 offset:23552
	v_med3_f32 v34, v34, 0, v196
	v_med3_f32 v35, v35, 0, v196
	v_cvt_pk_u8_f32 v34, v34, 0, 0
	v_med3_f32 v36, v36, 0, v196
	v_cvt_pk_u8_f32 v34, v35, 1, v34
	v_med3_f32 v37, v37, 0, v196
	v_cvt_pk_u8_f32 v34, v36, 2, v34
	v_cvt_pk_u8_f32 v162, v37, 3, v34
	v_med3_f32 v37, v38, 0, v196
	v_med3_f32 v36, v39, 0, v196
	v_cvt_pk_u8_f32 v37, v37, 0, 0
	v_med3_f32 v35, v40, 0, v196
	v_cvt_pk_u8_f32 v36, v36, 1, v37
	v_med3_f32 v37, v42, 0, v196
	v_mfma_f32_32x32x64_f8f6f4 v[50:65], v[74:81], v[130:137], v[50:65]
	v_med3_f32 v34, v41, 0, v196
	v_cvt_pk_u8_f32 v35, v35, 2, v36
	v_med3_f32 v36, v43, 0, v196
	v_cvt_pk_u8_f32 v37, v37, 0, 0
	v_cvt_pk_u8_f32 v163, v34, 3, v35
	v_med3_f32 v35, v44, 0, v196
	v_cvt_pk_u8_f32 v36, v36, 1, v37
	v_med3_f32 v37, v46, 0, v196
	v_med3_f32 v34, v45, 0, v196
	v_cvt_pk_u8_f32 v35, v35, 2, v36
	v_med3_f32 v36, v47, 0, v196
	v_cvt_pk_u8_f32 v37, v37, 0, 0
	v_cvt_pk_u8_f32 v164, v34, 3, v35
	v_med3_f32 v35, v48, 0, v196
	v_cvt_pk_u8_f32 v36, v36, 1, v37
	v_mfma_f32_32x32x64_f8f6f4 v[66:81], v[66:73], v[122:129], v[2:17]
	v_med3_f32 v34, v49, 0, v196
	v_cvt_pk_u8_f32 v35, v35, 2, v36
	v_med3_f32 v18, v33, 0, v196
	v_cvt_pk_u8_f32 v19, v19, 2, v20
	v_cvt_pk_u8_f32 v165, v34, 3, v35
	v_cvt_pk_u8_f32 v169, v18, 3, v19
	v_med3_f32 v50, v50, 0, v196
	v_med3_f32 v51, v51, 0, v196
	v_cvt_pk_u8_f32 v50, v50, 0, 0
	v_med3_f32 v52, v52, 0, v196
	v_cvt_pk_u8_f32 v50, v51, 1, v50
	v_med3_f32 v53, v53, 0, v196
	v_cvt_pk_u8_f32 v50, v52, 2, v50
	v_cvt_pk_u8_f32 v158, v53, 3, v50
	v_mfma_f32_32x32x64_f8f6f4 v[66:81], v[98:105], v[130:137], v[66:81]
	v_med3_f32 v53, v54, 0, v196
	v_med3_f32 v52, v55, 0, v196
	v_cvt_pk_u8_f32 v53, v53, 0, 0
	v_med3_f32 v51, v56, 0, v196
	v_cvt_pk_u8_f32 v52, v52, 1, v53
	v_med3_f32 v53, v58, 0, v196
	v_med3_f32 v50, v57, 0, v196
	v_cvt_pk_u8_f32 v51, v51, 2, v52
	v_med3_f32 v52, v59, 0, v196
	v_cvt_pk_u8_f32 v53, v53, 0, 0
	v_cvt_pk_u8_f32 v159, v50, 3, v51
	v_med3_f32 v51, v60, 0, v196
	v_cvt_pk_u8_f32 v52, v52, 1, v53
	v_med3_f32 v53, v62, 0, v196
	v_med3_f32 v50, v61, 0, v196
	v_mfma_f32_32x32x64_f8f6f4 v[34:49], v[82:89], v[162:169], 0 blgp:1
	ds_read_b128 v[98:101], v189 offset:24576
	ds_read_b128 v[102:105], v189 offset:25600
	ds_read_b128 v[170:173], v189 offset:26624
	ds_read_b128 v[174:177], v189 offset:27648
	ds_read_b128 v[82:85], v189 offset:28672
	ds_read_b128 v[86:89], v189 offset:29696
	ds_read_b128 v[106:109], v189 offset:30720
	ds_read_b128 v[110:113], v189 offset:31744
	v_med3_f32 v66, v66, 0, v196
	v_med3_f32 v67, v67, 0, v196
	v_cvt_pk_u8_f32 v66, v66, 0, 0
	v_med3_f32 v68, v68, 0, v196
	v_cvt_pk_u8_f32 v66, v67, 1, v66
	v_med3_f32 v69, v69, 0, v196
	v_cvt_pk_u8_f32 v66, v68, 2, v66
	v_cvt_pk_u8_f32 v154, v69, 3, v66
	v_med3_f32 v69, v70, 0, v196
	v_med3_f32 v68, v71, 0, v196
	v_cvt_pk_u8_f32 v69, v69, 0, 0
	v_med3_f32 v67, v72, 0, v196
	v_cvt_pk_u8_f32 v68, v68, 1, v69
	v_mfma_f32_32x32x64_f8f6f4 v[18:33], v[90:97], v[162:169], 0 blgp:1
	v_med3_f32 v69, v74, 0, v196
	v_med3_f32 v66, v73, 0, v196
	v_cvt_pk_u8_f32 v67, v67, 2, v68
	v_med3_f32 v68, v75, 0, v196
	v_cvt_pk_u8_f32 v69, v69, 0, 0
	v_cvt_pk_u8_f32 v155, v66, 3, v67
	v_med3_f32 v67, v76, 0, v196
	v_cvt_pk_u8_f32 v68, v68, 1, v69
	v_med3_f32 v69, v78, 0, v196
	v_med3_f32 v66, v77, 0, v196
	v_cvt_pk_u8_f32 v67, v67, 2, v68
	v_med3_f32 v68, v79, 0, v196
	v_cvt_pk_u8_f32 v69, v69, 0, 0
	v_cvt_pk_u8_f32 v51, v51, 2, v52
	v_med3_f32 v52, v63, 0, v196
	s_waitcnt lgkmcnt(0)
	v_mfma_f32_32x32x64_f8f6f4 v[82:97], v[82:89], v[122:129], v[2:17]
	v_cvt_pk_u8_f32 v53, v53, 0, 0
	v_cvt_pk_u8_f32 v156, v66, 3, v67
	v_med3_f32 v67, v80, 0, v196
	v_cvt_pk_u8_f32 v68, v68, 1, v69
	v_cvt_pk_u8_f32 v160, v50, 3, v51
	v_med3_f32 v51, v64, 0, v196
	v_cvt_pk_u8_f32 v52, v52, 1, v53
	v_med3_f32 v66, v81, 0, v196
	v_cvt_pk_u8_f32 v67, v67, 2, v68
	v_med3_f32 v50, v65, 0, v196
	v_cvt_pk_u8_f32 v51, v51, 2, v52
	v_cvt_pk_u8_f32 v157, v66, 3, v67
	v_cvt_pk_u8_f32 v161, v50, 3, v51
	v_mfma_f32_32x32x64_f8f6f4 v[82:97], v[106:113], v[130:137], v[82:97]
	v_mfma_f32_32x32x64_f8f6f4 v[98:113], v[98:105], v[122:129], v[2:17]
	s_nop 15
	s_nop 2
	v_med3_f32 v82, v82, 0, v196
	v_med3_f32 v83, v83, 0, v196
	v_cvt_pk_u8_f32 v82, v82, 0, 0
	v_med3_f32 v84, v84, 0, v196
	v_cvt_pk_u8_f32 v82, v83, 1, v82
	v_med3_f32 v85, v85, 0, v196
	v_cvt_pk_u8_f32 v82, v84, 2, v82
	v_med3_f32 v84, v87, 0, v196
	v_med3_f32 v83, v88, 0, v196
	v_mfma_f32_32x32x64_f8f6f4 v[98:113], v[170:177], v[130:137], v[98:113]
	v_mfma_f32_32x32x64_f8f6f4 v[50:65], v[114:121], v[162:169], 0 blgp:1
	s_nop 15
	s_nop 2
	v_med3_f32 v98, v98, 0, v196
	v_med3_f32 v99, v99, 0, v196
	v_cvt_pk_u8_f32 v98, v98, 0, 0
	v_med3_f32 v100, v100, 0, v196
	v_cvt_pk_u8_f32 v98, v99, 1, v98
	v_med3_f32 v101, v101, 0, v196
	v_cvt_pk_u8_f32 v98, v100, 2, v98
	v_med3_f32 v102, v102, 0, v196
	v_cvt_pk_u8_f32 v98, v101, 3, v98
	v_med3_f32 v101, v103, 0, v196
	v_cvt_pk_u8_f32 v102, v102, 0, 0
	v_med3_f32 v103, v106, 0, v196
	v_med3_f32 v100, v104, 0, v196
	v_cvt_pk_u8_f32 v101, v101, 1, v102
	v_med3_f32 v102, v107, 0, v196
	v_mfma_f32_32x32x64_f8f6f4 v[34:49], v[138:145], v[154:161], v[34:49] blgp:1
	v_cvt_pk_u8_f32 v103, v103, 0, 0
	v_med3_f32 v104, v110, 0, v196
	v_med3_f32 v99, v105, 0, v196
	v_cvt_pk_u8_f32 v100, v100, 2, v101
	v_med3_f32 v101, v108, 0, v196
	v_cvt_pk_u8_f32 v102, v102, 1, v103
	v_med3_f32 v103, v111, 0, v196
	v_cvt_pk_u8_f32 v104, v104, 0, 0
	v_cvt_pk_u8_f32 v99, v99, 3, v100
	v_med3_f32 v100, v109, 0, v196
	v_cvt_pk_u8_f32 v101, v101, 2, v102
	v_med3_f32 v102, v112, 0, v196
	v_cvt_pk_u8_f32 v103, v103, 1, v104
	v_cvt_pk_u8_f32 v100, v100, 3, v101
	v_med3_f32 v101, v113, 0, v196
	v_mfma_f32_32x32x64_f8f6f4 v[18:33], v[146:153], v[154:161], v[18:33] blgp:1
	ds_read_b128 v[138:141], v189 offset:32768
	ds_read_b128 v[142:145], v189 offset:33792
	ds_read_b128 v[146:149], v189 offset:34816
	ds_read_b128 v[150:153], v189 offset:35840
	ds_read_b128 v[66:69], v189 offset:36864
	ds_read_b128 v[70:73], v189 offset:37888
	ds_read_b128 v[162:165], v189 offset:38912
	ds_read_b128 v[166:169], v189 offset:39936
	ds_read_b128 v[170:173], v189 offset:40960
	ds_read_b128 v[174:177], v189 offset:41984
	ds_read_b128 v[198:201], v189 offset:43008
	ds_read_b128 v[202:205], v189 offset:44032
	v_cvt_pk_u8_f32 v102, v102, 2, v103
	v_cvt_pk_u8_f32 v101, v101, 3, v102
	v_cvt_pk_u8_f32 v102, v85, 3, v82
	v_med3_f32 v85, v86, 0, v196
	v_cvt_pk_u8_f32 v85, v85, 0, 0
	v_cvt_pk_u8_f32 v84, v84, 1, v85
	v_med3_f32 v85, v90, 0, v196
	v_med3_f32 v82, v89, 0, v196
	v_cvt_pk_u8_f32 v83, v83, 2, v84
	v_med3_f32 v84, v91, 0, v196
	v_cvt_pk_u8_f32 v85, v85, 0, 0
	v_cvt_pk_u8_f32 v103, v82, 3, v83
	v_med3_f32 v83, v92, 0, v196
	s_waitcnt lgkmcnt(0)
	v_mfma_f32_32x32x64_f8f6f4 v[66:81], v[66:73], v[122:129], v[2:17]
	v_cvt_pk_u8_f32 v84, v84, 1, v85
	v_med3_f32 v85, v94, 0, v196
	v_med3_f32 v82, v93, 0, v196
	v_cvt_pk_u8_f32 v83, v83, 2, v84
	v_med3_f32 v84, v95, 0, v196
	v_cvt_pk_u8_f32 v85, v85, 0, 0
	v_cvt_pk_u8_f32 v104, v82, 3, v83
	v_med3_f32 v83, v96, 0, v196
	v_cvt_pk_u8_f32 v84, v84, 1, v85
	v_med3_f32 v82, v97, 0, v196
	v_cvt_pk_u8_f32 v83, v83, 2, v84
	v_cvt_pk_u8_f32 v105, v82, 3, v83
	ds_read_b128 v[90:93], v189 offset:45056
	ds_read_b128 v[94:97], v189 offset:46080
	ds_read_b128 v[82:85], v189 offset:47104
	ds_read_b128 v[86:89], v189 offset:48128
	v_mfma_f32_32x32x64_f8f6f4 v[2:17], v[138:145], v[122:129], v[2:17]
	v_mfma_f32_32x32x64_f8f6f4 v[50:65], v[114:121], v[154:161], v[50:65] blgp:1
	v_mfma_f32_32x32x64_f8f6f4 v[2:17], v[146:153], v[130:137], v[2:17]
	v_mfma_f32_32x32x64_f8f6f4 v[66:81], v[162:169], v[130:137], v[66:81]
	s_nop 15
	s_nop 2
	v_med3_f32 v2, v2, 0, v196
	v_med3_f32 v3, v3, 0, v196
	v_cvt_pk_u8_f32 v2, v2, 0, 0
	v_med3_f32 v4, v4, 0, v196
	v_cvt_pk_u8_f32 v2, v3, 1, v2
	v_med3_f32 v5, v5, 0, v196
	v_cvt_pk_u8_f32 v2, v4, 2, v2
	v_med3_f32 v6, v6, 0, v196
	v_cvt_pk_u8_f32 v2, v5, 3, v2
	v_med3_f32 v5, v7, 0, v196
	v_cvt_pk_u8_f32 v6, v6, 0, 0
	v_med3_f32 v7, v10, 0, v196
	v_med3_f32 v4, v8, 0, v196
	v_cvt_pk_u8_f32 v5, v5, 1, v6
	v_med3_f32 v6, v11, 0, v196
	v_mfma_f32_32x32x64_f8f6f4 v[50:65], v[114:121], v[98:105], v[50:65] blgp:1
	v_cvt_pk_u8_f32 v7, v7, 0, 0
	v_med3_f32 v8, v14, 0, v196
	v_med3_f32 v3, v9, 0, v196
	v_cvt_pk_u8_f32 v4, v4, 2, v5
	v_med3_f32 v5, v12, 0, v196
	v_cvt_pk_u8_f32 v6, v6, 1, v7
	v_med3_f32 v7, v15, 0, v196
	v_cvt_pk_u8_f32 v8, v8, 0, 0
	v_med3_f32 v9, v66, 0, v196
	v_cvt_pk_u8_f32 v3, v3, 3, v4
	v_med3_f32 v4, v13, 0, v196
	v_cvt_pk_u8_f32 v5, v5, 2, v6
	v_med3_f32 v6, v16, 0, v196
	v_cvt_pk_u8_f32 v7, v7, 1, v8
	v_med3_f32 v8, v67, 0, v196
	v_cvt_pk_u8_f32 v9, v9, 0, 0
	v_med3_f32 v10, v70, 0, v196
	v_cvt_pk_u8_f32 v4, v4, 3, v5
	v_med3_f32 v5, v17, 0, v196
	v_cvt_pk_u8_f32 v6, v6, 2, v7
	v_med3_f32 v7, v68, 0, v196
	v_cvt_pk_u8_f32 v8, v8, 1, v9
	v_med3_f32 v9, v71, 0, v196
	v_cvt_pk_u8_f32 v10, v10, 0, 0
	v_med3_f32 v11, v74, 0, v196
	v_cvt_pk_u8_f32 v5, v5, 3, v6
	v_med3_f32 v6, v69, 0, v196
	v_cvt_pk_u8_f32 v7, v7, 2, v8
	v_med3_f32 v8, v72, 0, v196
	v_cvt_pk_u8_f32 v9, v9, 1, v10
	v_med3_f32 v10, v75, 0, v196
	v_cvt_pk_u8_f32 v11, v11, 0, 0
	v_med3_f32 v12, v78, 0, v196
	v_cvt_pk_u8_f32 v6, v6, 3, v7
	v_med3_f32 v7, v73, 0, v196
	v_cvt_pk_u8_f32 v8, v8, 2, v9
	v_med3_f32 v9, v76, 0, v196
	v_cvt_pk_u8_f32 v10, v10, 1, v11
	v_med3_f32 v11, v79, 0, v196
	v_cvt_pk_u8_f32 v12, v12, 0, 0
	v_cvt_pk_u8_f32 v7, v7, 3, v8
	v_med3_f32 v8, v77, 0, v196
	v_cvt_pk_u8_f32 v9, v9, 2, v10
	v_med3_f32 v10, v80, 0, v196
	v_cvt_pk_u8_f32 v11, v11, 1, v12
	v_mfma_f32_32x32x64_f8f6f4 v[34:49], v[170:177], v[98:105], v[34:49] blgp:1
	v_cvt_pk_u8_f32 v8, v8, 3, v9
	v_med3_f32 v9, v81, 0, v196
	v_cvt_pk_u8_f32 v10, v10, 2, v11
	v_cvt_pk_u8_f32 v9, v9, 3, v10
	v_mfma_f32_32x32x64_f8f6f4 v[18:33], v[198:205], v[98:105], v[18:33] blgp:1
	s_nop 0
	v_mfma_f32_32x32x64_f8f6f4 v[50:65], v[114:121], v[2:9], v[50:65] blgp:1
	s_waitcnt lgkmcnt(0)
	v_mfma_f32_32x32x64_f8f6f4 v[34:49], v[90:97], v[2:9], v[34:49] blgp:1
	s_nop 15
	s_nop 1
	v_cmp_nlt_f32_e32 vcc, 0, v50
	v_cmp_ngt_f32_e64 s[12:13], s29, v50
	s_or_b64 s[12:13], vcc, s[12:13]
	s_cmp_gt_i32 s34, 15
	v_mfma_f32_32x32x64_f8f6f4 v[18:33], v[82:89], v[2:9], v[18:33] blgp:1
	v_div_scale_f32 v2, s[36:37], v50, v50, 1.0
	v_rcp_f32_e32 v3, v2
	s_nop 0
	v_fma_f32 v4, -v2, v3, 1.0
	v_fmac_f32_e32 v3, v4, v3
	v_div_scale_f32 v4, vcc, 1.0, v50, 1.0
	v_mul_f32_e32 v5, v4, v3
	v_fma_f32 v6, -v2, v5, v4
	v_fmac_f32_e32 v5, v6, v3
	v_fma_f32 v2, -v2, v5, v4
	v_div_fmas_f32 v2, v2, v3, v5
	v_div_fixup_f32 v2, v2, v50, 1.0
	v_cndmask_b32_e64 v4, v2, 0, s[12:13]
	v_lshl_add_u64 v[6:7], v[186:187], 0, v[184:185]
	v_lshl_add_u64 v[2:3], v[6:7], 0, s[20:21]
	v_pk_mul_f32 v[8:9], v[34:35], v[4:5] op_sel_hi:[1,0]
	v_pk_mul_f32 v[10:11], v[36:37], v[4:5] op_sel_hi:[1,0]
	v_add_co_u32_e32 v6, vcc, s31, v6
	v_cvt_pk_bf16_f32 v8, v8, v9
	v_cvt_pk_bf16_f32 v9, v10, v11
	v_addc_co_u32_e32 v7, vcc, 0, v7, vcc
	global_store_dwordx2 v[6:7], v[8:9], off offset:1280
	v_pk_mul_f32 v[6:7], v[38:39], v[4:5] op_sel_hi:[1,0]
	v_pk_mul_f32 v[8:9], v[40:41], v[4:5] op_sel_hi:[1,0]
	v_cvt_pk_bf16_f32 v6, v6, v7
	v_cvt_pk_bf16_f32 v7, v8, v9
	global_store_dwordx2 v[2:3], v[6:7], off offset:16
	v_pk_mul_f32 v[6:7], v[42:43], v[4:5] op_sel_hi:[1,0]
	v_pk_mul_f32 v[8:9], v[44:45], v[4:5] op_sel_hi:[1,0]
	v_cvt_pk_bf16_f32 v6, v6, v7
	v_cvt_pk_bf16_f32 v7, v8, v9
	global_store_dwordx2 v[2:3], v[6:7], off offset:32
	v_pk_mul_f32 v[6:7], v[46:47], v[4:5] op_sel_hi:[1,0]
	v_pk_mul_f32 v[8:9], v[48:49], v[4:5] op_sel_hi:[1,0]
	v_cvt_pk_bf16_f32 v6, v6, v7
	v_cvt_pk_bf16_f32 v7, v8, v9
	global_store_dwordx2 v[2:3], v[6:7], off offset:48
	v_pk_mul_f32 v[6:7], v[18:19], v[4:5] op_sel_hi:[1,0]
	v_pk_mul_f32 v[8:9], v[20:21], v[4:5] op_sel_hi:[1,0]
	v_cvt_pk_bf16_f32 v6, v6, v7
	v_cvt_pk_bf16_f32 v7, v8, v9
	global_store_dwordx2 v[2:3], v[6:7], off offset:64
	v_pk_mul_f32 v[6:7], v[22:23], v[4:5] op_sel_hi:[1,0]
	v_pk_mul_f32 v[8:9], v[24:25], v[4:5] op_sel_hi:[1,0]
	v_cvt_pk_bf16_f32 v6, v6, v7
	v_cvt_pk_bf16_f32 v7, v8, v9
	global_store_dwordx2 v[2:3], v[6:7], off offset:80
	v_pk_mul_f32 v[6:7], v[26:27], v[4:5] op_sel_hi:[1,0]
	v_pk_mul_f32 v[8:9], v[28:29], v[4:5] op_sel_hi:[1,0]
	v_cvt_pk_bf16_f32 v6, v6, v7
	v_cvt_pk_bf16_f32 v7, v8, v9
	global_store_dwordx2 v[2:3], v[6:7], off offset:96
	v_pk_mul_f32 v[6:7], v[30:31], v[4:5] op_sel_hi:[1,0]
	v_pk_mul_f32 v[4:5], v[32:33], v[4:5] op_sel_hi:[1,0]
	v_cvt_pk_bf16_f32 v6, v6, v7
	v_cvt_pk_bf16_f32 v7, v4, v5
	global_store_dwordx2 v[2:3], v[6:7], off offset:112
	s_barrier
	s_cbranch_scc0 .LBB0_4066

.LBB0_4070:
	s_lshl_b32 s4, s42, 5
	s_lshr_b32 s2, s42, 1
	s_and_b32 s4, s4, 32
	s_ashr_i32 s0, s12, 6
	s_and_b32 s1, s12, 63
	s_add_i32 s2, s2, s34
	s_add_i32 s4, s4, s31
	s_and_b64 s[12:13], s[18:19], exec
	s_cselect_b32 s0, s2, s0
	s_cselect_b32 s1, s4, s1
	s_ashr_i32 s2, s0, 3
	s_mul_i32 s4, s2, 0x4100
	s_lshl_b32 s1, s1, 8
	s_add_i32 s4, s4, s1
	v_add_u32_e32 v166, s4, v170
	v_ashrrev_i32_e32 v167, 31, v166
	s_and_b32 s43, s0, 7
	v_lshlrev_b64 v[2:3], 9, v[166:167]
	v_lshl_add_u64 v[2:3], s[20:21], 0, v[2:3]
	s_lshl_b32 s24, s43, 6
	v_lshl_add_u64 v[2:3], v[2:3], 0, s[24:25]
	s_lshl_b32 s24, s43, 2
	s_mul_i32 s44, s0, 0x104000
	s_mul_hi_i32 s45, s0, 0x104000
	s_add_u32 s1, s35, s44
	s_addc_u32 s4, s36, s45
	s_lshl_b32 s2, s2, 2
	s_bfe_u32 s5, s0, 0x20001
	s_or_b32 s52, s2, s5
	s_mul_hi_i32 s53, s52, 0x208000
	s_mul_i32 s52, s52, 0x208000
	s_add_u32 s2, s37, s52
	s_addc_u32 s5, s38, s53
	s_add_i32 s12, s0, 16
	s_ashr_i32 s13, s12, 31
	v_lshlrev_b64 v[4:5], 5, v[166:167]
	s_lshl_b64 s[12:13], s[12:13], 2
	v_lshl_add_u64 v[4:5], s[16:17], 0, v[4:5]
	s_add_u32 s12, s3, s12
	v_lshl_add_u64 v[4:5], v[4:5], 0, s[24:25]
	s_addc_u32 s13, s28, s13
	global_load_dword v42, v[4:5], off
	global_load_dword v18, v163, s[12:13]
	v_lshl_add_u64 v[2:3], v[2:3], 0, v[210:211]
	global_load_dwordx4 v[150:153], v[2:3], off offset:16
	global_load_dwordx4 v[146:149], v[2:3], off
	v_readfirstlane_b32 s0, v1
	s_ashr_i32 s0, s0, 6
	s_cmp_lt_i32 s0, 3
	s_mul_i32 s46, s0, 0xc00
	s_cselect_b64 s[14:15], -1, 0
	s_add_i32 s55, s46, 0xffffe000
	s_add_u32 s6, s2, s55
	s_addc_u32 s7, s5, 0
	s_ashr_i32 s47, s46, 31
	s_add_u32 s8, s1, s46
	s_addc_u32 s9, s4, s47
	s_and_b64 s[12:13], s[14:15], exec
	s_cselect_b32 s13, s9, s7
	s_cselect_b32 s12, s8, s6
	s_add_i32 s6, s46, 0x400
	s_add_i32 s24, s46, 0
	s_ashr_i32 s7, s6, 31
	s_add_u32 s10, s8, 0x400
	s_addc_u32 s11, s9, 0
	s_add_i32 s48, s46, 0xffffe400
	s_add_u32 s26, s2, s48
	s_addc_u32 s27, s5, 0
	v_lshl_add_u64 v[2:3], s[12:13], 0, v[164:165]
	s_mov_b32 m0, s24
	s_and_b64 s[12:13], s[14:15], exec
	v_lshrrev_b32 v154, 2, v0
	v_xor_b32 v154, v154, v0
	v_bfe_u32 v154, v154, 2, 1
	v_add_u32 v154, -1, v154
	v_and_b32 v154, 0x38383838, v154
	v_mov_b32 v155, v154
	v_mov_b32 v156, v154
	v_mov_b32 v157, v154
	v_mov_b32 v158, v154
	v_mov_b32 v159, v154
	v_mov_b32 v160, v154
	v_mov_b32 v161, v154
	global_load_lds_dwordx4 v[2:3], off
	s_cselect_b32 s13, s11, s27
	s_cselect_b32 s12, s10, s26
	s_add_i32 m0, s24, 0x400
	s_cmp_lt_i32 s0, 2
	s_cselect_b64 s[26:27], -1, 0
	s_add_i32 s0, s46, 0x800
	s_ashr_i32 s10, s0, 31
	s_add_u32 s8, s8, 0x800
	s_addc_u32 s9, s9, 0
	s_add_i32 s49, s46, 0xffffe800
	s_add_u32 s11, s2, s49
	s_addc_u32 s33, s5, 0
	v_lshl_add_u64 v[2:3], s[12:13], 0, v[164:165]
	s_and_b64 s[12:13], s[26:27], exec
	global_load_lds_dwordx4 v[2:3], off
	s_cselect_b32 s13, s9, s33
	s_cselect_b32 s12, s8, s11
	s_add_i32 m0, s24, 0x800
	s_add_u32 s2, s2, 0x4000
	s_addc_u32 s5, s5, 0
	s_add_u32 s1, s1, 0x2000
	s_addc_u32 s4, s4, 0
	s_add_u32 s8, s1, s46
	s_addc_u32 s9, s4, s47
	s_add_u32 s11, s2, s55
	s_addc_u32 s33, s5, 0
	v_lshl_add_u64 v[2:3], s[12:13], 0, v[164:165]
	s_and_b64 s[12:13], s[14:15], exec
	global_load_lds_dwordx4 v[2:3], off
	s_cselect_b32 s13, s9, s33
	s_cselect_b32 s12, s8, s11
	s_add_i32 m0, s24, 0x6000
	s_add_u32 s6, s1, s6
	s_addc_u32 s7, s4, s7
	s_add_u32 s8, s2, s48
	s_addc_u32 s9, s5, 0
	v_lshl_add_u64 v[2:3], s[12:13], 0, v[164:165]
	s_and_b64 s[12:13], s[14:15], exec
	global_load_lds_dwordx4 v[2:3], off
	s_cselect_b32 s13, s7, s9
	s_cselect_b32 s12, s6, s8
	s_add_i32 m0, s24, 0x6400
	s_add_u32 s0, s1, s0
	s_addc_u32 s1, s4, s10
	s_add_u32 s2, s2, s49
	s_addc_u32 s4, s5, 0
	v_lshl_add_u64 v[2:3], s[12:13], 0, v[164:165]
	s_and_b64 s[12:13], s[26:27], exec
	s_cselect_b32 s13, s1, s4
	s_cselect_b32 s12, s0, s2
	global_load_lds_dwordx4 v[2:3], off
	v_lshl_add_u64 v[2:3], s[12:13], 0, v[164:165]
	s_add_i32 m0, s24, 0x6800
	s_waitcnt vmcnt(0)
	v_mul_f32_e32 v19, 0x4f800000, v18
	global_load_lds_dwordx4 v[2:3], off
	s_waitcnt vmcnt(3)
	s_barrier
	ds_read_b128 v[2:5], v171
	ds_read_b128 v[6:9], v171 offset:1024
	v_cmp_gt_f32_e32 vcc, s39, v18
	s_waitcnt lgkmcnt(0)
	v_mfma_f32_32x32x64_f8f6f4 v[2:17], v[2:9], v[146:153], 0
	v_cndmask_b32_e32 v43, v18, v19, vcc
	v_sqrt_f32_e32 v26, v43
	ds_read_b128 v[18:21], v171 offset:2048
	ds_read_b128 v[22:25], v171 offset:3072
	s_add_u32 s44, s44, s46
	s_addc_u32 s45, s45, s47
	v_add_u32_e32 v27, -1, v26
	v_fma_f32 v28, -v27, v26, v43
	v_cmp_ge_f32_e64 s[12:13], 0, v28
	v_add_u32_e32 v28, 1, v26
	s_add_u32 s46, s52, s49
	v_cndmask_b32_e64 v27, v26, v27, s[12:13]
	v_fma_f32 v26, -v28, v26, v43
	v_cmp_lt_f32_e64 s[12:13], 0, v26
	s_addc_u32 s47, s53, 0
	s_add_u32 s48, s52, s48
	v_cndmask_b32_e64 v34, v27, v28, s[12:13]
	s_waitcnt lgkmcnt(0)
	v_mfma_f32_32x32x64_f8f6f4 v[18:33], v[18:25], v[146:153], 0
	v_max3_f32 v2, v2, s40, v3
	v_max3_f32 v2, v2, v4, v5
	v_max3_f32 v2, v2, v6, v7
	v_max3_f32 v2, v2, v8, v9
	v_mul_f32_e32 v35, 0x37800000, v34
	v_max3_f32 v2, v2, v10, v11
	v_cndmask_b32_e32 v44, v34, v35, vcc
	ds_read_b128 v[34:37], v171 offset:4096
	ds_read_b128 v[38:41], v171 offset:5120
	v_max3_f32 v2, v2, v12, v13
	v_max3_f32 v2, v2, v14, v15
	v_max3_f32 v2, v2, v16, v17
	v_cmp_lt_i32_e32 vcc, v176, v177
	s_addc_u32 s49, s53, 0
	s_add_u32 s52, s52, s55
	s_addc_u32 s53, s53, 0
	s_nop 3
	v_max3_f32 v2, v2, v18, v19
	v_max3_f32 v2, v2, v20, v21
	v_max3_f32 v18, v2, v22, v23
	s_waitcnt lgkmcnt(0)
	v_mfma_f32_32x32x64_f8f6f4 v[2:17], v[34:41], v[146:153], 0
	v_max3_f32 v18, v18, v24, v25
	v_max3_f32 v18, v18, v26, v27
	v_max3_f32 v18, v18, v28, v29
	v_max3_f32 v18, v18, v30, v31
	v_max3_f32 v26, v18, v32, v33
	ds_read_b128 v[18:21], v171 offset:6144
	ds_read_b128 v[22:25], v171 offset:7168
	s_mov_b32 s65, 0
	s_mov_b32 s55, 0
	v_mov_b32_e32 v27, v163
	v_mov_b32_e32 v28, v163
	v_mov_b32_e32 v29, v163
	v_mov_b32_e32 v30, v163
	v_mov_b32_e32 v31, v163
	v_mov_b32_e32 v32, v163
	v_mov_b32_e32 v33, v163
	s_nop 3
	v_max3_f32 v2, v26, v2, v3
	v_max3_f32 v2, v2, v4, v5
	v_max3_f32 v2, v2, v6, v7
	v_max3_f32 v2, v2, v8, v9
	v_max3_f32 v2, v2, v10, v11
	v_max3_f32 v2, v2, v12, v13
	v_max3_f32 v2, v2, v14, v15
	v_max3_f32 v26, v2, v16, v17
	s_waitcnt lgkmcnt(0)
	v_mfma_f32_32x32x64_f8f6f4 v[2:17], v[18:25], v[146:153], 0
	v_mov_b32_e32 v18, 0
	v_mov_b32_e32 v19, v163
	v_mov_b32_e32 v20, v163
	v_mov_b32_e32 v21, v163
	v_mov_b32_e32 v22, v163
	v_mov_b32_e32 v23, v163
	v_mov_b32_e32 v24, v163
	v_mov_b32_e32 v25, v163
	v_mov_b32_e32 v34, 0
	v_mov_b32_e32 v35, v163
	v_mov_b32_e32 v36, v163
	v_mov_b32_e32 v37, v163
	v_mov_b32_e32 v38, v163
	v_mov_b32_e32 v39, v163
	v_mov_b32_e32 v40, v163
	s_nop 4
	v_max3_f32 v2, v26, v2, v3
	v_max3_f32 v2, v2, v4, v5
	v_max3_f32 v2, v2, v6, v7
	v_max3_f32 v2, v2, v8, v9
	v_max3_f32 v2, v2, v10, v11
	v_max3_f32 v2, v2, v12, v13
	v_max3_f32 v2, v2, v14, v15
	v_cndmask_b32_e32 v3, v175, v176, vcc
	v_max3_f32 v2, v2, v16, v17
	v_lshlrev_b32_e32 v3, 2, v3
	ds_bpermute_b32 v3, v3, v2
	v_cmp_class_f32_e32 vcc, v43, v172
	v_mov_b32_e32 v5, v163
	v_mov_b32_e32 v6, v163
	v_cndmask_b32_e32 v4, v44, v43, vcc
	s_waitcnt lgkmcnt(0)
	v_max_f32_e32 v3, v3, v3
	v_mul_f32_e32 v4, v42, v4
	v_max_f32_e32 v2, v2, v3
	v_fmamk_f32 v4, v4, 0x3f90a3d7, v173
	v_add_f32_e32 v2, 0x42800000, v2
	v_min_f32_e32 v2, v4, v2
	v_add_f32_e32 v2, 0xc2ec0000, v2
	v_xor_b32_e32 v50, 0x80000000, v2
	v_mov_b32_e32 v51, v50
	v_mov_b32_e32 v52, v50
	v_mov_b32_e32 v53, v50
	v_mov_b32_e32 v54, v50
	v_mov_b32_e32 v55, v50
	v_mov_b32_e32 v56, v50
	v_mov_b32_e32 v57, v50
	v_mov_b32_e32 v58, v50
	v_mov_b32_e32 v59, v50
	v_mov_b32_e32 v60, v50
	v_mov_b32_e32 v61, v50
	v_mov_b32_e32 v62, v50
	v_mov_b32_e32 v63, v50
	v_mov_b32_e32 v64, v50
	v_mov_b32_e32 v65, v50
	v_mov_b32_e32 v2, 0
	v_mov_b32_e32 v3, v163
	v_mov_b32_e32 v4, v163
	v_mov_b32_e32 v7, v163
	v_mov_b32_e32 v8, v163
	v_mov_b32_e32 v9, v163
	v_mov_b32_e32 v10, v163
	v_mov_b32_e32 v11, v163
	v_mov_b32_e32 v12, v163
	v_mov_b32_e32 v13, v163
	v_mov_b32_e32 v14, v163
	v_mov_b32_e32 v15, v163
	v_mov_b32_e32 v16, v163
	v_mov_b32_e32 v17, v163
	v_mov_b32_e32 v26, v163
	v_mov_b32_e32 v41, v163
	v_mov_b32_e32 v42, v163
	v_mov_b32_e32 v43, v163
	v_mov_b32_e32 v44, v163
	v_mov_b32_e32 v45, v163
	v_mov_b32_e32 v46, v163
	v_mov_b32_e32 v47, v163
	v_mov_b32_e32 v48, v163
	v_mov_b32_e32 v49, v163
	v_mov_b32_e32 v66, 0
	v_mov_b32_e32 v67, v163
	v_mov_b32_e32 v68, v163
	v_mov_b32_e32 v69, v163
	v_mov_b32_e32 v70, v163
	v_mov_b32_e32 v71, v163
	v_mov_b32_e32 v72, v163
	v_mov_b32_e32 v73, v163
	v_mov_b32_e32 v74, v163
	v_mov_b32_e32 v75, v163
	v_mov_b32_e32 v76, v163
	v_mov_b32_e32 v77, v163
	v_mov_b32_e32 v78, v163
	v_mov_b32_e32 v79, v163
	v_mov_b32_e32 v80, v163
	v_mov_b32_e32 v81, v163
	v_mov_b32_e32 v82, 0
	v_mov_b32_e32 v83, v163
	v_mov_b32_e32 v84, v163
	v_mov_b32_e32 v85, v163
	v_mov_b32_e32 v86, v163
	v_mov_b32_e32 v87, v163
	v_mov_b32_e32 v88, v163
	v_mov_b32_e32 v89, v163
	v_mov_b32_e32 v90, v163
	v_mov_b32_e32 v91, v163
	v_mov_b32_e32 v92, v163
	v_mov_b32_e32 v93, v163
	v_mov_b32_e32 v94, v163
	v_mov_b32_e32 v95, v163
	v_mov_b32_e32 v96, v163
	v_mov_b32_e32 v97, v163
	v_mov_b32_e32 v142, v210
	v_mov_b32_e32 v143, v211
	v_mov_b32_e32 v144, v218
	v_mov_b32_e32 v145, v219
	v_mov_b32_e32 v118, v163
	v_mov_b32_e32 v119, v163
	v_mov_b32_e32 v120, v163
	v_mov_b32_e32 v121, v163
	v_mov_b32_e32 v122, v163
	v_mov_b32_e32 v123, v163
	v_mov_b32_e32 v124, v163
	v_mov_b32_e32 v125, v163
	v_mov_b32_e32 v126, v163
	v_mov_b32_e32 v127, v163
	v_mov_b32_e32 v128, v163
	v_mov_b32_e32 v129, v163
	v_mov_b32_e32 v130, v163
	v_mov_b32_e32 v131, v163
	v_mov_b32_e32 v132, v163
	v_mov_b32_e32 v133, v163
	v_mov_b32_e32 v180, v163
	v_mov_b32_e32 v181, v163
	v_mov_b32_e32 v182, v163
	v_mov_b32_e32 v183, v163
	v_mov_b32_e32 v184, v163
	v_mov_b32_e32 v185, v163
	v_mov_b32_e32 v186, v163
	v_mov_b32_e32 v187, v163
	v_mov_b32_e32 v188, v163
	v_mov_b32_e32 v189, v163
	v_mov_b32_e32 v190, v163
	v_mov_b32_e32 v191, v163
	v_mov_b32_e32 v192, v163
	v_mov_b32_e32 v193, v163
	v_mov_b32_e32 v194, v163
	v_mov_b32_e32 v195, v163
	v_mov_b32_e32 v220, v163
	v_mov_b32_e32 v221, v163
	v_mov_b32_e32 v222, v163
	v_mov_b32_e32 v223, v163
	v_mov_b32_e32 v224, v163
	v_mov_b32_e32 v225, v163
	v_mov_b32_e32 v226, v163
	v_mov_b32_e32 v227, v163
	v_mov_b32_e32 v228, v163
	v_mov_b32_e32 v229, v163
	v_mov_b32_e32 v230, v163
	v_mov_b32_e32 v231, v163
	v_mov_b32_e32 v232, v163
	v_mov_b32_e32 v233, v163
	v_mov_b32_e32 v234, v163
	v_mov_b32_e32 v235, v163
	v_mov_b32_e32 v236, v163
	v_mov_b32_e32 v237, v163
	v_mov_b32_e32 v238, v163
	v_mov_b32_e32 v239, v163
	v_mov_b32_e32 v240, v163
	v_mov_b32_e32 v241, v163
	v_mov_b32_e32 v242, v163
	v_mov_b32_e32 v243, v163
	v_mov_b32_e32 v244, v163
	v_mov_b32_e32 v245, v163
	v_mov_b32_e32 v246, v163
	v_mov_b32_e32 v247, v163
	v_mov_b32_e32 v248, v163
	v_mov_b32_e32 v249, v163
	v_mov_b32_e32 v250, v163
	v_mov_b32_e32 v251, v163
	s_add_u32 s98, s29, s44
	s_addc_u32 s99, s30, s45
	s_add_u32 s98, s98, 0x36532100
	s_addc_u32 s99, s99, 0
	s_add_u32 s100, s29, s52
	s_addc_u32 s101, s30, s53
	s_add_u32 s100, s100, 0x385b6100
	s_addc_u32 s101, s101, 0
	s_movk_i32 s2, 0x4000
	s_and_b64 s[0:1], s[14:15], exec
	s_cselect_b32 s1, s99, s101
	s_cselect_b32 s0, s98, s100
	s_cselect_b32 s2, 0x2000, s2
	s_add_u32 s8, s0, s2
	s_addc_u32 s9, s1, 0
	s_lshl_b32 s2, s2, 1
	s_add_u32 s98, s29, s44
	s_addc_u32 s99, s30, s45
	s_add_u32 s98, s98, 0x36532500
	s_addc_u32 s99, s99, 0
	s_add_u32 s100, s29, s48
	s_addc_u32 s101, s30, s49
	s_add_u32 s100, s100, 0x385b6100
	s_addc_u32 s101, s101, 0
	s_movk_i32 s33, 0x4000
	s_and_b64 s[4:5], s[14:15], exec
	s_cselect_b32 s5, s99, s101
	s_cselect_b32 s4, s98, s100
	s_cselect_b32 s33, 0x2000, s33
	s_add_u32 s10, s4, s33
	s_addc_u32 s11, s5, 0
	s_lshl_b32 s33, s33, 1
	s_add_u32 s98, s29, s44
	s_addc_u32 s99, s30, s45
	s_add_u32 s98, s98, 0x36532900
	s_addc_u32 s99, s99, 0
	s_add_u32 s100, s29, s46
	s_addc_u32 s101, s30, s47
	s_add_u32 s100, s100, 0x385b6100
	s_addc_u32 s101, s101, 0
	s_movk_i32 s50, 0x4000
	s_and_b64 s[6:7], s[26:27], exec
	s_cselect_b32 s7, s99, s101
	s_cselect_b32 s6, s98, s100
	s_cselect_b32 s50, 0x2000, s50
	s_add_u32 s66, s6, s50
	s_addc_u32 s67, s7, 0
	s_lshl_b32 s50, s50, 1
	s_mov_b64 s[98:99], 0
	s_branch .LBB0_4072
.LBB0_4072:
	s_waitcnt vmcnt(0) lgkmcnt(0)
	s_barrier
	s_cmpk_gt_u32 s55, 0x7f
	s_cselect_b64 vcc, 0, exec
	s_mul_i32 s100, s65, 0x6000
	s_add_i32 s55, s55, 2
	s_xor_b32 s65, s65, 2
	v_add_u32_e32 v179, s100, v171

.Lback_dif1_0:
	v_cvt_pk_u8_f32 v196, v118, 0, 0
	v_cvt_pk_u8_f32 v197, v122, 0, 0
	v_cvt_pk_u8_f32 v198, v126, 0, 0
	v_cvt_pk_u8_f32 v199, v130, 0, 0
	v_cvt_pk_u8_f32 v196, v119, 1, v196
	v_cvt_pk_u8_f32 v197, v123, 1, v197
	v_cvt_pk_u8_f32 v198, v127, 1, v198
	v_cvt_pk_u8_f32 v199, v131, 1, v199
	s_waitcnt lgkmcnt(2)
	v_mfma_f32_32x32x64_f8f6f4 v[86:101], v[204:211], v[146:153], v[50:65]
	v_cvt_pk_u8_f32 v196, v120, 2, v196
	v_cvt_pk_u8_f32 v197, v124, 2, v197
	v_cvt_pk_u8_f32 v198, v128, 2, v198
	v_cvt_pk_u8_f32 v199, v132, 2, v199
	v_cvt_pk_u8_f32 v196, v121, 3, v196
	v_cvt_pk_u8_f32 v197, v125, 3, v197
	v_cvt_pk_u8_f32 v198, v129, 3, v198
	v_cvt_pk_u8_f32 v199, v133, 3, v199
	v_cvt_pk_u8_f32 v200, v180, 0, 0
	v_cvt_pk_u8_f32 v201, v184, 0, 0
	v_cvt_pk_u8_f32 v202, v188, 0, 0
	v_cvt_pk_u8_f32 v203, v192, 0, 0
	s_waitcnt lgkmcnt(0)
	v_mfma_f32_32x32x64_f8f6f4 v[102:117], v[212:219], v[146:153], v[50:65]
	v_cvt_pk_u8_f32 v200, v181, 1, v200
	v_cvt_pk_u8_f32 v201, v185, 1, v201
	v_cvt_pk_u8_f32 v202, v189, 1, v202
	v_cvt_pk_u8_f32 v203, v193, 1, v203
	v_cvt_pk_u8_f32 v200, v182, 2, v200
	v_cvt_pk_u8_f32 v201, v186, 2, v201
	v_cvt_pk_u8_f32 v202, v190, 2, v202
	v_cvt_pk_u8_f32 v203, v194, 2, v203
	v_cvt_pk_u8_f32 v200, v183, 3, v200
	v_cvt_pk_u8_f32 v201, v187, 3, v201
	v_cvt_pk_u8_f32 v202, v191, 3, v202
	v_cvt_pk_u8_f32 v203, v195, 3, v203
	s_nop 0
	s_nop 0
	v_mfma_f32_32x32x64_f8f6f4 v[66:81], v[220:227], v[196:203], v[66:81] blgp:1
	ds_read_b128 v[204:207], v179 offset:4096
	ds_read_b128 v[208:211], v179 offset:5120
	ds_read_b128 v[212:215], v179 offset:6144
	ds_read_b128 v[216:219], v179 offset:7168
	s_cbranch_vccz .Ldma_dif1_skip0
	s_mul_i32 s101, s65, 0x6000
	s_add_i32 s101, s101, s24
	s_mov_b32 m0, s101
	s_nop 0
	global_load_lds_dwordx4 v164, s[0:1]
.Ldma_dif1_skip0:
	v_mfma_f32_32x32x64_f8f6f4 v[34:49], v[228:235], v[196:203], v[34:49] blgp:1
	ds_read_b128 v[220:223], v179 offset:8192
	ds_read_b128 v[224:227], v179 offset:9216
	s_cbranch_vccz .Ldma_dif1_skip1
	s_add_i32 m0, s101, 0x400
	s_add_u32 s0, s0, s2
	s_addc_u32 s1, s1, 0
	global_load_lds_dwordx4 v164, s[4:5]

.Lback_dif1_1:
	v_cvt_pk_u8_f32 v196, v86, 0, 0
	v_cvt_pk_u8_f32 v197, v90, 0, 0
	v_cvt_pk_u8_f32 v198, v94, 0, 0
	v_cvt_pk_u8_f32 v199, v98, 0, 0
	v_cvt_pk_u8_f32 v196, v87, 1, v196
	v_cvt_pk_u8_f32 v197, v91, 1, v197
	v_cvt_pk_u8_f32 v198, v95, 1, v198
	v_cvt_pk_u8_f32 v199, v99, 1, v199
	s_waitcnt lgkmcnt(8)
	v_mfma_f32_32x32x64_f8f6f4 v[118:133], v[204:211], v[146:153], v[50:65]
	v_cvt_pk_u8_f32 v196, v88, 2, v196
	v_cvt_pk_u8_f32 v197, v92, 2, v197
	v_cvt_pk_u8_f32 v198, v96, 2, v198
	v_cvt_pk_u8_f32 v199, v100, 2, v199
	v_cvt_pk_u8_f32 v196, v89, 3, v196
	v_cvt_pk_u8_f32 v197, v93, 3, v197
	v_cvt_pk_u8_f32 v198, v97, 3, v198
	v_cvt_pk_u8_f32 v199, v101, 3, v199
	v_cvt_pk_u8_f32 v200, v102, 0, 0
	v_cvt_pk_u8_f32 v201, v106, 0, 0
	v_cvt_pk_u8_f32 v202, v110, 0, 0
	v_cvt_pk_u8_f32 v203, v114, 0, 0
	v_mfma_f32_32x32x64_f8f6f4 v[180:195], v[212:219], v[146:153], v[50:65]
	v_cvt_pk_u8_f32 v200, v103, 1, v200
	v_cvt_pk_u8_f32 v201, v107, 1, v201
	v_cvt_pk_u8_f32 v202, v111, 1, v202
	v_cvt_pk_u8_f32 v203, v115, 1, v203
	v_cvt_pk_u8_f32 v200, v104, 2, v200
	v_cvt_pk_u8_f32 v201, v108, 2, v201
	v_cvt_pk_u8_f32 v202, v112, 2, v202
	v_cvt_pk_u8_f32 v203, v116, 2, v203
	v_cvt_pk_u8_f32 v200, v105, 3, v200
	v_cvt_pk_u8_f32 v201, v109, 3, v201
	v_cvt_pk_u8_f32 v202, v113, 3, v202
	v_cvt_pk_u8_f32 v203, v117, 3, v203
	s_nop 0
	s_waitcnt lgkmcnt(0)
	v_mfma_f32_32x32x64_f8f6f4 v[66:81], v[220:227], v[196:203], v[66:81] blgp:1
	ds_read_b128 v[204:207], v179 offset:24576
	ds_read_b128 v[208:211], v179 offset:25600
	ds_read_b128 v[212:215], v179 offset:26624
	ds_read_b128 v[216:219], v179 offset:27648
	s_cbranch_vccz .Ldma_dif1_skip2
	s_add_i32 m0, s101, 0x800
	s_add_u32 s4, s4, s33
	s_addc_u32 s5, s5, 0
	global_load_lds_dwordx4 v164, s[6:7]
.Ldma_dif1_skip2:
	v_mfma_f32_32x32x64_f8f6f4 v[34:49], v[228:235], v[196:203], v[34:49] blgp:1
	ds_read_b128 v[220:223], v179 offset:16384
	ds_read_b128 v[224:227], v179 offset:17408
	s_cbranch_vccz .Ldma_dif1_skip3
	s_add_i32 m0, s101, 0x6000
	s_add_u32 s6, s6, s50
	s_addc_u32 s7, s7, 0
	global_load_lds_dwordx4 v164, s[8:9]

.Lback_dif1_2:
	v_cvt_pk_u8_f32 v196, v118, 0, 0
	v_cvt_pk_u8_f32 v197, v122, 0, 0
	v_cvt_pk_u8_f32 v198, v126, 0, 0
	v_cvt_pk_u8_f32 v199, v130, 0, 0
	v_cvt_pk_u8_f32 v196, v119, 1, v196
	v_cvt_pk_u8_f32 v197, v123, 1, v197
	v_cvt_pk_u8_f32 v198, v127, 1, v198
	v_cvt_pk_u8_f32 v199, v131, 1, v199
	s_waitcnt lgkmcnt(8)
	v_mfma_f32_32x32x64_f8f6f4 v[86:101], v[204:211], v[146:153], v[50:65]
	v_cvt_pk_u8_f32 v196, v120, 2, v196
	v_cvt_pk_u8_f32 v197, v124, 2, v197
	v_cvt_pk_u8_f32 v198, v128, 2, v198
	v_cvt_pk_u8_f32 v199, v132, 2, v199
	v_cvt_pk_u8_f32 v196, v121, 3, v196
	v_cvt_pk_u8_f32 v197, v125, 3, v197
	v_cvt_pk_u8_f32 v198, v129, 3, v198
	v_cvt_pk_u8_f32 v199, v133, 3, v199
	v_cvt_pk_u8_f32 v200, v180, 0, 0
	v_cvt_pk_u8_f32 v201, v184, 0, 0
	v_cvt_pk_u8_f32 v202, v188, 0, 0
	v_cvt_pk_u8_f32 v203, v192, 0, 0
	v_mfma_f32_32x32x64_f8f6f4 v[102:117], v[212:219], v[146:153], v[50:65]
	v_cvt_pk_u8_f32 v200, v181, 1, v200
	v_cvt_pk_u8_f32 v201, v185, 1, v201
	v_cvt_pk_u8_f32 v202, v189, 1, v202
	v_cvt_pk_u8_f32 v203, v193, 1, v203
	v_cvt_pk_u8_f32 v200, v182, 2, v200
	v_cvt_pk_u8_f32 v201, v186, 2, v201
	v_cvt_pk_u8_f32 v202, v190, 2, v202
	v_cvt_pk_u8_f32 v203, v194, 2, v203
	v_cvt_pk_u8_f32 v200, v183, 3, v200
	v_cvt_pk_u8_f32 v201, v187, 3, v201
	v_cvt_pk_u8_f32 v202, v191, 3, v202
	v_cvt_pk_u8_f32 v203, v195, 3, v203
	s_nop 0
	s_waitcnt lgkmcnt(0)
	v_mfma_f32_32x32x64_f8f6f4 v[66:81], v[220:227], v[196:203], v[66:81] blgp:1
	ds_read_b128 v[204:207], v179 offset:28672
	ds_read_b128 v[208:211], v179 offset:29696
	ds_read_b128 v[212:215], v179 offset:30720
	ds_read_b128 v[216:219], v179 offset:31744
	s_cbranch_vccz .Ldma_dif1_skip4
	s_add_i32 m0, s101, 0x6400
	s_add_u32 s8, s8, s2
	s_addc_u32 s9, s9, 0
	global_load_lds_dwordx4 v164, s[10:11]
.Ldma_dif1_skip4:
	v_mfma_f32_32x32x64_f8f6f4 v[34:49], v[228:235], v[196:203], v[34:49] blgp:1
	ds_read_b128 v[220:223], v179 offset:32768
	ds_read_b128 v[224:227], v179 offset:33792
	s_cbranch_vccz .Ldma_dif1_skip5
	s_add_i32 m0, s101, 0x6800
	s_add_u32 s10, s10, s33
	s_addc_u32 s11, s11, 0
	global_load_lds_dwordx4 v164, s[66:67]
	s_add_u32 s66, s66, s50
	s_addc_u32 s67, s67, 0

.LBB0_4076:
	s_ashr_i32 s0, s30, 3
	s_mul_i32 s2, s0, 0x4100
	v_add_u32_e32 v2, s2, v219
	v_ashrrev_i32_e32 v3, 31, v2
	s_and_b32 s1, s30, 7
	v_lshlrev_b64 v[4:5], 9, v[2:3]
	v_lshl_add_u64 v[4:5], s[14:15], 0, v[4:5]
	s_lshl_b32 s20, s1, 6
	v_lshl_add_u64 v[4:5], v[4:5], 0, s[20:21]
	s_lshl_b32 s20, s1, 2
	s_mul_i32 s4, s30, 0x104000
	s_mul_hi_i32 s2, s30, 0x104000
	s_add_u32 s31, s22, s4
	s_addc_u32 s34, s23, s2
	s_lshl_b32 s0, s0, 2
	s_bfe_u32 s2, s30, 0x20001
	s_or_b32 s0, s0, s2
	s_mul_hi_i32 s2, s0, 0x208000
	s_mul_i32 s0, s0, 0x208000
	s_add_u32 s35, s24, s0
	s_addc_u32 s36, s25, s2
	s_add_i32 s12, s30, 16
	s_ashr_i32 s13, s12, 31
	v_lshlrev_b64 v[6:7], 5, v[2:3]
	s_lshl_b64 s[12:13], s[12:13], 2
	v_lshl_add_u64 v[6:7], s[16:17], 0, v[6:7]
	s_add_u32 s12, s3, s12
	v_lshl_add_u64 v[6:7], v[6:7], 0, s[20:21]
	s_addc_u32 s13, s28, s13
	global_load_dword v6, v[6:7], off
	v_lshlrev_b64 v[2:3], 11, v[2:3]
	global_load_dword v7, v211, s[12:13]
	v_lshl_add_u64 v[2:3], s[18:19], 0, v[2:3]
	s_lshl_b32 s20, s1, 8
	v_lshl_add_u64 v[216:217], v[2:3], 0, s[20:21]
	v_lshl_add_u64 v[2:3], v[4:5], 0, v[210:211]
	global_load_dwordx4 v[158:161], v[2:3], off offset:16
	global_load_dwordx4 v[154:157], v[2:3], off
	v_readfirstlane_b32 s0, v1
	s_ashr_i32 s0, s0, 6
	s_mul_i32 s1, s0, 0xc00
	s_add_i32 s2, s1, 0xffffe000
	s_add_u32 s4, s35, s2
	s_addc_u32 s5, s36, 0
	s_ashr_i32 s6, s1, 31
	s_add_u32 s7, s31, s1
	s_addc_u32 s8, s34, s6
	s_add_i32 s10, s1, 0x400
	s_add_i32 s9, s1, 0
	s_ashr_i32 s11, s10, 31
	s_add_u32 s20, s7, 0x400
	s_addc_u32 s33, s8, 0
	s_mov_b32 m0, s9
	v_mov_b32 v146, 0x38383838
	v_mov_b32 v147, 0x38383838
	v_mov_b32 v148, 0x38383838
	v_mov_b32 v149, 0x38383838
	v_mov_b32 v150, 0x38383838
	v_mov_b32 v151, 0x38383838
	v_mov_b32 v152, 0x38383838
	v_mov_b32 v153, 0x38383838
	s_waitcnt vmcnt(0)
	v_cmp_gt_f32_e32 vcc, s26, v7
	v_mul_f32_e32 v2, 0x4f800000, v7
	s_nop 0
	v_cndmask_b32_e32 v2, v7, v2, vcc
	v_sqrt_f32_e32 v3, v2
	s_nop 0
	v_add_u32_e32 v4, -1, v3
	v_fma_f32 v5, -v4, v3, v2
	v_cmp_ge_f32_e64 s[12:13], 0, v5
	v_add_u32_e32 v5, 1, v3
	s_nop 0
	v_cndmask_b32_e64 v4, v3, v4, s[12:13]
	v_fma_f32 v3, -v5, v3, v2
	v_cmp_lt_f32_e64 s[12:13], 0, v3
	s_nop 1
	v_cndmask_b32_e64 v3, v4, v5, s[12:13]
	s_add_i32 s12, s1, 0xffffe400
	s_add_u32 s37, s35, s12
	s_addc_u32 s38, s36, 0
	s_add_i32 s40, s1, 0x800
	s_add_i32 s39, s9, 0x400
	s_ashr_i32 s41, s40, 31
	s_add_u32 s42, s7, 0x800
	s_addc_u32 s43, s8, 0
	s_add_i32 s44, s1, 0xffffe800
	s_add_u32 s45, s35, s44
	s_addc_u32 s46, s36, 0
	s_add_i32 s47, s9, 0x800
	s_add_u32 s48, s35, 0x4000
	s_addc_u32 s36, s36, 0
	s_add_u32 s31, s31, 0x2000
	s_addc_u32 s49, s34, 0
	s_add_u32 s1, s31, s1
	s_addc_u32 s6, s49, s6
	s_add_u32 s2, s48, s2
	s_addc_u32 s34, s36, 0
	s_add_i32 s50, s9, 0x6000
	s_add_u32 s10, s31, s10
	s_addc_u32 s11, s49, s11
	s_add_u32 s35, s48, s12
	v_mul_f32_e32 v4, 0x37800000, v3
	s_addc_u32 s51, s36, 0
	v_cndmask_b32_e32 v3, v3, v4, vcc
	v_cmp_class_f32_e32 vcc, v2, v221
	s_cmp_lt_i32 s0, 3
	s_cselect_b32 s13, s8, s5
	v_cndmask_b32_e32 v2, v3, v2, vcc
	s_cselect_b32 s12, s7, s4
	v_mul_f32_e32 v4, v6, v2
	v_lshl_add_u64 v[2:3], s[12:13], 0, v[212:213]
	s_cselect_b32 s13, s33, s38
	s_cselect_b32 s12, s20, s37
	global_load_lds_dwordx4 v[2:3], off
	v_lshl_add_u64 v[2:3], s[12:13], 0, v[212:213]
	s_cselect_b32 s12, s1, s2
	s_cselect_b32 s13, s6, s34
	s_cselect_b32 s34, s10, s35
	s_cselect_b32 s35, s11, s51
	s_add_i32 s1, s9, 0x6400
	s_add_u32 s2, s31, s40
	s_addc_u32 s4, s49, s41
	s_add_u32 s5, s48, s44
	s_addc_u32 s6, s36, 0
	s_cmp_lt_i32 s0, 2
	s_mov_b32 m0, s39
	s_cselect_b32 s37, s43, s46
	s_cselect_b32 s36, s42, s45
	global_load_lds_dwordx4 v[2:3], off
	v_lshl_add_u64 v[2:3], s[36:37], 0, v[212:213]
	s_mov_b32 m0, s47
	v_fmamk_f32 v18, v4, 0x3f90a3d7, v222
	global_load_lds_dwordx4 v[2:3], off
	v_lshl_add_u64 v[2:3], s[12:13], 0, v[212:213]
	s_mov_b32 m0, s50
	s_cselect_b32 s13, s4, s6
	global_load_lds_dwordx4 v[2:3], off
	v_lshl_add_u64 v[2:3], s[34:35], 0, v[212:213]
	s_mov_b32 m0, s1
	s_cselect_b32 s12, s2, s5
	global_load_lds_dwordx4 v[2:3], off
	v_lshl_add_u64 v[2:3], s[12:13], 0, v[212:213]
	s_add_i32 m0, s9, 0x6800
	v_cmp_lt_i32_e32 vcc, v225, v226
	global_load_lds_dwordx4 v[2:3], off
	s_waitcnt vmcnt(3)
	s_barrier
	ds_read_b128 v[2:5], v220
	ds_read_b128 v[6:9], v220 offset:1024
	s_waitcnt lgkmcnt(0)
	v_mfma_f32_32x32x64_f8f6f4 v[2:17], v[2:9], v[154:161], 0
	s_add_i32 s30, s30, s52
	s_nop 15
	s_nop 2
	v_max3_f32 v2, v2, s27, v3
	v_max3_f32 v2, v2, v4, v5
	v_max3_f32 v2, v2, v6, v7
	v_max3_f32 v2, v2, v8, v9
	v_max3_f32 v2, v2, v10, v11
	v_max3_f32 v2, v2, v12, v13
	v_max3_f32 v2, v2, v14, v15
	v_max3_f32 v19, v2, v16, v17
	ds_read_b128 v[2:5], v220 offset:2048
	ds_read_b128 v[6:9], v220 offset:3072
	s_waitcnt lgkmcnt(0)
	v_mfma_f32_32x32x64_f8f6f4 v[2:17], v[2:9], v[154:161], 0
	s_nop 15
	s_nop 3
	v_max3_f32 v2, v19, v2, v3
	v_max3_f32 v2, v2, v4, v5
	v_max3_f32 v2, v2, v6, v7
	v_max3_f32 v2, v2, v8, v9
	v_max3_f32 v2, v2, v10, v11
	v_max3_f32 v2, v2, v12, v13
	v_max3_f32 v2, v2, v14, v15
	v_max3_f32 v19, v2, v16, v17
	ds_read_b128 v[2:5], v220 offset:4096
	ds_read_b128 v[6:9], v220 offset:5120
	s_waitcnt lgkmcnt(0)
	v_mfma_f32_32x32x64_f8f6f4 v[2:17], v[2:9], v[154:161], 0
	s_nop 15
	s_nop 3
	v_max3_f32 v2, v19, v2, v3
	v_max3_f32 v2, v2, v4, v5
	v_max3_f32 v2, v2, v6, v7
	v_max3_f32 v2, v2, v8, v9
	v_max3_f32 v2, v2, v10, v11
	v_max3_f32 v2, v2, v12, v13
	v_max3_f32 v2, v2, v14, v15
	v_max3_f32 v19, v2, v16, v17
	ds_read_b128 v[2:5], v220 offset:6144
	ds_read_b128 v[6:9], v220 offset:7168
	s_waitcnt lgkmcnt(0)
	v_mfma_f32_32x32x64_f8f6f4 v[2:17], v[2:9], v[154:161], 0
	s_waitcnt vmcnt(0)
	s_barrier
	s_nop 15
	s_nop 2
	v_max3_f32 v2, v19, v2, v3
	v_max3_f32 v2, v2, v4, v5
	v_max3_f32 v2, v2, v6, v7
	v_max3_f32 v2, v2, v8, v9
	v_max3_f32 v2, v2, v10, v11
	v_max3_f32 v2, v2, v12, v13
	v_max3_f32 v2, v2, v14, v15
	v_cndmask_b32_e32 v3, v224, v225, vcc
	v_max3_f32 v2, v2, v16, v17
	v_lshlrev_b32_e32 v3, 2, v3
	ds_bpermute_b32 v3, v3, v2
	s_waitcnt lgkmcnt(0)
	v_max_f32_e32 v3, v3, v3
	v_max_f32_e32 v2, v2, v3
	v_add_f32_e32 v2, 0x42800000, v2
	v_min_f32_e32 v2, v18, v2
	v_add_f32_e32 v2, 0xc2ec0000, v2
	v_xor_b32_e32 v2, 0x80000000, v2
	v_mov_b32_e32 v3, v2
	v_mov_b32_e32 v4, v2
	v_mov_b32_e32 v5, v2
	v_mov_b32_e32 v6, v2
	v_mov_b32_e32 v7, v2
	v_mov_b32_e32 v8, v2
	v_mov_b32_e32 v9, v2
	v_mov_b32_e32 v10, v2
	v_mov_b32_e32 v11, v2
	v_mov_b32_e32 v12, v2
	v_mov_b32_e32 v13, v2
	v_mov_b32_e32 v14, v2
	v_mov_b32_e32 v15, v2
	v_mov_b32_e32 v16, v2
	v_mov_b32_e32 v17, v2
	ds_read_b128 v[18:21], v220
	ds_read_b128 v[22:25], v220 offset:1024
	ds_read_b128 v[50:53], v220 offset:2048
	ds_read_b128 v[54:57], v220 offset:3072
	ds_read_b128 v[34:37], v220 offset:8192
	ds_read_b128 v[38:41], v220 offset:9216
	ds_read_b128 v[42:45], v220 offset:10240
	ds_read_b128 v[46:49], v220 offset:11264
	ds_read_b128 v[114:117], v220 offset:12288
	ds_read_b128 v[118:121], v220 offset:13312
	ds_read_b128 v[122:125], v220 offset:14336
	ds_read_b128 v[126:129], v220 offset:15360
	s_waitcnt lgkmcnt(0)
	v_mfma_f32_32x32x64_f8f6f4 v[18:33], v[18:25], v[154:161], v[2:17]
	ds_read_b128 v[66:69], v220 offset:4096
	ds_read_b128 v[70:73], v220 offset:5120
	ds_read_b128 v[58:61], v220 offset:6144
	ds_read_b128 v[62:65], v220 offset:7168
	s_nop 15
	v_med3_f32 v18, v18, 0, v227
	v_med3_f32 v19, v19, 0, v227
	v_cvt_pk_u8_f32 v18, v18, 0, 0
	v_med3_f32 v20, v20, 0, v227
	v_cvt_pk_u8_f32 v18, v19, 1, v18
	v_med3_f32 v21, v21, 0, v227
	v_cvt_pk_u8_f32 v18, v20, 2, v18
	v_cvt_pk_u8_f32 v130, v21, 3, v18
	v_med3_f32 v21, v22, 0, v227
	v_med3_f32 v20, v23, 0, v227
	v_cvt_pk_u8_f32 v21, v21, 0, 0
	v_med3_f32 v19, v24, 0, v227
	v_cvt_pk_u8_f32 v20, v20, 1, v21
	v_med3_f32 v21, v26, 0, v227
	v_med3_f32 v18, v25, 0, v227
	v_cvt_pk_u8_f32 v19, v19, 2, v20
	v_med3_f32 v20, v27, 0, v227
	v_cvt_pk_u8_f32 v21, v21, 0, 0
	v_cvt_pk_u8_f32 v131, v18, 3, v19
	v_med3_f32 v19, v28, 0, v227
	v_cvt_pk_u8_f32 v20, v20, 1, v21
	v_med3_f32 v21, v30, 0, v227
	v_med3_f32 v18, v29, 0, v227
	v_cvt_pk_u8_f32 v19, v19, 2, v20
	v_med3_f32 v20, v31, 0, v227
	v_cvt_pk_u8_f32 v21, v21, 0, 0
	v_cvt_pk_u8_f32 v132, v18, 3, v19
	v_med3_f32 v19, v32, 0, v227
	v_cvt_pk_u8_f32 v20, v20, 1, v21
	v_med3_f32 v18, v33, 0, v227
	v_cvt_pk_u8_f32 v19, v19, 2, v20
	v_cvt_pk_u8_f32 v133, v18, 3, v19
	v_mfma_f32_32x32x64_f8f6f4 v[18:33], v[50:57], v[154:161], v[2:17]
	s_waitcnt lgkmcnt(0)
	v_mfma_f32_32x32x64_f8f6f4 v[82:97], v[66:73], v[154:161], v[2:17]
	s_nop 15
	s_nop 1
	v_med3_f32 v18, v18, 0, v227
	v_med3_f32 v19, v19, 0, v227
	v_cvt_pk_u8_f32 v18, v18, 0, 0
	v_med3_f32 v20, v20, 0, v227
	v_cvt_pk_u8_f32 v18, v19, 1, v18
	v_med3_f32 v21, v21, 0, v227
	v_cvt_pk_u8_f32 v18, v20, 2, v18
	v_cvt_pk_u8_f32 v134, v21, 3, v18
	v_med3_f32 v21, v22, 0, v227
	v_med3_f32 v20, v23, 0, v227
	v_cvt_pk_u8_f32 v21, v21, 0, 0
	v_med3_f32 v19, v24, 0, v227
	v_cvt_pk_u8_f32 v20, v20, 1, v21
	v_med3_f32 v21, v26, 0, v227
	v_med3_f32 v18, v25, 0, v227
	v_mfma_f32_32x32x64_f8f6f4 v[98:113], v[58:65], v[154:161], v[2:17]
	v_med3_f32 v82, v82, 0, v227
	v_med3_f32 v83, v83, 0, v227
	v_cvt_pk_u8_f32 v82, v82, 0, 0
	v_med3_f32 v84, v84, 0, v227
	v_cvt_pk_u8_f32 v82, v83, 1, v82
	v_cvt_pk_u8_f32 v19, v19, 2, v20
	v_med3_f32 v20, v27, 0, v227
	v_cvt_pk_u8_f32 v21, v21, 0, 0
	v_med3_f32 v85, v85, 0, v227
	v_cvt_pk_u8_f32 v82, v84, 2, v82
	v_cvt_pk_u8_f32 v135, v18, 3, v19
	v_med3_f32 v19, v28, 0, v227
	v_cvt_pk_u8_f32 v20, v20, 1, v21
	v_med3_f32 v21, v30, 0, v227
	v_cvt_pk_u8_f32 v194, v85, 3, v82
	v_med3_f32 v85, v86, 0, v227
	v_med3_f32 v18, v29, 0, v227
	v_cvt_pk_u8_f32 v19, v19, 2, v20
	v_med3_f32 v20, v31, 0, v227
	v_cvt_pk_u8_f32 v21, v21, 0, 0
	v_med3_f32 v84, v87, 0, v227
	v_cvt_pk_u8_f32 v85, v85, 0, 0
	v_cvt_pk_u8_f32 v136, v18, 3, v19
	v_med3_f32 v19, v32, 0, v227
	v_cvt_pk_u8_f32 v20, v20, 1, v21
	v_med3_f32 v83, v88, 0, v227
	v_cvt_pk_u8_f32 v84, v84, 1, v85
	v_med3_f32 v85, v90, 0, v227
	v_med3_f32 v18, v33, 0, v227
	v_cvt_pk_u8_f32 v19, v19, 2, v20
	v_med3_f32 v82, v89, 0, v227
	v_cvt_pk_u8_f32 v83, v83, 2, v84
	v_med3_f32 v84, v91, 0, v227
	v_cvt_pk_u8_f32 v85, v85, 0, 0
	v_cvt_pk_u8_f32 v137, v18, 3, v19
	v_cvt_pk_u8_f32 v195, v82, 3, v83
	v_med3_f32 v83, v92, 0, v227
	v_cvt_pk_u8_f32 v84, v84, 1, v85
	v_med3_f32 v85, v94, 0, v227
	v_mfma_f32_32x32x64_f8f6f4 v[66:81], v[34:41], v[130:137], 0 blgp:1
	v_med3_f32 v82, v93, 0, v227
	v_cvt_pk_u8_f32 v83, v83, 2, v84
	v_med3_f32 v84, v95, 0, v227
	v_cvt_pk_u8_f32 v85, v85, 0, 0
	v_cvt_pk_u8_f32 v196, v82, 3, v83
	v_med3_f32 v83, v96, 0, v227
	v_cvt_pk_u8_f32 v84, v84, 1, v85
	v_med3_f32 v82, v97, 0, v227
	v_cvt_pk_u8_f32 v83, v83, 2, v84
	v_cvt_pk_u8_f32 v197, v82, 3, v83
	v_med3_f32 v98, v98, 0, v227
	v_med3_f32 v99, v99, 0, v227
	v_cvt_pk_u8_f32 v98, v98, 0, 0
	v_med3_f32 v100, v100, 0, v227
	v_cvt_pk_u8_f32 v98, v99, 1, v98
	v_mfma_f32_32x32x64_f8f6f4 v[50:65], v[42:49], v[130:137], 0 blgp:1
	v_med3_f32 v101, v101, 0, v227
	v_cvt_pk_u8_f32 v98, v100, 2, v98
	v_cvt_pk_u8_f32 v198, v101, 3, v98
	v_med3_f32 v101, v102, 0, v227
	v_med3_f32 v100, v103, 0, v227
	v_cvt_pk_u8_f32 v101, v101, 0, 0
	v_med3_f32 v99, v104, 0, v227
	v_cvt_pk_u8_f32 v100, v100, 1, v101
	v_med3_f32 v101, v106, 0, v227
	v_med3_f32 v98, v105, 0, v227
	v_cvt_pk_u8_f32 v99, v99, 2, v100
	v_med3_f32 v100, v107, 0, v227
	v_cvt_pk_u8_f32 v101, v101, 0, 0
	v_cvt_pk_u8_f32 v199, v98, 3, v99
	v_med3_f32 v99, v108, 0, v227
	v_mfma_f32_32x32x64_f8f6f4 v[34:49], v[114:121], v[130:137], 0 blgp:1
	ds_read_b128 v[162:165], v220 offset:16384
	ds_read_b128 v[166:169], v220 offset:17408
	ds_read_b128 v[170:173], v220 offset:18432
	ds_read_b128 v[174:177], v220 offset:19456
	ds_read_b128 v[178:181], v220 offset:20480
	ds_read_b128 v[182:185], v220 offset:21504
	ds_read_b128 v[186:189], v220 offset:22528
	ds_read_b128 v[190:193], v220 offset:23552
	ds_read_b128 v[114:117], v220 offset:24576
	ds_read_b128 v[118:121], v220 offset:25600
	ds_read_b128 v[138:141], v220 offset:26624
	ds_read_b128 v[142:145], v220 offset:27648
	v_cvt_pk_u8_f32 v100, v100, 1, v101
	v_med3_f32 v101, v110, 0, v227
	v_med3_f32 v98, v109, 0, v227
	v_cvt_pk_u8_f32 v99, v99, 2, v100
	v_med3_f32 v100, v111, 0, v227
	v_cvt_pk_u8_f32 v101, v101, 0, 0
	v_cvt_pk_u8_f32 v200, v98, 3, v99
	v_med3_f32 v99, v112, 0, v227
	v_cvt_pk_u8_f32 v100, v100, 1, v101
	v_med3_f32 v98, v113, 0, v227
	v_cvt_pk_u8_f32 v99, v99, 2, v100
	v_cvt_pk_u8_f32 v201, v98, 3, v99
	v_mfma_f32_32x32x64_f8f6f4 v[18:33], v[122:129], v[130:137], 0 blgp:1
	v_mfma_f32_32x32x64_f8f6f4 v[82:97], v[146:153], v[130:137], 0 blgp:1
	s_waitcnt lgkmcnt(0)
	v_mfma_f32_32x32x64_f8f6f4 v[114:129], v[114:121], v[154:161], v[2:17]
	v_mfma_f32_32x32x64_f8f6f4 v[130:145], v[138:145], v[154:161], v[2:17]
	s_nop 15
	s_nop 2
	v_med3_f32 v114, v114, 0, v227
	v_med3_f32 v115, v115, 0, v227
	v_cvt_pk_u8_f32 v114, v114, 0, 0
	v_med3_f32 v116, v116, 0, v227
	v_cvt_pk_u8_f32 v114, v115, 1, v114
	v_med3_f32 v117, v117, 0, v227
	v_cvt_pk_u8_f32 v114, v116, 2, v114
	v_med3_f32 v118, v118, 0, v227
	v_cvt_pk_u8_f32 v114, v117, 3, v114
	v_med3_f32 v117, v119, 0, v227
	v_cvt_pk_u8_f32 v118, v118, 0, 0
	v_med3_f32 v119, v122, 0, v227
	v_med3_f32 v116, v120, 0, v227
	v_cvt_pk_u8_f32 v117, v117, 1, v118
	v_med3_f32 v118, v123, 0, v227
	v_mfma_f32_32x32x64_f8f6f4 v[66:81], v[162:169], v[194:201], v[66:81] blgp:1
	v_cvt_pk_u8_f32 v119, v119, 0, 0
	v_med3_f32 v120, v126, 0, v227
	v_med3_f32 v115, v121, 0, v227
	v_cvt_pk_u8_f32 v116, v116, 2, v117
	v_med3_f32 v117, v124, 0, v227
	v_cvt_pk_u8_f32 v118, v118, 1, v119
	v_med3_f32 v119, v127, 0, v227
	v_cvt_pk_u8_f32 v120, v120, 0, 0
	v_med3_f32 v121, v130, 0, v227
	v_cvt_pk_u8_f32 v115, v115, 3, v116
	v_med3_f32 v116, v125, 0, v227
	v_cvt_pk_u8_f32 v117, v117, 2, v118
	v_med3_f32 v118, v128, 0, v227
	v_cvt_pk_u8_f32 v119, v119, 1, v120
	v_med3_f32 v120, v131, 0, v227
	v_mfma_f32_32x32x64_f8f6f4 v[50:65], v[170:177], v[194:201], v[50:65] blgp:1
	v_cvt_pk_u8_f32 v121, v121, 0, 0
	v_med3_f32 v122, v134, 0, v227
	v_cvt_pk_u8_f32 v116, v116, 3, v117
	v_med3_f32 v117, v129, 0, v227
	v_cvt_pk_u8_f32 v118, v118, 2, v119
	v_med3_f32 v119, v132, 0, v227
	v_cvt_pk_u8_f32 v120, v120, 1, v121
	v_med3_f32 v121, v135, 0, v227
	v_cvt_pk_u8_f32 v122, v122, 0, 0
	v_med3_f32 v123, v138, 0, v227
	v_cvt_pk_u8_f32 v117, v117, 3, v118
	v_med3_f32 v118, v133, 0, v227
	v_cvt_pk_u8_f32 v119, v119, 2, v120
	v_med3_f32 v120, v136, 0, v227
	v_cvt_pk_u8_f32 v121, v121, 1, v122
	v_mfma_f32_32x32x64_f8f6f4 v[34:49], v[178:185], v[194:201], v[34:49] blgp:1
	v_med3_f32 v122, v139, 0, v227
	v_cvt_pk_u8_f32 v123, v123, 0, 0
	v_med3_f32 v124, v142, 0, v227
	v_cvt_pk_u8_f32 v118, v118, 3, v119
	v_med3_f32 v119, v137, 0, v227
	v_cvt_pk_u8_f32 v120, v120, 2, v121
	v_med3_f32 v121, v140, 0, v227
	v_cvt_pk_u8_f32 v122, v122, 1, v123
	v_med3_f32 v123, v143, 0, v227
	v_cvt_pk_u8_f32 v124, v124, 0, 0
	v_cvt_pk_u8_f32 v119, v119, 3, v120
	v_med3_f32 v120, v141, 0, v227
	v_cvt_pk_u8_f32 v121, v121, 2, v122
	v_med3_f32 v122, v144, 0, v227
	v_cvt_pk_u8_f32 v123, v123, 1, v124
	v_mfma_f32_32x32x64_f8f6f4 v[18:33], v[186:193], v[194:201], v[18:33] blgp:1
	ds_read_b128 v[98:101], v220 offset:28672
	ds_read_b128 v[102:105], v220 offset:29696
	ds_read_b128 v[202:205], v220 offset:30720
	ds_read_b128 v[206:209], v220 offset:31744
	ds_read_b128 v[162:165], v220 offset:32768
	ds_read_b128 v[166:169], v220 offset:33792
	ds_read_b128 v[170:173], v220 offset:34816
	ds_read_b128 v[174:177], v220 offset:35840
	ds_read_b128 v[178:181], v220 offset:36864
	ds_read_b128 v[182:185], v220 offset:37888
	ds_read_b128 v[186:189], v220 offset:38912
	ds_read_b128 v[190:193], v220 offset:39936
	v_cvt_pk_u8_f32 v120, v120, 3, v121
	v_med3_f32 v121, v145, 0, v227
	v_cvt_pk_u8_f32 v122, v122, 2, v123
	v_cvt_pk_u8_f32 v121, v121, 3, v122
	s_waitcnt lgkmcnt(0)
	v_mfma_f32_32x32x64_f8f6f4 v[98:113], v[98:105], v[154:161], v[2:17]
	v_mfma_f32_32x32x64_f8f6f4 v[82:97], v[146:153], v[194:201], v[82:97] blgp:1
	s_nop 15
	s_nop 2
	v_med3_f32 v98, v98, 0, v227
	v_med3_f32 v99, v99, 0, v227
	v_cvt_pk_u8_f32 v98, v98, 0, 0
	v_med3_f32 v100, v100, 0, v227
	v_cvt_pk_u8_f32 v98, v99, 1, v98
	v_med3_f32 v101, v101, 0, v227
	v_cvt_pk_u8_f32 v98, v100, 2, v98
	v_med3_f32 v102, v102, 0, v227
	v_cvt_pk_u8_f32 v98, v101, 3, v98
	v_med3_f32 v101, v103, 0, v227
	v_cvt_pk_u8_f32 v102, v102, 0, 0
	v_med3_f32 v103, v106, 0, v227
	v_med3_f32 v100, v104, 0, v227
	v_cvt_pk_u8_f32 v101, v101, 1, v102
	v_med3_f32 v102, v107, 0, v227
	v_mfma_f32_32x32x64_f8f6f4 v[2:17], v[202:209], v[154:161], v[2:17]
	v_cvt_pk_u8_f32 v103, v103, 0, 0
	v_med3_f32 v104, v110, 0, v227
	v_med3_f32 v99, v105, 0, v227
	v_cvt_pk_u8_f32 v100, v100, 2, v101
	v_med3_f32 v101, v108, 0, v227
	v_cvt_pk_u8_f32 v102, v102, 1, v103
	v_med3_f32 v103, v111, 0, v227
	v_cvt_pk_u8_f32 v104, v104, 0, 0
	v_cvt_pk_u8_f32 v99, v99, 3, v100
	v_med3_f32 v100, v109, 0, v227
	v_cvt_pk_u8_f32 v101, v101, 2, v102
	v_med3_f32 v102, v112, 0, v227
	v_cvt_pk_u8_f32 v103, v103, 1, v104
	v_cvt_pk_u8_f32 v100, v100, 3, v101
	v_med3_f32 v101, v113, 0, v227
	v_mfma_f32_32x32x64_f8f6f4 v[82:97], v[146:153], v[114:121], v[82:97] blgp:1
	s_nop 3
	v_med3_f32 v2, v2, 0, v227
	v_med3_f32 v3, v3, 0, v227
	v_cvt_pk_u8_f32 v2, v2, 0, 0
	v_med3_f32 v4, v4, 0, v227
	v_cvt_pk_u8_f32 v2, v3, 1, v2
	v_cvt_pk_u8_f32 v102, v102, 2, v103
	v_med3_f32 v5, v5, 0, v227
	v_cvt_pk_u8_f32 v2, v4, 2, v2
	v_cvt_pk_u8_f32 v101, v101, 3, v102
	v_cvt_pk_u8_f32 v102, v5, 3, v2
	v_med3_f32 v5, v6, 0, v227
	v_med3_f32 v4, v7, 0, v227
	v_cvt_pk_u8_f32 v5, v5, 0, 0
	v_med3_f32 v3, v8, 0, v227
	v_cvt_pk_u8_f32 v4, v4, 1, v5
	v_med3_f32 v5, v10, 0, v227
	v_med3_f32 v2, v9, 0, v227
	v_cvt_pk_u8_f32 v3, v3, 2, v4
	v_med3_f32 v4, v11, 0, v227
	v_cvt_pk_u8_f32 v5, v5, 0, 0
	v_cvt_pk_u8_f32 v103, v2, 3, v3
	v_med3_f32 v3, v12, 0, v227
	v_cvt_pk_u8_f32 v4, v4, 1, v5
	v_med3_f32 v5, v14, 0, v227
	v_med3_f32 v2, v13, 0, v227
	v_cvt_pk_u8_f32 v3, v3, 2, v4
	v_med3_f32 v4, v15, 0, v227
	v_cvt_pk_u8_f32 v5, v5, 0, 0
	v_cvt_pk_u8_f32 v104, v2, 3, v3
	v_med3_f32 v3, v16, 0, v227
	v_cvt_pk_u8_f32 v4, v4, 1, v5
	v_mfma_f32_32x32x64_f8f6f4 v[66:81], v[162:169], v[114:121], v[66:81] blgp:1
	v_med3_f32 v2, v17, 0, v227
	v_cvt_pk_u8_f32 v3, v3, 2, v4
	v_cvt_pk_u8_f32 v105, v2, 3, v3
	ds_read_b128 v[154:157], v220 offset:40960
	ds_read_b128 v[158:161], v220 offset:41984
	ds_read_b128 v[138:141], v220 offset:43008
	ds_read_b128 v[142:145], v220 offset:44032
	ds_read_b128 v[130:133], v220 offset:45056
	ds_read_b128 v[134:137], v220 offset:46080
	ds_read_b128 v[122:125], v220 offset:47104
	ds_read_b128 v[126:129], v220 offset:48128
	v_mfma_f32_32x32x64_f8f6f4 v[82:97], v[146:153], v[98:105], v[82:97] blgp:1
	v_mfma_f32_32x32x64_f8f6f4 v[50:65], v[170:177], v[114:121], v[50:65] blgp:1
	s_nop 15
	s_nop 2
	v_div_scale_f32 v2, s[34:35], v82, v82, 1.0
	v_rcp_f32_e32 v3, v2
	v_cmp_nlt_f32_e32 vcc, 0, v82
	v_cmp_ngt_f32_e64 s[12:13], s29, v82
	s_or_b64 s[12:13], vcc, s[12:13]
	v_fma_f32 v4, -v2, v3, 1.0
	v_fmac_f32_e32 v3, v4, v3
	v_div_scale_f32 v4, vcc, 1.0, v82, 1.0
	v_mul_f32_e32 v5, v4, v3
	v_fma_f32 v6, -v2, v5, v4
	v_fmac_f32_e32 v5, v6, v3
	v_fma_f32 v2, -v2, v5, v4
	v_div_fmas_f32 v2, v2, v3, v5
	v_mfma_f32_32x32x64_f8f6f4 v[34:49], v[178:185], v[114:121], v[34:49] blgp:1
	v_div_fixup_f32 v2, v2, v82, 1.0
	v_cndmask_b32_e64 v4, v2, 0, s[12:13]
	v_lshl_add_u64 v[2:3], v[216:217], 0, v[214:215]
	s_cmp_gt_i32 s30, 15
	s_waitcnt lgkmcnt(0)
	v_mfma_f32_32x32x64_f8f6f4 v[66:81], v[154:161], v[98:105], v[66:81] blgp:1
	v_mfma_f32_32x32x64_f8f6f4 v[18:33], v[186:193], v[114:121], v[18:33] blgp:1
	s_nop 15
	s_nop 2
	v_mul_f32_e64 v6, v66, v4
	v_mul_f32_e64 v7, v67, v4
	v_mul_f32_e64 v8, v68, v4
	v_mul_f32_e64 v9, v69, v4
	v_cvt_pk_bf16_f32 v6, v6, v7
	v_cvt_pk_bf16_f32 v7, v8, v9
	global_store_dwordx2 v[2:3], v[6:7], off
	v_mul_f32_e64 v6, v70, v4
	v_mul_f32_e64 v7, v71, v4
	v_mul_f32_e64 v8, v72, v4
	v_mul_f32_e64 v9, v73, v4
	v_cvt_pk_bf16_f32 v6, v6, v7
	v_cvt_pk_bf16_f32 v7, v8, v9
	global_store_dwordx2 v[2:3], v[6:7], off offset:16
	v_pk_mul_f32 v[6:7], v[74:75], v[4:5] op_sel_hi:[1,0]
	v_pk_mul_f32 v[8:9], v[76:77], v[4:5] op_sel_hi:[1,0]
	v_cvt_pk_bf16_f32 v6, v6, v7
	v_cvt_pk_bf16_f32 v7, v8, v9
	global_store_dwordx2 v[2:3], v[6:7], off offset:32
	v_mfma_f32_32x32x64_f8f6f4 v[50:65], v[138:145], v[98:105], v[50:65] blgp:1
	v_mul_f32_e64 v6, v78, v4
	v_mul_f32_e64 v7, v79, v4
	v_mul_f32_e64 v8, v80, v4
	v_mul_f32_e64 v9, v81, v4
	v_cvt_pk_bf16_f32 v6, v6, v7
	v_cvt_pk_bf16_f32 v7, v8, v9
	global_store_dwordx2 v[2:3], v[6:7], off offset:48
	s_nop 12
	v_pk_mul_f32 v[6:7], v[50:51], v[4:5] op_sel_hi:[1,0]
	v_mfma_f32_32x32x64_f8f6f4 v[34:49], v[130:137], v[98:105], v[34:49] blgp:1
	v_mul_f32_e64 v8, v52, v4
	v_mul_f32_e64 v9, v53, v4
	v_cvt_pk_bf16_f32 v6, v6, v7
	v_cvt_pk_bf16_f32 v7, v8, v9
	global_store_dwordx2 v[2:3], v[6:7], off offset:64
	v_mul_f32_e64 v6, v54, v4
	v_mul_f32_e64 v7, v55, v4
	v_mul_f32_e64 v8, v56, v4
	v_mul_f32_e64 v9, v57, v4
	v_cvt_pk_bf16_f32 v6, v6, v7
	v_cvt_pk_bf16_f32 v7, v8, v9
	global_store_dwordx2 v[2:3], v[6:7], off offset:80
	v_mul_f32_e64 v6, v58, v4
	v_mul_f32_e64 v7, v59, v4
	v_pk_mul_f32 v[8:9], v[60:61], v[4:5] op_sel_hi:[1,0]
	v_cvt_pk_bf16_f32 v6, v6, v7
	v_cvt_pk_bf16_f32 v7, v8, v9
	global_store_dwordx2 v[2:3], v[6:7], off offset:96
	v_pk_mul_f32 v[6:7], v[62:63], v[4:5] op_sel_hi:[1,0]
	v_mfma_f32_32x32x64_f8f6f4 v[18:33], v[122:129], v[98:105], v[18:33] blgp:1
	v_mul_f32_e64 v8, v64, v4
	v_mul_f32_e64 v9, v65, v4
	v_cvt_pk_bf16_f32 v6, v6, v7
	v_cvt_pk_bf16_f32 v7, v8, v9
	global_store_dwordx2 v[2:3], v[6:7], off offset:112
	v_mul_f32_e64 v6, v34, v4
	v_mul_f32_e64 v7, v35, v4
	v_mul_f32_e64 v8, v36, v4
	v_mul_f32_e64 v9, v37, v4
	v_cvt_pk_bf16_f32 v6, v6, v7
	v_cvt_pk_bf16_f32 v7, v8, v9
	global_store_dwordx2 v[2:3], v[6:7], off offset:128
	v_mul_f32_e64 v6, v38, v4
	v_mul_f32_e64 v7, v39, v4
	v_pk_mul_f32 v[8:9], v[40:41], v[4:5] op_sel_hi:[1,0]
	v_cvt_pk_bf16_f32 v6, v6, v7
	v_cvt_pk_bf16_f32 v7, v8, v9
	global_store_dwordx2 v[2:3], v[6:7], off offset:144
	v_pk_mul_f32 v[6:7], v[42:43], v[4:5] op_sel_hi:[1,0]
	v_pk_mul_f32 v[8:9], v[44:45], v[4:5] op_sel_hi:[1,0]
	v_cvt_pk_bf16_f32 v6, v6, v7
	v_cvt_pk_bf16_f32 v7, v8, v9
	global_store_dwordx2 v[2:3], v[6:7], off offset:160
	v_pk_mul_f32 v[6:7], v[46:47], v[4:5] op_sel_hi:[1,0]
	v_pk_mul_f32 v[8:9], v[48:49], v[4:5] op_sel_hi:[1,0]
	v_cvt_pk_bf16_f32 v6, v6, v7
	v_cvt_pk_bf16_f32 v7, v8, v9
	global_store_dwordx2 v[2:3], v[6:7], off offset:176
	v_pk_mul_f32 v[6:7], v[18:19], v[4:5] op_sel_hi:[1,0]
	v_pk_mul_f32 v[8:9], v[20:21], v[4:5] op_sel_hi:[1,0]
	v_cvt_pk_bf16_f32 v6, v6, v7
	v_cvt_pk_bf16_f32 v7, v8, v9
	global_store_dwordx2 v[2:3], v[6:7], off offset:192
	v_pk_mul_f32 v[6:7], v[22:23], v[4:5] op_sel_hi:[1,0]
	v_pk_mul_f32 v[8:9], v[24:25], v[4:5] op_sel_hi:[1,0]
	v_cvt_pk_bf16_f32 v6, v6, v7
	v_cvt_pk_bf16_f32 v7, v8, v9
	global_store_dwordx2 v[2:3], v[6:7], off offset:208
	v_pk_mul_f32 v[6:7], v[26:27], v[4:5] op_sel_hi:[1,0]
	v_pk_mul_f32 v[8:9], v[28:29], v[4:5] op_sel_hi:[1,0]
	v_cvt_pk_bf16_f32 v6, v6, v7
	v_cvt_pk_bf16_f32 v7, v8, v9
	global_store_dwordx2 v[2:3], v[6:7], off offset:224
	v_pk_mul_f32 v[6:7], v[30:31], v[4:5] op_sel_hi:[1,0]
	v_pk_mul_f32 v[4:5], v[32:33], v[4:5] op_sel_hi:[1,0]
	v_cvt_pk_bf16_f32 v6, v6, v7
	v_cvt_pk_bf16_f32 v7, v4, v5
	global_store_dwordx2 v[2:3], v[6:7], off offset:240
	s_barrier
	s_cbranch_scc0 .LBB0_4076

.LBB0_4318:
	ds_read_b128 v[2:5], v167
	ds_read_b128 v[6:9], v171
	ds_read_b128 v[10:13], v172
	ds_read_b128 v[14:17], v173
	s_add_u32 s0, s30, 0xfffe0080
	s_addc_u32 s1, s31, -1
	s_cmp_eq_u32 s73, 4
	s_cselect_b32 s37, s23, s1
	s_cselect_b32 s36, s69, s0
	s_cselect_b32 s35, s21, s72
	s_cselect_b32 s34, s70, s71
	v_lshl_add_u64 v[158:159], s[30:31], 0, v[152:153]
	s_add_i32 m0, s29, 0xc000
	ds_read_b128 v[186:189], v184
	ds_read_b128 v[190:193], v184 offset:1024
	ds_read_b128 v[194:197], v184 offset:2048
	ds_read_b128 v[198:201], v184 offset:3072
	ds_read_b128 v[202:205], v184 offset:4096
	ds_read_b128 v[206:209], v184 offset:5120
	ds_read_b128 v[210:213], v184 offset:6144
	ds_read_b128 v[214:217], v184 offset:7168
	global_load_lds_dwordx4 v[158:159], off
	v_lshl_add_u64 v[158:159], s[30:31], 0, v[150:151]
	s_add_i32 m0, s29, 0xe000
	s_nop 0
	global_load_lds_dwordx4 v[158:159], off
	s_waitcnt lgkmcnt(8)
	s_barrier
	s_waitcnt lgkmcnt(0)
	s_setprio 1
	s_waitcnt lgkmcnt(0)
	v_mfma_f32_16x16x128_f8f6f4 v[142:145], v[2:9], v[186:193], v[142:145]
	v_mfma_f32_16x16x128_f8f6f4 v[138:141], v[10:17], v[186:193], v[138:141]
	v_mfma_f32_16x16x128_f8f6f4 v[126:129], v[2:9], v[194:201], v[126:129]
	v_mfma_f32_16x16x128_f8f6f4 v[122:125], v[10:17], v[194:201], v[122:125]
	v_mfma_f32_16x16x128_f8f6f4 v[110:113], v[2:9], v[202:209], v[110:113]
	v_mfma_f32_16x16x128_f8f6f4 v[106:109], v[10:17], v[202:209], v[106:109]
	v_mfma_f32_16x16x128_f8f6f4 v[94:97], v[2:9], v[210:217], v[94:97]
	v_mfma_f32_16x16x128_f8f6f4 v[90:93], v[10:17], v[210:217], v[90:93]
	s_setprio 0
	s_barrier
	s_mov_b32 m0, s43
	v_lshl_add_u64 v[158:159], s[34:35], 0, v[148:149]
	ds_read_b128 v[220:223], v168
	ds_read_b128 v[224:227], v174
	ds_read_b128 v[228:231], v175
	ds_read_b128 v[232:235], v176
	global_load_lds_dwordx4 v[158:159], off
	v_lshl_add_u64 v[160:161], s[34:35], 0, v[146:147]
	s_mov_b32 m0, s44
	s_nop 0
	global_load_lds_dwordx4 v[160:161], off
	s_barrier
	s_waitcnt lgkmcnt(0)
	s_setprio 1
	s_waitcnt lgkmcnt(0)
	v_mfma_f32_16x16x128_f8f6f4 v[134:137], v[220:227], v[186:193], v[134:137]
	v_mfma_f32_16x16x128_f8f6f4 v[130:133], v[228:235], v[186:193], v[130:133]
	v_mfma_f32_16x16x128_f8f6f4 v[118:121], v[220:227], v[194:201], v[118:121]
	v_mfma_f32_16x16x128_f8f6f4 v[114:117], v[228:235], v[194:201], v[114:117]
	v_mfma_f32_16x16x128_f8f6f4 v[102:105], v[220:227], v[202:209], v[102:105]
	v_mfma_f32_16x16x128_f8f6f4 v[98:101], v[228:235], v[202:209], v[98:101]
	v_mfma_f32_16x16x128_f8f6f4 v[86:89], v[220:227], v[210:217], v[86:89]
	v_mfma_f32_16x16x128_f8f6f4 v[82:85], v[228:235], v[210:217], v[82:85]
	s_setprio 0
	s_mov_b32 m0, s29
	v_lshl_add_u64 v[162:163], s[36:37], 0, v[148:149]
	s_barrier
	ds_read_b128 v[186:189], v184 offset:16384
	ds_read_b128 v[190:193], v184 offset:17408
	ds_read_b128 v[194:197], v184 offset:18432
	ds_read_b128 v[198:201], v184 offset:19456
	ds_read_b128 v[202:205], v184 offset:20480
	ds_read_b128 v[206:209], v184 offset:21504
	ds_read_b128 v[210:213], v184 offset:22528
	ds_read_b128 v[214:217], v184 offset:23552
	global_load_lds_dwordx4 v[162:163], off
	v_lshl_add_u64 v[164:165], s[36:37], 0, v[146:147]
	s_mov_b32 m0, s45
	s_nop 0
	global_load_lds_dwordx4 v[164:165], off
	s_barrier
	s_waitcnt lgkmcnt(0)
	s_setprio 1
	s_waitcnt lgkmcnt(0)
	v_mfma_f32_16x16x128_f8f6f4 v[78:81], v[2:9], v[186:193], v[78:81]
	v_mfma_f32_16x16x128_f8f6f4 v[74:77], v[10:17], v[186:193], v[74:77]
	v_mfma_f32_16x16x128_f8f6f4 v[62:65], v[2:9], v[194:201], v[62:65]
	v_mfma_f32_16x16x128_f8f6f4 v[58:61], v[10:17], v[194:201], v[58:61]
	v_mfma_f32_16x16x128_f8f6f4 v[46:49], v[2:9], v[202:209], v[46:49]
	v_mfma_f32_16x16x128_f8f6f4 v[42:45], v[10:17], v[202:209], v[42:45]
	v_mfma_f32_16x16x128_f8f6f4 v[30:33], v[2:9], v[210:217], v[30:33]
	v_mfma_f32_16x16x128_f8f6f4 v[26:29], v[10:17], v[210:217], v[26:29]
	s_setprio 0
	s_barrier
	s_add_u32 s74, s34, 0x20000
	s_addc_u32 s75, s35, 0
	s_mov_b32 m0, s46
	v_lshl_add_u64 v[2:3], s[74:75], 0, v[148:149]
	global_load_lds_dwordx4 v[2:3], off
	v_lshl_add_u64 v[2:3], s[74:75], 0, v[146:147]
	s_mov_b32 m0, s47
	s_nop 0
	global_load_lds_dwordx4 v[2:3], off
	s_waitcnt vmcnt(6)
	s_barrier
	s_setprio 1
	v_mfma_f32_16x16x128_f8f6f4 v[70:73], v[220:227], v[186:193], v[70:73]
	v_mfma_f32_16x16x128_f8f6f4 v[66:69], v[228:235], v[186:193], v[66:69]
	v_mfma_f32_16x16x128_f8f6f4 v[54:57], v[220:227], v[194:201], v[54:57]
	v_mfma_f32_16x16x128_f8f6f4 v[50:53], v[228:235], v[194:201], v[50:53]
	v_mfma_f32_16x16x128_f8f6f4 v[38:41], v[220:227], v[202:209], v[38:41]
	v_mfma_f32_16x16x128_f8f6f4 v[34:37], v[228:235], v[202:209], v[34:37]
	v_mfma_f32_16x16x128_f8f6f4 v[22:25], v[220:227], v[210:217], v[22:25]
	v_mfma_f32_16x16x128_f8f6f4 v[18:21], v[228:235], v[210:217], v[18:21]
	s_setprio 0
	s_barrier
	ds_read_b128 v[2:5], v169
	ds_read_b128 v[6:9], v177
	ds_read_b128 v[10:13], v178
	ds_read_b128 v[14:17], v179
	s_add_u32 s36, s36, 0x20000
	s_addc_u32 s37, s37, 0
	s_mov_b32 m0, s48
	v_lshl_add_u64 v[220:221], s[36:37], 0, v[148:149]
	ds_read_b128 v[186:189], v184 offset:32768
	ds_read_b128 v[190:193], v184 offset:33792
	ds_read_b128 v[194:197], v184 offset:34816
	ds_read_b128 v[198:201], v184 offset:35840
	ds_read_b128 v[202:205], v184 offset:36864
	ds_read_b128 v[206:209], v184 offset:37888
	ds_read_b128 v[210:213], v184 offset:38912
	ds_read_b128 v[214:217], v184 offset:39936
	global_load_lds_dwordx4 v[220:221], off
	v_lshl_add_u64 v[220:221], s[36:37], 0, v[146:147]
	s_mov_b32 m0, s49
	s_nop 0
	global_load_lds_dwordx4 v[220:221], off
	s_waitcnt lgkmcnt(8)
	s_barrier
	s_waitcnt lgkmcnt(0)
	s_setprio 1
	s_waitcnt lgkmcnt(0)
	v_mfma_f32_16x16x128_f8f6f4 v[142:145], v[2:9], v[186:193], v[142:145]
	v_mfma_f32_16x16x128_f8f6f4 v[138:141], v[10:17], v[186:193], v[138:141]
	v_mfma_f32_16x16x128_f8f6f4 v[126:129], v[2:9], v[194:201], v[126:129]
	v_mfma_f32_16x16x128_f8f6f4 v[122:125], v[10:17], v[194:201], v[122:125]
	v_mfma_f32_16x16x128_f8f6f4 v[110:113], v[2:9], v[202:209], v[110:113]
	v_mfma_f32_16x16x128_f8f6f4 v[106:109], v[10:17], v[202:209], v[106:109]
	v_mfma_f32_16x16x128_f8f6f4 v[94:97], v[2:9], v[210:217], v[94:97]
	v_mfma_f32_16x16x128_f8f6f4 v[90:93], v[10:17], v[210:217], v[90:93]
	s_setprio 0
	s_barrier
	s_mov_b32 m0, s53
	v_lshl_add_u64 v[158:159], v[158:159], 0, s[16:17]
	ds_read_b128 v[220:223], v170
	ds_read_b128 v[224:227], v180
	ds_read_b128 v[228:231], v181
	ds_read_b128 v[232:235], v182
	global_load_lds_dwordx4 v[158:159], off
	v_lshl_add_u64 v[158:159], v[160:161], 0, s[16:17]
	s_mov_b32 m0, s55
	s_nop 0
	global_load_lds_dwordx4 v[158:159], off
	s_barrier
	s_waitcnt lgkmcnt(0)
	s_setprio 1
	s_waitcnt lgkmcnt(0)
	v_mfma_f32_16x16x128_f8f6f4 v[134:137], v[220:227], v[186:193], v[134:137]
	v_mfma_f32_16x16x128_f8f6f4 v[130:133], v[228:235], v[186:193], v[130:133]
	v_mfma_f32_16x16x128_f8f6f4 v[118:121], v[220:227], v[194:201], v[118:121]
	v_mfma_f32_16x16x128_f8f6f4 v[114:117], v[228:235], v[194:201], v[114:117]
	v_mfma_f32_16x16x128_f8f6f4 v[102:105], v[220:227], v[202:209], v[102:105]
	v_mfma_f32_16x16x128_f8f6f4 v[98:101], v[228:235], v[202:209], v[98:101]
	v_mfma_f32_16x16x128_f8f6f4 v[86:89], v[220:227], v[210:217], v[86:89]
	v_mfma_f32_16x16x128_f8f6f4 v[82:85], v[228:235], v[210:217], v[82:85]
	s_setprio 0
	s_mov_b32 m0, s62
	v_lshl_add_u64 v[158:159], v[162:163], 0, s[16:17]
	s_barrier
	ds_read_b128 v[186:189], v184 offset:49152
	ds_read_b128 v[190:193], v184 offset:50176
	ds_read_b128 v[194:197], v184 offset:51200
	ds_read_b128 v[198:201], v184 offset:52224
	ds_read_b128 v[202:205], v184 offset:53248
	ds_read_b128 v[206:209], v184 offset:54272
	ds_read_b128 v[210:213], v184 offset:55296
	ds_read_b128 v[214:217], v184 offset:56320
	global_load_lds_dwordx4 v[158:159], off
	v_lshl_add_u64 v[158:159], v[164:165], 0, s[16:17]
	s_mov_b32 m0, s63
	s_nop 0
	global_load_lds_dwordx4 v[158:159], off
	s_barrier
	s_waitcnt lgkmcnt(0)
	s_setprio 1
	s_waitcnt lgkmcnt(0)
	v_mfma_f32_16x16x128_f8f6f4 v[78:81], v[2:9], v[186:193], v[78:81]
	v_mfma_f32_16x16x128_f8f6f4 v[74:77], v[10:17], v[186:193], v[74:77]
	v_mfma_f32_16x16x128_f8f6f4 v[62:65], v[2:9], v[194:201], v[62:65]
	v_mfma_f32_16x16x128_f8f6f4 v[58:61], v[10:17], v[194:201], v[58:61]
	v_mfma_f32_16x16x128_f8f6f4 v[46:49], v[2:9], v[202:209], v[46:49]
	v_mfma_f32_16x16x128_f8f6f4 v[42:45], v[10:17], v[202:209], v[42:45]
	v_mfma_f32_16x16x128_f8f6f4 v[30:33], v[2:9], v[210:217], v[30:33]
	v_mfma_f32_16x16x128_f8f6f4 v[26:29], v[10:17], v[210:217], v[26:29]
	s_setprio 0
	s_barrier
	s_add_u32 s34, s34, 0x20080
	s_addc_u32 s35, s35, 0
	s_mov_b32 m0, s64
	v_lshl_add_u64 v[2:3], s[34:35], 0, v[148:149]
	global_load_lds_dwordx4 v[2:3], off
	v_lshl_add_u64 v[2:3], s[34:35], 0, v[146:147]
	s_mov_b32 m0, s65
	s_nop 0
	global_load_lds_dwordx4 v[2:3], off
	s_waitcnt vmcnt(6)
	s_barrier
	s_setprio 1
	v_mfma_f32_16x16x128_f8f6f4 v[70:73], v[220:227], v[186:193], v[70:73]
	v_mfma_f32_16x16x128_f8f6f4 v[66:69], v[228:235], v[186:193], v[66:69]
	v_mfma_f32_16x16x128_f8f6f4 v[54:57], v[220:227], v[194:201], v[54:57]
	v_mfma_f32_16x16x128_f8f6f4 v[50:53], v[228:235], v[194:201], v[50:53]
	v_mfma_f32_16x16x128_f8f6f4 v[38:41], v[220:227], v[202:209], v[38:41]
	v_mfma_f32_16x16x128_f8f6f4 v[34:37], v[228:235], v[202:209], v[34:37]
	v_mfma_f32_16x16x128_f8f6f4 v[22:25], v[220:227], v[210:217], v[22:25]
	v_mfma_f32_16x16x128_f8f6f4 v[18:21], v[228:235], v[210:217], v[18:21]
	s_setprio 0
	s_add_i32 s73, s73, 2
	s_add_u32 s71, s71, 0x100
	s_addc_u32 s72, s72, 0
	s_add_u32 s30, s30, 0x100
	s_addc_u32 s31, s31, 0
	s_cmp_gt_u32 s73, 5
	s_barrier
	s_cbranch_scc0 .LBB0_4318
	v_lshl_or_b32 v10, s68, 8, v183
	v_or_b32_e32 v2, 0x80, v10
	v_ashrrev_i32_e32 v3, 31, v2
	v_lshl_add_u64 v[14:15], v[2:3], 2, s[14:15]
	v_or_b32_e32 v2, 16, v10
	v_ashrrev_i32_e32 v11, 31, v10
	v_ashrrev_i32_e32 v3, 31, v2
	s_nop 15
	s_nop 15
	v_lshl_add_u64 v[16:17], v[10:11], 2, s[14:15]
	v_lshl_add_u64 v[158:159], v[2:3], 2, s[14:15]
	global_load_dwordx4 v[186:189], v[16:17], off
	global_load_dwordx4 v[190:193], v[158:159], off
	global_load_dwordx4 v[6:9], v[14:15], off
	v_or_b32_e32 v2, 0x90, v10
	v_ashrrev_i32_e32 v3, 31, v2
	v_lshl_add_u64 v[160:161], v[2:3], 2, s[14:15]
	global_load_dwordx4 v[2:5], v[160:161], off
	v_lshl_add_u32 v162, s28, 8, v166
	v_mov_b64_e32 v[12:13], s[12:13]
	v_mad_i64_i32 v[164:165], s[30:31], v162, s67, v[12:13]
	v_lshlrev_b64 v[10:11], 1, v[10:11]
	v_lshl_add_u64 v[164:165], v[164:165], 0, v[10:11]
	s_and_b64 vcc, exec, s[8:9]
	s_mov_b32 s68, s20
	s_mov_b32 s28, s22
	s_mov_b64 s[34:35], s[24:25]
	s_waitcnt vmcnt(0)
	v_pk_fma_f32 v[142:143], v[142:143], s[18:19], v[186:187] op_sel_hi:[1,0,1]
	v_pk_fma_f32 v[136:137], v[136:137], s[18:19], v[8:9] op_sel_hi:[1,0,1]
	v_pk_fma_f32 v[134:135], v[134:135], s[18:19], v[6:7] op_sel_hi:[1,0,1]
	v_mul_f32_e32 v142, 0xbfb8aa3b, v142
	v_mul_f32_e32 v143, 0xbfb8aa3b, v143
	v_mul_f32_e32 v134, 0xbfb8aa3b, v134
	v_mul_f32_e32 v135, 0xbfb8aa3b, v135
	v_mul_f32_e32 v136, 0xbfb8aa3b, v136
	v_mul_f32_e32 v137, 0xbfb8aa3b, v137
	v_pk_fma_f32 v[144:145], v[144:145], s[18:19], v[188:189] op_sel_hi:[1,0,1]
	v_exp_f32_e32 v142, v142
	v_exp_f32_e32 v143, v143
	v_exp_f32_e32 v134, v134
	v_exp_f32_e32 v135, v135
	v_exp_f32_e32 v136, v136
	v_exp_f32_e32 v137, v137
	v_mul_f32_e32 v144, 0xbfb8aa3b, v144
	v_mul_f32_e32 v145, 0xbfb8aa3b, v145
	v_pk_fma_f32 v[140:141], v[140:141], s[18:19], v[192:193] op_sel_hi:[1,0,1]
	v_pk_fma_f32 v[138:139], v[138:139], s[18:19], v[190:191] op_sel_hi:[1,0,1]
	v_pk_fma_f32 v[132:133], v[132:133], s[18:19], v[4:5] op_sel_hi:[1,0,1]
	v_pk_fma_f32 v[130:131], v[130:131], s[18:19], v[2:3] op_sel_hi:[1,0,1]
	v_exp_f32_e32 v144, v144
	v_exp_f32_e32 v145, v145
	v_mul_f32_e32 v138, 0xbfb8aa3b, v138
	v_mul_f32_e32 v139, 0xbfb8aa3b, v139
	v_mul_f32_e32 v140, 0xbfb8aa3b, v140
	v_mul_f32_e32 v141, 0xbfb8aa3b, v141
	v_mul_f32_e32 v130, 0xbfb8aa3b, v130
	v_mul_f32_e32 v132, 0xbfb8aa3b, v132
	v_mul_f32_e32 v133, 0xbfb8aa3b, v133
	v_exp_f32_e32 v138, v138
	v_exp_f32_e32 v139, v139
	v_exp_f32_e32 v140, v140
	v_exp_f32_e32 v141, v141
	v_exp_f32_e32 v130, v130
	v_exp_f32_e32 v163, v132
	v_exp_f32_e32 v133, v133
	v_add_f32_e32 v132, 1.0, v142
	v_add_f32_e32 v142, 1.0, v143
	v_add_f32_e32 v134, 1.0, v134
	v_add_f32_e32 v135, 1.0, v135
	v_add_f32_e32 v136, 1.0, v136
	v_add_f32_e32 v137, 1.0, v137
	v_rcp_f32_e32 v132, v132
	v_rcp_f32_e32 v142, v142
	v_rcp_f32_e32 v134, v134
	v_rcp_f32_e32 v135, v135
	v_rcp_f32_e32 v136, v136
	v_rcp_f32_e32 v137, v137
	v_mul_f32_e32 v131, 0xbfb8aa3b, v131
	v_add_f32_e32 v143, 1.0, v144
	v_add_f32_e32 v144, 1.0, v145
	v_exp_f32_e32 v131, v131
	v_rcp_f32_e32 v143, v143
	v_rcp_f32_e32 v144, v144
	v_add_f32_e32 v138, 1.0, v138
	v_add_f32_e32 v139, 1.0, v139
	v_add_f32_e32 v140, 1.0, v140
	v_add_f32_e32 v141, 1.0, v141
	v_add_f32_e32 v130, 1.0, v130
	v_rcp_f32_e32 v138, v138
	v_rcp_f32_e32 v139, v139
	v_rcp_f32_e32 v140, v140
	v_rcp_f32_e32 v141, v141
	v_add_f32_e32 v133, 1.0, v133
	v_pk_fma_f32 v[126:127], v[126:127], s[18:19], v[186:187] op_sel_hi:[1,0,1]
	v_pk_fma_f32 v[6:7], v[118:119], s[18:19], v[6:7] op_sel_hi:[1,0,1]
	v_rcp_f32_e32 v185, v130
	v_cvt_pk_bf16_f32 v130, v132, v142
	v_cvt_pk_bf16_f32 v132, v134, v135
	v_rcp_f32_e32 v134, v133
	v_cvt_pk_bf16_f32 v133, v136, v137
	v_mul_f32_e32 v126, 0xbfb8aa3b, v126
	v_mul_f32_e32 v6, 0xbfb8aa3b, v6
	global_store_dwordx2 v[164:165], v[132:133], off offset:256
	v_exp_f32_e32 v132, v126
	v_mul_f32_e32 v126, 0xbfb8aa3b, v127
	v_exp_f32_e32 v118, v6
	v_mul_f32_e32 v6, 0xbfb8aa3b, v7
	v_add_f32_e32 v145, 1.0, v131
	v_cvt_pk_bf16_f32 v131, v143, v144
	v_exp_f32_e32 v133, v126
	v_exp_f32_e32 v119, v6
	global_store_dwordx2 v[164:165], v[130:131], off
	v_cvt_pk_bf16_f32 v130, v138, v139
	v_cvt_pk_bf16_f32 v131, v140, v141
	v_pk_fma_f32 v[126:127], v[128:129], s[18:19], v[188:189] op_sel_hi:[1,0,1]
	global_store_dwordx2 v[164:165], v[130:131], off offset:32
	v_add_f32_e32 v131, 1.0, v163
	v_mul_f32_e32 v126, 0xbfb8aa3b, v126
	v_rcp_f32_e32 v130, v145
	v_rcp_f32_e32 v131, v131
	v_exp_f32_e32 v126, v126
	v_mul_f32_e32 v127, 0xbfb8aa3b, v127
	v_add_f32_e32 v128, 1.0, v132
	v_add_f32_e32 v129, 1.0, v133
	v_exp_f32_e32 v127, v127
	v_pk_fma_f32 v[6:7], v[120:121], s[18:19], v[8:9] op_sel_hi:[1,0,1]
	v_add_f32_e32 v8, 1.0, v118
	v_add_f32_e32 v9, 1.0, v119
	v_rcp_f32_e32 v128, v128
	v_rcp_f32_e32 v129, v129
	v_rcp_f32_e32 v8, v8
	v_rcp_f32_e32 v9, v9
	v_cvt_pk_bf16_f32 v130, v185, v130
	v_cvt_pk_bf16_f32 v131, v131, v134
	v_add_f32_e32 v126, 1.0, v126
	v_pk_fma_f32 v[122:123], v[122:123], s[18:19], v[190:191] op_sel_hi:[1,0,1]
	v_mul_f32_e32 v6, 0xbfb8aa3b, v6
	v_pk_fma_f32 v[2:3], v[114:115], s[18:19], v[2:3] op_sel_hi:[1,0,1]
	v_rcp_f32_e32 v132, v126
	v_add_f32_e32 v126, 1.0, v127
	global_store_dwordx2 v[164:165], v[130:131], off offset:288
	v_or_b32_e32 v130, 16, v162
	v_mul_f32_e32 v122, 0xbfb8aa3b, v122
	v_exp_f32_e32 v118, v6
	v_mul_f32_e32 v6, 0xbfb8aa3b, v7
	v_mul_f32_e32 v2, 0xbfb8aa3b, v2
	v_rcp_f32_e32 v127, v126
	v_cvt_pk_bf16_f32 v126, v128, v129
	v_mad_i64_i32 v[128:129], s[30:31], v130, s67, v[12:13]
	v_exp_f32_e32 v130, v122
	v_mul_f32_e32 v122, 0xbfb8aa3b, v123
	v_exp_f32_e32 v7, v6
	v_cvt_pk_bf16_f32 v6, v8, v9
	v_exp_f32_e32 v9, v2
	v_mul_f32_e32 v2, 0xbfb8aa3b, v3
	v_exp_f32_e32 v131, v122
	v_pk_fma_f32 v[122:123], v[124:125], s[18:19], v[192:193] op_sel_hi:[1,0,1]
	v_exp_f32_e32 v114, v2
	v_pk_fma_f32 v[2:3], v[116:117], s[18:19], v[4:5] op_sel_hi:[1,0,1]
	v_mul_f32_e32 v122, 0xbfb8aa3b, v122
	v_mul_f32_e32 v2, 0xbfb8aa3b, v2
	v_exp_f32_e32 v122, v122
	v_mul_f32_e32 v123, 0xbfb8aa3b, v123
	v_exp_f32_e32 v2, v2
	v_mul_f32_e32 v3, 0xbfb8aa3b, v3
	v_exp_f32_e32 v123, v123
	v_exp_f32_e32 v3, v3
	v_add_f32_e32 v122, 1.0, v122
	v_add_f32_e32 v2, 1.0, v2
	v_add_f32_e32 v124, 1.0, v130
	v_add_f32_e32 v125, 1.0, v131
	v_rcp_f32_e32 v130, v122
	v_add_f32_e32 v122, 1.0, v123
	v_add_f32_e32 v8, 1.0, v118
	v_add_f32_e32 v7, 1.0, v7
	v_add_f32_e32 v4, 1.0, v9
	v_add_f32_e32 v5, 1.0, v114
	v_rcp_f32_e32 v9, v2
	v_add_f32_e32 v2, 1.0, v3
	v_rcp_f32_e32 v124, v124
	v_rcp_f32_e32 v125, v125
	v_rcp_f32_e32 v131, v122
	v_rcp_f32_e32 v8, v8
	v_rcp_f32_e32 v7, v7
	v_rcp_f32_e32 v4, v4
	v_rcp_f32_e32 v5, v5
	v_rcp_f32_e32 v3, v2
	v_cvt_pk_bf16_f32 v127, v132, v127
	v_lshl_add_u64 v[122:123], v[128:129], 0, v[10:11]
	v_cvt_pk_bf16_f32 v124, v124, v125
	v_cvt_pk_bf16_f32 v125, v130, v131
	v_cvt_pk_bf16_f32 v7, v8, v7
	v_cvt_pk_bf16_f32 v2, v4, v5
	v_cvt_pk_bf16_f32 v3, v9, v3
	global_store_dwordx2 v[122:123], v[126:127], off
	global_store_dwordx2 v[122:123], v[124:125], off offset:32
	global_store_dwordx2 v[122:123], v[6:7], off offset:256
	global_store_dwordx2 v[122:123], v[2:3], off offset:288
	global_load_dwordx4 v[6:9], v[16:17], off
	s_nop 0
	global_load_dwordx4 v[114:117], v[158:159], off
	global_load_dwordx4 v[118:121], v[14:15], off
	global_load_dwordx4 v[2:5], v[160:161], off
	s_waitcnt vmcnt(0)
	v_pk_fma_f32 v[110:111], v[110:111], s[18:19], v[6:7] op_sel_hi:[1,0,1]
	s_nop 0
	v_mul_f32_e32 v110, 0xbfb8aa3b, v110
	v_exp_f32_e32 v122, v110
	v_mul_f32_e32 v110, 0xbfb8aa3b, v111
	v_exp_f32_e32 v123, v110
	v_pk_fma_f32 v[110:111], v[112:113], s[18:19], v[8:9] op_sel_hi:[1,0,1]
	v_pk_fma_f32 v[6:7], v[94:95], s[18:19], v[6:7] op_sel_hi:[1,0,1]
	v_mul_f32_e32 v110, 0xbfb8aa3b, v110
	v_exp_f32_e32 v110, v110
	v_mul_f32_e32 v111, 0xbfb8aa3b, v111
	v_exp_f32_e32 v111, v111
	v_mul_f32_e32 v6, 0xbfb8aa3b, v6
	v_add_f32_e32 v110, 1.0, v110
	v_exp_f32_e32 v94, v6
	v_mul_f32_e32 v6, 0xbfb8aa3b, v7
	v_add_f32_e32 v112, 1.0, v122
	v_rcp_f32_e32 v122, v110
	v_add_f32_e32 v110, 1.0, v111
	v_exp_f32_e32 v95, v6
	v_pk_fma_f32 v[6:7], v[96:97], s[18:19], v[8:9] op_sel_hi:[1,0,1]
	v_add_f32_e32 v113, 1.0, v123
	v_rcp_f32_e32 v111, v110
	v_mul_f32_e32 v6, 0xbfb8aa3b, v6
	v_rcp_f32_e32 v112, v112
	v_rcp_f32_e32 v113, v113
	v_exp_f32_e32 v6, v6
	v_mul_f32_e32 v7, 0xbfb8aa3b, v7
	v_pk_fma_f32 v[106:107], v[106:107], s[18:19], v[114:115] op_sel_hi:[1,0,1]
	v_exp_f32_e32 v7, v7
	v_mul_f32_e32 v106, 0xbfb8aa3b, v106
	v_or_b32_e32 v123, 32, v162
	v_cvt_pk_bf16_f32 v111, v122, v111
	v_exp_f32_e32 v122, v106
	v_mul_f32_e32 v106, 0xbfb8aa3b, v107
	v_cvt_pk_bf16_f32 v110, v112, v113
	v_mad_i64_i32 v[112:113], s[30:31], v123, s67, v[12:13]
	v_exp_f32_e32 v123, v106
	v_pk_fma_f32 v[106:107], v[108:109], s[18:19], v[116:117] op_sel_hi:[1,0,1]
	v_add_f32_e32 v6, 1.0, v6
	v_mul_f32_e32 v106, 0xbfb8aa3b, v106
	v_add_f32_e32 v8, 1.0, v94
	v_rcp_f32_e32 v94, v6
	v_add_f32_e32 v6, 1.0, v7
	v_exp_f32_e32 v106, v106
	v_mul_f32_e32 v107, 0xbfb8aa3b, v107
	v_add_f32_e32 v9, 1.0, v95
	v_rcp_f32_e32 v7, v6
	v_exp_f32_e32 v107, v107
	v_rcp_f32_e32 v8, v8
	v_rcp_f32_e32 v9, v9
	v_pk_fma_f32 v[90:91], v[90:91], s[18:19], v[114:115] op_sel_hi:[1,0,1]
	v_add_f32_e32 v106, 1.0, v106
	v_mul_f32_e32 v90, 0xbfb8aa3b, v90
	v_or_b32_e32 v95, 48, v162
	v_cvt_pk_bf16_f32 v7, v94, v7
	v_exp_f32_e32 v94, v90
	v_mul_f32_e32 v90, 0xbfb8aa3b, v91
	v_add_f32_e32 v108, 1.0, v122
	v_add_f32_e32 v109, 1.0, v123
	v_rcp_f32_e32 v122, v106
	v_add_f32_e32 v106, 1.0, v107
	v_cvt_pk_bf16_f32 v6, v8, v9
	v_mad_i64_i32 v[8:9], s[30:31], v95, s67, v[12:13]
	v_exp_f32_e32 v95, v90
	v_pk_fma_f32 v[90:91], v[92:93], s[18:19], v[116:117] op_sel_hi:[1,0,1]
	v_rcp_f32_e32 v108, v108
	v_rcp_f32_e32 v109, v109
	v_rcp_f32_e32 v123, v106
	v_mul_f32_e32 v90, 0xbfb8aa3b, v90
	v_mul_f32_e32 v91, 0xbfb8aa3b, v91
	v_exp_f32_e32 v90, v90
	v_exp_f32_e32 v91, v91
	v_pk_fma_f32 v[102:103], v[102:103], s[18:19], v[118:119] op_sel_hi:[1,0,1]
	v_lshl_add_u64 v[106:107], v[112:113], 0, v[10:11]
	v_cvt_pk_bf16_f32 v108, v108, v109
	v_cvt_pk_bf16_f32 v109, v122, v123
	v_mul_f32_e32 v102, 0xbfb8aa3b, v102
	global_store_dwordx2 v[106:107], v[108:109], off offset:32
	v_exp_f32_e32 v108, v102
	v_mul_f32_e32 v102, 0xbfb8aa3b, v103
	v_add_f32_e32 v92, 1.0, v94
	v_add_f32_e32 v93, 1.0, v95
	v_add_f32_e32 v90, 1.0, v90
	v_add_f32_e32 v91, 1.0, v91
	v_exp_f32_e32 v109, v102
	v_rcp_f32_e32 v92, v92
	v_rcp_f32_e32 v93, v93
	v_rcp_f32_e32 v90, v90
	v_rcp_f32_e32 v91, v91
	v_lshl_add_u64 v[8:9], v[8:9], 0, v[10:11]
	v_pk_fma_f32 v[102:103], v[104:105], s[18:19], v[120:121] op_sel_hi:[1,0,1]
	v_add_f32_e32 v104, 1.0, v108
	v_add_f32_e32 v105, 1.0, v109
	global_store_dwordx2 v[8:9], v[6:7], off
	v_cvt_pk_bf16_f32 v6, v92, v93
	v_cvt_pk_bf16_f32 v7, v90, v91
	v_rcp_f32_e32 v104, v104
	v_rcp_f32_e32 v105, v105
	v_mul_f32_e32 v102, 0xbfb8aa3b, v102
	global_store_dwordx2 v[8:9], v[6:7], off offset:32
	v_pk_fma_f32 v[6:7], v[86:87], s[18:19], v[118:119] op_sel_hi:[1,0,1]
	v_exp_f32_e32 v108, v102
	v_mul_f32_e32 v6, 0xbfb8aa3b, v6
	v_pk_fma_f32 v[98:99], v[98:99], s[18:19], v[2:3] op_sel_hi:[1,0,1]
	v_exp_f32_e32 v86, v6
	v_mul_f32_e32 v6, 0xbfb8aa3b, v7
	v_pk_fma_f32 v[2:3], v[82:83], s[18:19], v[2:3] op_sel_hi:[1,0,1]
	v_mul_f32_e32 v102, 0xbfb8aa3b, v103
	v_mul_f32_e32 v98, 0xbfb8aa3b, v98
	v_exp_f32_e32 v87, v6
	v_mul_f32_e32 v2, 0xbfb8aa3b, v2
	v_exp_f32_e32 v103, v102
	v_cvt_pk_bf16_f32 v102, v104, v105
	v_exp_f32_e32 v105, v98
	v_mul_f32_e32 v98, 0xbfb8aa3b, v99
	v_exp_f32_e32 v82, v2
	v_mul_f32_e32 v2, 0xbfb8aa3b, v3
	v_add_f32_e32 v104, 1.0, v108
	v_exp_f32_e32 v108, v98
	v_pk_fma_f32 v[98:99], v[100:101], s[18:19], v[4:5] op_sel_hi:[1,0,1]
	v_pk_fma_f32 v[6:7], v[88:89], s[18:19], v[120:121] op_sel_hi:[1,0,1]
	v_exp_f32_e32 v83, v2
	v_pk_fma_f32 v[2:3], v[84:85], s[18:19], v[4:5] op_sel_hi:[1,0,1]
	v_mul_f32_e32 v98, 0xbfb8aa3b, v98
	v_mul_f32_e32 v6, 0xbfb8aa3b, v6
	v_mul_f32_e32 v2, 0xbfb8aa3b, v2
	v_exp_f32_e32 v98, v98
	v_mul_f32_e32 v99, 0xbfb8aa3b, v99
	v_add_f32_e32 v86, 1.0, v86
	v_add_f32_e32 v87, 1.0, v87
	v_exp_f32_e32 v88, v6
	v_mul_f32_e32 v6, 0xbfb8aa3b, v7
	v_exp_f32_e32 v2, v2
	v_mul_f32_e32 v3, 0xbfb8aa3b, v3
	v_exp_f32_e32 v99, v99
	v_rcp_f32_e32 v86, v86
	v_rcp_f32_e32 v87, v87
	v_exp_f32_e32 v7, v6
	v_exp_f32_e32 v3, v3
	v_add_f32_e32 v98, 1.0, v98
	v_add_f32_e32 v2, 1.0, v2
	v_add_f32_e32 v103, 1.0, v103
	v_add_f32_e32 v100, 1.0, v105
	v_add_f32_e32 v101, 1.0, v108
	v_rcp_f32_e32 v105, v98
	v_add_f32_e32 v98, 1.0, v99
	v_cvt_pk_bf16_f32 v6, v86, v87
	v_add_f32_e32 v86, 1.0, v88
	v_add_f32_e32 v7, 1.0, v7
	v_add_f32_e32 v4, 1.0, v82
	v_add_f32_e32 v5, 1.0, v83
	v_rcp_f32_e32 v82, v2
	v_add_f32_e32 v2, 1.0, v3
	v_rcp_f32_e32 v104, v104
	v_rcp_f32_e32 v103, v103
	v_rcp_f32_e32 v100, v100
	v_rcp_f32_e32 v101, v101
	v_rcp_f32_e32 v99, v98
	v_rcp_f32_e32 v86, v86
	v_rcp_f32_e32 v7, v7
	v_rcp_f32_e32 v4, v4
	v_rcp_f32_e32 v5, v5
	v_rcp_f32_e32 v3, v2
	v_cvt_pk_bf16_f32 v103, v104, v103
	v_cvt_pk_bf16_f32 v98, v100, v101
	v_cvt_pk_bf16_f32 v99, v105, v99
	v_cvt_pk_bf16_f32 v7, v86, v7
	v_cvt_pk_bf16_f32 v2, v4, v5
	v_cvt_pk_bf16_f32 v3, v82, v3
	global_store_dwordx2 v[106:107], v[110:111], off
	global_store_dwordx2 v[106:107], v[102:103], off offset:256
	global_store_dwordx2 v[106:107], v[98:99], off offset:288
	global_store_dwordx2 v[8:9], v[6:7], off offset:256
	global_store_dwordx2 v[8:9], v[2:3], off offset:288
	global_load_dwordx4 v[6:9], v[16:17], off
	s_nop 0
	global_load_dwordx4 v[82:85], v[158:159], off
	global_load_dwordx4 v[86:89], v[14:15], off
	global_load_dwordx4 v[2:5], v[160:161], off
	s_waitcnt vmcnt(0)
	v_pk_fma_f32 v[78:79], v[78:79], s[18:19], v[6:7] op_sel_hi:[1,0,1]
	s_nop 0
	v_mul_f32_e32 v78, 0xbfb8aa3b, v78
	v_exp_f32_e32 v90, v78
	v_mul_f32_e32 v78, 0xbfb8aa3b, v79
	v_exp_f32_e32 v91, v78
	v_pk_fma_f32 v[78:79], v[80:81], s[18:19], v[8:9] op_sel_hi:[1,0,1]
	v_pk_fma_f32 v[6:7], v[62:63], s[18:19], v[6:7] op_sel_hi:[1,0,1]
	v_mul_f32_e32 v78, 0xbfb8aa3b, v78
	v_exp_f32_e32 v78, v78
	v_mul_f32_e32 v79, 0xbfb8aa3b, v79
	v_exp_f32_e32 v79, v79
	v_mul_f32_e32 v6, 0xbfb8aa3b, v6
	v_add_f32_e32 v78, 1.0, v78
	v_exp_f32_e32 v62, v6
	v_mul_f32_e32 v6, 0xbfb8aa3b, v7
	v_add_f32_e32 v80, 1.0, v90
	v_rcp_f32_e32 v90, v78
	v_add_f32_e32 v78, 1.0, v79
	v_exp_f32_e32 v63, v6
	v_pk_fma_f32 v[6:7], v[64:65], s[18:19], v[8:9] op_sel_hi:[1,0,1]
	v_add_f32_e32 v81, 1.0, v91
	v_rcp_f32_e32 v79, v78
	v_mul_f32_e32 v6, 0xbfb8aa3b, v6
	v_rcp_f32_e32 v80, v80
	v_rcp_f32_e32 v81, v81
	v_exp_f32_e32 v6, v6
	v_mul_f32_e32 v7, 0xbfb8aa3b, v7
	v_pk_fma_f32 v[74:75], v[74:75], s[18:19], v[82:83] op_sel_hi:[1,0,1]
	v_exp_f32_e32 v7, v7
	v_mul_f32_e32 v74, 0xbfb8aa3b, v74
	v_add_u32_e32 v91, 0x80, v162
	v_cvt_pk_bf16_f32 v79, v90, v79
	v_exp_f32_e32 v90, v74
	v_mul_f32_e32 v74, 0xbfb8aa3b, v75
	v_cvt_pk_bf16_f32 v78, v80, v81
	v_mad_i64_i32 v[80:81], s[30:31], v91, s67, v[12:13]
	v_exp_f32_e32 v91, v74
	v_pk_fma_f32 v[74:75], v[76:77], s[18:19], v[84:85] op_sel_hi:[1,0,1]
	v_add_f32_e32 v6, 1.0, v6
	v_mul_f32_e32 v74, 0xbfb8aa3b, v74
	v_add_f32_e32 v8, 1.0, v62
	v_rcp_f32_e32 v62, v6
	v_add_f32_e32 v6, 1.0, v7
	v_exp_f32_e32 v74, v74
	v_mul_f32_e32 v75, 0xbfb8aa3b, v75
	v_add_f32_e32 v9, 1.0, v63
	v_rcp_f32_e32 v7, v6
	v_exp_f32_e32 v75, v75
	v_rcp_f32_e32 v8, v8
	v_rcp_f32_e32 v9, v9
	v_pk_fma_f32 v[58:59], v[58:59], s[18:19], v[82:83] op_sel_hi:[1,0,1]
	v_add_f32_e32 v74, 1.0, v74
	v_mul_f32_e32 v58, 0xbfb8aa3b, v58
	v_add_u32_e32 v63, 0x90, v162
	v_cvt_pk_bf16_f32 v7, v62, v7
	v_exp_f32_e32 v62, v58
	v_mul_f32_e32 v58, 0xbfb8aa3b, v59
	v_add_f32_e32 v76, 1.0, v90
	v_add_f32_e32 v77, 1.0, v91
	v_rcp_f32_e32 v90, v74
	v_add_f32_e32 v74, 1.0, v75
	v_cvt_pk_bf16_f32 v6, v8, v9
	v_mad_i64_i32 v[8:9], s[30:31], v63, s67, v[12:13]
	v_exp_f32_e32 v63, v58
	v_pk_fma_f32 v[58:59], v[60:61], s[18:19], v[84:85] op_sel_hi:[1,0,1]
	v_rcp_f32_e32 v76, v76
	v_rcp_f32_e32 v77, v77
	v_rcp_f32_e32 v91, v74
	v_mul_f32_e32 v58, 0xbfb8aa3b, v58
	v_mul_f32_e32 v59, 0xbfb8aa3b, v59
	v_exp_f32_e32 v58, v58
	v_exp_f32_e32 v59, v59
	v_pk_fma_f32 v[70:71], v[70:71], s[18:19], v[86:87] op_sel_hi:[1,0,1]
	v_lshl_add_u64 v[74:75], v[80:81], 0, v[10:11]
	v_cvt_pk_bf16_f32 v76, v76, v77
	v_cvt_pk_bf16_f32 v77, v90, v91
	v_mul_f32_e32 v70, 0xbfb8aa3b, v70
	global_store_dwordx2 v[74:75], v[76:77], off offset:32
	v_exp_f32_e32 v76, v70
	v_mul_f32_e32 v70, 0xbfb8aa3b, v71
	v_add_f32_e32 v60, 1.0, v62
	v_add_f32_e32 v61, 1.0, v63
	v_add_f32_e32 v58, 1.0, v58
	v_add_f32_e32 v59, 1.0, v59
	v_exp_f32_e32 v77, v70
	v_rcp_f32_e32 v60, v60
	v_rcp_f32_e32 v61, v61
	v_rcp_f32_e32 v58, v58
	v_rcp_f32_e32 v59, v59
	v_lshl_add_u64 v[8:9], v[8:9], 0, v[10:11]
	v_pk_fma_f32 v[70:71], v[72:73], s[18:19], v[88:89] op_sel_hi:[1,0,1]
	v_add_f32_e32 v72, 1.0, v76
	v_add_f32_e32 v73, 1.0, v77
	global_store_dwordx2 v[8:9], v[6:7], off
	v_cvt_pk_bf16_f32 v6, v60, v61
	v_cvt_pk_bf16_f32 v7, v58, v59
	v_rcp_f32_e32 v72, v72
	v_rcp_f32_e32 v73, v73
	v_mul_f32_e32 v70, 0xbfb8aa3b, v70
	global_store_dwordx2 v[8:9], v[6:7], off offset:32
	v_pk_fma_f32 v[6:7], v[54:55], s[18:19], v[86:87] op_sel_hi:[1,0,1]
	v_exp_f32_e32 v76, v70
	v_mul_f32_e32 v6, 0xbfb8aa3b, v6
	v_pk_fma_f32 v[66:67], v[66:67], s[18:19], v[2:3] op_sel_hi:[1,0,1]
	v_exp_f32_e32 v54, v6
	v_mul_f32_e32 v6, 0xbfb8aa3b, v7
	v_pk_fma_f32 v[2:3], v[50:51], s[18:19], v[2:3] op_sel_hi:[1,0,1]
	v_mul_f32_e32 v70, 0xbfb8aa3b, v71
	v_mul_f32_e32 v66, 0xbfb8aa3b, v66
	v_exp_f32_e32 v55, v6
	v_mul_f32_e32 v2, 0xbfb8aa3b, v2
	v_exp_f32_e32 v71, v70
	v_cvt_pk_bf16_f32 v70, v72, v73
	v_exp_f32_e32 v73, v66
	v_mul_f32_e32 v66, 0xbfb8aa3b, v67
	v_exp_f32_e32 v50, v2
	v_mul_f32_e32 v2, 0xbfb8aa3b, v3
	v_add_f32_e32 v72, 1.0, v76
	v_exp_f32_e32 v76, v66
	v_pk_fma_f32 v[66:67], v[68:69], s[18:19], v[4:5] op_sel_hi:[1,0,1]
	v_pk_fma_f32 v[6:7], v[56:57], s[18:19], v[88:89] op_sel_hi:[1,0,1]
	v_exp_f32_e32 v51, v2
	v_pk_fma_f32 v[2:3], v[52:53], s[18:19], v[4:5] op_sel_hi:[1,0,1]
	v_mul_f32_e32 v66, 0xbfb8aa3b, v66
	v_mul_f32_e32 v6, 0xbfb8aa3b, v6
	v_mul_f32_e32 v2, 0xbfb8aa3b, v2
	v_exp_f32_e32 v66, v66
	v_mul_f32_e32 v67, 0xbfb8aa3b, v67
	v_add_f32_e32 v54, 1.0, v54
	v_add_f32_e32 v55, 1.0, v55
	v_exp_f32_e32 v56, v6
	v_mul_f32_e32 v6, 0xbfb8aa3b, v7
	v_exp_f32_e32 v2, v2
	v_mul_f32_e32 v3, 0xbfb8aa3b, v3
	v_exp_f32_e32 v67, v67
	v_rcp_f32_e32 v54, v54
	v_rcp_f32_e32 v55, v55
	v_exp_f32_e32 v7, v6
	v_exp_f32_e32 v3, v3
	v_add_f32_e32 v66, 1.0, v66
	v_add_f32_e32 v2, 1.0, v2
	v_add_f32_e32 v71, 1.0, v71
	v_add_f32_e32 v68, 1.0, v73
	v_add_f32_e32 v69, 1.0, v76
	v_rcp_f32_e32 v73, v66
	v_add_f32_e32 v66, 1.0, v67
	v_cvt_pk_bf16_f32 v6, v54, v55
	v_add_f32_e32 v54, 1.0, v56
	v_add_f32_e32 v7, 1.0, v7
	v_add_f32_e32 v4, 1.0, v50
	v_add_f32_e32 v5, 1.0, v51
	v_rcp_f32_e32 v50, v2
	v_add_f32_e32 v2, 1.0, v3
	v_rcp_f32_e32 v72, v72
	v_rcp_f32_e32 v71, v71
	v_rcp_f32_e32 v68, v68
	v_rcp_f32_e32 v69, v69
	v_rcp_f32_e32 v67, v66
	v_rcp_f32_e32 v54, v54
	v_rcp_f32_e32 v7, v7
	v_rcp_f32_e32 v4, v4
	v_rcp_f32_e32 v5, v5
	v_rcp_f32_e32 v3, v2
	v_cvt_pk_bf16_f32 v71, v72, v71
	v_cvt_pk_bf16_f32 v66, v68, v69
	v_cvt_pk_bf16_f32 v67, v73, v67
	v_cvt_pk_bf16_f32 v7, v54, v7
	v_cvt_pk_bf16_f32 v2, v4, v5
	v_cvt_pk_bf16_f32 v3, v50, v3
	global_store_dwordx2 v[74:75], v[78:79], off
	global_store_dwordx2 v[74:75], v[70:71], off offset:256
	global_store_dwordx2 v[74:75], v[66:67], off offset:288
	global_store_dwordx2 v[8:9], v[6:7], off offset:256
	global_store_dwordx2 v[8:9], v[2:3], off offset:288
	global_load_dwordx4 v[6:9], v[16:17], off
	s_nop 0
	global_load_dwordx4 v[50:53], v[158:159], off
	s_nop 0
	global_load_dwordx4 v[14:17], v[14:15], off
	s_nop 0
	global_load_dwordx4 v[2:5], v[160:161], off
	s_waitcnt vmcnt(0)
	v_pk_fma_f32 v[46:47], v[46:47], s[18:19], v[6:7] op_sel_hi:[1,0,1]
	v_pk_fma_f32 v[6:7], v[30:31], s[18:19], v[6:7] op_sel_hi:[1,0,1]
	v_mul_f32_e32 v46, 0xbfb8aa3b, v46
	v_mul_f32_e32 v6, 0xbfb8aa3b, v6
	v_exp_f32_e32 v54, v46
	v_mul_f32_e32 v46, 0xbfb8aa3b, v47
	v_exp_f32_e32 v30, v6
	v_mul_f32_e32 v6, 0xbfb8aa3b, v7
	v_exp_f32_e32 v55, v46
	v_pk_fma_f32 v[46:47], v[48:49], s[18:19], v[8:9] op_sel_hi:[1,0,1]
	v_exp_f32_e32 v31, v6
	v_mul_f32_e32 v46, 0xbfb8aa3b, v46
	v_pk_fma_f32 v[6:7], v[32:33], s[18:19], v[8:9] op_sel_hi:[1,0,1]
	v_exp_f32_e32 v46, v46
	v_mul_f32_e32 v47, 0xbfb8aa3b, v47
	v_mul_f32_e32 v6, 0xbfb8aa3b, v6
	v_exp_f32_e32 v47, v47
	v_exp_f32_e32 v6, v6
	v_mul_f32_e32 v7, 0xbfb8aa3b, v7
	v_add_f32_e32 v48, 1.0, v54
	v_add_f32_e32 v49, 1.0, v55
	v_add_f32_e32 v8, 1.0, v30
	v_add_f32_e32 v9, 1.0, v31
	v_exp_f32_e32 v7, v7
	v_rcp_f32_e32 v48, v48
	v_rcp_f32_e32 v49, v49
	v_rcp_f32_e32 v8, v8
	v_rcp_f32_e32 v9, v9
	v_add_f32_e32 v46, 1.0, v46
	v_rcp_f32_e32 v54, v46
	v_add_f32_e32 v46, 1.0, v47
	v_add_f32_e32 v6, 1.0, v6
	v_rcp_f32_e32 v47, v46
	v_add_u32_e32 v55, 0xa0, v162
	v_rcp_f32_e32 v30, v6
	v_add_f32_e32 v6, 1.0, v7
	v_add_u32_e32 v31, 0xb0, v162
	v_cvt_pk_bf16_f32 v46, v48, v49
	v_mad_i64_i32 v[48:49], s[30:31], v55, s67, v[12:13]
	v_rcp_f32_e32 v7, v6
	v_cvt_pk_bf16_f32 v6, v8, v9
	v_mad_i64_i32 v[8:9], s[30:31], v31, s67, v[12:13]
	v_pk_fma_f32 v[12:13], v[26:27], s[18:19], v[50:51] op_sel_hi:[1,0,1]
	v_pk_fma_f32 v[42:43], v[42:43], s[18:19], v[50:51] op_sel_hi:[1,0,1]
	v_mul_f32_e32 v12, 0xbfb8aa3b, v12
	v_mul_f32_e32 v42, 0xbfb8aa3b, v42
	v_exp_f32_e32 v26, v12
	v_mul_f32_e32 v12, 0xbfb8aa3b, v13
	v_cvt_pk_bf16_f32 v47, v54, v47
	v_exp_f32_e32 v54, v42
	v_mul_f32_e32 v42, 0xbfb8aa3b, v43
	v_exp_f32_e32 v27, v12
	v_pk_fma_f32 v[12:13], v[28:29], s[18:19], v[52:53] op_sel_hi:[1,0,1]
	v_exp_f32_e32 v55, v42
	v_pk_fma_f32 v[42:43], v[44:45], s[18:19], v[52:53] op_sel_hi:[1,0,1]
	v_mul_f32_e32 v12, 0xbfb8aa3b, v12
	v_mul_f32_e32 v13, 0xbfb8aa3b, v13
	v_mul_f32_e32 v42, 0xbfb8aa3b, v42
	v_exp_f32_e32 v12, v12
	v_exp_f32_e32 v13, v13
	v_exp_f32_e32 v42, v42
	v_mul_f32_e32 v43, 0xbfb8aa3b, v43
	v_exp_f32_e32 v43, v43
	v_add_f32_e32 v26, 1.0, v26
	v_add_f32_e32 v27, 1.0, v27
	v_add_f32_e32 v12, 1.0, v12
	v_add_f32_e32 v13, 1.0, v13
	v_add_f32_e32 v42, 1.0, v42
	v_rcp_f32_e32 v26, v26
	v_rcp_f32_e32 v27, v27
	v_rcp_f32_e32 v12, v12
	v_rcp_f32_e32 v13, v13
	v_add_f32_e32 v44, 1.0, v54
	v_add_f32_e32 v45, 1.0, v55
	v_rcp_f32_e32 v54, v42
	v_add_f32_e32 v42, 1.0, v43
	v_rcp_f32_e32 v44, v44
	v_rcp_f32_e32 v45, v45
	v_rcp_f32_e32 v55, v42
	v_cvt_pk_bf16_f32 v7, v30, v7
	v_lshl_add_u64 v[8:9], v[8:9], 0, v[10:11]
	global_store_dwordx2 v[8:9], v[6:7], off
	v_cvt_pk_bf16_f32 v6, v26, v27
	v_cvt_pk_bf16_f32 v7, v12, v13
	v_pk_fma_f32 v[38:39], v[38:39], s[18:19], v[14:15] op_sel_hi:[1,0,1]
	global_store_dwordx2 v[8:9], v[6:7], off offset:32
	v_pk_fma_f32 v[6:7], v[22:23], s[18:19], v[14:15] op_sel_hi:[1,0,1]
	v_lshl_add_u64 v[42:43], v[48:49], 0, v[10:11]
	v_cvt_pk_bf16_f32 v44, v44, v45
	v_cvt_pk_bf16_f32 v45, v54, v55
	v_mul_f32_e32 v38, 0xbfb8aa3b, v38
	v_mul_f32_e32 v6, 0xbfb8aa3b, v6
	global_store_dwordx2 v[42:43], v[44:45], off offset:32
	v_exp_f32_e32 v44, v38
	v_mul_f32_e32 v38, 0xbfb8aa3b, v39
	v_exp_f32_e32 v10, v6
	v_mul_f32_e32 v6, 0xbfb8aa3b, v7
	v_exp_f32_e32 v45, v38
	v_exp_f32_e32 v11, v6
	v_pk_fma_f32 v[38:39], v[40:41], s[18:19], v[16:17] op_sel_hi:[1,0,1]
	v_add_f32_e32 v40, 1.0, v44
	v_add_f32_e32 v41, 1.0, v45
	v_pk_fma_f32 v[6:7], v[24:25], s[18:19], v[16:17] op_sel_hi:[1,0,1]
	v_add_f32_e32 v10, 1.0, v10
	v_add_f32_e32 v11, 1.0, v11
	v_rcp_f32_e32 v40, v40
	v_rcp_f32_e32 v41, v41
	v_mul_f32_e32 v38, 0xbfb8aa3b, v38
	v_rcp_f32_e32 v10, v10
	v_rcp_f32_e32 v11, v11
	v_mul_f32_e32 v6, 0xbfb8aa3b, v6
	v_exp_f32_e32 v44, v38
	v_exp_f32_e32 v12, v6
	v_pk_fma_f32 v[34:35], v[34:35], s[18:19], v[2:3] op_sel_hi:[1,0,1]
	v_pk_fma_f32 v[2:3], v[18:19], s[18:19], v[2:3] op_sel_hi:[1,0,1]
	v_mul_f32_e32 v38, 0xbfb8aa3b, v39
	v_mul_f32_e32 v34, 0xbfb8aa3b, v34
	v_mul_f32_e32 v6, 0xbfb8aa3b, v7
	v_mul_f32_e32 v2, 0xbfb8aa3b, v2
	v_exp_f32_e32 v39, v38
	v_cvt_pk_bf16_f32 v38, v40, v41
	v_exp_f32_e32 v41, v34
	v_mul_f32_e32 v34, 0xbfb8aa3b, v35
	v_exp_f32_e32 v7, v6
	v_cvt_pk_bf16_f32 v6, v10, v11
	v_exp_f32_e32 v11, v2
	v_mul_f32_e32 v2, 0xbfb8aa3b, v3
	v_add_f32_e32 v40, 1.0, v44
	v_exp_f32_e32 v44, v34
	v_pk_fma_f32 v[34:35], v[36:37], s[18:19], v[4:5] op_sel_hi:[1,0,1]
	v_add_f32_e32 v10, 1.0, v12
	v_exp_f32_e32 v12, v2
	v_pk_fma_f32 v[2:3], v[20:21], s[18:19], v[4:5] op_sel_hi:[1,0,1]
	v_mul_f32_e32 v34, 0xbfb8aa3b, v34
	v_mul_f32_e32 v2, 0xbfb8aa3b, v2
	v_exp_f32_e32 v34, v34
	v_mul_f32_e32 v35, 0xbfb8aa3b, v35
	v_exp_f32_e32 v2, v2
	v_mul_f32_e32 v3, 0xbfb8aa3b, v3
	v_exp_f32_e32 v35, v35
	v_exp_f32_e32 v3, v3
	v_add_f32_e32 v34, 1.0, v34
	v_add_f32_e32 v2, 1.0, v2
	v_add_f32_e32 v39, 1.0, v39
	v_add_f32_e32 v36, 1.0, v41
	v_add_f32_e32 v37, 1.0, v44
	v_rcp_f32_e32 v41, v34
	v_add_f32_e32 v34, 1.0, v35
	v_add_f32_e32 v7, 1.0, v7
	v_add_f32_e32 v4, 1.0, v11
	v_add_f32_e32 v5, 1.0, v12
	v_rcp_f32_e32 v11, v2
	v_add_f32_e32 v2, 1.0, v3
	v_rcp_f32_e32 v40, v40
	v_rcp_f32_e32 v39, v39
	v_rcp_f32_e32 v36, v36
	v_rcp_f32_e32 v37, v37
	v_rcp_f32_e32 v35, v34
	v_rcp_f32_e32 v10, v10
	v_rcp_f32_e32 v7, v7
	v_rcp_f32_e32 v4, v4
	v_rcp_f32_e32 v5, v5
	v_rcp_f32_e32 v3, v2
	v_cvt_pk_bf16_f32 v39, v40, v39
	v_cvt_pk_bf16_f32 v34, v36, v37
	v_cvt_pk_bf16_f32 v35, v41, v35
	v_cvt_pk_bf16_f32 v7, v10, v7
	v_cvt_pk_bf16_f32 v2, v4, v5
	v_cvt_pk_bf16_f32 v3, v11, v3
	s_mov_b64 s[30:31], s[26:27]
	global_store_dwordx2 v[42:43], v[46:47], off
	global_store_dwordx2 v[42:43], v[38:39], off offset:256
	global_store_dwordx2 v[42:43], v[34:35], off offset:288
	global_store_dwordx2 v[8:9], v[6:7], off offset:256
	global_store_dwordx2 v[8:9], v[2:3], off offset:288
	s_cbranch_vccz .LBB0_4315
	s_waitcnt vmcnt(0)
	s_cmpk_gt_u32 s3, 0xff
	s_cbranch_scc1 .LBB0_4322
	s_barrier

.LBB0_5616:
	ds_read2_b32 v[2:3], v178 offset1:16
	s_add_u32 s0, s3, s24
	s_addc_u32 s1, s30, s25
	s_add_u32 s0, s0, 0x1b3c3200
	ds_read2_b32 v[168:169], v178 offset0:32 offset1:48
	s_waitcnt lgkmcnt(0)
	v_lshl_add_u32 v161, v2, 10, v1
	v_lshl_add_u32 v163, v3, 10, v176
	ds_read_b128 v[2:5], v179
	ds_read_b128 v[6:9], v184
	ds_read_b128 v[10:13], v185
	ds_read_b128 v[14:17], v186
	s_addc_u32 s1, s1, 0
	s_add_u32 s2, s62, s24
	s_addc_u32 s4, s63, s25
	s_cmpk_eq_i32 s24, 0x300
	s_cselect_b64 vcc, -1, 0
	s_and_b64 s[26:27], vcc, exec
	v_lshl_add_u32 v198, v168, 10, v1
	v_lshl_add_u32 v199, v169, 10, v176
	v_cndmask_b32_e32 v150, v200, v161, vcc
	s_cselect_b32 s29, s11, s1
	s_cselect_b32 s28, s10, s0
	v_cndmask_b32_e32 v172, v158, v163, vcc
	v_cndmask_b32_e32 v201, v160, v198, vcc
	s_cselect_b32 s27, s19, s4
	s_cselect_b32 s26, s61, s2
	v_cndmask_b32_e32 v219, v162, v199, vcc
	v_lshl_add_u64 v[168:169], v[166:167], 0, s[24:25]
	s_add_i32 m0, s38, 0xc000
	ds_read_b128 v[202:205], v196
	ds_read_b128 v[206:209], v196 offset:1024
	ds_read_b128 v[210:213], v196 offset:2048
	ds_read_b128 v[214:217], v196 offset:3072
	ds_read_b128 v[220:223], v196 offset:4096
	ds_read_b128 v[224:227], v196 offset:5120
	ds_read_b128 v[228:231], v196 offset:6144
	ds_read_b128 v[232:235], v196 offset:7168
	global_load_lds_dwordx4 v[168:169], off
	v_lshl_add_u64 v[168:169], v[164:165], 0, s[24:25]
	s_add_i32 m0, s38, 0xe000
	s_nop 0
	global_load_lds_dwordx4 v[168:169], off
	s_waitcnt lgkmcnt(8)
	s_barrier
	s_waitcnt lgkmcnt(0)
	s_setprio 1
	s_waitcnt lgkmcnt(0)
	v_mfma_f32_16x16x128_f8f6f4 v[142:145], v[2:9], v[202:209], v[142:145]
	v_mfma_f32_16x16x128_f8f6f4 v[138:141], v[10:17], v[202:209], v[138:141]
	v_mfma_f32_16x16x128_f8f6f4 v[126:129], v[2:9], v[210:217], v[126:129]
	v_mfma_f32_16x16x128_f8f6f4 v[122:125], v[10:17], v[210:217], v[122:125]
	v_mfma_f32_16x16x128_f8f6f4 v[110:113], v[2:9], v[220:227], v[110:113]
	v_mfma_f32_16x16x128_f8f6f4 v[106:109], v[10:17], v[220:227], v[106:109]
	v_mfma_f32_16x16x128_f8f6f4 v[94:97], v[2:9], v[228:235], v[94:97]
	v_mfma_f32_16x16x128_f8f6f4 v[90:93], v[10:17], v[228:235], v[90:93]
	s_setprio 0
	s_barrier
	s_mov_b32 m0, s39
	v_lshl_add_u64 v[168:169], s[26:27], 0, v[148:149]
	ds_read_b128 v[236:239], v180
	ds_read_b128 v[240:243], v187
	ds_read_b128 v[244:247], v188
	ds_read_b128 v[248:251], v189
	global_load_lds_dwordx4 v[168:169], off
	v_lshl_add_u64 v[170:171], s[26:27], 0, v[146:147]
	s_mov_b32 m0, s40
	s_nop 0
	global_load_lds_dwordx4 v[170:171], off
	s_barrier
	s_waitcnt lgkmcnt(0)
	s_setprio 1
	s_waitcnt lgkmcnt(0)
	v_mfma_f32_16x16x128_f8f6f4 v[134:137], v[236:243], v[202:209], v[134:137]
	v_mfma_f32_16x16x128_f8f6f4 v[130:133], v[244:251], v[202:209], v[130:133]
	v_mfma_f32_16x16x128_f8f6f4 v[118:121], v[236:243], v[210:217], v[118:121]
	v_mfma_f32_16x16x128_f8f6f4 v[114:117], v[244:251], v[210:217], v[114:117]
	v_mfma_f32_16x16x128_f8f6f4 v[102:105], v[236:243], v[220:227], v[102:105]
	v_mfma_f32_16x16x128_f8f6f4 v[98:101], v[244:251], v[220:227], v[98:101]
	v_mfma_f32_16x16x128_f8f6f4 v[86:89], v[236:243], v[228:235], v[86:89]
	v_mfma_f32_16x16x128_f8f6f4 v[82:85], v[244:251], v[228:235], v[82:85]
	s_setprio 0
	s_mov_b32 m0, s38
	s_barrier
	ds_read_b128 v[202:205], v196 offset:16384
	ds_read_b128 v[206:209], v196 offset:17408
	ds_read_b128 v[210:213], v196 offset:18432
	ds_read_b128 v[214:217], v196 offset:19456
	ds_read_b128 v[220:223], v196 offset:20480
	ds_read_b128 v[224:227], v196 offset:21504
	ds_read_b128 v[228:231], v196 offset:22528
	ds_read_b128 v[232:235], v196 offset:23552
	global_load_lds_dwordx4 v150, s[28:29]
	s_mov_b32 m0, s41
	v_mov_b32_e32 v173, v151
	global_load_lds_dwordx4 v172, s[28:29]
	s_barrier
	s_waitcnt lgkmcnt(0)
	v_lshl_add_u64 v[174:175], s[28:29], 0, v[150:151]
	v_lshl_add_u64 v[172:173], s[28:29], 0, v[172:173]
	s_setprio 1
	s_waitcnt lgkmcnt(0)
	v_mfma_f32_16x16x128_f8f6f4 v[78:81], v[2:9], v[202:209], v[78:81]
	v_mfma_f32_16x16x128_f8f6f4 v[74:77], v[10:17], v[202:209], v[74:77]
	v_mfma_f32_16x16x128_f8f6f4 v[62:65], v[2:9], v[210:217], v[62:65]
	v_mfma_f32_16x16x128_f8f6f4 v[58:61], v[10:17], v[210:217], v[58:61]
	v_mfma_f32_16x16x128_f8f6f4 v[46:49], v[2:9], v[220:227], v[46:49]
	v_mfma_f32_16x16x128_f8f6f4 v[42:45], v[10:17], v[220:227], v[42:45]
	v_mfma_f32_16x16x128_f8f6f4 v[30:33], v[2:9], v[228:235], v[30:33]
	v_mfma_f32_16x16x128_f8f6f4 v[26:29], v[10:17], v[228:235], v[26:29]
	s_setprio 0
	s_barrier
	s_add_u32 s66, s26, 0x20000
	s_addc_u32 s67, s27, 0
	s_mov_b32 m0, s42
	v_lshl_add_u64 v[2:3], s[66:67], 0, v[148:149]
	global_load_lds_dwordx4 v[2:3], off
	v_lshl_add_u64 v[2:3], s[66:67], 0, v[146:147]
	s_mov_b32 m0, s43
	s_nop 0
	global_load_lds_dwordx4 v[2:3], off
	s_waitcnt vmcnt(6)
	s_barrier
	s_setprio 1
	v_mfma_f32_16x16x128_f8f6f4 v[70:73], v[236:243], v[202:209], v[70:73]
	v_mfma_f32_16x16x128_f8f6f4 v[66:69], v[244:251], v[202:209], v[66:69]
	v_mfma_f32_16x16x128_f8f6f4 v[54:57], v[236:243], v[210:217], v[54:57]
	v_mfma_f32_16x16x128_f8f6f4 v[50:53], v[244:251], v[210:217], v[50:53]
	v_mfma_f32_16x16x128_f8f6f4 v[38:41], v[236:243], v[220:227], v[38:41]
	v_mfma_f32_16x16x128_f8f6f4 v[34:37], v[244:251], v[220:227], v[34:37]
	v_mfma_f32_16x16x128_f8f6f4 v[22:25], v[236:243], v[228:235], v[22:25]
	v_mfma_f32_16x16x128_f8f6f4 v[18:21], v[244:251], v[228:235], v[18:21]
	s_setprio 0
	s_barrier
	ds_read_b128 v[2:5], v181
	ds_read_b128 v[6:9], v190
	ds_read_b128 v[10:13], v191
	ds_read_b128 v[14:17], v192
	s_mov_b32 m0, s44
	ds_read_b128 v[202:205], v196 offset:32768
	ds_read_b128 v[206:209], v196 offset:33792
	ds_read_b128 v[210:213], v196 offset:34816
	ds_read_b128 v[214:217], v196 offset:35840
	ds_read_b128 v[220:223], v196 offset:36864
	ds_read_b128 v[224:227], v196 offset:37888
	ds_read_b128 v[228:231], v196 offset:38912
	ds_read_b128 v[232:235], v196 offset:39936
	global_load_lds_dwordx4 v201, s[28:29]
	s_mov_b32 m0, s45
	s_nop 0
	global_load_lds_dwordx4 v219, s[28:29]
	s_waitcnt lgkmcnt(8)
	s_barrier
	s_waitcnt lgkmcnt(0)
	s_setprio 1
	s_waitcnt lgkmcnt(0)
	v_mfma_f32_16x16x128_f8f6f4 v[142:145], v[2:9], v[202:209], v[142:145]
	v_mfma_f32_16x16x128_f8f6f4 v[138:141], v[10:17], v[202:209], v[138:141]
	v_mfma_f32_16x16x128_f8f6f4 v[126:129], v[2:9], v[210:217], v[126:129]
	v_mfma_f32_16x16x128_f8f6f4 v[122:125], v[10:17], v[210:217], v[122:125]
	v_mfma_f32_16x16x128_f8f6f4 v[110:113], v[2:9], v[220:227], v[110:113]
	v_mfma_f32_16x16x128_f8f6f4 v[106:109], v[10:17], v[220:227], v[106:109]
	v_mfma_f32_16x16x128_f8f6f4 v[94:97], v[2:9], v[228:235], v[94:97]
	v_mfma_f32_16x16x128_f8f6f4 v[90:93], v[10:17], v[228:235], v[90:93]
	s_setprio 0
	s_barrier
	s_mov_b32 m0, s47
	v_lshl_add_u64 v[168:169], v[168:169], 0, s[14:15]
	ds_read_b128 v[236:239], v182
	ds_read_b128 v[240:243], v193
	ds_read_b128 v[244:247], v194
	ds_read_b128 v[248:251], v195
	global_load_lds_dwordx4 v[168:169], off
	v_lshl_add_u64 v[168:169], v[170:171], 0, s[14:15]
	s_mov_b32 m0, s48
	s_nop 0
	global_load_lds_dwordx4 v[168:169], off
	s_barrier
	s_waitcnt lgkmcnt(0)
	s_setprio 1
	s_waitcnt lgkmcnt(0)
	v_mfma_f32_16x16x128_f8f6f4 v[134:137], v[236:243], v[202:209], v[134:137]
	v_mfma_f32_16x16x128_f8f6f4 v[130:133], v[244:251], v[202:209], v[130:133]
	v_mfma_f32_16x16x128_f8f6f4 v[118:121], v[236:243], v[210:217], v[118:121]
	v_mfma_f32_16x16x128_f8f6f4 v[114:117], v[244:251], v[210:217], v[114:117]
	v_mfma_f32_16x16x128_f8f6f4 v[102:105], v[236:243], v[220:227], v[102:105]
	v_mfma_f32_16x16x128_f8f6f4 v[98:101], v[244:251], v[220:227], v[98:101]
	v_mfma_f32_16x16x128_f8f6f4 v[86:89], v[236:243], v[228:235], v[86:89]
	v_mfma_f32_16x16x128_f8f6f4 v[82:85], v[244:251], v[228:235], v[82:85]
	s_setprio 0
	s_mov_b32 m0, s49
	v_lshl_add_u64 v[168:169], v[174:175], 0, s[14:15]
	s_barrier
	ds_read_b128 v[202:205], v196 offset:49152
	ds_read_b128 v[206:209], v196 offset:50176
	ds_read_b128 v[210:213], v196 offset:51200
	ds_read_b128 v[214:217], v196 offset:52224
	ds_read_b128 v[220:223], v196 offset:53248
	ds_read_b128 v[224:227], v196 offset:54272
	ds_read_b128 v[228:231], v196 offset:55296
	ds_read_b128 v[232:235], v196 offset:56320
	global_load_lds_dwordx4 v[168:169], off
	v_lshl_add_u64 v[168:169], v[172:173], 0, s[14:15]
	s_mov_b32 m0, s50
	s_nop 0
	global_load_lds_dwordx4 v[168:169], off
	s_barrier
	s_waitcnt lgkmcnt(0)
	s_setprio 1
	s_waitcnt lgkmcnt(0)
	v_mfma_f32_16x16x128_f8f6f4 v[78:81], v[2:9], v[202:209], v[78:81]
	v_mfma_f32_16x16x128_f8f6f4 v[74:77], v[10:17], v[202:209], v[74:77]
	v_mfma_f32_16x16x128_f8f6f4 v[62:65], v[2:9], v[210:217], v[62:65]
	v_mfma_f32_16x16x128_f8f6f4 v[58:61], v[10:17], v[210:217], v[58:61]
	v_mfma_f32_16x16x128_f8f6f4 v[46:49], v[2:9], v[220:227], v[46:49]
	v_mfma_f32_16x16x128_f8f6f4 v[42:45], v[10:17], v[220:227], v[42:45]
	v_mfma_f32_16x16x128_f8f6f4 v[30:33], v[2:9], v[228:235], v[30:33]
	v_mfma_f32_16x16x128_f8f6f4 v[26:29], v[10:17], v[228:235], v[26:29]
	s_setprio 0
	s_barrier
	s_add_u32 s26, s26, 0x20080
	s_addc_u32 s27, s27, 0
	s_mov_b32 m0, s51
	v_lshl_add_u64 v[2:3], s[26:27], 0, v[148:149]
	global_load_lds_dwordx4 v[2:3], off
	v_lshl_add_u64 v[2:3], s[26:27], 0, v[146:147]
	s_mov_b32 m0, s52
	s_nop 0
	global_load_lds_dwordx4 v[2:3], off
	s_waitcnt vmcnt(6)
	s_barrier
	s_setprio 1
	v_mfma_f32_16x16x128_f8f6f4 v[70:73], v[236:243], v[202:209], v[70:73]
	v_mfma_f32_16x16x128_f8f6f4 v[66:69], v[244:251], v[202:209], v[66:69]
	v_mfma_f32_16x16x128_f8f6f4 v[54:57], v[236:243], v[210:217], v[54:57]
	v_mfma_f32_16x16x128_f8f6f4 v[50:53], v[244:251], v[210:217], v[50:53]
	v_mfma_f32_16x16x128_f8f6f4 v[38:41], v[236:243], v[220:227], v[38:41]
	v_mfma_f32_16x16x128_f8f6f4 v[34:37], v[244:251], v[220:227], v[34:37]
	v_mfma_f32_16x16x128_f8f6f4 v[22:25], v[236:243], v[228:235], v[22:25]
	v_mfma_f32_16x16x128_f8f6f4 v[18:21], v[244:251], v[228:235], v[18:21]
	s_setprio 0
	s_add_i32 s64, s64, 2
	s_add_u32 s24, s24, 0x100
	s_addc_u32 s25, s25, 0
	s_cmp_gt_u32 s64, 5
	s_barrier
	s_cbranch_scc0 .LBB0_5616
	v_mul_f32_e32 v3, 0x3d000000, v142
	v_mul_f32_e32 v2, 0xbfb8aa3b, v3
	v_exp_f32_e32 v4, v2
	v_mul_f32_e32 v5, 0x3d000000, v143
	v_mul_f32_e32 v7, 0xbfb8aa3b, v5
	v_exp_f32_e32 v7, v7
	v_add_f32_e32 v4, 1.0, v4
	v_rcp_f32_e32 v4, v4
	v_mul_f32_e32 v8, 0x3d000000, v138
	v_mul_f32_e32 v10, 0x3d000000, v140
	v_mul_f32_e32 v12, 0x3d000000, v135
	v_mul_f32_e32 v3, v3, v4
	v_add_f32_e32 v4, 1.0, v7
	v_rcp_f32_e32 v4, v4
	v_mul_f32_e32 v3, v8, v3
	v_mul_f32_e32 v3, 4.0, v3
	v_med3_f32 v7, v3, s55, v197
	v_mul_f32_e32 v4, v5, v4
	v_mul_f32_e32 v5, 0x3d000000, v144
	v_mul_f32_e32 v8, 0xbfb8aa3b, v5
	v_exp_f32_e32 v8, v8
	v_mul_f32_e32 v3, 0x3d000000, v139
	v_mul_f32_e32 v3, v3, v4
	v_mul_f32_e32 v3, 4.0, v3
	v_add_f32_e32 v4, 1.0, v8
	v_mul_f32_e32 v8, 0x3d000000, v145
	v_mul_f32_e32 v9, 0xbfb8aa3b, v8
	v_rcp_f32_e32 v4, v4
	v_exp_f32_e32 v9, v9
	v_med3_f32 v3, v3, s55, v197
	v_cvt_pk_fp8_f32 v7, v7, v3
	v_mul_f32_e32 v4, v5, v4
	v_add_f32_e32 v5, 1.0, v9
	v_rcp_f32_e32 v5, v5
	v_mul_f32_e32 v9, 0x3d000000, v141
	v_mul_f32_e32 v4, v10, v4
	v_mul_f32_e32 v4, 4.0, v4
	v_mul_f32_e32 v5, v8, v5
	v_mul_f32_e32 v3, v9, v5
	v_mul_f32_e32 v3, 4.0, v3
	v_med3_f32 v4, v4, s55, v197
	v_med3_f32 v3, v3, s55, v197
	v_mul_f32_e32 v10, 0x3d000000, v134
	v_cvt_pk_fp8_f32 v7, v4, v3 op_sel:[0,0,1]
	v_mul_f32_e32 v3, 0xbfb8aa3b, v10
	v_exp_f32_e32 v11, v3
	v_mul_f32_e32 v13, 0xbfb8aa3b, v12
	v_exp_f32_e32 v13, v13
	v_mul_f32_e32 v14, 0x3d000000, v130
	v_add_f32_e32 v11, 1.0, v11
	v_rcp_f32_e32 v11, v11
	s_mul_hi_i32 s0, s22, 0x2e8ba2e9
	s_lshr_b32 s1, s0, 31
	s_lshr_b32 s0, s0, 2
	v_mul_f32_e32 v10, v10, v11
	v_add_f32_e32 v11, 1.0, v13
	v_rcp_f32_e32 v11, v11
	v_mul_f32_e32 v10, v14, v10
	v_mul_f32_e32 v13, 0x3d000000, v131
	v_mul_f32_e32 v10, 4.0, v10
	v_mul_f32_e32 v11, v12, v11
	v_mul_f32_e32 v12, 0x3d000000, v136
	v_mul_f32_e32 v14, 0xbfb8aa3b, v12
	v_exp_f32_e32 v14, v14
	v_mul_f32_e32 v11, v13, v11
	v_mul_f32_e32 v11, 4.0, v11
	v_med3_f32 v10, v10, s55, v197
	v_add_f32_e32 v13, 1.0, v14
	v_mul_f32_e32 v14, 0x3d000000, v137
	v_mul_f32_e32 v15, 0xbfb8aa3b, v14
	v_rcp_f32_e32 v13, v13
	v_exp_f32_e32 v15, v15
	v_med3_f32 v11, v11, s55, v197
	v_mul_f32_e32 v16, 0x3d000000, v132
	v_mul_f32_e32 v12, v12, v13
	v_add_f32_e32 v13, 1.0, v15
	v_rcp_f32_e32 v13, v13
	v_mul_f32_e32 v15, 0x3d000000, v133
	v_cvt_pk_fp8_f32 v10, v10, v11
	s_add_i32 s0, s0, s1
	v_mul_f32_e32 v13, v14, v13
	v_mul_f32_e32 v12, v16, v12
	v_mul_f32_e32 v11, v15, v13
	s_mul_i32 s0, s0, 22
	v_mul_f32_e32 v12, 4.0, v12
	v_mul_f32_e32 v11, 4.0, v11
	s_sub_i32 s0, s22, s0
	v_med3_f32 v12, v12, s55, v197
	v_med3_f32 v11, v11, s55, v197
	v_lshl_add_u32 v6, s60, 8, v159
	v_lshl_or_b32 v2, s0, 7, v183
	v_mov_b64_e32 v[4:5], s[12:13]
	v_cvt_pk_fp8_f32 v10, v12, v11 op_sel:[0,0,1]
	v_mad_i64_i32 v[8:9], s[24:25], v6, s58, v[4:5]
	v_ashrrev_i32_e32 v3, 31, v2
	v_lshl_add_u64 v[8:9], v[8:9], 0, v[2:3]
	s_nop 15
	s_nop 15
	v_mul_f32_e32 v11, 0x3d000000, v126
	global_store_dword v[8:9], v7, off
	global_store_dword v[8:9], v10, off offset:64
	v_mul_f32_e32 v9, 0x3d000000, v127
	v_mul_f32_e32 v12, 0xbfb8aa3b, v11
	v_mul_f32_e32 v10, 0xbfb8aa3b, v9
	v_exp_f32_e32 v12, v12
	v_exp_f32_e32 v10, v10
	v_mul_f32_e32 v14, 0x3d000000, v124
	v_or_b32_e32 v7, 16, v6
	v_add_f32_e32 v8, 1.0, v12
	v_add_f32_e32 v10, 1.0, v10
	v_rcp_f32_e32 v8, v8
	v_rcp_f32_e32 v10, v10
	v_mul_f32_e32 v12, 0x3d000000, v122
	v_mul_f32_e32 v16, 0x3d000000, v116
	v_mul_f32_e32 v8, v11, v8
	v_mul_f32_e32 v9, v9, v10
	v_mul_f32_e32 v10, 0x3d000000, v128
	v_mul_f32_e32 v8, v12, v8
	v_mul_f32_e32 v12, 0xbfb8aa3b, v10
	v_exp_f32_e32 v12, v12
	v_mul_f32_e32 v8, 4.0, v8
	v_med3_f32 v11, v8, s55, v197
	v_mul_f32_e32 v8, 0x3d000000, v123
	v_mul_f32_e32 v8, v8, v9
	v_add_f32_e32 v9, 1.0, v12
	v_mul_f32_e32 v12, 0x3d000000, v129
	v_mul_f32_e32 v13, 0xbfb8aa3b, v12
	v_rcp_f32_e32 v9, v9
	v_exp_f32_e32 v13, v13
	v_mul_f32_e32 v8, 4.0, v8
	v_med3_f32 v8, v8, s55, v197
	v_mul_f32_e32 v9, v10, v9
	v_add_f32_e32 v10, 1.0, v13
	v_rcp_f32_e32 v10, v10
	v_mul_f32_e32 v13, 0x3d000000, v125
	v_cvt_pk_fp8_f32 v11, v11, v8
	v_mul_f32_e32 v9, v14, v9
	v_mul_f32_e32 v10, v12, v10
	v_mul_f32_e32 v8, v13, v10
	v_mul_f32_e32 v9, 4.0, v9
	v_mul_f32_e32 v8, 4.0, v8
	v_med3_f32 v9, v9, s55, v197
	v_med3_f32 v8, v8, s55, v197
	v_mul_f32_e32 v10, 0x3d000000, v118
	v_cvt_pk_fp8_f32 v11, v9, v8 op_sel:[0,0,1]
	v_mul_f32_e32 v8, 0xbfb8aa3b, v10
	v_exp_f32_e32 v12, v8
	v_mad_i64_i32 v[8:9], s[24:25], v7, s58, v[4:5]
	v_mul_f32_e32 v14, 0x3d000000, v114
	v_add_f32_e32 v7, 1.0, v12
	v_mul_f32_e32 v12, 0x3d000000, v119
	v_mul_f32_e32 v13, 0xbfb8aa3b, v12
	v_rcp_f32_e32 v7, v7
	v_exp_f32_e32 v13, v13
	v_lshl_add_u64 v[8:9], v[8:9], 0, v[2:3]
	s_and_b64 vcc, exec, s[8:9]
	v_mul_f32_e32 v7, v10, v7
	v_add_f32_e32 v10, 1.0, v13
	v_rcp_f32_e32 v10, v10
	v_mul_f32_e32 v7, v14, v7
	v_mul_f32_e32 v13, 0x3d000000, v115
	v_mul_f32_e32 v7, 4.0, v7
	v_mul_f32_e32 v10, v12, v10
	v_mul_f32_e32 v12, 0x3d000000, v120
	v_mul_f32_e32 v14, 0xbfb8aa3b, v12
	v_exp_f32_e32 v14, v14
	v_mul_f32_e32 v10, v13, v10
	v_mul_f32_e32 v10, 4.0, v10
	v_med3_f32 v7, v7, s55, v197
	v_add_f32_e32 v13, 1.0, v14
	v_mul_f32_e32 v14, 0x3d000000, v121
	v_mul_f32_e32 v15, 0xbfb8aa3b, v14
	v_rcp_f32_e32 v13, v13
	v_exp_f32_e32 v15, v15
	v_med3_f32 v10, v10, s55, v197
	v_cvt_pk_fp8_f32 v7, v7, v10
	v_mul_f32_e32 v12, v12, v13
	v_add_f32_e32 v13, 1.0, v15
	v_rcp_f32_e32 v13, v13
	v_mul_f32_e32 v15, 0x3d000000, v117
	v_mul_f32_e32 v12, v16, v12
	v_mul_f32_e32 v12, 4.0, v12
	v_mul_f32_e32 v13, v14, v13
	v_mul_f32_e32 v10, v15, v13
	v_mul_f32_e32 v10, 4.0, v10
	v_med3_f32 v12, v12, s55, v197
	v_med3_f32 v10, v10, s55, v197
	v_cvt_pk_fp8_f32 v7, v12, v10 op_sel:[0,0,1]
	v_mul_f32_e32 v10, 0x3d000000, v110
	v_mul_f32_e32 v12, 0xbfb8aa3b, v10
	v_exp_f32_e32 v12, v12
	global_store_dword v[8:9], v11, off
	global_store_dword v[8:9], v7, off offset:64
	v_mul_f32_e32 v9, 0x3d000000, v111
	v_mul_f32_e32 v11, 0xbfb8aa3b, v9
	v_add_f32_e32 v8, 1.0, v12
	v_rcp_f32_e32 v8, v8
	v_exp_f32_e32 v11, v11
	v_mul_f32_e32 v12, 0x3d000000, v106
	v_mul_f32_e32 v14, 0x3d000000, v108
	v_mul_f32_e32 v8, v10, v8
	v_add_f32_e32 v10, 1.0, v11
	v_rcp_f32_e32 v10, v10
	v_mul_f32_e32 v8, v12, v8
	v_mul_f32_e32 v8, 4.0, v8
	v_med3_f32 v11, v8, s55, v197
	v_mul_f32_e32 v9, v9, v10
	v_mul_f32_e32 v10, 0x3d000000, v112
	v_mul_f32_e32 v12, 0xbfb8aa3b, v10
	v_exp_f32_e32 v12, v12
	v_mul_f32_e32 v8, 0x3d000000, v107
	v_mul_f32_e32 v8, v8, v9
	v_mul_f32_e32 v8, 4.0, v8
	v_add_f32_e32 v9, 1.0, v12
	v_mul_f32_e32 v12, 0x3d000000, v113
	v_mul_f32_e32 v13, 0xbfb8aa3b, v12
	v_rcp_f32_e32 v9, v9
	v_exp_f32_e32 v13, v13
	v_med3_f32 v8, v8, s55, v197
	v_cvt_pk_fp8_f32 v11, v11, v8
	v_mul_f32_e32 v9, v10, v9
	v_add_f32_e32 v10, 1.0, v13
	v_rcp_f32_e32 v10, v10
	v_mul_f32_e32 v13, 0x3d000000, v109
	v_mul_f32_e32 v9, v14, v9
	v_mul_f32_e32 v9, 4.0, v9
	v_mul_f32_e32 v10, v12, v10
	v_mul_f32_e32 v8, v13, v10
	v_mul_f32_e32 v8, 4.0, v8
	v_med3_f32 v9, v9, s55, v197
	v_med3_f32 v8, v8, s55, v197
	v_mul_f32_e32 v10, 0x3d000000, v102
	v_cvt_pk_fp8_f32 v11, v9, v8 op_sel:[0,0,1]
	v_mul_f32_e32 v8, 0xbfb8aa3b, v10
	v_exp_f32_e32 v12, v8
	v_or_b32_e32 v7, 32, v6
	v_mad_i64_i32 v[8:9], s[24:25], v7, s58, v[4:5]
	v_add_f32_e32 v7, 1.0, v12
	v_mul_f32_e32 v12, 0x3d000000, v103
	v_mul_f32_e32 v13, 0xbfb8aa3b, v12
	v_rcp_f32_e32 v7, v7
	v_exp_f32_e32 v13, v13
	v_mul_f32_e32 v14, 0x3d000000, v98
	v_mul_f32_e32 v16, 0x3d000000, v100
	v_mul_f32_e32 v7, v10, v7
	v_add_f32_e32 v10, 1.0, v13
	v_rcp_f32_e32 v10, v10
	v_mul_f32_e32 v7, v14, v7
	v_mul_f32_e32 v13, 0x3d000000, v99
	v_mul_f32_e32 v7, 4.0, v7
	v_mul_f32_e32 v10, v12, v10
	v_mul_f32_e32 v12, 0x3d000000, v104
	v_mul_f32_e32 v14, 0xbfb8aa3b, v12
	v_exp_f32_e32 v14, v14
	v_mul_f32_e32 v10, v13, v10
	v_mul_f32_e32 v10, 4.0, v10
	v_med3_f32 v7, v7, s55, v197
	v_add_f32_e32 v13, 1.0, v14
	v_mul_f32_e32 v14, 0x3d000000, v105
	v_mul_f32_e32 v15, 0xbfb8aa3b, v14
	v_rcp_f32_e32 v13, v13
	v_exp_f32_e32 v15, v15
	v_med3_f32 v10, v10, s55, v197
	v_cvt_pk_fp8_f32 v7, v7, v10
	v_mul_f32_e32 v12, v12, v13
	v_add_f32_e32 v13, 1.0, v15
	v_rcp_f32_e32 v13, v13
	v_mul_f32_e32 v15, 0x3d000000, v101
	v_mul_f32_e32 v12, v16, v12
	v_mul_f32_e32 v12, 4.0, v12
	v_mul_f32_e32 v13, v14, v13
	v_mul_f32_e32 v10, v15, v13
	v_mul_f32_e32 v10, 4.0, v10
	v_med3_f32 v12, v12, s55, v197
	v_med3_f32 v10, v10, s55, v197
	v_cvt_pk_fp8_f32 v7, v12, v10 op_sel:[0,0,1]
	v_mul_f32_e32 v10, 0x3d000000, v94
	v_mul_f32_e32 v12, 0xbfb8aa3b, v10
	v_exp_f32_e32 v12, v12
	v_lshl_add_u64 v[8:9], v[8:9], 0, v[2:3]
	global_store_dword v[8:9], v11, off
	global_store_dword v[8:9], v7, off offset:64
	v_mul_f32_e32 v9, 0x3d000000, v95
	v_add_f32_e32 v8, 1.0, v12
	v_mul_f32_e32 v11, 0xbfb8aa3b, v9
	v_rcp_f32_e32 v8, v8
	v_exp_f32_e32 v11, v11
	v_mul_f32_e32 v12, 0x3d000000, v90
	v_mul_f32_e32 v14, 0x3d000000, v92
	v_mul_f32_e32 v8, v10, v8
	v_add_f32_e32 v10, 1.0, v11
	v_rcp_f32_e32 v10, v10
	v_mul_f32_e32 v8, v12, v8
	v_mul_f32_e32 v8, 4.0, v8
	v_med3_f32 v11, v8, s55, v197
	v_mul_f32_e32 v9, v9, v10
	v_mul_f32_e32 v10, 0x3d000000, v96
	v_mul_f32_e32 v12, 0xbfb8aa3b, v10
	v_exp_f32_e32 v12, v12
	v_mul_f32_e32 v8, 0x3d000000, v91
	v_mul_f32_e32 v8, v8, v9
	v_mul_f32_e32 v8, 4.0, v8
	v_add_f32_e32 v9, 1.0, v12
	v_mul_f32_e32 v12, 0x3d000000, v97
	v_mul_f32_e32 v13, 0xbfb8aa3b, v12
	v_rcp_f32_e32 v9, v9
	v_exp_f32_e32 v13, v13
	v_med3_f32 v8, v8, s55, v197
	v_cvt_pk_fp8_f32 v11, v11, v8
	v_mul_f32_e32 v9, v10, v9
	v_add_f32_e32 v10, 1.0, v13
	v_rcp_f32_e32 v10, v10
	v_mul_f32_e32 v13, 0x3d000000, v93
	v_mul_f32_e32 v9, v14, v9
	v_mul_f32_e32 v9, 4.0, v9
	v_mul_f32_e32 v10, v12, v10
	v_mul_f32_e32 v8, v13, v10
	v_mul_f32_e32 v8, 4.0, v8
	v_med3_f32 v9, v9, s55, v197
	v_med3_f32 v8, v8, s55, v197
	v_mul_f32_e32 v10, 0x3d000000, v86
	v_cvt_pk_fp8_f32 v11, v9, v8 op_sel:[0,0,1]
	v_mul_f32_e32 v8, 0xbfb8aa3b, v10
	v_exp_f32_e32 v12, v8
	v_or_b32_e32 v7, 48, v6
	v_mad_i64_i32 v[8:9], s[24:25], v7, s58, v[4:5]
	v_add_f32_e32 v7, 1.0, v12
	v_mul_f32_e32 v12, 0x3d000000, v87
	v_mul_f32_e32 v13, 0xbfb8aa3b, v12
	v_rcp_f32_e32 v7, v7
	v_exp_f32_e32 v13, v13
	v_mul_f32_e32 v14, 0x3d000000, v82
	v_mul_f32_e32 v16, 0x3d000000, v84
	v_mul_f32_e32 v7, v10, v7
	v_add_f32_e32 v10, 1.0, v13
	v_rcp_f32_e32 v10, v10
	v_mul_f32_e32 v7, v14, v7
	v_mul_f32_e32 v13, 0x3d000000, v83
	v_mul_f32_e32 v7, 4.0, v7
	v_mul_f32_e32 v10, v12, v10
	v_mul_f32_e32 v12, 0x3d000000, v88
	v_mul_f32_e32 v14, 0xbfb8aa3b, v12
	v_exp_f32_e32 v14, v14
	v_mul_f32_e32 v10, v13, v10
	v_mul_f32_e32 v10, 4.0, v10
	v_med3_f32 v7, v7, s55, v197
	v_add_f32_e32 v13, 1.0, v14
	v_mul_f32_e32 v14, 0x3d000000, v89
	v_mul_f32_e32 v15, 0xbfb8aa3b, v14
	v_rcp_f32_e32 v13, v13
	v_exp_f32_e32 v15, v15
	v_med3_f32 v10, v10, s55, v197
	v_cvt_pk_fp8_f32 v7, v7, v10
	v_mul_f32_e32 v12, v12, v13
	v_add_f32_e32 v13, 1.0, v15
	v_rcp_f32_e32 v13, v13
	v_mul_f32_e32 v15, 0x3d000000, v85
	v_mul_f32_e32 v12, v16, v12
	v_mul_f32_e32 v12, 4.0, v12
	v_mul_f32_e32 v13, v14, v13
	v_mul_f32_e32 v10, v15, v13
	v_mul_f32_e32 v10, 4.0, v10
	v_med3_f32 v12, v12, s55, v197
	v_med3_f32 v10, v10, s55, v197
	v_cvt_pk_fp8_f32 v7, v12, v10 op_sel:[0,0,1]
	v_mul_f32_e32 v10, 0x3d000000, v78
	v_mul_f32_e32 v12, 0xbfb8aa3b, v10
	v_exp_f32_e32 v12, v12
	v_lshl_add_u64 v[8:9], v[8:9], 0, v[2:3]
	global_store_dword v[8:9], v11, off
	global_store_dword v[8:9], v7, off offset:64
	v_mul_f32_e32 v9, 0x3d000000, v79
	v_add_f32_e32 v8, 1.0, v12
	v_mul_f32_e32 v11, 0xbfb8aa3b, v9
	v_rcp_f32_e32 v8, v8
	v_exp_f32_e32 v11, v11
	v_mul_f32_e32 v12, 0x3d000000, v74
	v_mul_f32_e32 v14, 0x3d000000, v76
	v_mul_f32_e32 v8, v10, v8
	v_add_f32_e32 v10, 1.0, v11
	v_rcp_f32_e32 v10, v10
	v_mul_f32_e32 v8, v12, v8
	v_mul_f32_e32 v8, 4.0, v8
	v_med3_f32 v11, v8, s55, v197
	v_mul_f32_e32 v9, v9, v10
	v_mul_f32_e32 v10, 0x3d000000, v80
	v_mul_f32_e32 v12, 0xbfb8aa3b, v10
	v_exp_f32_e32 v12, v12
	v_mul_f32_e32 v8, 0x3d000000, v75
	v_mul_f32_e32 v8, v8, v9
	v_mul_f32_e32 v8, 4.0, v8
	v_add_f32_e32 v9, 1.0, v12
	v_mul_f32_e32 v12, 0x3d000000, v81
	v_mul_f32_e32 v13, 0xbfb8aa3b, v12
	v_rcp_f32_e32 v9, v9
	v_exp_f32_e32 v13, v13
	v_med3_f32 v8, v8, s55, v197
	v_cvt_pk_fp8_f32 v11, v11, v8
	v_mul_f32_e32 v9, v10, v9
	v_add_f32_e32 v10, 1.0, v13
	v_rcp_f32_e32 v10, v10
	v_mul_f32_e32 v13, 0x3d000000, v77
	v_mul_f32_e32 v9, v14, v9
	v_mul_f32_e32 v9, 4.0, v9
	v_mul_f32_e32 v10, v12, v10
	v_mul_f32_e32 v8, v13, v10
	v_mul_f32_e32 v8, 4.0, v8
	v_med3_f32 v9, v9, s55, v197
	v_med3_f32 v8, v8, s55, v197
	v_mul_f32_e32 v10, 0x3d000000, v70
	v_cvt_pk_fp8_f32 v11, v9, v8 op_sel:[0,0,1]
	v_mul_f32_e32 v8, 0xbfb8aa3b, v10
	v_exp_f32_e32 v12, v8
	v_add_u32_e32 v7, 0x80, v6
	v_mad_i64_i32 v[8:9], s[24:25], v7, s58, v[4:5]
	v_add_f32_e32 v7, 1.0, v12
	v_mul_f32_e32 v12, 0x3d000000, v71
	v_mul_f32_e32 v13, 0xbfb8aa3b, v12
	v_rcp_f32_e32 v7, v7
	v_exp_f32_e32 v13, v13
	v_mul_f32_e32 v14, 0x3d000000, v66
	v_mul_f32_e32 v16, 0x3d000000, v68
	v_mul_f32_e32 v7, v10, v7
	v_add_f32_e32 v10, 1.0, v13
	v_rcp_f32_e32 v10, v10
	v_mul_f32_e32 v7, v14, v7
	v_mul_f32_e32 v13, 0x3d000000, v67
	v_mul_f32_e32 v7, 4.0, v7
	v_mul_f32_e32 v10, v12, v10
	v_mul_f32_e32 v12, 0x3d000000, v72
	v_mul_f32_e32 v14, 0xbfb8aa3b, v12
	v_exp_f32_e32 v14, v14
	v_mul_f32_e32 v10, v13, v10
	v_mul_f32_e32 v10, 4.0, v10
	v_med3_f32 v7, v7, s55, v197
	v_add_f32_e32 v13, 1.0, v14
	v_mul_f32_e32 v14, 0x3d000000, v73
	v_mul_f32_e32 v15, 0xbfb8aa3b, v14
	v_rcp_f32_e32 v13, v13
	v_exp_f32_e32 v15, v15
	v_med3_f32 v10, v10, s55, v197
	v_cvt_pk_fp8_f32 v7, v7, v10
	v_mul_f32_e32 v12, v12, v13
	v_add_f32_e32 v13, 1.0, v15
	v_rcp_f32_e32 v13, v13
	v_mul_f32_e32 v15, 0x3d000000, v69
	v_mul_f32_e32 v12, v16, v12
	v_mul_f32_e32 v12, 4.0, v12
	v_mul_f32_e32 v13, v14, v13
	v_mul_f32_e32 v10, v15, v13
	v_mul_f32_e32 v10, 4.0, v10
	v_med3_f32 v12, v12, s55, v197
	v_med3_f32 v10, v10, s55, v197
	v_cvt_pk_fp8_f32 v7, v12, v10 op_sel:[0,0,1]
	v_mul_f32_e32 v10, 0x3d000000, v62
	v_mul_f32_e32 v12, 0xbfb8aa3b, v10
	v_exp_f32_e32 v12, v12
	v_lshl_add_u64 v[8:9], v[8:9], 0, v[2:3]
	global_store_dword v[8:9], v11, off
	global_store_dword v[8:9], v7, off offset:64
	v_mul_f32_e32 v9, 0x3d000000, v63
	v_add_f32_e32 v8, 1.0, v12
	v_mul_f32_e32 v11, 0xbfb8aa3b, v9
	v_rcp_f32_e32 v8, v8
	v_exp_f32_e32 v11, v11
	v_mul_f32_e32 v12, 0x3d000000, v58
	v_mul_f32_e32 v14, 0x3d000000, v60
	v_mul_f32_e32 v8, v10, v8
	v_add_f32_e32 v10, 1.0, v11
	v_rcp_f32_e32 v10, v10
	v_mul_f32_e32 v8, v12, v8
	v_mul_f32_e32 v8, 4.0, v8
	v_med3_f32 v11, v8, s55, v197
	v_mul_f32_e32 v9, v9, v10
	v_mul_f32_e32 v10, 0x3d000000, v64
	v_mul_f32_e32 v12, 0xbfb8aa3b, v10
	v_exp_f32_e32 v12, v12
	v_mul_f32_e32 v8, 0x3d000000, v59
	v_mul_f32_e32 v8, v8, v9
	v_mul_f32_e32 v8, 4.0, v8
	v_add_f32_e32 v9, 1.0, v12
	v_mul_f32_e32 v12, 0x3d000000, v65
	v_mul_f32_e32 v13, 0xbfb8aa3b, v12
	v_rcp_f32_e32 v9, v9
	v_exp_f32_e32 v13, v13
	v_med3_f32 v8, v8, s55, v197
	v_cvt_pk_fp8_f32 v11, v11, v8
	v_mul_f32_e32 v9, v10, v9
	v_add_f32_e32 v10, 1.0, v13
	v_rcp_f32_e32 v10, v10
	v_mul_f32_e32 v13, 0x3d000000, v61
	v_mul_f32_e32 v9, v14, v9
	v_mul_f32_e32 v9, 4.0, v9
	v_mul_f32_e32 v10, v12, v10
	v_mul_f32_e32 v8, v13, v10
	v_mul_f32_e32 v8, 4.0, v8
	v_med3_f32 v9, v9, s55, v197
	v_med3_f32 v8, v8, s55, v197
	v_mul_f32_e32 v10, 0x3d000000, v54
	v_cvt_pk_fp8_f32 v11, v9, v8 op_sel:[0,0,1]
	v_mul_f32_e32 v8, 0xbfb8aa3b, v10
	v_exp_f32_e32 v12, v8
	v_add_u32_e32 v7, 0x90, v6
	v_mad_i64_i32 v[8:9], s[24:25], v7, s58, v[4:5]
	v_add_f32_e32 v7, 1.0, v12
	v_mul_f32_e32 v12, 0x3d000000, v55
	v_mul_f32_e32 v13, 0xbfb8aa3b, v12
	v_rcp_f32_e32 v7, v7
	v_exp_f32_e32 v13, v13
	v_mul_f32_e32 v14, 0x3d000000, v50
	v_mul_f32_e32 v16, 0x3d000000, v52
	v_mul_f32_e32 v7, v10, v7
	v_add_f32_e32 v10, 1.0, v13
	v_rcp_f32_e32 v10, v10
	v_mul_f32_e32 v7, v14, v7
	v_mul_f32_e32 v13, 0x3d000000, v51
	v_mul_f32_e32 v7, 4.0, v7
	v_mul_f32_e32 v10, v12, v10
	v_mul_f32_e32 v12, 0x3d000000, v56
	v_mul_f32_e32 v14, 0xbfb8aa3b, v12
	v_exp_f32_e32 v14, v14
	v_mul_f32_e32 v10, v13, v10
	v_mul_f32_e32 v10, 4.0, v10
	v_med3_f32 v7, v7, s55, v197
	v_add_f32_e32 v13, 1.0, v14
	v_mul_f32_e32 v14, 0x3d000000, v57
	v_mul_f32_e32 v15, 0xbfb8aa3b, v14
	v_rcp_f32_e32 v13, v13
	v_exp_f32_e32 v15, v15
	v_med3_f32 v10, v10, s55, v197
	v_cvt_pk_fp8_f32 v7, v7, v10
	v_mul_f32_e32 v12, v12, v13
	v_add_f32_e32 v13, 1.0, v15
	v_rcp_f32_e32 v13, v13
	v_mul_f32_e32 v15, 0x3d000000, v53
	v_mul_f32_e32 v12, v16, v12
	v_mul_f32_e32 v12, 4.0, v12
	v_mul_f32_e32 v13, v14, v13
	v_mul_f32_e32 v10, v15, v13
	v_mul_f32_e32 v10, 4.0, v10
	v_med3_f32 v12, v12, s55, v197
	v_med3_f32 v10, v10, s55, v197
	v_cvt_pk_fp8_f32 v7, v12, v10 op_sel:[0,0,1]
	v_mul_f32_e32 v10, 0x3d000000, v46
	v_mul_f32_e32 v12, 0xbfb8aa3b, v10
	v_exp_f32_e32 v12, v12
	v_lshl_add_u64 v[8:9], v[8:9], 0, v[2:3]
	global_store_dword v[8:9], v11, off
	global_store_dword v[8:9], v7, off offset:64
	v_mul_f32_e32 v9, 0x3d000000, v47
	v_add_f32_e32 v8, 1.0, v12
	v_mul_f32_e32 v11, 0xbfb8aa3b, v9
	v_rcp_f32_e32 v8, v8
	v_exp_f32_e32 v11, v11
	v_mul_f32_e32 v12, 0x3d000000, v42
	v_mul_f32_e32 v14, 0x3d000000, v44
	v_mul_f32_e32 v8, v10, v8
	v_add_f32_e32 v10, 1.0, v11
	v_rcp_f32_e32 v10, v10
	v_mul_f32_e32 v8, v12, v8
	v_mul_f32_e32 v8, 4.0, v8
	v_med3_f32 v11, v8, s55, v197
	v_mul_f32_e32 v9, v9, v10
	v_mul_f32_e32 v10, 0x3d000000, v48
	v_mul_f32_e32 v12, 0xbfb8aa3b, v10
	v_exp_f32_e32 v12, v12
	v_mul_f32_e32 v8, 0x3d000000, v43
	v_mul_f32_e32 v8, v8, v9
	v_mul_f32_e32 v8, 4.0, v8
	v_add_f32_e32 v9, 1.0, v12
	v_mul_f32_e32 v12, 0x3d000000, v49
	v_mul_f32_e32 v13, 0xbfb8aa3b, v12
	v_rcp_f32_e32 v9, v9
	v_exp_f32_e32 v13, v13
	v_med3_f32 v8, v8, s55, v197
	v_cvt_pk_fp8_f32 v11, v11, v8
	v_mul_f32_e32 v9, v10, v9
	v_add_f32_e32 v10, 1.0, v13
	v_rcp_f32_e32 v10, v10
	v_mul_f32_e32 v13, 0x3d000000, v45
	v_mul_f32_e32 v9, v14, v9
	v_mul_f32_e32 v9, 4.0, v9
	v_mul_f32_e32 v10, v12, v10
	v_mul_f32_e32 v8, v13, v10
	v_mul_f32_e32 v8, 4.0, v8
	v_med3_f32 v9, v9, s55, v197
	v_med3_f32 v8, v8, s55, v197
	v_mul_f32_e32 v10, 0x3d000000, v38
	v_cvt_pk_fp8_f32 v11, v9, v8 op_sel:[0,0,1]
	v_mul_f32_e32 v8, 0xbfb8aa3b, v10
	v_exp_f32_e32 v12, v8
	v_add_u32_e32 v7, 0xa0, v6
	v_mad_i64_i32 v[8:9], s[24:25], v7, s58, v[4:5]
	v_add_f32_e32 v7, 1.0, v12
	v_mul_f32_e32 v12, 0x3d000000, v39
	v_mul_f32_e32 v13, 0xbfb8aa3b, v12
	v_rcp_f32_e32 v7, v7
	v_exp_f32_e32 v13, v13
	v_mul_f32_e32 v14, 0x3d000000, v34
	v_mul_f32_e32 v16, 0x3d000000, v36
	v_mul_f32_e32 v7, v10, v7
	v_add_f32_e32 v10, 1.0, v13
	v_rcp_f32_e32 v10, v10
	v_mul_f32_e32 v7, v14, v7
	v_mul_f32_e32 v13, 0x3d000000, v35
	v_mul_f32_e32 v7, 4.0, v7
	v_mul_f32_e32 v10, v12, v10
	v_mul_f32_e32 v12, 0x3d000000, v40
	v_mul_f32_e32 v14, 0xbfb8aa3b, v12
	v_exp_f32_e32 v14, v14
	v_mul_f32_e32 v10, v13, v10
	v_mul_f32_e32 v10, 4.0, v10
	v_med3_f32 v7, v7, s55, v197
	v_add_f32_e32 v13, 1.0, v14
	v_mul_f32_e32 v14, 0x3d000000, v41
	v_mul_f32_e32 v15, 0xbfb8aa3b, v14
	v_rcp_f32_e32 v13, v13
	v_exp_f32_e32 v15, v15
	v_med3_f32 v10, v10, s55, v197
	v_cvt_pk_fp8_f32 v7, v7, v10
	v_mul_f32_e32 v12, v12, v13
	v_add_f32_e32 v13, 1.0, v15
	v_rcp_f32_e32 v13, v13
	v_mul_f32_e32 v15, 0x3d000000, v37
	v_mul_f32_e32 v12, v16, v12
	v_mul_f32_e32 v12, 4.0, v12
	v_mul_f32_e32 v13, v14, v13
	v_mul_f32_e32 v10, v15, v13
	v_mul_f32_e32 v10, 4.0, v10
	v_med3_f32 v12, v12, s55, v197
	v_med3_f32 v10, v10, s55, v197
	v_cvt_pk_fp8_f32 v7, v12, v10 op_sel:[0,0,1]
	v_lshl_add_u64 v[8:9], v[8:9], 0, v[2:3]
	v_mul_f32_e32 v10, 0x3d000000, v30
	global_store_dword v[8:9], v11, off
	global_store_dword v[8:9], v7, off offset:64
	v_mul_f32_e32 v8, 0x3d000000, v31
	v_mul_f32_e32 v12, 0xbfb8aa3b, v10
	v_mul_f32_e32 v9, 0xbfb8aa3b, v8
	v_exp_f32_e32 v12, v12
	v_exp_f32_e32 v9, v9
	v_mul_f32_e32 v11, 0x3d000000, v26
	v_mul_f32_e32 v13, 0x3d000000, v28
	v_add_f32_e32 v7, 1.0, v12
	v_add_f32_e32 v9, 1.0, v9
	v_rcp_f32_e32 v7, v7
	v_rcp_f32_e32 v9, v9
	v_mul_f32_e32 v14, 0x3d000000, v20
	v_add_u32_e32 v6, 0xb0, v6
	v_mul_f32_e32 v7, v10, v7
	v_mul_f32_e32 v8, v8, v9
	v_mul_f32_e32 v9, 0x3d000000, v32
	v_mul_f32_e32 v7, v11, v7
	v_mul_f32_e32 v11, 0xbfb8aa3b, v9
	v_exp_f32_e32 v11, v11
	v_mul_f32_e32 v10, 0x3d000000, v27
	v_mul_f32_e32 v8, v10, v8
	v_mul_f32_e32 v7, 4.0, v7
	v_add_f32_e32 v10, 1.0, v11
	v_mul_f32_e32 v11, 0x3d000000, v33
	v_mul_f32_e32 v12, 0xbfb8aa3b, v11
	v_rcp_f32_e32 v10, v10
	v_exp_f32_e32 v12, v12
	v_mul_f32_e32 v8, 4.0, v8
	v_med3_f32 v7, v7, s55, v197
	v_mul_f32_e32 v9, v9, v10
	v_add_f32_e32 v10, 1.0, v12
	v_rcp_f32_e32 v10, v10
	v_med3_f32 v8, v8, s55, v197
	v_cvt_pk_fp8_f32 v7, v7, v8
	v_mul_f32_e32 v8, 0x3d000000, v22
	v_mul_f32_e32 v12, 0x3d000000, v29
	v_mul_f32_e32 v10, v11, v10
	v_mul_f32_e32 v11, 0xbfb8aa3b, v8
	v_mul_f32_e32 v9, v13, v9
	v_mul_f32_e32 v10, v12, v10
	v_exp_f32_e32 v11, v11
	v_mul_f32_e32 v9, 4.0, v9
	v_mul_f32_e32 v10, 4.0, v10
	v_med3_f32 v9, v9, s55, v197
	v_med3_f32 v10, v10, s55, v197
	v_cvt_pk_fp8_f32 v7, v9, v10 op_sel:[0,0,1]
	v_mul_f32_e32 v10, 0x3d000000, v23
	v_add_f32_e32 v9, 1.0, v11
	v_mul_f32_e32 v11, 0xbfb8aa3b, v10
	v_rcp_f32_e32 v9, v9
	v_exp_f32_e32 v11, v11
	v_mul_f32_e32 v12, 0x3d000000, v18
	v_mad_i64_i32 v[4:5], s[24:25], v6, s58, v[4:5]
	v_mul_f32_e32 v8, v8, v9
	v_add_f32_e32 v9, 1.0, v11
	v_rcp_f32_e32 v9, v9
	v_mul_f32_e32 v8, v12, v8
	v_mul_f32_e32 v11, 0x3d000000, v19
	v_mul_f32_e32 v8, 4.0, v8
	v_mul_f32_e32 v9, v10, v9
	v_mul_f32_e32 v10, 0x3d000000, v24
	v_mul_f32_e32 v12, 0xbfb8aa3b, v10
	v_exp_f32_e32 v12, v12
	v_mul_f32_e32 v9, v11, v9
	v_mul_f32_e32 v9, 4.0, v9
	v_med3_f32 v8, v8, s55, v197
	v_add_f32_e32 v11, 1.0, v12
	v_mul_f32_e32 v12, 0x3d000000, v25
	v_mul_f32_e32 v13, 0xbfb8aa3b, v12
	v_rcp_f32_e32 v11, v11
	v_exp_f32_e32 v13, v13
	v_med3_f32 v9, v9, s55, v197
	v_cvt_pk_fp8_f32 v8, v8, v9
	v_mul_f32_e32 v10, v10, v11
	v_add_f32_e32 v11, 1.0, v13
	v_rcp_f32_e32 v11, v11
	v_mul_f32_e32 v13, 0x3d000000, v21
	v_mul_f32_e32 v10, v14, v10
	v_mul_f32_e32 v10, 4.0, v10
	v_mul_f32_e32 v11, v12, v11
	v_mul_f32_e32 v9, v13, v11
	v_mul_f32_e32 v9, 4.0, v9
	v_med3_f32 v10, v10, s55, v197
	v_med3_f32 v9, v9, s55, v197
	v_cvt_pk_fp8_f32 v8, v10, v9 op_sel:[0,0,1]
	v_lshl_add_u64 v[2:3], v[4:5], 0, v[2:3]
	v_mov_b32_e32 v200, v161
	v_mov_b32_e32 v158, v163
	v_mov_b32_e32 v160, v198
	v_mov_b32_e32 v162, v199
	s_mov_b32 s22, s18
	s_mov_b32 s60, s59
	s_mov_b64 s[24:25], s[20:21]
	global_store_dword v[2:3], v7, off
	global_store_dword v[2:3], v8, off offset:64
	s_cbranch_vccz .LBB0_5613
	s_waitcnt vmcnt(0)
	s_cmpk_gt_u32 s31, 0xff
	s_cbranch_scc1 .LBB0_5620
	s_barrier

.LBB0_5692:
	ds_read_b128 v[2:5], v167
	ds_read_b128 v[6:9], v171
	ds_read_b128 v[10:13], v172
	ds_read_b128 v[14:17], v173
	s_add_u32 s28, s26, 0x100
	s_addc_u32 s29, s27, 0
	s_cmp_eq_u32 s70, 18
	s_cselect_b32 s35, s9, s29
	s_cselect_b32 s34, s8, s28
	s_cselect_b32 s31, s11, s69
	s_cselect_b32 s30, s10, s68
	v_lshl_add_u64 v[158:159], s[26:27], 0, v[152:153]
	s_add_i32 m0, s41, 0xc000
	ds_read_b128 v[186:189], v184
	ds_read_b128 v[190:193], v184 offset:1024
	ds_read_b128 v[194:197], v184 offset:2048
	ds_read_b128 v[198:201], v184 offset:3072
	ds_read_b128 v[202:205], v184 offset:4096
	ds_read_b128 v[206:209], v184 offset:5120
	ds_read_b128 v[210:213], v184 offset:6144
	ds_read_b128 v[214:217], v184 offset:7168
	global_load_lds_dwordx4 v[158:159], off
	v_lshl_add_u64 v[158:159], s[26:27], 0, v[150:151]
	s_add_i32 m0, s41, 0xe000
	s_nop 0
	global_load_lds_dwordx4 v[158:159], off
	s_waitcnt lgkmcnt(8)
	s_barrier
	s_waitcnt lgkmcnt(0)
	s_setprio 1
	s_waitcnt lgkmcnt(0)
	v_mfma_f32_16x16x128_f8f6f4 v[142:145], v[2:9], v[186:193], v[142:145]
	v_mfma_f32_16x16x128_f8f6f4 v[138:141], v[10:17], v[186:193], v[138:141]
	v_mfma_f32_16x16x128_f8f6f4 v[134:137], v[2:9], v[194:201], v[134:137]
	v_mfma_f32_16x16x128_f8f6f4 v[130:133], v[10:17], v[194:201], v[130:133]
	v_mfma_f32_16x16x128_f8f6f4 v[110:113], v[2:9], v[202:209], v[110:113]
	v_mfma_f32_16x16x128_f8f6f4 v[106:109], v[10:17], v[202:209], v[106:109]
	v_mfma_f32_16x16x128_f8f6f4 v[102:105], v[2:9], v[210:217], v[102:105]
	v_mfma_f32_16x16x128_f8f6f4 v[98:101], v[10:17], v[210:217], v[98:101]
	s_setprio 0
	s_barrier
	s_mov_b32 m0, s42
	v_lshl_add_u64 v[158:159], s[30:31], 0, v[146:147]
	ds_read_b128 v[220:223], v168
	ds_read_b128 v[224:227], v174
	ds_read_b128 v[228:231], v175
	ds_read_b128 v[232:235], v176
	global_load_lds_dwordx4 v[158:159], off
	v_lshl_add_u64 v[160:161], s[30:31], 0, v[148:149]
	s_mov_b32 m0, s43
	s_nop 0
	global_load_lds_dwordx4 v[160:161], off
	s_barrier
	s_waitcnt lgkmcnt(0)
	s_setprio 1
	s_waitcnt lgkmcnt(0)
	v_mfma_f32_16x16x128_f8f6f4 v[126:129], v[220:227], v[186:193], v[126:129]
	v_mfma_f32_16x16x128_f8f6f4 v[122:125], v[228:235], v[186:193], v[122:125]
	v_mfma_f32_16x16x128_f8f6f4 v[118:121], v[220:227], v[194:201], v[118:121]
	v_mfma_f32_16x16x128_f8f6f4 v[114:117], v[228:235], v[194:201], v[114:117]
	v_mfma_f32_16x16x128_f8f6f4 v[94:97], v[220:227], v[202:209], v[94:97]
	v_mfma_f32_16x16x128_f8f6f4 v[90:93], v[228:235], v[202:209], v[90:93]
	v_mfma_f32_16x16x128_f8f6f4 v[86:89], v[220:227], v[210:217], v[86:89]
	v_mfma_f32_16x16x128_f8f6f4 v[82:85], v[228:235], v[210:217], v[82:85]
	s_setprio 0
	s_mov_b32 m0, s41
	v_lshl_add_u64 v[162:163], s[34:35], 0, v[146:147]
	s_barrier
	ds_read_b128 v[186:189], v184 offset:16384
	ds_read_b128 v[190:193], v184 offset:17408
	ds_read_b128 v[194:197], v184 offset:18432
	ds_read_b128 v[198:201], v184 offset:19456
	ds_read_b128 v[202:205], v184 offset:20480
	ds_read_b128 v[206:209], v184 offset:21504
	ds_read_b128 v[210:213], v184 offset:22528
	ds_read_b128 v[214:217], v184 offset:23552
	global_load_lds_dwordx4 v[162:163], off
	v_lshl_add_u64 v[164:165], s[34:35], 0, v[148:149]
	s_mov_b32 m0, s44
	s_nop 0
	global_load_lds_dwordx4 v[164:165], off
	s_barrier
	s_waitcnt lgkmcnt(0)
	s_setprio 1
	s_waitcnt lgkmcnt(0)
	v_mfma_f32_16x16x128_f8f6f4 v[78:81], v[2:9], v[186:193], v[78:81]
	v_mfma_f32_16x16x128_f8f6f4 v[74:77], v[10:17], v[186:193], v[74:77]
	v_mfma_f32_16x16x128_f8f6f4 v[70:73], v[2:9], v[194:201], v[70:73]
	v_mfma_f32_16x16x128_f8f6f4 v[66:69], v[10:17], v[194:201], v[66:69]
	v_mfma_f32_16x16x128_f8f6f4 v[46:49], v[2:9], v[202:209], v[46:49]
	v_mfma_f32_16x16x128_f8f6f4 v[42:45], v[10:17], v[202:209], v[42:45]
	v_mfma_f32_16x16x128_f8f6f4 v[38:41], v[2:9], v[210:217], v[38:41]
	v_mfma_f32_16x16x128_f8f6f4 v[34:37], v[10:17], v[210:217], v[34:37]
	s_setprio 0
	s_barrier
	s_add_u32 s26, s30, 0x58000
	s_addc_u32 s27, s31, 0
	s_mov_b32 m0, s45
	v_lshl_add_u64 v[2:3], s[26:27], 0, v[146:147]
	global_load_lds_dwordx4 v[2:3], off
	v_lshl_add_u64 v[2:3], s[26:27], 0, v[148:149]
	s_mov_b32 m0, s46
	s_nop 0
	global_load_lds_dwordx4 v[2:3], off
	s_waitcnt vmcnt(6)
	s_barrier
	s_setprio 1
	v_mfma_f32_16x16x128_f8f6f4 v[62:65], v[220:227], v[186:193], v[62:65]
	v_mfma_f32_16x16x128_f8f6f4 v[58:61], v[228:235], v[186:193], v[58:61]
	v_mfma_f32_16x16x128_f8f6f4 v[54:57], v[220:227], v[194:201], v[54:57]
	v_mfma_f32_16x16x128_f8f6f4 v[50:53], v[228:235], v[194:201], v[50:53]
	v_mfma_f32_16x16x128_f8f6f4 v[30:33], v[220:227], v[202:209], v[30:33]
	v_mfma_f32_16x16x128_f8f6f4 v[26:29], v[228:235], v[202:209], v[26:29]
	v_mfma_f32_16x16x128_f8f6f4 v[22:25], v[220:227], v[210:217], v[22:25]
	v_mfma_f32_16x16x128_f8f6f4 v[18:21], v[228:235], v[210:217], v[18:21]
	s_setprio 0
	s_barrier
	ds_read_b128 v[2:5], v169
	ds_read_b128 v[6:9], v177
	ds_read_b128 v[10:13], v178
	ds_read_b128 v[14:17], v179
	s_add_u32 s26, s34, 0x58000
	s_addc_u32 s27, s35, 0
	s_mov_b32 m0, s47
	v_lshl_add_u64 v[220:221], s[26:27], 0, v[146:147]
	ds_read_b128 v[186:189], v184 offset:32768
	ds_read_b128 v[190:193], v184 offset:33792
	ds_read_b128 v[194:197], v184 offset:34816
	ds_read_b128 v[198:201], v184 offset:35840
	ds_read_b128 v[202:205], v184 offset:36864
	ds_read_b128 v[206:209], v184 offset:37888
	ds_read_b128 v[210:213], v184 offset:38912
	ds_read_b128 v[214:217], v184 offset:39936
	global_load_lds_dwordx4 v[220:221], off
	v_lshl_add_u64 v[220:221], s[26:27], 0, v[148:149]
	s_mov_b32 m0, s48
	s_nop 0
	global_load_lds_dwordx4 v[220:221], off
	s_waitcnt lgkmcnt(8)
	s_barrier
	s_waitcnt lgkmcnt(0)
	s_setprio 1
	s_waitcnt lgkmcnt(0)
	v_mfma_f32_16x16x128_f8f6f4 v[142:145], v[2:9], v[186:193], v[142:145]
	v_mfma_f32_16x16x128_f8f6f4 v[138:141], v[10:17], v[186:193], v[138:141]
	v_mfma_f32_16x16x128_f8f6f4 v[134:137], v[2:9], v[194:201], v[134:137]
	v_mfma_f32_16x16x128_f8f6f4 v[130:133], v[10:17], v[194:201], v[130:133]
	v_mfma_f32_16x16x128_f8f6f4 v[110:113], v[2:9], v[202:209], v[110:113]
	v_mfma_f32_16x16x128_f8f6f4 v[106:109], v[10:17], v[202:209], v[106:109]
	v_mfma_f32_16x16x128_f8f6f4 v[102:105], v[2:9], v[210:217], v[102:105]
	v_mfma_f32_16x16x128_f8f6f4 v[98:101], v[10:17], v[210:217], v[98:101]
	s_setprio 0
	s_barrier
	s_mov_b32 m0, s50
	v_lshl_add_u64 v[158:159], v[158:159], 0, s[18:19]
	ds_read_b128 v[220:223], v170
	ds_read_b128 v[224:227], v180
	ds_read_b128 v[228:231], v181
	ds_read_b128 v[232:235], v182
	global_load_lds_dwordx4 v[158:159], off
	v_lshl_add_u64 v[158:159], v[160:161], 0, s[18:19]
	s_mov_b32 m0, s51
	s_nop 0
	global_load_lds_dwordx4 v[158:159], off
	s_barrier
	s_waitcnt lgkmcnt(0)
	s_setprio 1
	s_waitcnt lgkmcnt(0)
	v_mfma_f32_16x16x128_f8f6f4 v[126:129], v[220:227], v[186:193], v[126:129]
	v_mfma_f32_16x16x128_f8f6f4 v[122:125], v[228:235], v[186:193], v[122:125]
	v_mfma_f32_16x16x128_f8f6f4 v[118:121], v[220:227], v[194:201], v[118:121]
	v_mfma_f32_16x16x128_f8f6f4 v[114:117], v[228:235], v[194:201], v[114:117]
	v_mfma_f32_16x16x128_f8f6f4 v[94:97], v[220:227], v[202:209], v[94:97]
	v_mfma_f32_16x16x128_f8f6f4 v[90:93], v[228:235], v[202:209], v[90:93]
	v_mfma_f32_16x16x128_f8f6f4 v[86:89], v[220:227], v[210:217], v[86:89]
	v_mfma_f32_16x16x128_f8f6f4 v[82:85], v[228:235], v[210:217], v[82:85]
	s_setprio 0
	s_mov_b32 m0, s52
	v_lshl_add_u64 v[158:159], v[162:163], 0, s[18:19]
	s_barrier
	ds_read_b128 v[186:189], v184 offset:49152
	ds_read_b128 v[190:193], v184 offset:50176
	ds_read_b128 v[194:197], v184 offset:51200
	ds_read_b128 v[198:201], v184 offset:52224
	ds_read_b128 v[202:205], v184 offset:53248
	ds_read_b128 v[206:209], v184 offset:54272
	ds_read_b128 v[210:213], v184 offset:55296
	ds_read_b128 v[214:217], v184 offset:56320
	global_load_lds_dwordx4 v[158:159], off
	v_lshl_add_u64 v[158:159], v[164:165], 0, s[18:19]
	s_mov_b32 m0, s53
	s_nop 0
	global_load_lds_dwordx4 v[158:159], off
	s_barrier
	s_waitcnt lgkmcnt(0)
	s_setprio 1
	s_waitcnt lgkmcnt(0)
	v_mfma_f32_16x16x128_f8f6f4 v[78:81], v[2:9], v[186:193], v[78:81]
	v_mfma_f32_16x16x128_f8f6f4 v[74:77], v[10:17], v[186:193], v[74:77]
	v_mfma_f32_16x16x128_f8f6f4 v[70:73], v[2:9], v[194:201], v[70:73]
	v_mfma_f32_16x16x128_f8f6f4 v[66:69], v[10:17], v[194:201], v[66:69]
	v_mfma_f32_16x16x128_f8f6f4 v[46:49], v[2:9], v[202:209], v[46:49]
	v_mfma_f32_16x16x128_f8f6f4 v[42:45], v[10:17], v[202:209], v[42:45]
	v_mfma_f32_16x16x128_f8f6f4 v[38:41], v[2:9], v[210:217], v[38:41]
	v_mfma_f32_16x16x128_f8f6f4 v[34:37], v[10:17], v[210:217], v[34:37]
	s_setprio 0
	s_barrier
	s_add_u32 s26, s30, 0x58080
	s_addc_u32 s27, s31, 0
	s_mov_b32 m0, s55
	v_lshl_add_u64 v[2:3], s[26:27], 0, v[146:147]
	global_load_lds_dwordx4 v[2:3], off
	v_lshl_add_u64 v[2:3], s[26:27], 0, v[148:149]
	s_mov_b32 m0, s58
	s_nop 0
	global_load_lds_dwordx4 v[2:3], off
	s_waitcnt vmcnt(6)
	s_barrier
	s_setprio 1
	v_mfma_f32_16x16x128_f8f6f4 v[62:65], v[220:227], v[186:193], v[62:65]
	v_mfma_f32_16x16x128_f8f6f4 v[58:61], v[228:235], v[186:193], v[58:61]
	v_mfma_f32_16x16x128_f8f6f4 v[54:57], v[220:227], v[194:201], v[54:57]
	v_mfma_f32_16x16x128_f8f6f4 v[50:53], v[228:235], v[194:201], v[50:53]
	v_mfma_f32_16x16x128_f8f6f4 v[30:33], v[220:227], v[202:209], v[30:33]
	v_mfma_f32_16x16x128_f8f6f4 v[26:29], v[228:235], v[202:209], v[26:29]
	v_mfma_f32_16x16x128_f8f6f4 v[22:25], v[220:227], v[210:217], v[22:25]
	v_mfma_f32_16x16x128_f8f6f4 v[18:21], v[228:235], v[210:217], v[18:21]
	s_setprio 0
	s_add_i32 s70, s70, 2
	s_add_u32 s68, s68, 0x100
	s_addc_u32 s69, s69, 0
	s_cmp_gt_u32 s70, 19
	s_mov_b64 s[26:27], s[28:29]
	s_barrier
	s_cbranch_scc0 .LBB0_5692
	v_lshl_add_u32 v6, s67, 8, v166
	v_ashrrev_i32_e32 v7, 31, v6
	v_or_b32_e32 v4, 16, v6
	s_nop 15
	s_nop 15
	v_lshl_add_u64 v[2:3], v[6:7], 2, s[16:17]
	v_ashrrev_i32_e32 v5, 31, v4
	global_load_dword v158, v[2:3], off
	v_lshl_add_u64 v[8:9], v[4:5], 2, s[16:17]
	global_load_dword v159, v[8:9], off
	s_ashr_i32 s0, s66, 31
	s_lshr_b32 s0, s0, 30
	s_add_i32 s0, s66, s0
	s_and_b32 s0, s0, 0xfffffc
	v_lshlrev_b64 v[4:5], 11, v[4:5]
	s_sub_i32 s0, s66, s0
	v_lshl_add_u64 v[14:15], s[14:15], 0, v[4:5]
	v_lshl_or_b32 v4, s0, 8, v183
	v_lshlrev_b64 v[10:11], 11, v[6:7]
	v_ashrrev_i32_e32 v5, 31, v4
	v_lshl_add_u64 v[10:11], s[14:15], 0, v[10:11]
	v_lshlrev_b64 v[16:17], 1, v[4:5]
	v_lshl_add_u64 v[4:5], v[10:11], 0, v[16:17]
	v_lshl_add_u64 v[10:11], v[14:15], 0, v[16:17]
	v_or_b32_e32 v8, 32, v6
	v_ashrrev_i32_e32 v9, 31, v8
	v_lshl_add_u64 v[12:13], v[8:9], 2, s[16:17]
	v_or_b32_e32 v6, 48, v6
	v_ashrrev_i32_e32 v7, 31, v6
	v_lshlrev_b64 v[8:9], 11, v[8:9]
	v_lshlrev_b64 v[6:7], 11, v[6:7]
	v_lshl_add_u64 v[8:9], s[14:15], 0, v[8:9]
	v_lshl_add_u64 v[6:7], s[14:15], 0, v[6:7]
	v_lshl_add_u64 v[8:9], v[8:9], 0, v[16:17]
	v_lshl_add_u64 v[6:7], v[6:7], 0, v[16:17]
	s_mov_b32 s67, s64
	s_mov_b64 s[28:29], s[10:11]
	s_mov_b64 s[26:27], s[8:9]
	s_mov_b32 s66, s65
	s_waitcnt vmcnt(0)
	v_mul_f32_e32 v14, 0x3b800000, v158
	v_pk_mul_f32 v[142:143], v[142:143], v[14:15] op_sel_hi:[1,0]
	v_pk_mul_f32 v[144:145], v[144:145], v[14:15] op_sel_hi:[1,0]
	v_pk_mul_f32 v[138:139], v[138:139], v[14:15] op_sel_hi:[1,0]
	v_pk_mul_f32 v[140:141], v[140:141], v[14:15] op_sel_hi:[1,0]
	v_pk_mul_f32 v[126:127], v[126:127], v[14:15] op_sel_hi:[1,0]
	v_pk_mul_f32 v[128:129], v[128:129], v[14:15] op_sel_hi:[1,0]
	v_pk_mul_f32 v[122:123], v[122:123], v[14:15] op_sel_hi:[1,0]
	v_pk_mul_f32 v[14:15], v[124:125], v[14:15] op_sel_hi:[1,0]
	v_mul_f32_e32 v124, 0x3b800000, v159
	v_cvt_pk_bf16_f32 v126, v126, v127
	v_cvt_pk_bf16_f32 v127, v128, v129
	v_cvt_pk_bf16_f32 v122, v122, v123
	v_cvt_pk_bf16_f32 v123, v14, v15
	v_pk_mul_f32 v[14:15], v[134:135], v[124:125] op_sel_hi:[1,0]
	v_pk_mul_f32 v[128:129], v[136:137], v[124:125] op_sel_hi:[1,0]
	v_cvt_pk_bf16_f32 v142, v142, v143
	v_cvt_pk_bf16_f32 v143, v144, v145
	v_pk_mul_f32 v[130:131], v[130:131], v[124:125] op_sel_hi:[1,0]
	v_pk_mul_f32 v[132:133], v[132:133], v[124:125] op_sel_hi:[1,0]
	v_pk_mul_f32 v[118:119], v[118:119], v[124:125] op_sel_hi:[1,0]
	v_pk_mul_f32 v[120:121], v[120:121], v[124:125] op_sel_hi:[1,0]
	v_pk_mul_f32 v[114:115], v[114:115], v[124:125] op_sel_hi:[1,0]
	v_pk_mul_f32 v[116:117], v[116:117], v[124:125] op_sel_hi:[1,0]
	v_cvt_pk_bf16_f32 v14, v14, v15
	v_cvt_pk_bf16_f32 v15, v128, v129
	v_cvt_pk_bf16_f32 v138, v138, v139
	v_cvt_pk_bf16_f32 v139, v140, v141
	global_store_dwordx2 v[4:5], v[142:143], off
	global_store_dwordx2 v[4:5], v[138:139], off offset:32
	global_store_dwordx2 v[4:5], v[126:127], off offset:256
	global_store_dwordx2 v[4:5], v[122:123], off offset:288
	v_cvt_pk_bf16_f32 v122, v130, v131
	v_cvt_pk_bf16_f32 v123, v132, v133
	v_cvt_pk_bf16_f32 v118, v118, v119
	v_cvt_pk_bf16_f32 v119, v120, v121
	v_cvt_pk_bf16_f32 v114, v114, v115
	v_cvt_pk_bf16_f32 v115, v116, v117
	global_store_dwordx2 v[10:11], v[14:15], off
	global_store_dwordx2 v[10:11], v[122:123], off offset:32
	global_store_dwordx2 v[10:11], v[118:119], off offset:256
	global_store_dwordx2 v[10:11], v[114:115], off offset:288
	global_load_dword v10, v[12:13], off
	s_nop 0
	global_load_dword v11, v[2:3], off offset:192
	s_waitcnt vmcnt(0)
	v_mul_f32_e32 v10, 0x3b800000, v10
	v_mul_f32_e32 v12, 0x3b800000, v11
	v_pk_mul_f32 v[14:15], v[110:111], v[10:11] op_sel_hi:[1,0]
	v_pk_mul_f32 v[16:17], v[112:113], v[10:11] op_sel_hi:[1,0]
	v_pk_mul_f32 v[106:107], v[106:107], v[10:11] op_sel_hi:[1,0]
	v_pk_mul_f32 v[108:109], v[108:109], v[10:11] op_sel_hi:[1,0]
	v_pk_mul_f32 v[94:95], v[94:95], v[10:11] op_sel_hi:[1,0]
	v_pk_mul_f32 v[96:97], v[96:97], v[10:11] op_sel_hi:[1,0]
	v_pk_mul_f32 v[90:91], v[90:91], v[10:11] op_sel_hi:[1,0]
	v_pk_mul_f32 v[10:11], v[92:93], v[10:11] op_sel_hi:[1,0]
	v_pk_mul_f32 v[92:93], v[102:103], v[12:13] op_sel_hi:[1,0]
	v_pk_mul_f32 v[102:103], v[104:105], v[12:13] op_sel_hi:[1,0]
	v_pk_mul_f32 v[98:99], v[98:99], v[12:13] op_sel_hi:[1,0]
	v_pk_mul_f32 v[100:101], v[100:101], v[12:13] op_sel_hi:[1,0]
	v_pk_mul_f32 v[86:87], v[86:87], v[12:13] op_sel_hi:[1,0]
	v_pk_mul_f32 v[88:89], v[88:89], v[12:13] op_sel_hi:[1,0]
	v_pk_mul_f32 v[82:83], v[82:83], v[12:13] op_sel_hi:[1,0]
	v_pk_mul_f32 v[12:13], v[84:85], v[12:13] op_sel_hi:[1,0]
	v_cvt_pk_bf16_f32 v14, v14, v15
	v_cvt_pk_bf16_f32 v15, v16, v17
	v_cvt_pk_bf16_f32 v16, v106, v107
	v_cvt_pk_bf16_f32 v17, v108, v109
	v_cvt_pk_bf16_f32 v84, v94, v95
	v_cvt_pk_bf16_f32 v85, v96, v97
	v_cvt_pk_bf16_f32 v90, v90, v91
	v_cvt_pk_bf16_f32 v91, v10, v11
	v_cvt_pk_bf16_f32 v10, v92, v93
	v_cvt_pk_bf16_f32 v11, v102, v103
	v_cvt_pk_bf16_f32 v92, v98, v99
	v_cvt_pk_bf16_f32 v93, v100, v101
	v_cvt_pk_bf16_f32 v86, v86, v87
	v_cvt_pk_bf16_f32 v87, v88, v89
	v_cvt_pk_bf16_f32 v82, v82, v83
	v_cvt_pk_bf16_f32 v83, v12, v13
	global_store_dwordx2 v[8:9], v[14:15], off
	global_store_dwordx2 v[8:9], v[16:17], off offset:32
	global_store_dwordx2 v[8:9], v[84:85], off offset:256
	global_store_dwordx2 v[8:9], v[90:91], off offset:288
	global_store_dwordx2 v[6:7], v[10:11], off
	global_store_dwordx2 v[6:7], v[92:93], off offset:32
	global_store_dwordx2 v[6:7], v[86:87], off offset:256
	global_store_dwordx2 v[6:7], v[82:83], off offset:288
	global_load_dword v14, v[2:3], off offset:512
	global_load_dword v15, v[2:3], off offset:576
	v_add_co_u32_e32 v8, vcc, s60, v4
	v_lshl_add_u64 v[6:7], v[4:5], 0, s[20:21]
	s_nop 0
	v_addc_co_u32_e32 v9, vcc, 0, v5, vcc
	v_add_co_u32_e32 v12, vcc, s61, v4
	v_lshl_add_u64 v[10:11], v[4:5], 0, s[22:23]
	s_nop 0
	v_addc_co_u32_e32 v13, vcc, 0, v5, vcc
	s_and_b64 vcc, exec, s[6:7]
	s_waitcnt vmcnt(0)
	v_mul_f32_e32 v14, 0x3b800000, v14
	v_mul_f32_e32 v16, 0x3b800000, v15
	v_pk_mul_f32 v[78:79], v[78:79], v[14:15] op_sel_hi:[1,0]
	v_pk_mul_f32 v[80:81], v[80:81], v[14:15] op_sel_hi:[1,0]
	v_pk_mul_f32 v[74:75], v[74:75], v[14:15] op_sel_hi:[1,0]
	v_pk_mul_f32 v[76:77], v[76:77], v[14:15] op_sel_hi:[1,0]
	v_pk_mul_f32 v[62:63], v[62:63], v[14:15] op_sel_hi:[1,0]
	v_pk_mul_f32 v[64:65], v[64:65], v[14:15] op_sel_hi:[1,0]
	v_pk_mul_f32 v[58:59], v[58:59], v[14:15] op_sel_hi:[1,0]
	v_pk_mul_f32 v[14:15], v[60:61], v[14:15] op_sel_hi:[1,0]
	v_pk_mul_f32 v[60:61], v[70:71], v[16:17] op_sel_hi:[1,0]
	v_pk_mul_f32 v[70:71], v[72:73], v[16:17] op_sel_hi:[1,0]
	v_pk_mul_f32 v[66:67], v[66:67], v[16:17] op_sel_hi:[1,0]
	v_pk_mul_f32 v[68:69], v[68:69], v[16:17] op_sel_hi:[1,0]
	v_pk_mul_f32 v[54:55], v[54:55], v[16:17] op_sel_hi:[1,0]
	v_pk_mul_f32 v[56:57], v[56:57], v[16:17] op_sel_hi:[1,0]
	v_pk_mul_f32 v[50:51], v[50:51], v[16:17] op_sel_hi:[1,0]
	v_pk_mul_f32 v[16:17], v[52:53], v[16:17] op_sel_hi:[1,0]
	v_cvt_pk_bf16_f32 v52, v78, v79
	v_cvt_pk_bf16_f32 v53, v80, v81
	v_cvt_pk_bf16_f32 v72, v74, v75
	v_cvt_pk_bf16_f32 v73, v76, v77
	v_cvt_pk_bf16_f32 v62, v62, v63
	v_cvt_pk_bf16_f32 v63, v64, v65
	v_cvt_pk_bf16_f32 v58, v58, v59
	v_cvt_pk_bf16_f32 v59, v14, v15
	v_cvt_pk_bf16_f32 v14, v60, v61
	v_cvt_pk_bf16_f32 v15, v70, v71
	v_cvt_pk_bf16_f32 v60, v66, v67
	v_cvt_pk_bf16_f32 v61, v68, v69
	v_cvt_pk_bf16_f32 v54, v54, v55
	v_cvt_pk_bf16_f32 v55, v56, v57
	v_cvt_pk_bf16_f32 v50, v50, v51
	v_cvt_pk_bf16_f32 v51, v16, v17
	global_store_dwordx2 v[8:9], v[52:53], off
	global_store_dwordx2 v[6:7], v[72:73], off offset:32
	global_store_dwordx2 v[6:7], v[62:63], off offset:256
	global_store_dwordx2 v[6:7], v[58:59], off offset:288
	global_store_dwordx2 v[12:13], v[14:15], off
	global_store_dwordx2 v[10:11], v[60:61], off offset:32
	global_store_dwordx2 v[10:11], v[54:55], off offset:256
	global_store_dwordx2 v[10:11], v[50:51], off offset:288
	global_load_dword v10, v[2:3], off offset:640
	s_nop 0
	global_load_dword v11, v[2:3], off offset:704
	v_add_co_u32_e64 v6, s[6:7], s62, v4
	v_lshl_add_u64 v[2:3], v[4:5], 0, s[24:25]
	s_nop 0
	v_addc_co_u32_e64 v7, s[6:7], 0, v5, s[6:7]
	v_lshl_add_u64 v[8:9], v[4:5], 0, s[12:13]
	v_add_co_u32_e64 v4, s[6:7], s63, v4
	s_waitcnt vmcnt(0)
	v_mul_f32_e32 v10, 0x3b800000, v10
	v_mul_f32_e32 v12, 0x3b800000, v11
	v_pk_mul_f32 v[14:15], v[46:47], v[10:11] op_sel_hi:[1,0]
	v_pk_mul_f32 v[16:17], v[48:49], v[10:11] op_sel_hi:[1,0]
	v_pk_mul_f32 v[42:43], v[42:43], v[10:11] op_sel_hi:[1,0]
	v_pk_mul_f32 v[44:45], v[44:45], v[10:11] op_sel_hi:[1,0]
	v_pk_mul_f32 v[30:31], v[30:31], v[10:11] op_sel_hi:[1,0]
	v_pk_mul_f32 v[32:33], v[32:33], v[10:11] op_sel_hi:[1,0]
	v_pk_mul_f32 v[26:27], v[26:27], v[10:11] op_sel_hi:[1,0]
	v_pk_mul_f32 v[10:11], v[28:29], v[10:11] op_sel_hi:[1,0]
	v_pk_mul_f32 v[28:29], v[38:39], v[12:13] op_sel_hi:[1,0]
	v_pk_mul_f32 v[38:39], v[40:41], v[12:13] op_sel_hi:[1,0]
	v_pk_mul_f32 v[34:35], v[34:35], v[12:13] op_sel_hi:[1,0]
	v_pk_mul_f32 v[36:37], v[36:37], v[12:13] op_sel_hi:[1,0]
	v_pk_mul_f32 v[22:23], v[22:23], v[12:13] op_sel_hi:[1,0]
	v_pk_mul_f32 v[24:25], v[24:25], v[12:13] op_sel_hi:[1,0]
	v_pk_mul_f32 v[18:19], v[18:19], v[12:13] op_sel_hi:[1,0]
	v_pk_mul_f32 v[12:13], v[20:21], v[12:13] op_sel_hi:[1,0]
	v_cvt_pk_bf16_f32 v14, v14, v15
	v_cvt_pk_bf16_f32 v15, v16, v17
	v_addc_co_u32_e64 v5, s[6:7], 0, v5, s[6:7]
	v_cvt_pk_bf16_f32 v16, v42, v43
	v_cvt_pk_bf16_f32 v17, v44, v45
	v_cvt_pk_bf16_f32 v20, v30, v31
	v_cvt_pk_bf16_f32 v21, v32, v33
	v_cvt_pk_bf16_f32 v26, v26, v27
	v_cvt_pk_bf16_f32 v27, v10, v11
	v_cvt_pk_bf16_f32 v10, v28, v29
	v_cvt_pk_bf16_f32 v11, v38, v39
	v_cvt_pk_bf16_f32 v28, v34, v35
	v_cvt_pk_bf16_f32 v29, v36, v37
	v_cvt_pk_bf16_f32 v22, v22, v23
	v_cvt_pk_bf16_f32 v23, v24, v25
	v_cvt_pk_bf16_f32 v18, v18, v19
	v_cvt_pk_bf16_f32 v19, v12, v13
	global_store_dwordx2 v[6:7], v[14:15], off
	global_store_dwordx2 v[2:3], v[16:17], off offset:32
	global_store_dwordx2 v[2:3], v[20:21], off offset:256
	global_store_dwordx2 v[2:3], v[26:27], off offset:288
	global_store_dwordx2 v[4:5], v[10:11], off
	global_store_dwordx2 v[8:9], v[28:29], off offset:32
	global_store_dwordx2 v[8:9], v[22:23], off offset:256
	global_store_dwordx2 v[8:9], v[18:19], off offset:288
	s_cbranch_vccz .LBB0_5681
	s_waitcnt vmcnt(0)
	s_cmpk_gt_u32 s3, 0xff
	s_cbranch_scc1 .LBB0_5696
	s_barrier
